# v6_rcp_waits_norm_xcdbarrier
# speedup vs baseline: 1.0623x; 1.0195x over previous
.LBB0_18:
	s_or_b64 exec, exec, s[0:1]
	v_mul_f32_e32 v30, v28, v28
	v_fmamk_f32 v31, v30, 0xb94c1982, v19
	v_fmaak_f32 v31, v30, v31, 0xbe2aaa9d
	v_mul_f32_e32 v31, v30, v31
	v_fmac_f32_e32 v28, v28, v31
	v_fmamk_f32 v31, v30, 0x37d75334, v20
	v_fmaak_f32 v31, v30, v31, 0x3d2aabf7
	v_fmaak_f32 v31, v30, v31, 0xbf000004
	v_fma_f32 v30, v30, v31, 1.0
	v_and_b32_e32 v31, 1, v17
	v_cmp_eq_u32_e32 vcc, 0, v31
	v_lshlrev_b32_e32 v17, 30, v17
	v_xor_b32_e32 v14, v14, v11
	v_cndmask_b32_e32 v28, v30, v28, vcc
	v_cmp_class_f32_e64 vcc, v11, s45
	v_mul_f32_e32 v11, 0x3fb8aa3b, v9
	v_and_b32_e32 v17, 0x80000000, v17
	v_rndne_f32_e32 v11, v11
	v_xor_b32_e32 v14, v14, v17
	v_fmamk_f32 v17, v11, 0xbf317218, v9
	v_fmac_f32_e32 v17, 0x3102e308, v11
	v_xor_b32_e32 v14, v14, v28
	v_fmamk_f32 v28, v17, 0x395133b1, v21
	v_fmaak_f32 v28, v17, v28, 0x3c0887f9
	v_fmaak_f32 v28, v17, v28, 0x3d2aaa81
	v_cvt_i32_f32_e32 v30, v11
	v_fmaak_f32 v28, v17, v28, 0x3e2aaaab
	v_fma_f32 v28, v17, v28, 0.5
	v_mul_f32_e32 v28, v17, v28
	v_cndmask_b32_e32 v14, v24, v14, vcc
	v_fmac_f32_e32 v17, v17, v28
	v_ldexp_f32 v28, 1.0, v30
	v_cmp_eq_f32_e32 vcc, s46, v11
	s_mov_b64 s[0:1], s[78:79]
	s_load_dwordx2 s[4:5], s[0:1], 0x100
	v_cndmask_b32_e32 v11, v28, v25, vcc
	v_add_f32_e32 v28, -1.0, v11
	v_fmac_f32_e32 v28, v11, v17
	s_mov_b64 s[0:1], s[78:79]
	v_add_f32_e32 v11, v28, v28
	s_mov_b64 s[6:7], s[78:79]
	v_cndmask_b32_e32 v11, v28, v11, vcc
	v_cmp_nlt_f32_e32 vcc, s47, v9
	s_load_dwordx2 s[0:1], s[0:1], 0x60
	s_load_dwordx2 s[6:7], s[6:7], 0x68
	v_cndmask_b32_e32 v11, v18, v11, vcc
	v_cmp_ngt_f32_e32 vcc, s48, v9
	v_mul_f32_e32 v28, v16, v16
	v_fmamk_f32 v32, v28, 0xb94c1982, v19
	v_cndmask_b32_e32 v17, -1.0, v11, vcc
	v_ashrrev_i32_e32 v11, 31, v10
	v_lshlrev_b64 v[10:11], 10, v[10:11]
	v_or3_b32 v9, 0, v11, 0
	v_or3_b32 v8, v8, v10, v34
	v_lshlrev_b64 v[10:11], 6, v[8:9]
	s_waitcnt lgkmcnt(0)
	v_lshl_add_u64 v[8:9], s[0:1], 0, v[10:11]
	v_lshl_add_u64 v[10:11], s[6:7], 0, v[10:11]
	global_load_dword v30, v[10:11], off
	global_load_dword v31, v[8:9], off
	v_fmaak_f32 v32, v28, v32, 0xbe2aaa9d
	v_mul_f32_e32 v32, v28, v32
	v_fmac_f32_e32 v16, v16, v32
	v_fmamk_f32 v32, v28, 0x37d75334, v20
	v_fmaak_f32 v32, v28, v32, 0x3d2aabf7
	v_fmaak_f32 v32, v28, v32, 0xbf000004
	v_fma_f32 v28, v28, v32, 1.0
	v_and_b32_e32 v32, 1, v15
	v_cmp_eq_u32_e32 vcc, 0, v32
	v_lshlrev_b32_e32 v15, 30, v15
	v_lshl_add_u64 v[4:5], v[4:5], 2, s[4:5]
	v_cndmask_b32_e64 v16, -v16, v28, vcc
	v_bitop3_b32 v15, v15, v16, s44 bitop3:0x6c
	v_cmp_class_f32_e64 vcc, v12, s45
	v_add_f32_e32 v16, v14, v14
	v_mul_f32_e32 v14, v14, v16
	v_cndmask_b32_e32 v15, v24, v15, vcc
	v_mul_f32_e32 v16, v29, v29
	v_fma_f32 v14, v17, v15, -v14
	v_add_f32_e32 v15, 1.0, v17
	v_fmamk_f32 v17, v16, 0xb94c1982, v19
	v_fmaak_f32 v17, v16, v17, 0xbe2aaa9d
	v_mul_f32_e32 v17, v16, v17
	v_fmac_f32_e32 v29, v29, v17
	v_fmamk_f32 v17, v16, 0x37d75334, v20
	v_fmaak_f32 v17, v16, v17, 0x3d2aabf7
	v_fmaak_f32 v17, v16, v17, 0xbf000004
	v_fma_f32 v16, v16, v17, 1.0
	v_and_b32_e32 v17, 1, v2
	v_lshlrev_b32_e32 v2, 30, v2
	v_cmp_eq_u32_e64 s[0:1], 0, v17
	v_and_b32_e32 v2, 0x80000000, v2
	v_xor_b32_e32 v12, v13, v12
	v_cndmask_b32_e64 v16, v16, v29, s[0:1]
	v_xor_b32_e32 v2, v12, v2
	v_xor_b32_e32 v2, v2, v16
	v_cndmask_b32_e32 v2, v24, v2, vcc
	v_mul_f32_e32 v2, v15, v2
	v_mul_f32_e32 v12, v27, v27
	v_mul_f32_e32 v13, v27, v2
	v_fmac_f32_e32 v12, v26, v26
	v_fmac_f32_e32 v13, v26, v14
	v_mul_f32_e32 v14, v27, v14
	v_fma_f32 v2, v26, v2, -v14
	v_rcp_f32_e32 v15, v12
	s_nop 0
	v_mul_f32_e32 v15, v13, v15
	v_add_u32_e32 v7, s26, v7
	v_rcp_f32_e32 v13, v12
	s_nop 0
	v_mul_f32_e32 v14, v2, v13
	v_lshlrev_b32_e32 v2, 7, v6
	v_lshl_add_u64 v[4:5], v[4:5], 0, v[2:3]
	v_add_co_u32_e32 v12, vcc, s49, v4
	s_waitcnt vmcnt(1)
	v_mul_f32_e32 v2, v14, v30
	s_waitcnt vmcnt(0)
	v_fma_f32 v2, v15, v31, -v2
	v_addc_co_u32_e32 v13, vcc, 0, v5, vcc
	global_store_dword v[12:13], v2, off
	global_load_dword v2, v[8:9], off
	s_nop 0
	global_load_dword v6, v[10:11], off
	v_lshl_add_u64 v[4:5], v[4:5], 0, s[22:23]
	v_cmp_lt_i32_e32 vcc, s50, v7
	s_or_b64 s[14:15], vcc, s[14:15]
	s_waitcnt vmcnt(1)
	v_mul_f32_e32 v2, v14, v2
	s_waitcnt vmcnt(0)
	v_fmac_f32_e32 v2, v15, v6
	global_store_dword v[4:5], v2, off offset:4
	global_load_dword v2, v[10:11], off offset:4
	s_nop 0
	global_load_dword v6, v[8:9], off offset:4
	s_waitcnt vmcnt(1)
	v_mul_f32_e32 v2, v14, v2
	s_waitcnt vmcnt(0)
	v_fma_f32 v2, v15, v6, -v2
	global_store_dword v[4:5], v2, off offset:8
	global_load_dword v2, v[8:9], off offset:4
	s_nop 0
	global_load_dword v6, v[10:11], off offset:4
	s_waitcnt vmcnt(1)
	v_mul_f32_e32 v2, v14, v2
	s_waitcnt vmcnt(0)
	v_fmac_f32_e32 v2, v15, v6
	global_store_dword v[4:5], v2, off offset:12
	global_load_dword v2, v[10:11], off offset:8
	s_nop 0
	global_load_dword v6, v[8:9], off offset:8
	s_waitcnt vmcnt(1)
	v_mul_f32_e32 v2, v14, v2
	s_waitcnt vmcnt(0)
	v_fma_f32 v2, v15, v6, -v2
	global_store_dword v[4:5], v2, off offset:16
	global_load_dword v2, v[8:9], off offset:8
	s_nop 0
	global_load_dword v6, v[10:11], off offset:8
	s_waitcnt vmcnt(1)
	v_mul_f32_e32 v2, v14, v2
	s_waitcnt vmcnt(0)
	v_fmac_f32_e32 v2, v15, v6
	global_store_dword v[4:5], v2, off offset:20
	global_load_dword v2, v[10:11], off offset:12
	s_nop 0
	global_load_dword v6, v[8:9], off offset:12
	s_waitcnt vmcnt(1)
	v_mul_f32_e32 v2, v14, v2
	s_waitcnt vmcnt(0)
	v_fma_f32 v2, v15, v6, -v2
	global_store_dword v[4:5], v2, off offset:24
	global_load_dword v2, v[8:9], off offset:12
	s_nop 0
	global_load_dword v6, v[10:11], off offset:12
	s_waitcnt vmcnt(1)
	v_mul_f32_e32 v2, v14, v2
	s_waitcnt vmcnt(0)
	v_fmac_f32_e32 v2, v15, v6
	global_store_dword v[4:5], v2, off offset:28
	global_load_dword v2, v[10:11], off offset:16
	s_nop 0
	global_load_dword v6, v[8:9], off offset:16
	s_waitcnt vmcnt(1)
	v_mul_f32_e32 v2, v14, v2
	s_waitcnt vmcnt(0)
	v_fma_f32 v2, v15, v6, -v2
	global_store_dword v[4:5], v2, off offset:32
	global_load_dword v2, v[8:9], off offset:16
	s_nop 0
	global_load_dword v6, v[10:11], off offset:16
	s_waitcnt vmcnt(1)
	v_mul_f32_e32 v2, v14, v2
	s_waitcnt vmcnt(0)
	v_fmac_f32_e32 v2, v15, v6
	global_store_dword v[4:5], v2, off offset:36
	global_load_dword v2, v[10:11], off offset:20
	s_nop 0
	global_load_dword v6, v[8:9], off offset:20
	s_waitcnt vmcnt(1)
	v_mul_f32_e32 v2, v14, v2
	s_waitcnt vmcnt(0)
	v_fma_f32 v2, v15, v6, -v2
	global_store_dword v[4:5], v2, off offset:40
	global_load_dword v2, v[8:9], off offset:20
	s_nop 0
	global_load_dword v6, v[10:11], off offset:20
	s_waitcnt vmcnt(1)
	v_mul_f32_e32 v2, v14, v2
	s_waitcnt vmcnt(0)
	v_fmac_f32_e32 v2, v15, v6
	global_store_dword v[4:5], v2, off offset:44
	global_load_dword v2, v[10:11], off offset:24
	s_nop 0
	global_load_dword v6, v[8:9], off offset:24
	s_waitcnt vmcnt(1)
	v_mul_f32_e32 v2, v14, v2
	s_waitcnt vmcnt(0)
	v_fma_f32 v2, v15, v6, -v2
	global_store_dword v[4:5], v2, off offset:48
	global_load_dword v2, v[8:9], off offset:24
	s_nop 0
	global_load_dword v6, v[10:11], off offset:24
	s_waitcnt vmcnt(1)
	v_mul_f32_e32 v2, v14, v2
	s_waitcnt vmcnt(0)
	v_fmac_f32_e32 v2, v15, v6
	global_store_dword v[4:5], v2, off offset:52
	global_load_dword v2, v[10:11], off offset:28
	s_nop 0
	global_load_dword v6, v[8:9], off offset:28
	s_waitcnt vmcnt(1)
	v_mul_f32_e32 v2, v14, v2
	s_waitcnt vmcnt(0)
	v_fma_f32 v2, v15, v6, -v2
	global_store_dword v[4:5], v2, off offset:56
	global_load_dword v2, v[8:9], off offset:28
	s_nop 0
	global_load_dword v6, v[10:11], off offset:28
	s_waitcnt vmcnt(1)
	v_mul_f32_e32 v2, v14, v2
	s_waitcnt vmcnt(0)
	v_fmac_f32_e32 v2, v15, v6
	global_store_dword v[4:5], v2, off offset:60
	global_load_dword v2, v[10:11], off offset:32
	s_nop 0
	global_load_dword v6, v[8:9], off offset:32
	s_waitcnt vmcnt(1)
	v_mul_f32_e32 v2, v14, v2
	s_waitcnt vmcnt(0)
	v_fma_f32 v2, v15, v6, -v2
	global_store_dword v[4:5], v2, off offset:64
	global_load_dword v2, v[8:9], off offset:32
	s_nop 0
	global_load_dword v6, v[10:11], off offset:32
	s_waitcnt vmcnt(1)
	v_mul_f32_e32 v2, v14, v2
	s_waitcnt vmcnt(0)
	v_fmac_f32_e32 v2, v15, v6
	global_store_dword v[4:5], v2, off offset:68
	global_load_dword v2, v[10:11], off offset:36
	s_nop 0
	global_load_dword v6, v[8:9], off offset:36
	s_waitcnt vmcnt(1)
	v_mul_f32_e32 v2, v14, v2
	s_waitcnt vmcnt(0)
	v_fma_f32 v2, v15, v6, -v2
	global_store_dword v[4:5], v2, off offset:72
	global_load_dword v2, v[8:9], off offset:36
	s_nop 0
	global_load_dword v6, v[10:11], off offset:36
	s_waitcnt vmcnt(1)
	v_mul_f32_e32 v2, v14, v2
	s_waitcnt vmcnt(0)
	v_fmac_f32_e32 v2, v15, v6
	global_store_dword v[4:5], v2, off offset:76
	global_load_dword v2, v[10:11], off offset:40
	s_nop 0
	global_load_dword v6, v[8:9], off offset:40
	s_waitcnt vmcnt(1)
	v_mul_f32_e32 v2, v14, v2
	s_waitcnt vmcnt(0)
	v_fma_f32 v2, v15, v6, -v2
	global_store_dword v[4:5], v2, off offset:80
	global_load_dword v2, v[8:9], off offset:40
	s_nop 0
	global_load_dword v6, v[10:11], off offset:40
	s_waitcnt vmcnt(1)
	v_mul_f32_e32 v2, v14, v2
	s_waitcnt vmcnt(0)
	v_fmac_f32_e32 v2, v15, v6
	global_store_dword v[4:5], v2, off offset:84
	global_load_dword v2, v[10:11], off offset:44
	s_nop 0
	global_load_dword v6, v[8:9], off offset:44
	s_waitcnt vmcnt(1)
	v_mul_f32_e32 v2, v14, v2
	s_waitcnt vmcnt(0)
	v_fma_f32 v2, v15, v6, -v2
	global_store_dword v[4:5], v2, off offset:88
	global_load_dword v2, v[8:9], off offset:44
	s_nop 0
	global_load_dword v6, v[10:11], off offset:44
	s_waitcnt vmcnt(1)
	v_mul_f32_e32 v2, v14, v2
	s_waitcnt vmcnt(0)
	v_fmac_f32_e32 v2, v15, v6
	global_store_dword v[4:5], v2, off offset:92
	global_load_dword v2, v[10:11], off offset:48
	s_nop 0
	global_load_dword v6, v[8:9], off offset:48
	s_waitcnt vmcnt(1)
	v_mul_f32_e32 v2, v14, v2
	s_waitcnt vmcnt(0)
	v_fma_f32 v2, v15, v6, -v2
	global_store_dword v[4:5], v2, off offset:96
	global_load_dword v2, v[8:9], off offset:48
	s_nop 0
	global_load_dword v6, v[10:11], off offset:48
	s_waitcnt vmcnt(1)
	v_mul_f32_e32 v2, v14, v2
	s_waitcnt vmcnt(0)
	v_fmac_f32_e32 v2, v15, v6
	global_store_dword v[4:5], v2, off offset:100
	global_load_dword v2, v[10:11], off offset:52
	s_nop 0
	global_load_dword v6, v[8:9], off offset:52
	s_waitcnt vmcnt(1)
	v_mul_f32_e32 v2, v14, v2
	s_waitcnt vmcnt(0)
	v_fma_f32 v2, v15, v6, -v2
	global_store_dword v[4:5], v2, off offset:104
	global_load_dword v2, v[8:9], off offset:52
	s_nop 0
	global_load_dword v6, v[10:11], off offset:52
	s_waitcnt vmcnt(1)
	v_mul_f32_e32 v2, v14, v2
	s_waitcnt vmcnt(0)
	v_fmac_f32_e32 v2, v15, v6
	global_store_dword v[4:5], v2, off offset:108
	global_load_dword v2, v[10:11], off offset:56
	s_nop 0
	global_load_dword v6, v[8:9], off offset:56
	s_waitcnt vmcnt(1)
	v_mul_f32_e32 v2, v14, v2
	s_waitcnt vmcnt(0)
	v_fma_f32 v2, v15, v6, -v2
	global_store_dword v[4:5], v2, off offset:112
	global_load_dword v2, v[8:9], off offset:56
	s_nop 0
	global_load_dword v6, v[10:11], off offset:56
	s_waitcnt vmcnt(1)
	v_mul_f32_e32 v2, v14, v2
	s_waitcnt vmcnt(0)
	v_fmac_f32_e32 v2, v15, v6
	global_store_dword v[4:5], v2, off offset:116
	global_load_dword v2, v[10:11], off offset:60
	s_nop 0
	global_load_dword v6, v[8:9], off offset:60
	s_waitcnt vmcnt(1)
	v_mul_f32_e32 v2, v14, v2
	s_waitcnt vmcnt(0)
	v_fma_f32 v2, v15, v6, -v2
	global_store_dword v[4:5], v2, off offset:120
	global_load_dword v2, v[8:9], off offset:60
	s_nop 0
	global_load_dword v6, v[10:11], off offset:60
	s_waitcnt vmcnt(1)
	v_mul_f32_e32 v2, v14, v2
	s_waitcnt vmcnt(0)
	v_fmac_f32_e32 v2, v15, v6
	global_store_dword v[4:5], v2, off offset:124
	s_andn2_b64 exec, exec, s[14:15]
	s_cbranch_execz .LBB0_41

.LBB0_44:
	s_or_b64 exec, exec, s[0:1]
	v_lshlrev_b32_e32 v2, 2, v6
	v_and_b32_e32 v2, 0xff0, v2
	v_lshl_add_u64 v[4:5], v[4:5], 0, v[2:3]
	global_load_dwordx4 v[10:13], v[4:5], off
	v_add_u32_e32 v15, 0x200, v7
	v_cmp_lt_i32_e32 vcc, s14, v7
	v_mul_i32_i24_e32 v14, 0x1010, v8
	s_or_b64 s[12:13], vcc, s[12:13]
	v_add3_u32 v2, 0, v14, v2
	v_add_u32_e32 v6, 0x800, v6
	s_waitcnt vmcnt(0)
	v_mul_f32_e32 v7, 0xbfb8aa3b, v12
	v_mul_f32_e32 v9, 0xbfb8aa3b, v13
	v_exp_f32_e32 v8, v7
	v_exp_f32_e32 v9, v9
	v_mul_f32_e32 v4, 0xbfb8aa3b, v10
	v_mul_f32_e32 v5, 0xbfb8aa3b, v11
	v_exp_f32_e32 v4, v4
	v_exp_f32_e32 v5, v5
	v_pk_add_f32 v[8:9], v[8:9], 1.0 op_sel_hi:[1,0]
	v_pk_add_f32 v[4:5], v[4:5], 1.0 op_sel_hi:[1,0]
	s_mov_b64 vcc, s[0:1]
	v_rcp_f32_e32 v7, v9
	s_nop 0
	v_mul_f32_e32 v13, v13, v7
	s_mov_b64 vcc, s[4:5]
	v_rcp_f32_e32 v7, v8
	s_nop 0
	v_mul_f32_e32 v12, v12, v7
	s_mov_b64 vcc, s[6:7]
	v_rcp_f32_e32 v7, v5
	s_nop 0
	v_mul_f32_e32 v11, v11, v7
	v_rcp_f32_e32 v5, v4
	s_nop 0
	v_mul_f32_e32 v10, v10, v5
	v_mov_b32_e32 v7, v15
	ds_write_b128 v2, v[10:13]
	s_andn2_b64 exec, exec, s[12:13]
	s_cbranch_execz .LBB0_49

.LBB0_55:
	v_lshrrev_b32_e32 v1, 20, v0
	v_lshrrev_b32_e32 v0, 10, v0
	s_waitcnt vmcnt(0) lgkmcnt(0)
	v_or_b32_e32 v0, v0, v1
	s_movk_i32 s0, 0x3ff
	v_and_or_b32 v0, v0, s0, v224
	v_cmp_eq_u32_e32 vcc, 0, v0
	s_mov_b64 s[6:7], s[78:79]
	s_getreg_b32 s8, hwreg(HW_REG_XCC_ID, 0, 4)
	s_waitcnt vmcnt(0)
	s_barrier
	s_mov_b64 s[4:5], exec
	v_readlane_b32 s10, v252, 0
	v_readlane_b32 s11, v252, 1
	s_and_b64 s[10:11], s[4:5], s[10:11]
	s_mov_b64 exec, s[10:11]
	s_cbranch_execz .Lgs_227
	s_add_i32 s9, 0, 0x27ff0
	v_mov_b32_e32 v0, s9
	s_load_dwordx2 s[6:7], s[6:7], 0x100
	s_waitcnt vmcnt(0) expcnt(0) lgkmcnt(0)
	ds_read_b32 v2, v0
	s_add_i32 s9, 0, 0x27ff4
	v_mov_b32_e32 v0, s9
	ds_read_b32 v0, v0
	s_and_b32 s50, s8, 15
	s_waitcnt lgkmcnt(1)
	v_cmp_ne_u32_e32 vcc, 0, v2
	s_cbranch_vccnz .Lgs_191
	s_add_u32 s8, s6, 0x3b314200
	s_addc_u32 s9, s7, 0
	s_add_u32 s10, s6, 0x3b314400
	s_addc_u32 s11, s7, 0
	s_add_u32 s12, s6, 0x3b314500
	s_addc_u32 s13, s7, 0
	s_add_u32 s14, s6, 0x3b314600
	s_addc_u32 s15, s7, 0
	s_add_u32 s16, s6, 0x3b314700
	s_addc_u32 s17, s7, 0
	s_add_u32 s18, s6, 0x3b314800
	s_addc_u32 s19, s7, 0
	s_add_u32 s20, s6, 0x3b314900
	s_addc_u32 s21, s7, 0
	s_add_u32 s22, s6, 0x3b314a00
	s_addc_u32 s23, s7, 0
	s_add_u32 s24, s6, 0x3b314b00
	s_addc_u32 s25, s7, 0
	s_add_u32 s26, s6, 0x3b314c00
	s_addc_u32 s27, s7, 0
	s_add_u32 s28, s6, 0x3b314d00
	s_addc_u32 s29, s7, 0
	s_add_u32 s30, s6, 0x3b314e00
	s_addc_u32 s31, s7, 0
	s_add_u32 s34, s6, 0x3b314f00
	s_addc_u32 s35, s7, 0
	s_add_u32 s36, s6, 0x3b315000
	s_addc_u32 s37, s7, 0
	s_add_u32 s38, s6, 0x3b315100
	s_addc_u32 s39, s7, 0
	s_add_u32 s40, s6, 0x3b315200
	s_addc_u32 s41, s7, 0
	s_mul_i32 s51, s65, s33
	s_add_u32 s42, s6, 0x3b315300
	s_mul_i32 s51, s51, s64
	s_addc_u32 s43, s7, 0
	s_mov_b32 s52, 1
	v_mov_b32_e32 v16, 0
	s_branch .Lgs_179

.Lgs_227:
	s_or_b64 exec, exec, s[4:5]
	s_lshl_b32 s38, s2, 9
	v_mov_b32_e32 v4, v224
	s_barrier
	s_mov_b64 s[4:5], s[78:79]
	v_readfirstlane_b32 s0, v4
	s_ashr_i32 s40, s0, 6
	s_mul_i32 s0, s40, 0x2100
	s_add_i32 s41, s0, 0
	s_mov_b64 s[0:1], s[78:79]
	s_load_dwordx2 s[0:1], s[0:1], 0x100
	s_load_dwordx2 s[8:9], s[4:5], 0x40
	s_lshl_b32 s70, s2, 3
	s_lshl_b32 s63, s64, 3
	s_add_i32 s39, s40, s70
	v_and_b32_e32 v0, 63, v4
	s_cmpk_lt_i32 s39, 0xe0
	s_cselect_b64 s[4:5], -1, 0
	s_cmpk_gt_i32 s39, 0xdf
	v_lshrrev_b32_e32 v12, 5, v0
	v_lshlrev_b32_e32 v15, 2, v4
	v_lshrrev_b32_e32 v13, 3, v0
	v_lshlrev_b32_e32 v14, 3, v0
	s_cbranch_scc1 .LBB0_68
	v_and_b32_e32 v2, 0x7c, v15
	v_mov_b32_e32 v3, 0
	s_waitcnt lgkmcnt(0)
	v_lshl_add_u64 v[0:1], s[8:9], 0, v[2:3]
	v_add_u32_e32 v6, s41, v2
	v_mul_u32_u24_e32 v7, 0x84, v12
	v_and_b32_e32 v2, 56, v14
	v_mul_u32_u24_e32 v5, 0x84, v2
	v_lshlrev_b32_e32 v2, 1, v2
	v_lshlrev_b32_e32 v8, 2, v13
	s_lshl_b32 s3, s2, 8
	s_lshl_b32 s6, s40, 5
	v_add_u32_e32 v6, v6, v7
	v_lshl_add_u64 v[2:3], s[0:1], 0, v[2:3]
	v_add3_u32 v5, s41, v5, v8
	s_add_i32 s3, s3, s6
	s_lshl_b32 s12, s64, 8
	s_movk_i32 s13, 0x5880
	v_add_u32_e32 v7, 0x400, v6
	v_add_u32_e32 v8, 0x800, v6
	v_add_u32_e32 v9, 0xc00, v6
	v_add_u32_e32 v10, 0x1000, v6
	v_add_u32_e32 v11, 0x1400, v6
	v_add_u32_e32 v16, 0x1800, v6
	v_add_u32_e32 v17, 0x1c00, v6
	s_mov_b32 s14, s39

.LBB0_822:
	s_add_u32 s12, s10, 0x100
	s_addc_u32 s13, s11, 0
	s_add_i32 s42, 0, 0x10000
	v_add_u32_e32 v158, s42, v147
	ds_read_b128 v[142:145], v158
	ds_read_b128 v[150:153], v158 offset:1024
	ds_read_b128 v[154:157], v158 offset:2048
	ds_read_b128 v[158:161], v158 offset:3072
	s_cmp_eq_u32 s41, 8
	s_cselect_b32 s17, s5, s13
	s_cselect_b32 s16, s4, s12
	s_cselect_b32 s15, s7, s40
	s_cselect_b32 s14, s6, s39
	v_lshl_add_u64 v[198:199], s[10:11], 0, v[138:139]
	s_add_i32 m0, s24, 0xc000
	ds_read_b128 v[162:165], v149
	ds_read_b128 v[166:169], v149 offset:1024
	ds_read_b128 v[170:173], v149 offset:2048
	ds_read_b128 v[174:177], v149 offset:3072
	ds_read_b128 v[178:181], v149 offset:4096
	ds_read_b128 v[182:185], v149 offset:5120
	ds_read_b128 v[186:189], v149 offset:6144
	ds_read_b128 v[190:193], v149 offset:7168
	global_load_lds_dwordx4 v[198:199], off
	v_lshl_add_u64 v[198:199], s[10:11], 0, v[140:141]
	s_add_i32 m0, s24, 0xe000
	s_nop 0
	global_load_lds_dwordx4 v[198:199], off
	s_waitcnt lgkmcnt(8)
	s_barrier
	s_waitcnt lgkmcnt(0)
	s_setprio 1
	s_waitcnt lgkmcnt(0)
	v_mfma_f32_16x16x32_bf16 v[126:129], v[142:145], v[162:165], v[126:129]
	v_mfma_f32_16x16x32_bf16 v[122:125], v[154:157], v[162:165], v[122:125]
	v_mfma_f32_16x16x32_bf16 v[110:113], v[142:145], v[170:173], v[110:113]
	v_mfma_f32_16x16x32_bf16 v[106:109], v[154:157], v[170:173], v[106:109]
	v_mfma_f32_16x16x32_bf16 v[94:97], v[142:145], v[178:181], v[94:97]
	v_mfma_f32_16x16x32_bf16 v[90:93], v[154:157], v[178:181], v[90:93]
	v_mfma_f32_16x16x32_bf16 v[78:81], v[142:145], v[186:189], v[78:81]
	v_mfma_f32_16x16x32_bf16 v[74:77], v[154:157], v[186:189], v[74:77]
	v_mfma_f32_16x16x32_bf16 v[126:129], v[150:153], v[166:169], v[126:129]
	v_mfma_f32_16x16x32_bf16 v[122:125], v[158:161], v[166:169], v[122:125]
	v_mfma_f32_16x16x32_bf16 v[110:113], v[150:153], v[174:177], v[110:113]
	v_mfma_f32_16x16x32_bf16 v[106:109], v[158:161], v[174:177], v[106:109]
	v_mfma_f32_16x16x32_bf16 v[94:97], v[150:153], v[182:185], v[94:97]
	v_mfma_f32_16x16x32_bf16 v[90:93], v[158:161], v[182:185], v[90:93]
	v_mfma_f32_16x16x32_bf16 v[78:81], v[150:153], v[190:193], v[78:81]
	v_mfma_f32_16x16x32_bf16 v[74:77], v[158:161], v[190:193], v[74:77]
	s_setprio 0
	s_barrier
	s_add_i32 s43, 0, 0x14000
	s_add_i32 s10, s42, s23
	v_add_u32_e32 v210, s43, v147
	v_lshl_add_u64 v[214:215], s[14:15], 0, v[134:135]
	s_mov_b32 m0, s10
	ds_read_b128 v[198:201], v210
	ds_read_b128 v[202:205], v210 offset:1024
	ds_read_b128 v[206:209], v210 offset:2048
	ds_read_b128 v[210:213], v210 offset:3072
	global_load_lds_dwordx4 v[214:215], off
	v_lshl_add_u64 v[216:217], s[14:15], 0, v[130:131]
	s_add_i32 m0, s10, 0x2000
	s_nop 0
	global_load_lds_dwordx4 v[216:217], off
	s_barrier
	s_waitcnt lgkmcnt(0)
	s_setprio 1
	s_waitcnt lgkmcnt(0)
	v_mfma_f32_16x16x32_bf16 v[118:121], v[198:201], v[162:165], v[118:121]
	v_mfma_f32_16x16x32_bf16 v[114:117], v[206:209], v[162:165], v[114:117]
	v_mfma_f32_16x16x32_bf16 v[102:105], v[198:201], v[170:173], v[102:105]
	v_mfma_f32_16x16x32_bf16 v[98:101], v[206:209], v[170:173], v[98:101]
	v_mfma_f32_16x16x32_bf16 v[86:89], v[198:201], v[178:181], v[86:89]
	v_mfma_f32_16x16x32_bf16 v[82:85], v[206:209], v[178:181], v[82:85]
	v_mfma_f32_16x16x32_bf16 v[70:73], v[198:201], v[186:189], v[70:73]
	v_mfma_f32_16x16x32_bf16 v[66:69], v[206:209], v[186:189], v[66:69]
	v_mfma_f32_16x16x32_bf16 v[118:121], v[202:205], v[166:169], v[118:121]
	v_mfma_f32_16x16x32_bf16 v[114:117], v[210:213], v[166:169], v[114:117]
	v_mfma_f32_16x16x32_bf16 v[102:105], v[202:205], v[174:177], v[102:105]
	v_mfma_f32_16x16x32_bf16 v[98:101], v[210:213], v[174:177], v[98:101]
	v_mfma_f32_16x16x32_bf16 v[86:89], v[202:205], v[182:185], v[86:89]
	v_mfma_f32_16x16x32_bf16 v[82:85], v[210:213], v[182:185], v[82:85]
	v_mfma_f32_16x16x32_bf16 v[70:73], v[202:205], v[190:193], v[70:73]
	v_mfma_f32_16x16x32_bf16 v[66:69], v[210:213], v[190:193], v[66:69]
	s_setprio 0
	s_mov_b32 m0, s24
	v_lshl_add_u64 v[218:219], s[16:17], 0, v[136:137]
	s_barrier
	ds_read_b128 v[162:165], v149 offset:16384
	ds_read_b128 v[166:169], v149 offset:17408
	ds_read_b128 v[170:173], v149 offset:18432
	ds_read_b128 v[174:177], v149 offset:19456
	ds_read_b128 v[178:181], v149 offset:20480
	ds_read_b128 v[182:185], v149 offset:21504
	ds_read_b128 v[186:189], v149 offset:22528
	ds_read_b128 v[190:193], v149 offset:23552
	global_load_lds_dwordx4 v[218:219], off
	v_lshl_add_u64 v[220:221], s[16:17], 0, v[132:133]
	s_mov_b32 m0, s25
	s_nop 0
	global_load_lds_dwordx4 v[220:221], off
	s_barrier
	s_waitcnt lgkmcnt(0)
	s_setprio 1
	s_waitcnt lgkmcnt(0)
	v_mfma_f32_16x16x32_bf16 v[62:65], v[142:145], v[162:165], v[62:65]
	v_mfma_f32_16x16x32_bf16 v[58:61], v[154:157], v[162:165], v[58:61]
	v_mfma_f32_16x16x32_bf16 v[44:47], v[142:145], v[170:173], v[44:47]
	v_mfma_f32_16x16x32_bf16 v[40:43], v[154:157], v[170:173], v[40:43]
	v_mfma_f32_16x16x32_bf16 v[28:31], v[142:145], v[178:181], v[28:31]
	v_mfma_f32_16x16x32_bf16 v[24:27], v[154:157], v[178:181], v[24:27]
	v_mfma_f32_16x16x32_bf16 v[12:15], v[142:145], v[186:189], v[12:15]
	v_mfma_f32_16x16x32_bf16 v[8:11], v[154:157], v[186:189], v[8:11]
	v_mfma_f32_16x16x32_bf16 v[62:65], v[150:153], v[166:169], v[62:65]
	v_mfma_f32_16x16x32_bf16 v[58:61], v[158:161], v[166:169], v[58:61]
	v_mfma_f32_16x16x32_bf16 v[44:47], v[150:153], v[174:177], v[44:47]
	v_mfma_f32_16x16x32_bf16 v[40:43], v[158:161], v[174:177], v[40:43]
	v_mfma_f32_16x16x32_bf16 v[28:31], v[150:153], v[182:185], v[28:31]
	v_mfma_f32_16x16x32_bf16 v[24:27], v[158:161], v[182:185], v[24:27]
	v_mfma_f32_16x16x32_bf16 v[12:15], v[150:153], v[190:193], v[12:15]
	v_mfma_f32_16x16x32_bf16 v[8:11], v[158:161], v[190:193], v[8:11]
	s_setprio 0
	s_barrier
	s_add_u32 s10, s14, 0x30000
	s_addc_u32 s11, s15, 0
	s_add_i32 s42, s43, s23
	v_lshl_add_u64 v[142:143], s[10:11], 0, v[134:135]
	s_mov_b32 m0, s42
	s_nop 0
	global_load_lds_dwordx4 v[142:143], off
	v_lshl_add_u64 v[142:143], s[10:11], 0, v[130:131]
	s_add_i32 m0, s42, 0x2000
	s_nop 0
	global_load_lds_dwordx4 v[142:143], off
	s_waitcnt vmcnt(6)
	s_barrier
	s_setprio 1
	v_mfma_f32_16x16x32_bf16 v[54:57], v[198:201], v[162:165], v[54:57]
	v_mfma_f32_16x16x32_bf16 v[50:53], v[206:209], v[162:165], v[50:53]
	v_mfma_f32_16x16x32_bf16 v[36:39], v[198:201], v[170:173], v[36:39]
	v_mfma_f32_16x16x32_bf16 v[32:35], v[206:209], v[170:173], v[32:35]
	v_mfma_f32_16x16x32_bf16 v[20:23], v[198:201], v[178:181], v[20:23]
	v_mfma_f32_16x16x32_bf16 v[16:19], v[206:209], v[178:181], v[16:19]
	v_mfma_f32_16x16x32_bf16 v[4:7], v[198:201], v[186:189], v[4:7]
	v_mfma_f32_16x16x32_bf16 v[0:3], v[206:209], v[186:189], v[0:3]
	v_mfma_f32_16x16x32_bf16 v[54:57], v[202:205], v[166:169], v[54:57]
	v_mfma_f32_16x16x32_bf16 v[50:53], v[210:213], v[166:169], v[50:53]
	v_mfma_f32_16x16x32_bf16 v[36:39], v[202:205], v[174:177], v[36:39]
	v_mfma_f32_16x16x32_bf16 v[32:35], v[210:213], v[174:177], v[32:35]
	v_mfma_f32_16x16x32_bf16 v[20:23], v[202:205], v[182:185], v[20:23]
	v_mfma_f32_16x16x32_bf16 v[16:19], v[210:213], v[182:185], v[16:19]
	v_mfma_f32_16x16x32_bf16 v[4:7], v[202:205], v[190:193], v[4:7]
	v_mfma_f32_16x16x32_bf16 v[0:3], v[210:213], v[190:193], v[0:3]
	s_setprio 0
	s_add_i32 s42, 0, 0x18000
	v_add_u32_e32 v158, s42, v147
	s_barrier
	ds_read_b128 v[142:145], v158
	ds_read_b128 v[150:153], v158 offset:1024
	ds_read_b128 v[154:157], v158 offset:2048
	ds_read_b128 v[158:161], v158 offset:3072
	s_add_u32 s10, s16, 0x30000
	s_addc_u32 s11, s17, 0
	s_mov_b32 m0, s26
	v_lshl_add_u64 v[198:199], s[10:11], 0, v[136:137]
	ds_read_b128 v[162:165], v149 offset:32768
	ds_read_b128 v[166:169], v149 offset:33792
	ds_read_b128 v[170:173], v149 offset:34816
	ds_read_b128 v[174:177], v149 offset:35840
	ds_read_b128 v[178:181], v149 offset:36864
	ds_read_b128 v[182:185], v149 offset:37888
	ds_read_b128 v[186:189], v149 offset:38912
	ds_read_b128 v[190:193], v149 offset:39936
	global_load_lds_dwordx4 v[198:199], off
	v_lshl_add_u64 v[198:199], s[10:11], 0, v[132:133]
	s_mov_b32 m0, s27
	s_nop 0
	global_load_lds_dwordx4 v[198:199], off
	s_waitcnt lgkmcnt(8)
	s_barrier
	s_waitcnt lgkmcnt(0)
	s_setprio 1
	s_waitcnt lgkmcnt(0)
	v_mfma_f32_16x16x32_bf16 v[126:129], v[142:145], v[162:165], v[126:129]
	v_mfma_f32_16x16x32_bf16 v[122:125], v[154:157], v[162:165], v[122:125]
	v_mfma_f32_16x16x32_bf16 v[110:113], v[142:145], v[170:173], v[110:113]
	v_mfma_f32_16x16x32_bf16 v[106:109], v[154:157], v[170:173], v[106:109]
	v_mfma_f32_16x16x32_bf16 v[94:97], v[142:145], v[178:181], v[94:97]
	v_mfma_f32_16x16x32_bf16 v[90:93], v[154:157], v[178:181], v[90:93]
	v_mfma_f32_16x16x32_bf16 v[78:81], v[142:145], v[186:189], v[78:81]
	v_mfma_f32_16x16x32_bf16 v[74:77], v[154:157], v[186:189], v[74:77]
	v_mfma_f32_16x16x32_bf16 v[126:129], v[150:153], v[166:169], v[126:129]
	v_mfma_f32_16x16x32_bf16 v[122:125], v[158:161], v[166:169], v[122:125]
	v_mfma_f32_16x16x32_bf16 v[110:113], v[150:153], v[174:177], v[110:113]
	v_mfma_f32_16x16x32_bf16 v[106:109], v[158:161], v[174:177], v[106:109]
	v_mfma_f32_16x16x32_bf16 v[94:97], v[150:153], v[182:185], v[94:97]
	v_mfma_f32_16x16x32_bf16 v[90:93], v[158:161], v[182:185], v[90:93]
	v_mfma_f32_16x16x32_bf16 v[78:81], v[150:153], v[190:193], v[78:81]
	v_mfma_f32_16x16x32_bf16 v[74:77], v[158:161], v[190:193], v[74:77]
	s_setprio 0
	s_barrier
	s_add_i32 s16, 0, 0x1c000
	s_add_i32 s10, s42, s23
	v_add_u32_e32 v210, s16, v147
	v_lshl_add_u64 v[214:215], v[214:215], 0, s[66:67]
	s_mov_b32 m0, s10
	ds_read_b128 v[198:201], v210
	ds_read_b128 v[202:205], v210 offset:1024
	ds_read_b128 v[206:209], v210 offset:2048
	ds_read_b128 v[210:213], v210 offset:3072
	global_load_lds_dwordx4 v[214:215], off
	v_lshl_add_u64 v[214:215], v[216:217], 0, s[66:67]
	s_add_i32 m0, s10, 0x2000
	s_nop 0
	global_load_lds_dwordx4 v[214:215], off
	s_barrier
	s_waitcnt lgkmcnt(0)
	s_setprio 1
	s_waitcnt lgkmcnt(0)
	v_mfma_f32_16x16x32_bf16 v[118:121], v[198:201], v[162:165], v[118:121]
	v_mfma_f32_16x16x32_bf16 v[114:117], v[206:209], v[162:165], v[114:117]
	v_mfma_f32_16x16x32_bf16 v[102:105], v[198:201], v[170:173], v[102:105]
	v_mfma_f32_16x16x32_bf16 v[98:101], v[206:209], v[170:173], v[98:101]
	v_mfma_f32_16x16x32_bf16 v[86:89], v[198:201], v[178:181], v[86:89]
	v_mfma_f32_16x16x32_bf16 v[82:85], v[206:209], v[178:181], v[82:85]
	v_mfma_f32_16x16x32_bf16 v[70:73], v[198:201], v[186:189], v[70:73]
	v_mfma_f32_16x16x32_bf16 v[66:69], v[206:209], v[186:189], v[66:69]
	v_mfma_f32_16x16x32_bf16 v[118:121], v[202:205], v[166:169], v[118:121]
	v_mfma_f32_16x16x32_bf16 v[114:117], v[210:213], v[166:169], v[114:117]
	v_mfma_f32_16x16x32_bf16 v[102:105], v[202:205], v[174:177], v[102:105]
	v_mfma_f32_16x16x32_bf16 v[98:101], v[210:213], v[174:177], v[98:101]
	v_mfma_f32_16x16x32_bf16 v[86:89], v[202:205], v[182:185], v[86:89]
	v_mfma_f32_16x16x32_bf16 v[82:85], v[210:213], v[182:185], v[82:85]
	v_mfma_f32_16x16x32_bf16 v[70:73], v[202:205], v[190:193], v[70:73]
	v_mfma_f32_16x16x32_bf16 v[66:69], v[210:213], v[190:193], v[66:69]
	s_setprio 0
	s_mov_b32 m0, s28
	v_lshl_add_u64 v[214:215], v[218:219], 0, s[66:67]
	s_barrier
	ds_read_b128 v[162:165], v149 offset:49152
	ds_read_b128 v[166:169], v149 offset:50176
	ds_read_b128 v[170:173], v149 offset:51200
	ds_read_b128 v[174:177], v149 offset:52224
	ds_read_b128 v[178:181], v149 offset:53248
	ds_read_b128 v[182:185], v149 offset:54272
	ds_read_b128 v[186:189], v149 offset:55296
	ds_read_b128 v[190:193], v149 offset:56320
	global_load_lds_dwordx4 v[214:215], off
	v_lshl_add_u64 v[214:215], v[220:221], 0, s[66:67]
	s_mov_b32 m0, s29
	s_nop 0
	global_load_lds_dwordx4 v[214:215], off
	s_barrier
	s_waitcnt lgkmcnt(0)
	s_setprio 1
	s_waitcnt lgkmcnt(0)
	v_mfma_f32_16x16x32_bf16 v[62:65], v[142:145], v[162:165], v[62:65]
	v_mfma_f32_16x16x32_bf16 v[58:61], v[154:157], v[162:165], v[58:61]
	v_mfma_f32_16x16x32_bf16 v[44:47], v[142:145], v[170:173], v[44:47]
	v_mfma_f32_16x16x32_bf16 v[40:43], v[154:157], v[170:173], v[40:43]
	v_mfma_f32_16x16x32_bf16 v[28:31], v[142:145], v[178:181], v[28:31]
	v_mfma_f32_16x16x32_bf16 v[24:27], v[154:157], v[178:181], v[24:27]
	v_mfma_f32_16x16x32_bf16 v[12:15], v[142:145], v[186:189], v[12:15]
	v_mfma_f32_16x16x32_bf16 v[8:11], v[154:157], v[186:189], v[8:11]
	v_mfma_f32_16x16x32_bf16 v[62:65], v[150:153], v[166:169], v[62:65]
	v_mfma_f32_16x16x32_bf16 v[58:61], v[158:161], v[166:169], v[58:61]
	v_mfma_f32_16x16x32_bf16 v[44:47], v[150:153], v[174:177], v[44:47]
	v_mfma_f32_16x16x32_bf16 v[40:43], v[158:161], v[174:177], v[40:43]
	v_mfma_f32_16x16x32_bf16 v[28:31], v[150:153], v[182:185], v[28:31]
	v_mfma_f32_16x16x32_bf16 v[24:27], v[158:161], v[182:185], v[24:27]
	v_mfma_f32_16x16x32_bf16 v[12:15], v[150:153], v[190:193], v[12:15]
	v_mfma_f32_16x16x32_bf16 v[8:11], v[158:161], v[190:193], v[8:11]
	s_setprio 0
	s_barrier
	s_add_u32 s10, s14, 0x30080
	s_addc_u32 s11, s15, 0
	s_add_i32 s14, s16, s23
	v_lshl_add_u64 v[142:143], s[10:11], 0, v[134:135]
	s_mov_b32 m0, s14
	s_nop 0
	global_load_lds_dwordx4 v[142:143], off
	v_lshl_add_u64 v[142:143], s[10:11], 0, v[130:131]
	s_add_i32 m0, s14, 0x2000
	s_nop 0
	global_load_lds_dwordx4 v[142:143], off
	s_waitcnt vmcnt(6)
	s_barrier
	s_setprio 1
	v_mfma_f32_16x16x32_bf16 v[54:57], v[198:201], v[162:165], v[54:57]
	v_mfma_f32_16x16x32_bf16 v[50:53], v[206:209], v[162:165], v[50:53]
	v_mfma_f32_16x16x32_bf16 v[36:39], v[198:201], v[170:173], v[36:39]
	v_mfma_f32_16x16x32_bf16 v[32:35], v[206:209], v[170:173], v[32:35]
	v_mfma_f32_16x16x32_bf16 v[20:23], v[198:201], v[178:181], v[20:23]
	v_mfma_f32_16x16x32_bf16 v[16:19], v[206:209], v[178:181], v[16:19]
	v_mfma_f32_16x16x32_bf16 v[4:7], v[198:201], v[186:189], v[4:7]
	v_mfma_f32_16x16x32_bf16 v[0:3], v[206:209], v[186:189], v[0:3]
	v_mfma_f32_16x16x32_bf16 v[54:57], v[202:205], v[166:169], v[54:57]
	v_mfma_f32_16x16x32_bf16 v[50:53], v[210:213], v[166:169], v[50:53]
	v_mfma_f32_16x16x32_bf16 v[36:39], v[202:205], v[174:177], v[36:39]
	v_mfma_f32_16x16x32_bf16 v[32:35], v[210:213], v[174:177], v[32:35]
	v_mfma_f32_16x16x32_bf16 v[20:23], v[202:205], v[182:185], v[20:23]
	v_mfma_f32_16x16x32_bf16 v[16:19], v[210:213], v[182:185], v[16:19]
	v_mfma_f32_16x16x32_bf16 v[4:7], v[202:205], v[190:193], v[4:7]
	v_mfma_f32_16x16x32_bf16 v[0:3], v[210:213], v[190:193], v[0:3]
	s_setprio 0
	s_add_i32 s41, s41, 2
	s_add_u32 s39, s39, 0x100
	s_addc_u32 s40, s40, 0
	s_cmp_gt_u32 s41, 9
	s_mov_b64 s[10:11], s[12:13]
	s_barrier
	s_cbranch_scc0 .LBB0_822
	v_lshl_add_u32 v142, s38, 8, v146
	v_ashrrev_i32_e32 v143, 31, v142
	v_lshlrev_b64 v[144:145], 14, v[142:143]
	v_mul_f32_e32 v143, 0x3d372713, v126
	v_mul_f32_e32 v143, v126, v143
	v_fma_f32 v143, v126, v143, v126
	v_mul_f32_e32 v143, 0xbfcc422a, v143
	v_mul_f32_e32 v143, 0x3fb8aa3b, v143
	v_exp_f32_e32 v150, v143
	v_mul_f32_e32 v143, 0x3d372713, v122
	v_mul_f32_e32 v143, v122, v143
	v_fma_f32 v143, v122, v143, v122
	v_mul_f32_e32 v143, 0xbfcc422a, v143
	v_mul_f32_e32 v143, 0x3fb8aa3b, v143
	v_exp_f32_e32 v152, v143
	v_mul_f32_e32 v143, 0x3d372713, v127
	v_mul_f32_e32 v143, v127, v143
	v_fma_f32 v143, v127, v143, v127
	v_mul_f32_e32 v143, 0xbfcc422a, v143
	v_mul_f32_e32 v143, 0x3fb8aa3b, v143
	v_exp_f32_e32 v151, v143
	v_lshl_or_b32 v154, s37, 8, v148
	s_lshl_b32 s10, s36, 4
	s_ashr_i32 s11, s10, 31
	v_pk_add_f32 v[150:151], v[150:151], 1.0 op_sel_hi:[1,0]
	s_lshl_b64 s[10:11], s[10:11], 1
	s_mov_b32 s36, s31
	s_mov_b32 s37, s35
	s_mov_b32 s38, s34
	v_rcp_f32_e32 v143, v151
	s_nop 0
	v_mul_f32_e32 v143, v127, v143
	s_nop 0
	v_rcp_f32_e32 v127, v150
	s_nop 0
	v_mul_f32_e32 v150, v126, v127
	v_mul_f32_e32 v126, 0x3d372713, v123
	v_mul_f32_e32 v126, v123, v126
	v_fma_f32 v126, v123, v126, v123
	v_mul_f32_e32 v126, 0xbfcc422a, v126
	v_mul_f32_e32 v126, 0x3fb8aa3b, v126
	v_exp_f32_e32 v153, v126
	v_cvt_pk_bf16_f32 v150, v150, v143
	v_pk_add_f32 v[126:127], v[152:153], 1.0 op_sel_hi:[1,0]
	s_nop 0
	s_nop 0
	v_rcp_f32_e32 v151, v127
	s_nop 0
	v_mul_f32_e32 v152, v123, v151
	s_nop 0
	v_rcp_f32_e32 v123, v126
	s_nop 0
	v_mul_f32_e32 v153, v122, v123
	v_mul_f32_e32 v123, 0x3d372713, v124
	v_mul_f32_e32 v123, v124, v123
	v_fma_f32 v123, v124, v123, v124
	v_mul_f32_e32 v123, 0xbfcc422a, v123
	v_mul_f32_e32 v123, 0x3fb8aa3b, v123
	v_mul_f32_e32 v122, 0x3d372713, v128
	v_exp_f32_e32 v126, v123
	v_mul_f32_e32 v123, 0x3d372713, v129
	v_mul_f32_e32 v122, v128, v122
	v_mul_f32_e32 v123, v129, v123
	v_fma_f32 v122, v128, v122, v128
	v_fma_f32 v123, v129, v123, v129
	v_mul_f32_e32 v122, 0xbfcc422a, v122
	v_mul_f32_e32 v123, 0xbfcc422a, v123
	v_mul_f32_e32 v122, 0x3fb8aa3b, v122
	v_mul_f32_e32 v123, 0x3fb8aa3b, v123
	v_exp_f32_e32 v122, v122
	v_exp_f32_e32 v123, v123
	v_cvt_pk_bf16_f32 v152, v153, v152
	v_pk_add_f32 v[122:123], v[122:123], 1.0 op_sel_hi:[1,0]
	s_nop 0
	s_nop 0
	v_rcp_f32_e32 v127, v123
	s_nop 0
	v_mul_f32_e32 v129, v129, v127
	s_nop 0
	v_rcp_f32_e32 v123, v122
	s_nop 0
	v_mul_f32_e32 v128, v128, v123
	v_mul_f32_e32 v122, 0x3d372713, v125
	v_mul_f32_e32 v122, v125, v122
	v_fma_f32 v122, v125, v122, v125
	v_mul_f32_e32 v122, 0xbfcc422a, v122
	v_mul_f32_e32 v122, 0x3fb8aa3b, v122
	v_exp_f32_e32 v127, v122
	s_nop 0
	v_pk_add_f32 v[122:123], v[126:127], 1.0 op_sel_hi:[1,0]
	s_nop 0
	s_nop 0
	v_rcp_f32_e32 v126, v123
	s_nop 0
	v_mul_f32_e32 v123, v125, v126
	s_nop 0
	v_ashrrev_i32_e32 v126, 4, v154
	v_ashrrev_i32_e32 v127, 31, v126
	v_rcp_f32_e32 v125, v122
	s_nop 0
	v_mul_f32_e32 v122, v124, v125
	v_lshlrev_b64 v[124:125], 9, v[126:127]
	v_mul_f32_e32 v127, 0x3d372713, v118
	v_cvt_pk_bf16_f32 v153, v122, v123
	v_lshl_add_u64 v[122:123], s[0:1], 0, v[144:145]
	v_mul_f32_e32 v127, v118, v127
	v_cvt_pk_bf16_f32 v151, v128, v129
	v_lshl_add_u64 v[128:129], v[122:123], 0, v[124:125]
	v_fma_f32 v127, v118, v127, v118
	v_lshl_add_u64 v[128:129], v[128:129], 0, s[10:11]
	v_mul_f32_e32 v127, 0xbfcc422a, v127
	v_lshl_add_u64 v[128:129], v[128:129], 0, v[48:49]
	v_mul_f32_e32 v127, 0x3fb8aa3b, v127
	global_store_dwordx4 v[128:129], v[150:153], off
	v_exp_f32_e32 v128, v127
	v_mul_f32_e32 v127, 0x3d372713, v114
	v_mul_f32_e32 v127, v114, v127
	v_fma_f32 v127, v114, v127, v114
	v_mul_f32_e32 v127, 0xbfcc422a, v127
	v_mul_f32_e32 v127, 0x3fb8aa3b, v127
	v_exp_f32_e32 v144, v127
	v_mul_f32_e32 v127, 0x3d372713, v119
	v_mul_f32_e32 v127, v119, v127
	v_fma_f32 v127, v119, v127, v119
	v_mul_f32_e32 v127, 0xbfcc422a, v127
	v_mul_f32_e32 v127, 0x3fb8aa3b, v127
	v_exp_f32_e32 v129, v127
	s_nop 0
	v_pk_add_f32 v[128:129], v[128:129], 1.0 op_sel_hi:[1,0]
	s_nop 0
	s_nop 0
	v_rcp_f32_e32 v127, v129
	s_nop 0
	v_mul_f32_e32 v127, v119, v127
	s_nop 0
	v_rcp_f32_e32 v119, v128
	s_nop 0
	v_mul_f32_e32 v128, v118, v119
	v_mul_f32_e32 v118, 0x3d372713, v115
	v_mul_f32_e32 v118, v115, v118
	v_fma_f32 v118, v115, v118, v115
	v_mul_f32_e32 v118, 0xbfcc422a, v118
	v_mul_f32_e32 v118, 0x3fb8aa3b, v118
	v_exp_f32_e32 v145, v118
	s_nop 0
	v_pk_add_f32 v[118:119], v[144:145], 1.0 op_sel_hi:[1,0]
	s_nop 0
	s_nop 0
	v_rcp_f32_e32 v129, v119
	s_nop 0
	v_mul_f32_e32 v129, v115, v129
	s_nop 0
	v_rcp_f32_e32 v115, v118
	s_nop 0
	v_mul_f32_e32 v143, v114, v115
	v_mul_f32_e32 v115, 0x3d372713, v116
	v_mul_f32_e32 v115, v116, v115
	v_fma_f32 v115, v116, v115, v116
	v_mul_f32_e32 v115, 0xbfcc422a, v115
	v_mul_f32_e32 v115, 0x3fb8aa3b, v115
	v_mul_f32_e32 v114, 0x3d372713, v120
	v_exp_f32_e32 v118, v115
	v_mul_f32_e32 v115, 0x3d372713, v121
	v_mul_f32_e32 v114, v120, v114
	v_mul_f32_e32 v115, v121, v115
	v_fma_f32 v114, v120, v114, v120
	v_fma_f32 v115, v121, v115, v121
	v_mul_f32_e32 v114, 0xbfcc422a, v114
	v_mul_f32_e32 v115, 0xbfcc422a, v115
	v_mul_f32_e32 v114, 0x3fb8aa3b, v114
	v_mul_f32_e32 v115, 0x3fb8aa3b, v115
	v_exp_f32_e32 v114, v114
	v_exp_f32_e32 v115, v115
	s_nop 0
	v_pk_add_f32 v[114:115], v[114:115], 1.0 op_sel_hi:[1,0]
	s_nop 0
	s_nop 0
	v_rcp_f32_e32 v119, v115
	s_nop 0
	v_mul_f32_e32 v121, v121, v119
	s_nop 0
	v_rcp_f32_e32 v115, v114
	s_nop 0
	v_mul_f32_e32 v120, v120, v115
	v_mul_f32_e32 v114, 0x3d372713, v117
	v_mul_f32_e32 v114, v117, v114
	v_fma_f32 v114, v117, v114, v117
	v_mul_f32_e32 v114, 0xbfcc422a, v114
	v_mul_f32_e32 v114, 0x3fb8aa3b, v114
	v_exp_f32_e32 v119, v114
	s_nop 0
	v_pk_add_f32 v[114:115], v[118:119], 1.0 op_sel_hi:[1,0]
	s_nop 0
	s_nop 0
	v_rcp_f32_e32 v118, v115
	s_nop 0
	v_mul_f32_e32 v115, v117, v118
	s_nop 0
	v_rcp_f32_e32 v117, v114
	s_nop 0
	v_mul_f32_e32 v119, v116, v117
	v_or_b32_e32 v114, 8, v126
	v_cvt_pk_bf16_f32 v119, v119, v115
	v_ashrrev_i32_e32 v115, 31, v114
	v_lshlrev_b64 v[114:115], 9, v[114:115]
	v_cvt_pk_bf16_f32 v117, v120, v121
	v_lshl_add_u64 v[120:121], v[122:123], 0, v[114:115]
	v_lshl_add_u64 v[120:121], v[120:121], 0, s[10:11]
	v_cvt_pk_bf16_f32 v116, v128, v127
	v_cvt_pk_bf16_f32 v118, v143, v129
	v_lshl_add_u64 v[120:121], v[120:121], 0, v[48:49]
	global_store_dwordx4 v[120:121], v[116:119], off
	s_nop 1
	v_mul_f32_e32 v119, 0x3d372713, v106
	v_mul_f32_e32 v119, v106, v119
	v_fma_f32 v119, v106, v119, v106
	v_mul_f32_e32 v119, 0xbfcc422a, v119
	v_mul_f32_e32 v119, 0x3fb8aa3b, v119
	v_mul_f32_e32 v118, 0x3d372713, v110
	v_exp_f32_e32 v120, v119
	v_mul_f32_e32 v119, 0x3d372713, v111
	v_mul_f32_e32 v118, v110, v118
	v_mul_f32_e32 v119, v111, v119
	v_fma_f32 v118, v110, v118, v110
	v_fma_f32 v119, v111, v119, v111
	v_mul_f32_e32 v118, 0xbfcc422a, v118
	v_mul_f32_e32 v119, 0xbfcc422a, v119
	v_mul_f32_e32 v118, 0x3fb8aa3b, v118
	v_mul_f32_e32 v119, 0x3fb8aa3b, v119
	v_exp_f32_e32 v118, v118
	v_exp_f32_e32 v119, v119
	v_or_b32_e32 v116, 16, v142
	v_ashrrev_i32_e32 v117, 31, v116
	v_lshlrev_b64 v[116:117], 14, v[116:117]
	v_pk_add_f32 v[118:119], v[118:119], 1.0 op_sel_hi:[1,0]
	s_nop 0
	s_nop 0
	v_rcp_f32_e32 v121, v119
	s_nop 0
	v_mul_f32_e32 v119, v111, v121
	s_nop 0
	v_rcp_f32_e32 v111, v118
	s_nop 0
	v_mul_f32_e32 v118, v110, v111
	v_mul_f32_e32 v110, 0x3d372713, v107
	v_mul_f32_e32 v110, v107, v110
	v_fma_f32 v110, v107, v110, v107
	v_mul_f32_e32 v110, 0xbfcc422a, v110
	v_mul_f32_e32 v110, 0x3fb8aa3b, v110
	v_exp_f32_e32 v121, v110
	s_nop 0
	v_pk_add_f32 v[110:111], v[120:121], 1.0 op_sel_hi:[1,0]
	s_nop 0
	s_nop 0
	v_rcp_f32_e32 v120, v111
	s_nop 0
	v_mul_f32_e32 v120, v107, v120
	s_nop 0
	v_rcp_f32_e32 v107, v110
	s_nop 0
	v_mul_f32_e32 v121, v106, v107
	v_mul_f32_e32 v107, 0x3d372713, v108
	v_mul_f32_e32 v107, v108, v107
	v_fma_f32 v107, v108, v107, v108
	v_mul_f32_e32 v107, 0xbfcc422a, v107
	v_mul_f32_e32 v107, 0x3fb8aa3b, v107
	v_mul_f32_e32 v106, 0x3d372713, v112
	v_exp_f32_e32 v110, v107
	v_mul_f32_e32 v107, 0x3d372713, v113
	v_mul_f32_e32 v106, v112, v106
	v_mul_f32_e32 v107, v113, v107
	v_fma_f32 v106, v112, v106, v112
	v_fma_f32 v107, v113, v107, v113
	v_mul_f32_e32 v106, 0xbfcc422a, v106
	v_mul_f32_e32 v107, 0xbfcc422a, v107
	v_mul_f32_e32 v106, 0x3fb8aa3b, v106
	v_mul_f32_e32 v107, 0x3fb8aa3b, v107
	v_exp_f32_e32 v106, v106
	v_exp_f32_e32 v107, v107
	s_nop 0
	v_pk_add_f32 v[106:107], v[106:107], 1.0 op_sel_hi:[1,0]
	s_nop 0
	s_nop 0
	v_rcp_f32_e32 v111, v107
	s_nop 0
	v_mul_f32_e32 v113, v113, v111
	s_nop 0
	v_rcp_f32_e32 v107, v106
	s_nop 0
	v_mul_f32_e32 v112, v112, v107
	v_mul_f32_e32 v106, 0x3d372713, v109
	v_mul_f32_e32 v106, v109, v106
	v_fma_f32 v106, v109, v106, v109
	v_mul_f32_e32 v106, 0xbfcc422a, v106
	v_mul_f32_e32 v106, 0x3fb8aa3b, v106
	v_exp_f32_e32 v111, v106
	s_nop 0
	v_pk_add_f32 v[106:107], v[110:111], 1.0 op_sel_hi:[1,0]
	s_nop 0
	s_nop 0
	v_rcp_f32_e32 v110, v107
	s_nop 0
	v_mul_f32_e32 v107, v109, v110
	s_nop 0
	v_rcp_f32_e32 v109, v106
	s_nop 0
	v_mul_f32_e32 v106, v108, v109
	v_cvt_pk_bf16_f32 v111, v106, v107
	v_lshl_add_u64 v[106:107], s[0:1], 0, v[116:117]
	v_cvt_pk_bf16_f32 v109, v112, v113
	v_lshl_add_u64 v[112:113], v[106:107], 0, v[124:125]
	v_lshl_add_u64 v[112:113], v[112:113], 0, s[10:11]
	v_cvt_pk_bf16_f32 v108, v118, v119
	v_cvt_pk_bf16_f32 v110, v121, v120
	v_lshl_add_u64 v[112:113], v[112:113], 0, v[48:49]
	global_store_dwordx4 v[112:113], v[108:111], off
	s_nop 1
	v_mul_f32_e32 v109, 0x3d372713, v98
	v_mul_f32_e32 v109, v98, v109
	v_fma_f32 v109, v98, v109, v98
	v_mul_f32_e32 v109, 0xbfcc422a, v109
	v_mul_f32_e32 v109, 0x3fb8aa3b, v109
	v_mul_f32_e32 v108, 0x3d372713, v102
	v_exp_f32_e32 v110, v109
	v_mul_f32_e32 v109, 0x3d372713, v103
	v_mul_f32_e32 v108, v102, v108
	v_mul_f32_e32 v109, v103, v109
	v_fma_f32 v108, v102, v108, v102
	v_fma_f32 v109, v103, v109, v103
	v_mul_f32_e32 v108, 0xbfcc422a, v108
	v_mul_f32_e32 v109, 0xbfcc422a, v109
	v_mul_f32_e32 v108, 0x3fb8aa3b, v108
	v_mul_f32_e32 v109, 0x3fb8aa3b, v109
	v_exp_f32_e32 v108, v108
	v_exp_f32_e32 v109, v109
	s_nop 0
	v_pk_add_f32 v[108:109], v[108:109], 1.0 op_sel_hi:[1,0]
	s_nop 0
	s_nop 0
	v_rcp_f32_e32 v111, v109
	s_nop 0
	v_mul_f32_e32 v109, v103, v111
	s_nop 0
	v_rcp_f32_e32 v103, v108
	s_nop 0
	v_mul_f32_e32 v108, v102, v103
	v_mul_f32_e32 v102, 0x3d372713, v99
	v_mul_f32_e32 v102, v99, v102
	v_fma_f32 v102, v99, v102, v99
	v_mul_f32_e32 v102, 0xbfcc422a, v102
	v_mul_f32_e32 v102, 0x3fb8aa3b, v102
	v_exp_f32_e32 v111, v102
	s_nop 0
	v_pk_add_f32 v[102:103], v[110:111], 1.0 op_sel_hi:[1,0]
	s_nop 0
	s_nop 0
	v_rcp_f32_e32 v110, v103
	s_nop 0
	v_mul_f32_e32 v110, v99, v110
	s_nop 0
	v_rcp_f32_e32 v99, v102
	s_nop 0
	v_mul_f32_e32 v111, v98, v99
	v_mul_f32_e32 v99, 0x3d372713, v100
	v_mul_f32_e32 v99, v100, v99
	v_fma_f32 v99, v100, v99, v100
	v_mul_f32_e32 v99, 0xbfcc422a, v99
	v_mul_f32_e32 v99, 0x3fb8aa3b, v99
	v_mul_f32_e32 v98, 0x3d372713, v104
	v_exp_f32_e32 v102, v99
	v_mul_f32_e32 v99, 0x3d372713, v105
	v_mul_f32_e32 v98, v104, v98
	v_mul_f32_e32 v99, v105, v99
	v_fma_f32 v98, v104, v98, v104
	v_fma_f32 v99, v105, v99, v105
	v_mul_f32_e32 v98, 0xbfcc422a, v98
	v_mul_f32_e32 v99, 0xbfcc422a, v99
	v_mul_f32_e32 v98, 0x3fb8aa3b, v98
	v_mul_f32_e32 v99, 0x3fb8aa3b, v99
	v_exp_f32_e32 v98, v98
	v_exp_f32_e32 v99, v99
	s_nop 0
	v_pk_add_f32 v[98:99], v[98:99], 1.0 op_sel_hi:[1,0]
	s_nop 0
	s_nop 0
	v_rcp_f32_e32 v103, v99
	s_nop 0
	v_mul_f32_e32 v105, v105, v103
	s_nop 0
	v_rcp_f32_e32 v99, v98
	s_nop 0
	v_mul_f32_e32 v104, v104, v99
	v_mul_f32_e32 v98, 0x3d372713, v101
	v_mul_f32_e32 v98, v101, v98
	v_fma_f32 v98, v101, v98, v101
	v_mul_f32_e32 v98, 0xbfcc422a, v98
	v_mul_f32_e32 v98, 0x3fb8aa3b, v98
	v_exp_f32_e32 v103, v98
	s_nop 0
	v_pk_add_f32 v[98:99], v[102:103], 1.0 op_sel_hi:[1,0]
	s_nop 0
	s_nop 0
	v_rcp_f32_e32 v102, v99
	s_nop 0
	v_mul_f32_e32 v101, v101, v102
	s_nop 0
	v_rcp_f32_e32 v99, v98
	s_nop 0
	v_mul_f32_e32 v102, v100, v99
	v_cvt_pk_bf16_f32 v101, v102, v101
	v_lshl_add_u64 v[102:103], v[106:107], 0, v[114:115]
	v_lshl_add_u64 v[102:103], v[102:103], 0, s[10:11]
	v_cvt_pk_bf16_f32 v98, v108, v109
	v_cvt_pk_bf16_f32 v99, v104, v105
	v_cvt_pk_bf16_f32 v100, v111, v110
	v_lshl_add_u64 v[102:103], v[102:103], 0, v[48:49]
	global_store_dwordx4 v[102:103], v[98:101], off
	s_nop 1
	v_mul_f32_e32 v101, 0x3d372713, v90
	v_mul_f32_e32 v101, v90, v101
	v_fma_f32 v101, v90, v101, v90
	v_mul_f32_e32 v101, 0xbfcc422a, v101
	v_mul_f32_e32 v101, 0x3fb8aa3b, v101
	v_mul_f32_e32 v100, 0x3d372713, v94
	v_exp_f32_e32 v102, v101
	v_mul_f32_e32 v101, 0x3d372713, v95
	v_mul_f32_e32 v100, v94, v100
	v_mul_f32_e32 v101, v95, v101
	v_fma_f32 v100, v94, v100, v94
	v_fma_f32 v101, v95, v101, v95
	v_mul_f32_e32 v100, 0xbfcc422a, v100
	v_mul_f32_e32 v101, 0xbfcc422a, v101
	v_mul_f32_e32 v100, 0x3fb8aa3b, v100
	v_mul_f32_e32 v101, 0x3fb8aa3b, v101
	v_exp_f32_e32 v100, v100
	v_exp_f32_e32 v101, v101
	v_or_b32_e32 v98, 32, v142
	v_ashrrev_i32_e32 v99, 31, v98
	v_lshlrev_b64 v[98:99], 14, v[98:99]
	v_pk_add_f32 v[100:101], v[100:101], 1.0 op_sel_hi:[1,0]
	s_nop 0
	s_nop 0
	v_rcp_f32_e32 v103, v101
	s_nop 0
	v_mul_f32_e32 v101, v95, v103
	s_nop 0
	v_rcp_f32_e32 v95, v100
	s_nop 0
	v_mul_f32_e32 v100, v94, v95
	v_mul_f32_e32 v94, 0x3d372713, v91
	v_mul_f32_e32 v94, v91, v94
	v_fma_f32 v94, v91, v94, v91
	v_mul_f32_e32 v94, 0xbfcc422a, v94
	v_mul_f32_e32 v94, 0x3fb8aa3b, v94
	v_exp_f32_e32 v103, v94
	s_nop 0
	v_pk_add_f32 v[94:95], v[102:103], 1.0 op_sel_hi:[1,0]
	s_nop 0
	s_nop 0
	v_rcp_f32_e32 v102, v95
	s_nop 0
	v_mul_f32_e32 v102, v91, v102
	s_nop 0
	v_rcp_f32_e32 v91, v94
	s_nop 0
	v_mul_f32_e32 v103, v90, v91
	v_mul_f32_e32 v91, 0x3d372713, v92
	v_mul_f32_e32 v91, v92, v91
	v_fma_f32 v91, v92, v91, v92
	v_mul_f32_e32 v91, 0xbfcc422a, v91
	v_mul_f32_e32 v91, 0x3fb8aa3b, v91
	v_mul_f32_e32 v90, 0x3d372713, v96
	v_exp_f32_e32 v94, v91
	v_mul_f32_e32 v91, 0x3d372713, v97
	v_mul_f32_e32 v90, v96, v90
	v_mul_f32_e32 v91, v97, v91
	v_fma_f32 v90, v96, v90, v96
	v_fma_f32 v91, v97, v91, v97
	v_mul_f32_e32 v90, 0xbfcc422a, v90
	v_mul_f32_e32 v91, 0xbfcc422a, v91
	v_mul_f32_e32 v90, 0x3fb8aa3b, v90
	v_mul_f32_e32 v91, 0x3fb8aa3b, v91
	v_exp_f32_e32 v90, v90
	v_exp_f32_e32 v91, v91
	s_nop 0
	v_pk_add_f32 v[90:91], v[90:91], 1.0 op_sel_hi:[1,0]
	s_nop 0
	s_nop 0
	v_rcp_f32_e32 v95, v91
	s_nop 0
	v_mul_f32_e32 v97, v97, v95
	s_nop 0
	v_rcp_f32_e32 v91, v90
	s_nop 0
	v_mul_f32_e32 v96, v96, v91
	v_mul_f32_e32 v90, 0x3d372713, v93
	v_mul_f32_e32 v90, v93, v90
	v_fma_f32 v90, v93, v90, v93
	v_mul_f32_e32 v90, 0xbfcc422a, v90
	v_mul_f32_e32 v90, 0x3fb8aa3b, v90
	v_exp_f32_e32 v95, v90
	s_nop 0
	v_pk_add_f32 v[90:91], v[94:95], 1.0 op_sel_hi:[1,0]
	s_nop 0
	s_nop 0
	v_rcp_f32_e32 v94, v91
	s_nop 0
	v_mul_f32_e32 v91, v93, v94
	s_nop 0
	v_rcp_f32_e32 v93, v90
	s_nop 0
	v_mul_f32_e32 v90, v92, v93
	v_cvt_pk_bf16_f32 v95, v90, v91
	v_lshl_add_u64 v[90:91], s[0:1], 0, v[98:99]
	v_cvt_pk_bf16_f32 v93, v96, v97
	v_lshl_add_u64 v[96:97], v[90:91], 0, v[124:125]
	v_lshl_add_u64 v[96:97], v[96:97], 0, s[10:11]
	v_cvt_pk_bf16_f32 v92, v100, v101
	v_cvt_pk_bf16_f32 v94, v103, v102
	v_lshl_add_u64 v[96:97], v[96:97], 0, v[48:49]
	global_store_dwordx4 v[96:97], v[92:95], off
	s_nop 1
	v_mul_f32_e32 v93, 0x3d372713, v82
	v_mul_f32_e32 v93, v82, v93
	v_fma_f32 v93, v82, v93, v82
	v_mul_f32_e32 v93, 0xbfcc422a, v93
	v_mul_f32_e32 v93, 0x3fb8aa3b, v93
	v_mul_f32_e32 v92, 0x3d372713, v86
	v_exp_f32_e32 v94, v93
	v_mul_f32_e32 v93, 0x3d372713, v87
	v_mul_f32_e32 v92, v86, v92
	v_mul_f32_e32 v93, v87, v93
	v_fma_f32 v92, v86, v92, v86
	v_fma_f32 v93, v87, v93, v87
	v_mul_f32_e32 v92, 0xbfcc422a, v92
	v_mul_f32_e32 v93, 0xbfcc422a, v93
	v_mul_f32_e32 v92, 0x3fb8aa3b, v92
	v_mul_f32_e32 v93, 0x3fb8aa3b, v93
	v_exp_f32_e32 v92, v92
	v_exp_f32_e32 v93, v93
	s_nop 0
	v_pk_add_f32 v[92:93], v[92:93], 1.0 op_sel_hi:[1,0]
	s_nop 0
	s_nop 0
	v_rcp_f32_e32 v95, v93
	s_nop 0
	v_mul_f32_e32 v93, v87, v95
	s_nop 0
	v_rcp_f32_e32 v87, v92
	s_nop 0
	v_mul_f32_e32 v92, v86, v87
	v_mul_f32_e32 v86, 0x3d372713, v83
	v_mul_f32_e32 v86, v83, v86
	v_fma_f32 v86, v83, v86, v83
	v_mul_f32_e32 v86, 0xbfcc422a, v86
	v_mul_f32_e32 v86, 0x3fb8aa3b, v86
	v_exp_f32_e32 v95, v86
	s_nop 0
	v_pk_add_f32 v[86:87], v[94:95], 1.0 op_sel_hi:[1,0]
	s_nop 0
	s_nop 0
	v_rcp_f32_e32 v94, v87
	s_nop 0
	v_mul_f32_e32 v94, v83, v94
	s_nop 0
	v_rcp_f32_e32 v83, v86
	s_nop 0
	v_mul_f32_e32 v95, v82, v83
	v_mul_f32_e32 v83, 0x3d372713, v84
	v_mul_f32_e32 v83, v84, v83
	v_fma_f32 v83, v84, v83, v84
	v_mul_f32_e32 v83, 0xbfcc422a, v83
	v_mul_f32_e32 v83, 0x3fb8aa3b, v83
	v_mul_f32_e32 v82, 0x3d372713, v88
	v_exp_f32_e32 v86, v83
	v_mul_f32_e32 v83, 0x3d372713, v89
	v_mul_f32_e32 v82, v88, v82
	v_mul_f32_e32 v83, v89, v83
	v_fma_f32 v82, v88, v82, v88
	v_fma_f32 v83, v89, v83, v89
	v_mul_f32_e32 v82, 0xbfcc422a, v82
	v_mul_f32_e32 v83, 0xbfcc422a, v83
	v_mul_f32_e32 v82, 0x3fb8aa3b, v82
	v_mul_f32_e32 v83, 0x3fb8aa3b, v83
	v_exp_f32_e32 v82, v82
	v_exp_f32_e32 v83, v83
	s_nop 0
	v_pk_add_f32 v[82:83], v[82:83], 1.0 op_sel_hi:[1,0]
	s_nop 0
	s_nop 0
	v_rcp_f32_e32 v87, v83
	s_nop 0
	v_mul_f32_e32 v89, v89, v87
	s_nop 0
	v_rcp_f32_e32 v83, v82
	s_nop 0
	v_mul_f32_e32 v88, v88, v83
	v_mul_f32_e32 v82, 0x3d372713, v85
	v_mul_f32_e32 v82, v85, v82
	v_fma_f32 v82, v85, v82, v85
	v_mul_f32_e32 v82, 0xbfcc422a, v82
	v_mul_f32_e32 v82, 0x3fb8aa3b, v82
	v_exp_f32_e32 v87, v82
	s_nop 0
	v_pk_add_f32 v[82:83], v[86:87], 1.0 op_sel_hi:[1,0]
	s_nop 0
	s_nop 0
	v_rcp_f32_e32 v86, v83
	s_nop 0
	v_mul_f32_e32 v85, v85, v86
	s_nop 0
	v_rcp_f32_e32 v83, v82
	s_nop 0
	v_mul_f32_e32 v86, v84, v83
	v_cvt_pk_bf16_f32 v85, v86, v85
	v_lshl_add_u64 v[86:87], v[90:91], 0, v[114:115]
	v_lshl_add_u64 v[86:87], v[86:87], 0, s[10:11]
	v_cvt_pk_bf16_f32 v82, v92, v93
	v_cvt_pk_bf16_f32 v83, v88, v89
	v_cvt_pk_bf16_f32 v84, v95, v94
	v_lshl_add_u64 v[86:87], v[86:87], 0, v[48:49]
	global_store_dwordx4 v[86:87], v[82:85], off
	s_nop 1
	v_mul_f32_e32 v85, 0x3d372713, v74
	v_mul_f32_e32 v85, v74, v85
	v_fma_f32 v85, v74, v85, v74
	v_mul_f32_e32 v85, 0xbfcc422a, v85
	v_mul_f32_e32 v85, 0x3fb8aa3b, v85
	v_mul_f32_e32 v84, 0x3d372713, v78
	v_exp_f32_e32 v86, v85
	v_mul_f32_e32 v85, 0x3d372713, v79
	v_mul_f32_e32 v84, v78, v84
	v_mul_f32_e32 v85, v79, v85
	v_fma_f32 v84, v78, v84, v78
	v_fma_f32 v85, v79, v85, v79
	v_mul_f32_e32 v84, 0xbfcc422a, v84
	v_mul_f32_e32 v85, 0xbfcc422a, v85
	v_mul_f32_e32 v84, 0x3fb8aa3b, v84
	v_mul_f32_e32 v85, 0x3fb8aa3b, v85
	v_exp_f32_e32 v84, v84
	v_exp_f32_e32 v85, v85
	v_or_b32_e32 v82, 48, v142
	v_ashrrev_i32_e32 v83, 31, v82
	v_lshlrev_b64 v[82:83], 14, v[82:83]
	v_pk_add_f32 v[84:85], v[84:85], 1.0 op_sel_hi:[1,0]
	s_nop 0
	s_nop 0
	v_rcp_f32_e32 v87, v85
	s_nop 0
	v_mul_f32_e32 v85, v79, v87
	s_nop 0
	v_rcp_f32_e32 v79, v84
	s_nop 0
	v_mul_f32_e32 v84, v78, v79
	v_mul_f32_e32 v78, 0x3d372713, v75
	v_mul_f32_e32 v78, v75, v78
	v_fma_f32 v78, v75, v78, v75
	v_mul_f32_e32 v78, 0xbfcc422a, v78
	v_mul_f32_e32 v78, 0x3fb8aa3b, v78
	v_exp_f32_e32 v87, v78
	s_nop 0
	v_pk_add_f32 v[78:79], v[86:87], 1.0 op_sel_hi:[1,0]
	s_nop 0
	s_nop 0
	v_rcp_f32_e32 v86, v79
	s_nop 0
	v_mul_f32_e32 v86, v75, v86
	s_nop 0
	v_rcp_f32_e32 v75, v78
	s_nop 0
	v_mul_f32_e32 v87, v74, v75
	v_mul_f32_e32 v75, 0x3d372713, v76
	v_mul_f32_e32 v75, v76, v75
	v_fma_f32 v75, v76, v75, v76
	v_mul_f32_e32 v75, 0xbfcc422a, v75
	v_mul_f32_e32 v75, 0x3fb8aa3b, v75
	v_mul_f32_e32 v74, 0x3d372713, v80
	v_exp_f32_e32 v78, v75
	v_mul_f32_e32 v75, 0x3d372713, v81
	v_mul_f32_e32 v74, v80, v74
	v_mul_f32_e32 v75, v81, v75
	v_fma_f32 v74, v80, v74, v80
	v_fma_f32 v75, v81, v75, v81
	v_mul_f32_e32 v74, 0xbfcc422a, v74
	v_mul_f32_e32 v75, 0xbfcc422a, v75
	v_mul_f32_e32 v74, 0x3fb8aa3b, v74
	v_mul_f32_e32 v75, 0x3fb8aa3b, v75
	v_exp_f32_e32 v74, v74
	v_exp_f32_e32 v75, v75
	s_nop 0
	v_pk_add_f32 v[74:75], v[74:75], 1.0 op_sel_hi:[1,0]
	s_nop 0
	s_nop 0
	v_rcp_f32_e32 v79, v75
	s_nop 0
	v_mul_f32_e32 v81, v81, v79
	s_nop 0
	v_rcp_f32_e32 v75, v74
	s_nop 0
	v_mul_f32_e32 v80, v80, v75
	v_mul_f32_e32 v74, 0x3d372713, v77
	v_mul_f32_e32 v74, v77, v74
	v_fma_f32 v74, v77, v74, v77
	v_mul_f32_e32 v74, 0xbfcc422a, v74
	v_mul_f32_e32 v74, 0x3fb8aa3b, v74
	v_exp_f32_e32 v79, v74
	s_nop 0
	v_pk_add_f32 v[74:75], v[78:79], 1.0 op_sel_hi:[1,0]
	s_nop 0
	s_nop 0
	v_rcp_f32_e32 v78, v75
	s_nop 0
	v_mul_f32_e32 v75, v77, v78
	s_nop 0
	v_rcp_f32_e32 v77, v74
	s_nop 0
	v_mul_f32_e32 v74, v76, v77
	v_cvt_pk_bf16_f32 v79, v74, v75
	v_lshl_add_u64 v[74:75], s[0:1], 0, v[82:83]
	v_cvt_pk_bf16_f32 v77, v80, v81
	v_lshl_add_u64 v[80:81], v[74:75], 0, v[124:125]
	v_lshl_add_u64 v[80:81], v[80:81], 0, s[10:11]
	v_cvt_pk_bf16_f32 v76, v84, v85
	v_cvt_pk_bf16_f32 v78, v87, v86
	v_lshl_add_u64 v[80:81], v[80:81], 0, v[48:49]
	global_store_dwordx4 v[80:81], v[76:79], off
	s_nop 1
	v_mul_f32_e32 v77, 0x3d372713, v66
	v_mul_f32_e32 v77, v66, v77
	v_fma_f32 v77, v66, v77, v66
	v_mul_f32_e32 v77, 0xbfcc422a, v77
	v_mul_f32_e32 v77, 0x3fb8aa3b, v77
	v_mul_f32_e32 v76, 0x3d372713, v70
	v_exp_f32_e32 v78, v77
	v_mul_f32_e32 v77, 0x3d372713, v71
	v_mul_f32_e32 v76, v70, v76
	v_mul_f32_e32 v77, v71, v77
	v_fma_f32 v76, v70, v76, v70
	v_fma_f32 v77, v71, v77, v71
	v_mul_f32_e32 v76, 0xbfcc422a, v76
	v_mul_f32_e32 v77, 0xbfcc422a, v77
	v_mul_f32_e32 v76, 0x3fb8aa3b, v76
	v_mul_f32_e32 v77, 0x3fb8aa3b, v77
	v_exp_f32_e32 v76, v76
	v_exp_f32_e32 v77, v77
	s_nop 0
	v_pk_add_f32 v[76:77], v[76:77], 1.0 op_sel_hi:[1,0]
	s_nop 0
	s_nop 0
	v_rcp_f32_e32 v79, v77
	s_nop 0
	v_mul_f32_e32 v77, v71, v79
	s_nop 0
	v_rcp_f32_e32 v71, v76
	s_nop 0
	v_mul_f32_e32 v76, v70, v71
	v_mul_f32_e32 v70, 0x3d372713, v67
	v_mul_f32_e32 v70, v67, v70
	v_fma_f32 v70, v67, v70, v67
	v_mul_f32_e32 v70, 0xbfcc422a, v70
	v_mul_f32_e32 v70, 0x3fb8aa3b, v70
	v_exp_f32_e32 v79, v70
	s_nop 0
	v_pk_add_f32 v[70:71], v[78:79], 1.0 op_sel_hi:[1,0]
	s_nop 0
	s_nop 0
	v_rcp_f32_e32 v78, v71
	s_nop 0
	v_mul_f32_e32 v78, v67, v78
	s_nop 0
	v_rcp_f32_e32 v67, v70
	s_nop 0
	v_mul_f32_e32 v79, v66, v67
	v_mul_f32_e32 v67, 0x3d372713, v68
	v_mul_f32_e32 v67, v68, v67
	v_fma_f32 v67, v68, v67, v68
	v_mul_f32_e32 v67, 0xbfcc422a, v67
	v_mul_f32_e32 v67, 0x3fb8aa3b, v67
	v_mul_f32_e32 v66, 0x3d372713, v72
	v_exp_f32_e32 v70, v67
	v_mul_f32_e32 v67, 0x3d372713, v73
	v_mul_f32_e32 v66, v72, v66
	v_mul_f32_e32 v67, v73, v67
	v_fma_f32 v66, v72, v66, v72
	v_fma_f32 v67, v73, v67, v73
	v_mul_f32_e32 v66, 0xbfcc422a, v66
	v_mul_f32_e32 v67, 0xbfcc422a, v67
	v_mul_f32_e32 v66, 0x3fb8aa3b, v66
	v_mul_f32_e32 v67, 0x3fb8aa3b, v67
	v_exp_f32_e32 v66, v66
	v_exp_f32_e32 v67, v67
	s_nop 0
	v_pk_add_f32 v[66:67], v[66:67], 1.0 op_sel_hi:[1,0]
	s_nop 0
	s_nop 0
	v_rcp_f32_e32 v71, v67
	s_nop 0
	v_mul_f32_e32 v73, v73, v71
	s_nop 0
	v_rcp_f32_e32 v67, v66
	s_nop 0
	v_mul_f32_e32 v72, v72, v67
	v_mul_f32_e32 v66, 0x3d372713, v69
	v_mul_f32_e32 v66, v69, v66
	v_fma_f32 v66, v69, v66, v69
	v_mul_f32_e32 v66, 0xbfcc422a, v66
	v_mul_f32_e32 v66, 0x3fb8aa3b, v66
	v_exp_f32_e32 v71, v66
	s_nop 0
	v_pk_add_f32 v[66:67], v[70:71], 1.0 op_sel_hi:[1,0]
	s_nop 0
	s_nop 0
	v_rcp_f32_e32 v70, v67
	s_nop 0
	v_mul_f32_e32 v69, v69, v70
	s_nop 0
	v_rcp_f32_e32 v67, v66
	s_nop 0
	v_mul_f32_e32 v70, v68, v67
	v_cvt_pk_bf16_f32 v69, v70, v69
	v_lshl_add_u64 v[70:71], v[74:75], 0, v[114:115]
	v_lshl_add_u64 v[70:71], v[70:71], 0, s[10:11]
	v_cvt_pk_bf16_f32 v66, v76, v77
	v_cvt_pk_bf16_f32 v67, v72, v73
	v_cvt_pk_bf16_f32 v68, v79, v78
	v_lshl_add_u64 v[70:71], v[70:71], 0, v[48:49]
	global_store_dwordx4 v[70:71], v[66:69], off
	s_nop 1
	v_mul_f32_e32 v67, 0x3d372713, v58
	v_mul_f32_e32 v67, v58, v67
	v_fma_f32 v67, v58, v67, v58
	v_mul_f32_e32 v67, 0xbfcc422a, v67
	v_mul_f32_e32 v67, 0x3fb8aa3b, v67
	v_mul_f32_e32 v66, 0x3d372713, v62
	v_exp_f32_e32 v68, v67
	v_mul_f32_e32 v67, 0x3d372713, v63
	v_mul_f32_e32 v66, v62, v66
	v_mul_f32_e32 v67, v63, v67
	v_fma_f32 v66, v62, v66, v62
	v_fma_f32 v67, v63, v67, v63
	v_mul_f32_e32 v66, 0xbfcc422a, v66
	v_mul_f32_e32 v67, 0xbfcc422a, v67
	v_mul_f32_e32 v66, 0x3fb8aa3b, v66
	v_mul_f32_e32 v67, 0x3fb8aa3b, v67
	v_exp_f32_e32 v66, v66
	v_exp_f32_e32 v67, v67
	s_nop 0
	v_pk_add_f32 v[66:67], v[66:67], 1.0 op_sel_hi:[1,0]
	s_nop 0
	s_nop 0
	v_rcp_f32_e32 v69, v67
	s_nop 0
	v_mul_f32_e32 v67, v63, v69
	s_nop 0
	v_rcp_f32_e32 v63, v66
	s_nop 0
	v_mul_f32_e32 v66, v62, v63
	v_mul_f32_e32 v62, 0x3d372713, v59
	v_mul_f32_e32 v62, v59, v62
	v_fma_f32 v62, v59, v62, v59
	v_mul_f32_e32 v62, 0xbfcc422a, v62
	v_mul_f32_e32 v62, 0x3fb8aa3b, v62
	v_exp_f32_e32 v69, v62
	s_nop 0
	v_pk_add_f32 v[62:63], v[68:69], 1.0 op_sel_hi:[1,0]
	s_nop 0
	s_nop 0
	v_rcp_f32_e32 v68, v63
	s_nop 0
	v_mul_f32_e32 v68, v59, v68
	s_nop 0
	v_rcp_f32_e32 v59, v62
	s_nop 0
	v_mul_f32_e32 v69, v58, v59
	v_mul_f32_e32 v59, 0x3d372713, v60
	v_mul_f32_e32 v59, v60, v59
	v_fma_f32 v59, v60, v59, v60
	v_mul_f32_e32 v59, 0xbfcc422a, v59
	v_mul_f32_e32 v59, 0x3fb8aa3b, v59
	v_mul_f32_e32 v58, 0x3d372713, v64
	v_exp_f32_e32 v62, v59
	v_mul_f32_e32 v59, 0x3d372713, v65
	v_mul_f32_e32 v58, v64, v58
	v_mul_f32_e32 v59, v65, v59
	v_fma_f32 v58, v64, v58, v64
	v_fma_f32 v59, v65, v59, v65
	v_mul_f32_e32 v58, 0xbfcc422a, v58
	v_mul_f32_e32 v59, 0xbfcc422a, v59
	v_mul_f32_e32 v58, 0x3fb8aa3b, v58
	v_mul_f32_e32 v59, 0x3fb8aa3b, v59
	v_exp_f32_e32 v58, v58
	v_exp_f32_e32 v59, v59
	s_nop 0
	v_pk_add_f32 v[58:59], v[58:59], 1.0 op_sel_hi:[1,0]
	s_nop 0
	s_nop 0
	v_rcp_f32_e32 v63, v59
	s_nop 0
	v_mul_f32_e32 v65, v65, v63
	s_nop 0
	v_rcp_f32_e32 v59, v58
	s_nop 0
	v_mul_f32_e32 v64, v64, v59
	v_mul_f32_e32 v58, 0x3d372713, v61
	v_mul_f32_e32 v58, v61, v58
	v_fma_f32 v58, v61, v58, v61
	v_mul_f32_e32 v58, 0xbfcc422a, v58
	v_mul_f32_e32 v58, 0x3fb8aa3b, v58
	v_exp_f32_e32 v63, v58
	s_nop 0
	v_pk_add_f32 v[58:59], v[62:63], 1.0 op_sel_hi:[1,0]
	s_nop 0
	s_nop 0
	v_rcp_f32_e32 v62, v59
	s_nop 0
	v_mul_f32_e32 v59, v61, v62
	s_mov_b64 s[12:13], 0x200000
	v_rcp_f32_e32 v61, v58
	s_nop 0
	v_mul_f32_e32 v58, v60, v61
	v_cvt_pk_bf16_f32 v63, v58, v59
	v_lshl_add_u64 v[58:59], v[122:123], 0, s[12:13]
	v_cvt_pk_bf16_f32 v61, v64, v65
	v_lshl_add_u64 v[64:65], v[58:59], 0, v[124:125]
	v_lshl_add_u64 v[64:65], v[64:65], 0, s[10:11]
	v_cvt_pk_bf16_f32 v60, v66, v67
	v_cvt_pk_bf16_f32 v62, v69, v68
	v_lshl_add_u64 v[64:65], v[64:65], 0, v[48:49]
	global_store_dwordx4 v[64:65], v[60:63], off
	s_nop 1
	v_mul_f32_e32 v61, 0x3d372713, v50
	v_mul_f32_e32 v61, v50, v61
	v_fma_f32 v61, v50, v61, v50
	v_mul_f32_e32 v61, 0xbfcc422a, v61
	v_mul_f32_e32 v61, 0x3fb8aa3b, v61
	v_mul_f32_e32 v60, 0x3d372713, v54
	v_exp_f32_e32 v62, v61
	v_mul_f32_e32 v61, 0x3d372713, v55
	v_mul_f32_e32 v60, v54, v60
	v_mul_f32_e32 v61, v55, v61
	v_fma_f32 v60, v54, v60, v54
	v_fma_f32 v61, v55, v61, v55
	v_mul_f32_e32 v60, 0xbfcc422a, v60
	v_mul_f32_e32 v61, 0xbfcc422a, v61
	v_mul_f32_e32 v60, 0x3fb8aa3b, v60
	v_mul_f32_e32 v61, 0x3fb8aa3b, v61
	v_exp_f32_e32 v60, v60
	v_exp_f32_e32 v61, v61
	s_nop 0
	v_pk_add_f32 v[60:61], v[60:61], 1.0 op_sel_hi:[1,0]
	s_nop 0
	s_nop 0
	v_rcp_f32_e32 v63, v61
	s_nop 0
	v_mul_f32_e32 v61, v55, v63
	s_nop 0
	v_rcp_f32_e32 v55, v60
	s_nop 0
	v_mul_f32_e32 v60, v54, v55
	v_mul_f32_e32 v54, 0x3d372713, v51
	v_mul_f32_e32 v54, v51, v54
	v_fma_f32 v54, v51, v54, v51
	v_mul_f32_e32 v54, 0xbfcc422a, v54
	v_mul_f32_e32 v54, 0x3fb8aa3b, v54
	v_exp_f32_e32 v63, v54
	s_nop 0
	v_pk_add_f32 v[54:55], v[62:63], 1.0 op_sel_hi:[1,0]
	s_nop 0
	s_nop 0
	v_rcp_f32_e32 v62, v55
	s_nop 0
	v_mul_f32_e32 v62, v51, v62
	s_nop 0
	v_rcp_f32_e32 v51, v54
	s_nop 0
	v_mul_f32_e32 v63, v50, v51
	v_mul_f32_e32 v51, 0x3d372713, v52
	v_mul_f32_e32 v51, v52, v51
	v_fma_f32 v51, v52, v51, v52
	v_mul_f32_e32 v51, 0xbfcc422a, v51
	v_mul_f32_e32 v51, 0x3fb8aa3b, v51
	v_mul_f32_e32 v50, 0x3d372713, v56
	v_exp_f32_e32 v54, v51
	v_mul_f32_e32 v51, 0x3d372713, v57
	v_mul_f32_e32 v50, v56, v50
	v_mul_f32_e32 v51, v57, v51
	v_fma_f32 v50, v56, v50, v56
	v_fma_f32 v51, v57, v51, v57
	v_mul_f32_e32 v50, 0xbfcc422a, v50
	v_mul_f32_e32 v51, 0xbfcc422a, v51
	v_mul_f32_e32 v50, 0x3fb8aa3b, v50
	v_mul_f32_e32 v51, 0x3fb8aa3b, v51
	v_exp_f32_e32 v50, v50
	v_exp_f32_e32 v51, v51
	s_nop 0
	v_pk_add_f32 v[50:51], v[50:51], 1.0 op_sel_hi:[1,0]
	s_nop 0
	s_nop 0
	v_rcp_f32_e32 v55, v51
	s_nop 0
	v_mul_f32_e32 v57, v57, v55
	s_nop 0
	v_rcp_f32_e32 v51, v50
	s_nop 0
	v_mul_f32_e32 v56, v56, v51
	v_mul_f32_e32 v50, 0x3d372713, v53
	v_mul_f32_e32 v50, v53, v50
	v_fma_f32 v50, v53, v50, v53
	v_mul_f32_e32 v50, 0xbfcc422a, v50
	v_mul_f32_e32 v50, 0x3fb8aa3b, v50
	v_exp_f32_e32 v55, v50
	s_nop 0
	v_pk_add_f32 v[50:51], v[54:55], 1.0 op_sel_hi:[1,0]
	s_nop 0
	s_nop 0
	v_rcp_f32_e32 v54, v51
	s_nop 0
	v_mul_f32_e32 v53, v53, v54
	s_nop 0
	v_rcp_f32_e32 v51, v50
	s_nop 0
	v_mul_f32_e32 v54, v52, v51
	v_cvt_pk_bf16_f32 v53, v54, v53
	v_lshl_add_u64 v[54:55], v[58:59], 0, v[114:115]
	v_lshl_add_u64 v[54:55], v[54:55], 0, s[10:11]
	v_cvt_pk_bf16_f32 v50, v60, v61
	v_cvt_pk_bf16_f32 v51, v56, v57
	v_cvt_pk_bf16_f32 v52, v63, v62
	v_lshl_add_u64 v[54:55], v[54:55], 0, v[48:49]
	global_store_dwordx4 v[54:55], v[50:53], off
	s_nop 1
	v_mul_f32_e32 v51, 0x3d372713, v40
	v_mul_f32_e32 v51, v40, v51
	v_fma_f32 v51, v40, v51, v40
	v_mul_f32_e32 v51, 0xbfcc422a, v51
	v_mul_f32_e32 v51, 0x3fb8aa3b, v51
	v_mul_f32_e32 v50, 0x3d372713, v44
	v_exp_f32_e32 v52, v51
	v_mul_f32_e32 v51, 0x3d372713, v45
	v_mul_f32_e32 v50, v44, v50
	v_mul_f32_e32 v51, v45, v51
	v_fma_f32 v50, v44, v50, v44
	v_fma_f32 v51, v45, v51, v45
	v_mul_f32_e32 v50, 0xbfcc422a, v50
	v_mul_f32_e32 v51, 0xbfcc422a, v51
	v_mul_f32_e32 v50, 0x3fb8aa3b, v50
	v_mul_f32_e32 v51, 0x3fb8aa3b, v51
	v_exp_f32_e32 v50, v50
	v_exp_f32_e32 v51, v51
	s_nop 0
	v_pk_add_f32 v[50:51], v[50:51], 1.0 op_sel_hi:[1,0]
	s_nop 0
	s_nop 0
	v_rcp_f32_e32 v53, v51
	s_nop 0
	v_mul_f32_e32 v51, v45, v53
	s_nop 0
	v_rcp_f32_e32 v45, v50
	s_nop 0
	v_mul_f32_e32 v50, v44, v45
	v_mul_f32_e32 v44, 0x3d372713, v41
	v_mul_f32_e32 v44, v41, v44
	v_fma_f32 v44, v41, v44, v41
	v_mul_f32_e32 v44, 0xbfcc422a, v44
	v_mul_f32_e32 v44, 0x3fb8aa3b, v44
	v_exp_f32_e32 v53, v44
	s_nop 0
	v_pk_add_f32 v[44:45], v[52:53], 1.0 op_sel_hi:[1,0]
	s_nop 0
	s_nop 0
	v_rcp_f32_e32 v52, v45
	s_nop 0
	v_mul_f32_e32 v52, v41, v52
	s_nop 0
	v_rcp_f32_e32 v41, v44
	s_nop 0
	v_mul_f32_e32 v53, v40, v41
	v_mul_f32_e32 v41, 0x3d372713, v42
	v_mul_f32_e32 v41, v42, v41
	v_fma_f32 v41, v42, v41, v42
	v_mul_f32_e32 v41, 0xbfcc422a, v41
	v_mul_f32_e32 v41, 0x3fb8aa3b, v41
	v_mul_f32_e32 v40, 0x3d372713, v46
	v_exp_f32_e32 v44, v41
	v_mul_f32_e32 v41, 0x3d372713, v47
	v_mul_f32_e32 v40, v46, v40
	v_mul_f32_e32 v41, v47, v41
	v_fma_f32 v40, v46, v40, v46
	v_fma_f32 v41, v47, v41, v47
	v_mul_f32_e32 v40, 0xbfcc422a, v40
	v_mul_f32_e32 v41, 0xbfcc422a, v41
	v_mul_f32_e32 v40, 0x3fb8aa3b, v40
	v_mul_f32_e32 v41, 0x3fb8aa3b, v41
	v_exp_f32_e32 v40, v40
	v_exp_f32_e32 v41, v41
	s_nop 0
	v_pk_add_f32 v[40:41], v[40:41], 1.0 op_sel_hi:[1,0]
	s_nop 0
	s_nop 0
	v_rcp_f32_e32 v45, v41
	s_nop 0
	v_mul_f32_e32 v47, v47, v45
	s_nop 0
	v_rcp_f32_e32 v41, v40
	s_nop 0
	v_mul_f32_e32 v46, v46, v41
	v_mul_f32_e32 v40, 0x3d372713, v43
	v_mul_f32_e32 v40, v43, v40
	v_fma_f32 v40, v43, v40, v43
	v_mul_f32_e32 v40, 0xbfcc422a, v40
	v_mul_f32_e32 v40, 0x3fb8aa3b, v40
	v_exp_f32_e32 v45, v40
	s_nop 0
	v_pk_add_f32 v[40:41], v[44:45], 1.0 op_sel_hi:[1,0]
	s_nop 0
	s_nop 0
	v_rcp_f32_e32 v44, v41
	s_nop 0
	v_mul_f32_e32 v41, v43, v44
	s_mov_b64 s[12:13], 0x240000
	v_rcp_f32_e32 v43, v40
	s_nop 0
	v_mul_f32_e32 v40, v42, v43
	v_cvt_pk_bf16_f32 v45, v40, v41
	v_lshl_add_u64 v[40:41], v[122:123], 0, s[12:13]
	v_cvt_pk_bf16_f32 v43, v46, v47
	v_lshl_add_u64 v[46:47], v[40:41], 0, v[124:125]
	v_lshl_add_u64 v[46:47], v[46:47], 0, s[10:11]
	v_cvt_pk_bf16_f32 v42, v50, v51
	v_cvt_pk_bf16_f32 v44, v53, v52
	v_lshl_add_u64 v[46:47], v[46:47], 0, v[48:49]
	global_store_dwordx4 v[46:47], v[42:45], off
	s_nop 1
	v_mul_f32_e32 v43, 0x3d372713, v32
	v_mul_f32_e32 v43, v32, v43
	v_fma_f32 v43, v32, v43, v32
	v_mul_f32_e32 v43, 0xbfcc422a, v43
	v_mul_f32_e32 v43, 0x3fb8aa3b, v43
	v_mul_f32_e32 v42, 0x3d372713, v36
	v_exp_f32_e32 v44, v43
	v_mul_f32_e32 v43, 0x3d372713, v37
	v_mul_f32_e32 v42, v36, v42
	v_mul_f32_e32 v43, v37, v43
	v_fma_f32 v42, v36, v42, v36
	v_fma_f32 v43, v37, v43, v37
	v_mul_f32_e32 v42, 0xbfcc422a, v42
	v_mul_f32_e32 v43, 0xbfcc422a, v43
	v_mul_f32_e32 v42, 0x3fb8aa3b, v42
	v_mul_f32_e32 v43, 0x3fb8aa3b, v43
	v_exp_f32_e32 v42, v42
	v_exp_f32_e32 v43, v43
	s_nop 0
	v_pk_add_f32 v[42:43], v[42:43], 1.0 op_sel_hi:[1,0]
	s_nop 0
	s_nop 0
	v_rcp_f32_e32 v45, v43
	s_nop 0
	v_mul_f32_e32 v43, v37, v45
	s_nop 0
	v_rcp_f32_e32 v37, v42
	s_nop 0
	v_mul_f32_e32 v42, v36, v37
	v_mul_f32_e32 v36, 0x3d372713, v33
	v_mul_f32_e32 v36, v33, v36
	v_fma_f32 v36, v33, v36, v33
	v_mul_f32_e32 v36, 0xbfcc422a, v36
	v_mul_f32_e32 v36, 0x3fb8aa3b, v36
	v_exp_f32_e32 v45, v36
	s_nop 0
	v_pk_add_f32 v[36:37], v[44:45], 1.0 op_sel_hi:[1,0]
	s_nop 0
	s_nop 0
	v_rcp_f32_e32 v44, v37
	s_nop 0
	v_mul_f32_e32 v44, v33, v44
	s_nop 0
	v_rcp_f32_e32 v33, v36
	s_nop 0
	v_mul_f32_e32 v45, v32, v33
	v_mul_f32_e32 v33, 0x3d372713, v34
	v_mul_f32_e32 v33, v34, v33
	v_fma_f32 v33, v34, v33, v34
	v_mul_f32_e32 v33, 0xbfcc422a, v33
	v_mul_f32_e32 v33, 0x3fb8aa3b, v33
	v_mul_f32_e32 v32, 0x3d372713, v38
	v_exp_f32_e32 v36, v33
	v_mul_f32_e32 v33, 0x3d372713, v39
	v_mul_f32_e32 v32, v38, v32
	v_mul_f32_e32 v33, v39, v33
	v_fma_f32 v32, v38, v32, v38
	v_fma_f32 v33, v39, v33, v39
	v_mul_f32_e32 v32, 0xbfcc422a, v32
	v_mul_f32_e32 v33, 0xbfcc422a, v33
	v_mul_f32_e32 v32, 0x3fb8aa3b, v32
	v_mul_f32_e32 v33, 0x3fb8aa3b, v33
	v_exp_f32_e32 v32, v32
	v_exp_f32_e32 v33, v33
	s_nop 0
	v_pk_add_f32 v[32:33], v[32:33], 1.0 op_sel_hi:[1,0]
	s_nop 0
	s_nop 0
	v_rcp_f32_e32 v37, v33
	s_nop 0
	v_mul_f32_e32 v39, v39, v37
	s_nop 0
	v_rcp_f32_e32 v33, v32
	s_nop 0
	v_mul_f32_e32 v38, v38, v33
	v_mul_f32_e32 v32, 0x3d372713, v35
	v_mul_f32_e32 v32, v35, v32
	v_fma_f32 v32, v35, v32, v35
	v_mul_f32_e32 v32, 0xbfcc422a, v32
	v_mul_f32_e32 v32, 0x3fb8aa3b, v32
	v_exp_f32_e32 v37, v32
	s_nop 0
	v_pk_add_f32 v[32:33], v[36:37], 1.0 op_sel_hi:[1,0]
	s_nop 0
	s_nop 0
	v_rcp_f32_e32 v36, v33
	s_nop 0
	v_mul_f32_e32 v35, v35, v36
	s_nop 0
	v_rcp_f32_e32 v33, v32
	s_nop 0
	v_mul_f32_e32 v36, v34, v33
	v_cvt_pk_bf16_f32 v35, v36, v35
	v_lshl_add_u64 v[36:37], v[40:41], 0, v[114:115]
	v_lshl_add_u64 v[36:37], v[36:37], 0, s[10:11]
	v_cvt_pk_bf16_f32 v32, v42, v43
	v_cvt_pk_bf16_f32 v33, v38, v39
	v_cvt_pk_bf16_f32 v34, v45, v44
	v_lshl_add_u64 v[36:37], v[36:37], 0, v[48:49]
	global_store_dwordx4 v[36:37], v[32:35], off
	s_nop 1
	v_mul_f32_e32 v33, 0x3d372713, v24
	v_mul_f32_e32 v33, v24, v33
	v_fma_f32 v33, v24, v33, v24
	v_mul_f32_e32 v33, 0xbfcc422a, v33
	v_mul_f32_e32 v33, 0x3fb8aa3b, v33
	v_mul_f32_e32 v32, 0x3d372713, v28
	v_exp_f32_e32 v34, v33
	v_mul_f32_e32 v33, 0x3d372713, v29
	v_mul_f32_e32 v32, v28, v32
	v_mul_f32_e32 v33, v29, v33
	v_fma_f32 v32, v28, v32, v28
	v_fma_f32 v33, v29, v33, v29
	v_mul_f32_e32 v32, 0xbfcc422a, v32
	v_mul_f32_e32 v33, 0xbfcc422a, v33
	v_mul_f32_e32 v32, 0x3fb8aa3b, v32
	v_mul_f32_e32 v33, 0x3fb8aa3b, v33
	v_exp_f32_e32 v32, v32
	v_exp_f32_e32 v33, v33
	s_nop 0
	v_pk_add_f32 v[32:33], v[32:33], 1.0 op_sel_hi:[1,0]
	s_nop 0
	s_nop 0
	v_rcp_f32_e32 v35, v33
	s_nop 0
	v_mul_f32_e32 v33, v29, v35
	s_nop 0
	v_rcp_f32_e32 v29, v32
	s_nop 0
	v_mul_f32_e32 v32, v28, v29
	v_mul_f32_e32 v28, 0x3d372713, v25
	v_mul_f32_e32 v28, v25, v28
	v_fma_f32 v28, v25, v28, v25
	v_mul_f32_e32 v28, 0xbfcc422a, v28
	v_mul_f32_e32 v28, 0x3fb8aa3b, v28
	v_exp_f32_e32 v35, v28
	s_nop 0
	v_pk_add_f32 v[28:29], v[34:35], 1.0 op_sel_hi:[1,0]
	s_nop 0
	s_nop 0
	v_rcp_f32_e32 v34, v29
	s_nop 0
	v_mul_f32_e32 v34, v25, v34
	s_nop 0
	v_rcp_f32_e32 v25, v28
	s_nop 0
	v_mul_f32_e32 v35, v24, v25
	v_mul_f32_e32 v25, 0x3d372713, v26
	v_mul_f32_e32 v25, v26, v25
	v_fma_f32 v25, v26, v25, v26
	v_mul_f32_e32 v25, 0xbfcc422a, v25
	v_mul_f32_e32 v25, 0x3fb8aa3b, v25
	v_mul_f32_e32 v24, 0x3d372713, v30
	v_exp_f32_e32 v28, v25
	v_mul_f32_e32 v25, 0x3d372713, v31
	v_mul_f32_e32 v24, v30, v24
	v_mul_f32_e32 v25, v31, v25
	v_fma_f32 v24, v30, v24, v30
	v_fma_f32 v25, v31, v25, v31
	v_mul_f32_e32 v24, 0xbfcc422a, v24
	v_mul_f32_e32 v25, 0xbfcc422a, v25
	v_mul_f32_e32 v24, 0x3fb8aa3b, v24
	v_mul_f32_e32 v25, 0x3fb8aa3b, v25
	v_exp_f32_e32 v24, v24
	v_exp_f32_e32 v25, v25
	s_nop 0
	v_pk_add_f32 v[24:25], v[24:25], 1.0 op_sel_hi:[1,0]
	s_nop 0
	s_nop 0
	v_rcp_f32_e32 v29, v25
	s_nop 0
	v_mul_f32_e32 v31, v31, v29
	s_nop 0
	v_rcp_f32_e32 v25, v24
	s_nop 0
	v_mul_f32_e32 v30, v30, v25
	v_mul_f32_e32 v24, 0x3d372713, v27
	v_mul_f32_e32 v24, v27, v24
	v_fma_f32 v24, v27, v24, v27
	v_mul_f32_e32 v24, 0xbfcc422a, v24
	v_mul_f32_e32 v24, 0x3fb8aa3b, v24
	v_exp_f32_e32 v29, v24
	s_nop 0
	v_pk_add_f32 v[24:25], v[28:29], 1.0 op_sel_hi:[1,0]
	s_nop 0
	s_nop 0
	v_rcp_f32_e32 v28, v25
	s_nop 0
	v_mul_f32_e32 v25, v27, v28
	s_mov_b64 s[12:13], 0x280000
	v_rcp_f32_e32 v27, v24
	s_nop 0
	v_mul_f32_e32 v24, v26, v27
	v_cvt_pk_bf16_f32 v29, v24, v25
	v_lshl_add_u64 v[24:25], v[122:123], 0, s[12:13]
	v_cvt_pk_bf16_f32 v27, v30, v31
	v_lshl_add_u64 v[30:31], v[24:25], 0, v[124:125]
	v_lshl_add_u64 v[30:31], v[30:31], 0, s[10:11]
	v_cvt_pk_bf16_f32 v26, v32, v33
	v_cvt_pk_bf16_f32 v28, v35, v34
	v_lshl_add_u64 v[30:31], v[30:31], 0, v[48:49]
	global_store_dwordx4 v[30:31], v[26:29], off
	s_nop 1
	v_mul_f32_e32 v27, 0x3d372713, v16
	v_mul_f32_e32 v27, v16, v27
	v_fma_f32 v27, v16, v27, v16
	v_mul_f32_e32 v27, 0xbfcc422a, v27
	v_mul_f32_e32 v27, 0x3fb8aa3b, v27
	v_mul_f32_e32 v26, 0x3d372713, v20
	v_exp_f32_e32 v28, v27
	v_mul_f32_e32 v27, 0x3d372713, v21
	v_mul_f32_e32 v26, v20, v26
	v_mul_f32_e32 v27, v21, v27
	v_fma_f32 v26, v20, v26, v20
	v_fma_f32 v27, v21, v27, v21
	v_mul_f32_e32 v26, 0xbfcc422a, v26
	v_mul_f32_e32 v27, 0xbfcc422a, v27
	v_mul_f32_e32 v26, 0x3fb8aa3b, v26
	v_mul_f32_e32 v27, 0x3fb8aa3b, v27
	v_exp_f32_e32 v26, v26
	v_exp_f32_e32 v27, v27
	s_nop 0
	v_pk_add_f32 v[26:27], v[26:27], 1.0 op_sel_hi:[1,0]
	s_nop 0
	s_nop 0
	v_rcp_f32_e32 v29, v27
	s_nop 0
	v_mul_f32_e32 v27, v21, v29
	s_nop 0
	v_rcp_f32_e32 v21, v26
	s_nop 0
	v_mul_f32_e32 v26, v20, v21
	v_mul_f32_e32 v20, 0x3d372713, v17
	v_mul_f32_e32 v20, v17, v20
	v_fma_f32 v20, v17, v20, v17
	v_mul_f32_e32 v20, 0xbfcc422a, v20
	v_mul_f32_e32 v20, 0x3fb8aa3b, v20
	v_exp_f32_e32 v29, v20
	s_nop 0
	v_pk_add_f32 v[20:21], v[28:29], 1.0 op_sel_hi:[1,0]
	s_nop 0
	s_nop 0
	v_rcp_f32_e32 v28, v21
	s_nop 0
	v_mul_f32_e32 v28, v17, v28
	s_nop 0
	v_rcp_f32_e32 v17, v20
	s_nop 0
	v_mul_f32_e32 v29, v16, v17
	v_mul_f32_e32 v17, 0x3d372713, v18
	v_mul_f32_e32 v17, v18, v17
	v_fma_f32 v17, v18, v17, v18
	v_mul_f32_e32 v17, 0xbfcc422a, v17
	v_mul_f32_e32 v17, 0x3fb8aa3b, v17
	v_mul_f32_e32 v16, 0x3d372713, v22
	v_exp_f32_e32 v20, v17
	v_mul_f32_e32 v17, 0x3d372713, v23
	v_mul_f32_e32 v16, v22, v16
	v_mul_f32_e32 v17, v23, v17
	v_fma_f32 v16, v22, v16, v22
	v_fma_f32 v17, v23, v17, v23
	v_mul_f32_e32 v16, 0xbfcc422a, v16
	v_mul_f32_e32 v17, 0xbfcc422a, v17
	v_mul_f32_e32 v16, 0x3fb8aa3b, v16
	v_mul_f32_e32 v17, 0x3fb8aa3b, v17
	v_exp_f32_e32 v16, v16
	v_exp_f32_e32 v17, v17
	s_nop 0
	v_pk_add_f32 v[16:17], v[16:17], 1.0 op_sel_hi:[1,0]
	s_nop 0
	s_nop 0
	v_rcp_f32_e32 v21, v17
	s_nop 0
	v_mul_f32_e32 v23, v23, v21
	s_nop 0
	v_rcp_f32_e32 v17, v16
	s_nop 0
	v_mul_f32_e32 v22, v22, v17
	v_mul_f32_e32 v16, 0x3d372713, v19
	v_mul_f32_e32 v16, v19, v16
	v_fma_f32 v16, v19, v16, v19
	v_mul_f32_e32 v16, 0xbfcc422a, v16
	v_mul_f32_e32 v16, 0x3fb8aa3b, v16
	v_exp_f32_e32 v21, v16
	s_nop 0
	v_pk_add_f32 v[16:17], v[20:21], 1.0 op_sel_hi:[1,0]
	s_nop 0
	s_nop 0
	v_rcp_f32_e32 v20, v17
	s_nop 0
	v_mul_f32_e32 v19, v19, v20
	s_nop 0
	v_rcp_f32_e32 v17, v16
	s_nop 0
	v_mul_f32_e32 v20, v18, v17
	v_cvt_pk_bf16_f32 v19, v20, v19
	v_lshl_add_u64 v[20:21], v[24:25], 0, v[114:115]
	v_lshl_add_u64 v[20:21], v[20:21], 0, s[10:11]
	v_cvt_pk_bf16_f32 v16, v26, v27
	v_cvt_pk_bf16_f32 v17, v22, v23
	v_cvt_pk_bf16_f32 v18, v29, v28
	v_lshl_add_u64 v[20:21], v[20:21], 0, v[48:49]
	global_store_dwordx4 v[20:21], v[16:19], off
	s_nop 1
	v_mul_f32_e32 v17, 0x3d372713, v8
	v_mul_f32_e32 v17, v8, v17
	v_fma_f32 v17, v8, v17, v8
	v_mul_f32_e32 v17, 0xbfcc422a, v17
	v_mul_f32_e32 v17, 0x3fb8aa3b, v17
	v_mul_f32_e32 v16, 0x3d372713, v12
	v_exp_f32_e32 v18, v17
	v_mul_f32_e32 v17, 0x3d372713, v13
	v_mul_f32_e32 v16, v12, v16
	v_mul_f32_e32 v17, v13, v17
	v_fma_f32 v16, v12, v16, v12
	v_fma_f32 v17, v13, v17, v13
	v_mul_f32_e32 v16, 0xbfcc422a, v16
	v_mul_f32_e32 v17, 0xbfcc422a, v17
	v_mul_f32_e32 v16, 0x3fb8aa3b, v16
	v_mul_f32_e32 v17, 0x3fb8aa3b, v17
	v_exp_f32_e32 v16, v16
	v_exp_f32_e32 v17, v17
	s_nop 0
	v_pk_add_f32 v[16:17], v[16:17], 1.0 op_sel_hi:[1,0]
	s_nop 0
	s_nop 0
	v_rcp_f32_e32 v19, v17
	s_nop 0
	v_mul_f32_e32 v17, v13, v19
	s_nop 0
	v_rcp_f32_e32 v13, v16
	s_nop 0
	v_mul_f32_e32 v16, v12, v13
	v_mul_f32_e32 v12, 0x3d372713, v9
	v_mul_f32_e32 v12, v9, v12
	v_fma_f32 v12, v9, v12, v9
	v_mul_f32_e32 v12, 0xbfcc422a, v12
	v_mul_f32_e32 v12, 0x3fb8aa3b, v12
	v_exp_f32_e32 v19, v12
	s_nop 0
	v_pk_add_f32 v[12:13], v[18:19], 1.0 op_sel_hi:[1,0]
	s_nop 0
	s_nop 0
	v_rcp_f32_e32 v18, v13
	s_nop 0
	v_mul_f32_e32 v18, v9, v18
	s_nop 0
	v_rcp_f32_e32 v9, v12
	s_nop 0
	v_mul_f32_e32 v19, v8, v9
	v_mul_f32_e32 v9, 0x3d372713, v10
	v_mul_f32_e32 v9, v10, v9
	v_fma_f32 v9, v10, v9, v10
	v_mul_f32_e32 v9, 0xbfcc422a, v9
	v_mul_f32_e32 v9, 0x3fb8aa3b, v9
	v_mul_f32_e32 v8, 0x3d372713, v14
	v_exp_f32_e32 v12, v9
	v_mul_f32_e32 v9, 0x3d372713, v15
	v_mul_f32_e32 v8, v14, v8
	v_mul_f32_e32 v9, v15, v9
	v_fma_f32 v8, v14, v8, v14
	v_fma_f32 v9, v15, v9, v15
	v_mul_f32_e32 v8, 0xbfcc422a, v8
	v_mul_f32_e32 v9, 0xbfcc422a, v9
	v_mul_f32_e32 v8, 0x3fb8aa3b, v8
	v_mul_f32_e32 v9, 0x3fb8aa3b, v9
	v_exp_f32_e32 v8, v8
	v_exp_f32_e32 v9, v9
	s_nop 0
	v_pk_add_f32 v[8:9], v[8:9], 1.0 op_sel_hi:[1,0]
	s_nop 0
	s_nop 0
	v_rcp_f32_e32 v13, v9
	s_nop 0
	v_mul_f32_e32 v15, v15, v13
	s_nop 0
	v_rcp_f32_e32 v9, v8
	s_nop 0
	v_mul_f32_e32 v14, v14, v9
	v_mul_f32_e32 v8, 0x3d372713, v11
	v_mul_f32_e32 v8, v11, v8
	v_fma_f32 v8, v11, v8, v11
	v_mul_f32_e32 v8, 0xbfcc422a, v8
	v_mul_f32_e32 v8, 0x3fb8aa3b, v8
	v_exp_f32_e32 v13, v8
	s_nop 0
	v_pk_add_f32 v[8:9], v[12:13], 1.0 op_sel_hi:[1,0]
	s_nop 0
	s_nop 0
	v_rcp_f32_e32 v12, v9
	s_nop 0
	v_mul_f32_e32 v9, v11, v12
	s_mov_b64 s[12:13], 0x2c0000
	v_rcp_f32_e32 v11, v8
	s_nop 0
	v_mul_f32_e32 v8, v10, v11
	v_cvt_pk_bf16_f32 v13, v8, v9
	v_lshl_add_u64 v[8:9], v[122:123], 0, s[12:13]
	v_cvt_pk_bf16_f32 v11, v14, v15
	v_lshl_add_u64 v[14:15], v[8:9], 0, v[124:125]
	v_lshl_add_u64 v[14:15], v[14:15], 0, s[10:11]
	v_cvt_pk_bf16_f32 v10, v16, v17
	v_cvt_pk_bf16_f32 v12, v19, v18
	v_lshl_add_u64 v[14:15], v[14:15], 0, v[48:49]
	global_store_dwordx4 v[14:15], v[10:13], off
	s_nop 1
	v_mul_f32_e32 v11, 0x3d372713, v0
	v_mul_f32_e32 v11, v0, v11
	v_fma_f32 v11, v0, v11, v0
	v_mul_f32_e32 v11, 0xbfcc422a, v11
	v_mul_f32_e32 v11, 0x3fb8aa3b, v11
	v_mul_f32_e32 v10, 0x3d372713, v4
	v_exp_f32_e32 v12, v11
	v_mul_f32_e32 v11, 0x3d372713, v5
	v_mul_f32_e32 v10, v4, v10
	v_mul_f32_e32 v11, v5, v11
	v_fma_f32 v10, v4, v10, v4
	v_fma_f32 v11, v5, v11, v5
	v_mul_f32_e32 v10, 0xbfcc422a, v10
	v_mul_f32_e32 v11, 0xbfcc422a, v11
	v_mul_f32_e32 v10, 0x3fb8aa3b, v10
	v_mul_f32_e32 v11, 0x3fb8aa3b, v11
	v_exp_f32_e32 v10, v10
	v_exp_f32_e32 v11, v11
	s_nop 0
	v_pk_add_f32 v[10:11], v[10:11], 1.0 op_sel_hi:[1,0]
	s_nop 0
	s_nop 0
	v_rcp_f32_e32 v13, v11
	s_nop 0
	v_mul_f32_e32 v11, v5, v13
	s_nop 0
	v_rcp_f32_e32 v5, v10
	s_nop 0
	v_mul_f32_e32 v10, v4, v5
	v_mul_f32_e32 v4, 0x3d372713, v1
	v_mul_f32_e32 v4, v1, v4
	v_fma_f32 v4, v1, v4, v1
	v_mul_f32_e32 v4, 0xbfcc422a, v4
	v_mul_f32_e32 v4, 0x3fb8aa3b, v4
	v_exp_f32_e32 v13, v4
	s_nop 0
	v_pk_add_f32 v[4:5], v[12:13], 1.0 op_sel_hi:[1,0]
	s_nop 0
	s_nop 0
	v_rcp_f32_e32 v12, v5
	s_nop 0
	v_mul_f32_e32 v12, v1, v12
	s_nop 0
	v_rcp_f32_e32 v1, v4
	s_nop 0
	v_mul_f32_e32 v13, v0, v1
	v_mul_f32_e32 v1, 0x3d372713, v2
	v_mul_f32_e32 v1, v2, v1
	v_fma_f32 v1, v2, v1, v2
	v_mul_f32_e32 v1, 0xbfcc422a, v1
	v_mul_f32_e32 v1, 0x3fb8aa3b, v1
	v_mul_f32_e32 v0, 0x3d372713, v6
	v_exp_f32_e32 v4, v1
	v_mul_f32_e32 v1, 0x3d372713, v7
	v_mul_f32_e32 v0, v6, v0
	v_mul_f32_e32 v1, v7, v1
	v_fma_f32 v0, v6, v0, v6
	v_fma_f32 v1, v7, v1, v7
	v_mul_f32_e32 v0, 0xbfcc422a, v0
	v_mul_f32_e32 v1, 0xbfcc422a, v1
	v_mul_f32_e32 v0, 0x3fb8aa3b, v0
	v_mul_f32_e32 v1, 0x3fb8aa3b, v1
	v_exp_f32_e32 v0, v0
	v_exp_f32_e32 v1, v1
	s_nop 0
	v_pk_add_f32 v[0:1], v[0:1], 1.0 op_sel_hi:[1,0]
	s_nop 0
	s_nop 0
	v_rcp_f32_e32 v5, v1
	s_nop 0
	v_mul_f32_e32 v7, v7, v5
	s_nop 0
	v_rcp_f32_e32 v1, v0
	s_nop 0
	v_mul_f32_e32 v6, v6, v1
	v_mul_f32_e32 v0, 0x3d372713, v3
	v_mul_f32_e32 v0, v3, v0
	v_fma_f32 v0, v3, v0, v3
	v_mul_f32_e32 v0, 0xbfcc422a, v0
	v_mul_f32_e32 v0, 0x3fb8aa3b, v0
	v_exp_f32_e32 v5, v0
	s_nop 0
	v_pk_add_f32 v[0:1], v[4:5], 1.0 op_sel_hi:[1,0]
	s_nop 0
	s_nop 0
	v_rcp_f32_e32 v4, v1
	s_nop 0
	v_mul_f32_e32 v3, v3, v4
	s_mov_b64 s[12:13], s[6:7]
	v_rcp_f32_e32 v1, v0
	s_nop 0
	v_mul_f32_e32 v4, v2, v1
	v_cvt_pk_bf16_f32 v3, v4, v3
	v_lshl_add_u64 v[4:5], v[8:9], 0, v[114:115]
	v_lshl_add_u64 v[4:5], v[4:5], 0, s[10:11]
	v_cvt_pk_bf16_f32 v0, v10, v11
	v_cvt_pk_bf16_f32 v1, v6, v7
	v_cvt_pk_bf16_f32 v2, v13, v12
	v_lshl_add_u64 v[4:5], v[4:5], 0, v[48:49]
	s_and_b64 vcc, exec, s[8:9]
	s_mov_b64 s[10:11], s[4:5]
	global_store_dwordx4 v[4:5], v[0:3], off
	s_cbranch_vccz .LBB0_819
	s_waitcnt vmcnt(0)
	s_cmpk_gt_u32 s18, 0xff
	s_cbranch_scc1 .LBB0_826
	s_barrier

.LBB0_920:
	s_xor_b64 s[62:63], s[62:63], -1
	s_andn2_b64 vcc, exec, s[80:81]
	s_cbranch_vccnz .LBB0_855
	ds_read_b128 v[0:3], v187 offset:52224
	ds_read_b128 v[4:7], v150 offset:27648
	ds_read_b128 v[32:35], v187 offset:52256
	ds_read_b128 v[36:39], v150 offset:27680
	v_readlane_b32 s0, v254, 2
	v_readlane_b32 s1, v254, 3
	s_waitcnt lgkmcnt(2)
	v_mfma_f32_32x32x16_bf16 v[16:31], v[0:3], v[4:7], 0
	ds_read_b128 v[0:3], v188 offset:52224
	ds_read_b128 v[4:7], v152 offset:27648
	ds_read_b128 v[40:43], v187 offset:52288
	ds_read_b128 v[44:47], v150 offset:27712
	v_cmp_lt_i32_e32 vcc, v231, v230
	v_lshl_add_u64 v[182:183], s[84:85], 0, v[154:155]
	s_nop 0
	v_cndmask_b32_e32 v48, v229, v231, vcc
	s_mul_i32 vcc_lo, s16, 0x180
	s_waitcnt lgkmcnt(2)
	v_mfma_f32_32x32x16_bf16 v[0:15], v[0:3], v[4:7], 0
	v_mfma_f32_32x32x16_bf16 v[16:31], v[32:35], v[36:39], v[16:31]
	ds_read_b128 v[32:35], v188 offset:52256
	ds_read_b128 v[36:39], v152 offset:27680
	ds_read_b128 v[98:101], v188 offset:52288
	ds_read_b128 v[102:105], v152 offset:27712
	s_waitcnt lgkmcnt(2)
	v_mfma_f32_32x32x16_bf16 v[0:15], v[32:35], v[36:39], v[0:15]
	v_mfma_f32_32x32x16_bf16 v[16:31], v[40:43], v[44:47], v[16:31]
	s_waitcnt lgkmcnt(0)
	v_mfma_f32_32x32x16_bf16 v[0:15], v[98:101], v[102:105], v[0:15]
	s_nop 9
	v_cndmask_b32_e64 v16, v16, 0, s[0:1]
	v_readlane_b32 s0, v254, 4
	v_readlane_b32 s1, v254, 5
	v_cndmask_b32_e64 v0, v0, 0, s[18:19]
	s_nop 0
	v_cndmask_b32_e64 v1, v1, 0, s[0:1]
	v_readlane_b32 s0, v254, 6
	v_add_f32_e32 v16, v16, v0
	v_cndmask_b32_e64 v0, 0, v17, s[18:19]
	v_readlane_b32 s1, v254, 7
	v_add_f32_e32 v17, v0, v1
	s_nop 0
	v_cndmask_b32_e64 v1, v19, 0, s[0:1]
	v_readlane_b32 s0, v254, 8
	v_readlane_b32 s1, v254, 9
	s_nop 1
	v_cndmask_b32_e64 v0, v18, 0, s[0:1]
	v_readlane_b32 s0, v254, 10
	v_readlane_b32 s1, v254, 11
	s_nop 1
	v_cndmask_b32_e64 v3, v3, 0, s[0:1]
	v_readlane_b32 s0, v254, 12
	v_readlane_b32 s1, v254, 13
	s_nop 1
	v_cndmask_b32_e64 v2, v2, 0, s[0:1]
	v_readlane_b32 s0, v254, 14
	v_pk_add_f32 v[0:1], v[0:1], v[2:3]
	v_readlane_b32 s1, v254, 15
	v_cvt_pk_bf16_f32 v3, v0, v1
	v_cvt_pk_bf16_f32 v2, v16, v17
	v_cndmask_b32_e64 v1, v21, 0, s[0:1]
	v_readlane_b32 s0, v254, 16
	v_readlane_b32 s1, v254, 17
	s_nop 1
	v_cndmask_b32_e64 v0, v20, 0, s[0:1]
	v_readlane_b32 s0, v254, 23
	v_readlane_b32 s1, v254, 24
	s_nop 1
	v_cndmask_b32_e64 v5, v5, 0, s[0:1]
	v_readlane_b32 s0, v254, 25
	v_readlane_b32 s1, v254, 26
	s_nop 1
	v_cndmask_b32_e64 v4, v4, 0, s[0:1]
	v_readlane_b32 s0, v254, 27
	v_readlane_b32 s1, v254, 28
	v_pk_add_f32 v[0:1], v[0:1], v[4:5]
	s_nop 0
	v_cndmask_b32_e64 v5, v23, 0, s[0:1]
	v_readlane_b32 s0, v254, 29
	v_readlane_b32 s1, v254, 30
	v_cvt_pk_bf16_f32 v0, v0, v1
	s_nop 0
	v_cndmask_b32_e64 v4, v22, 0, s[0:1]
	v_readlane_b32 s0, v254, 31
	v_readlane_b32 s1, v254, 32
	s_nop 1
	v_cndmask_b32_e64 v7, v7, 0, s[0:1]
	v_readlane_b32 s0, v254, 33
	v_readlane_b32 s1, v254, 34
	s_nop 1
	v_cndmask_b32_e64 v6, v6, 0, s[0:1]
	v_pk_add_f32 v[4:5], v[4:5], v[6:7]
	v_readlane_b32 s0, v254, 35
	v_cvt_pk_bf16_f32 v1, v4, v5
	v_readlane_b32 s1, v254, 36
	ds_write2_b64 v151, v[2:3], v[0:1] offset1:2
	s_nop 0
	v_cndmask_b32_e64 v1, v25, 0, s[0:1]
	v_readlane_b32 s0, v254, 37
	v_readlane_b32 s1, v254, 38
	s_nop 1
	v_cndmask_b32_e64 v0, v24, 0, s[0:1]
	v_readlane_b32 s0, v254, 39
	v_readlane_b32 s1, v254, 40
	s_nop 1
	v_cndmask_b32_e64 v3, v9, 0, s[0:1]
	v_readlane_b32 s0, v254, 41
	v_readlane_b32 s1, v254, 42
	s_nop 1
	v_cndmask_b32_e64 v2, v8, 0, s[0:1]
	v_readlane_b32 s0, v254, 43
	v_readlane_b32 s1, v254, 44
	v_pk_add_f32 v[0:1], v[0:1], v[2:3]
	s_nop 0
	v_cndmask_b32_e64 v3, v27, 0, s[0:1]
	v_readlane_b32 s0, v254, 45
	v_readlane_b32 s1, v254, 46
	v_cvt_pk_bf16_f32 v0, v0, v1
	s_nop 0
	v_cndmask_b32_e64 v2, v26, 0, s[0:1]
	v_readlane_b32 s0, v254, 47
	v_readlane_b32 s1, v254, 48
	s_nop 1
	v_cndmask_b32_e64 v5, v11, 0, s[0:1]
	v_readlane_b32 s0, v254, 49
	v_readlane_b32 s1, v254, 50
	s_nop 1
	v_cndmask_b32_e64 v4, v10, 0, s[0:1]
	v_readlane_b32 s0, v254, 51
	v_pk_add_f32 v[2:3], v[2:3], v[4:5]
	v_readlane_b32 s1, v254, 52
	v_cvt_pk_bf16_f32 v1, v2, v3
	s_nop 0
	v_cndmask_b32_e64 v3, v29, 0, s[0:1]
	v_readlane_b32 s0, v254, 53
	v_readlane_b32 s1, v254, 54
	s_nop 1
	v_cndmask_b32_e64 v2, v28, 0, s[0:1]
	v_readlane_b32 s0, v254, 55
	v_readlane_b32 s1, v254, 56
	s_nop 1
	v_cndmask_b32_e64 v5, v13, 0, s[0:1]
	v_readlane_b32 s0, v254, 57
	v_readlane_b32 s1, v254, 58
	s_nop 1
	v_cndmask_b32_e64 v4, v12, 0, s[0:1]
	v_readlane_b32 s0, v254, 59
	v_readlane_b32 s1, v254, 60
	v_pk_add_f32 v[2:3], v[2:3], v[4:5]
	s_nop 0
	v_cndmask_b32_e64 v5, v31, 0, s[0:1]
	v_readlane_b32 s0, v254, 61
	v_readlane_b32 s1, v254, 62
	v_cvt_pk_bf16_f32 v2, v2, v3
	s_nop 0
	v_cndmask_b32_e64 v4, v30, 0, s[0:1]
	v_readlane_b32 s0, v254, 63
	v_readlane_b32 s1, v255, 0
	s_nop 1
	v_cndmask_b32_e64 v7, v15, 0, s[0:1]
	v_readlane_b32 s0, v255, 1
	v_readlane_b32 s1, v255, 2
	s_nop 1
	v_cndmask_b32_e64 v6, v14, 0, s[0:1]
	v_pk_add_f32 v[4:5], v[4:5], v[6:7]
	v_readlane_b32 s0, v255, 3
	v_cvt_pk_bf16_f32 v3, v4, v5
	ds_write2_b64 v151, v[0:1], v[2:3] offset0:4 offset1:6
	ds_read_b128 v[0:3], v187 offset:55296
	ds_read_b128 v[4:7], v150 offset:27648
	ds_read_b128 v[32:35], v187 offset:55328
	ds_read_b128 v[36:39], v150 offset:27680
	s_waitcnt lgkmcnt(2)
	v_mfma_f32_32x32x16_bf16 v[0:15], v[0:3], v[4:7], 0
	ds_read_b128 v[16:19], v187 offset:61440
	ds_read_b128 v[20:23], v152 offset:27648
	ds_read_b128 v[40:43], v187 offset:55360
	ds_read_b128 v[44:47], v150 offset:27712
	v_readlane_b32 s1, v255, 4
	s_waitcnt lgkmcnt(2)
	v_mfma_f32_32x32x16_bf16 v[16:31], v[16:19], v[20:23], 0
	v_mfma_f32_32x32x16_bf16 v[0:15], v[32:35], v[36:39], v[0:15]
	ds_read_b128 v[32:35], v187 offset:61472
	ds_read_b128 v[36:39], v152 offset:27680
	ds_read_b128 v[98:101], v187 offset:61504
	ds_read_b128 v[102:105], v152 offset:27712
	s_waitcnt lgkmcnt(2)
	v_mfma_f32_32x32x16_bf16 v[16:31], v[32:35], v[36:39], v[16:31]
	v_mfma_f32_32x32x16_bf16 v[0:15], v[40:43], v[44:47], v[0:15]
	s_waitcnt lgkmcnt(0)
	v_mfma_f32_32x32x16_bf16 v[16:31], v[98:101], v[102:105], v[16:31]
	s_nop 9
	v_cndmask_b32_e64 v1, v1, 0, s[0:1]
	v_readlane_b32 s0, v255, 5
	v_readlane_b32 s1, v255, 6
	s_nop 1
	v_cndmask_b32_e64 v0, v0, 0, s[0:1]
	v_readlane_b32 s0, v255, 7
	v_readlane_b32 s1, v255, 8
	s_nop 1
	v_cndmask_b32_e64 v17, v17, 0, s[0:1]
	v_readlane_b32 s0, v255, 9
	v_readlane_b32 s1, v255, 10
	s_nop 1
	v_cndmask_b32_e64 v16, v16, 0, s[0:1]
	v_readlane_b32 s0, v255, 11
	v_readlane_b32 s1, v255, 12
	v_pk_add_f32 v[0:1], v[0:1], v[16:17]
	s_nop 0
	v_cndmask_b32_e64 v3, v3, 0, s[0:1]
	v_readlane_b32 s0, v255, 13
	v_readlane_b32 s1, v255, 14
	v_cvt_pk_bf16_f32 v0, v0, v1
	s_nop 0
	v_cndmask_b32_e64 v2, v2, 0, s[0:1]
	v_readlane_b32 s0, v255, 15
	v_readlane_b32 s1, v255, 16
	s_nop 1
	v_cndmask_b32_e64 v17, v19, 0, s[0:1]
	v_readlane_b32 s0, v255, 17
	v_readlane_b32 s1, v255, 18
	s_nop 1
	v_cndmask_b32_e64 v16, v18, 0, s[0:1]
	v_readlane_b32 s0, v255, 19
	v_pk_add_f32 v[2:3], v[2:3], v[16:17]
	v_readlane_b32 s1, v255, 20
	v_cvt_pk_bf16_f32 v1, v2, v3
	s_nop 0
	v_cndmask_b32_e64 v3, v5, 0, s[0:1]
	v_readlane_b32 s0, v255, 21
	v_readlane_b32 s1, v255, 22
	s_nop 1
	v_cndmask_b32_e64 v2, v4, 0, s[0:1]
	v_readlane_b32 s0, v255, 23
	v_readlane_b32 s1, v255, 24
	s_nop 1
	v_cndmask_b32_e64 v5, v21, 0, s[0:1]
	v_readlane_b32 s0, v255, 25
	v_readlane_b32 s1, v255, 26
	s_nop 1
	v_cndmask_b32_e64 v4, v20, 0, s[0:1]
	v_readlane_b32 s0, v255, 27
	v_readlane_b32 s1, v255, 28
	v_pk_add_f32 v[2:3], v[2:3], v[4:5]
	s_nop 0
	v_cndmask_b32_e64 v5, v7, 0, s[0:1]
	v_readlane_b32 s0, v255, 29
	v_readlane_b32 s1, v255, 30
	v_cvt_pk_bf16_f32 v2, v2, v3
	s_nop 0
	v_cndmask_b32_e64 v4, v6, 0, s[0:1]
	v_readlane_b32 s0, v255, 31
	v_readlane_b32 s1, v255, 32
	v_cndmask_b32_e64 v6, v22, 0, s[24:25]
	s_nop 0
	v_cndmask_b32_e64 v7, v23, 0, s[0:1]
	v_pk_add_f32 v[4:5], v[4:5], v[6:7]
	v_cndmask_b32_e64 v7, v31, 0, s[56:57]
	v_cvt_pk_bf16_f32 v3, v4, v5
	ds_write2_b64 v151, v[0:1], v[2:3] offset0:8 offset1:10
	v_cndmask_b32_e64 v1, v9, 0, s[26:27]
	v_cndmask_b32_e64 v0, v8, 0, s[28:29]
	v_cndmask_b32_e64 v3, v25, 0, s[30:31]
	v_cndmask_b32_e64 v2, v24, 0, s[34:35]
	v_pk_add_f32 v[0:1], v[0:1], v[2:3]
	v_cndmask_b32_e64 v3, v11, 0, s[36:37]
	v_cndmask_b32_e64 v2, v10, 0, s[38:39]
	v_cndmask_b32_e64 v5, v27, 0, s[40:41]
	v_cndmask_b32_e64 v4, v26, 0, s[42:43]
	v_pk_add_f32 v[2:3], v[2:3], v[4:5]
	v_cvt_pk_bf16_f32 v0, v0, v1
	v_cvt_pk_bf16_f32 v1, v2, v3
	v_cndmask_b32_e64 v3, v13, 0, s[44:45]
	v_cndmask_b32_e64 v2, v12, 0, s[46:47]
	v_cndmask_b32_e64 v5, v29, 0, s[48:49]
	v_cndmask_b32_e64 v4, v28, 0, s[50:51]
	v_pk_add_f32 v[2:3], v[2:3], v[4:5]
	v_cndmask_b32_e64 v5, v15, 0, s[52:53]
	v_cndmask_b32_e64 v4, v14, 0, s[54:55]
	v_cndmask_b32_e64 v6, v30, 0, s[58:59]
	v_pk_add_f32 v[4:5], v[4:5], v[6:7]
	v_cvt_pk_bf16_f32 v2, v2, v3
	v_cvt_pk_bf16_f32 v3, v4, v5
	ds_write2_b64 v151, v[0:1], v[2:3] offset0:12 offset1:14
	s_waitcnt lgkmcnt(0)
	ds_read_b128 v[0:3], v189
	v_add_u32_e32 v12, v151, v186
	ds_read_b128 v[4:7], v12
	ds_read_b128 v[8:11], v189 offset:32
	ds_read_b128 v[130:133], v12 offset:32
	s_waitcnt lgkmcnt(2)
	v_mfma_f32_32x32x16_bf16 v[32:47], v[0:3], v[4:7], 0
	s_lshl_b32 s0, s17, 1
	s_add_i32 s0, s0, s6
	s_lshl_b32 s1, vcc_lo, 2
	s_mul_i32 s84, s0, 0x60
	s_add_i32 s16, s1, 0
	s_lshl_b32 s0, s84, 2
	s_add_i32 s16, s16, s0
	s_waitcnt lgkmcnt(0)
	v_mfma_f32_32x32x16_bf16 v[32:47], v[8:11], v[130:133], v[32:47]
	ds_read_b128 v[0:3], v189 offset:64
	ds_read_b128 v[126:129], v12 offset:64
	ds_read_b128 v[8:11], v189 offset:96
	ds_read_b128 v[118:121], v12 offset:96
	s_add_i32 s16, s16, 0x20400
	s_and_b64 s[0:1], s[60:61], exec
	v_readlane_b32 s0, v253, 42
	v_readlane_b32 s1, v253, 43
	s_movk_i32 s17, 0x140
	s_waitcnt lgkmcnt(2)
	v_mfma_f32_32x32x16_bf16 v[32:47], v[0:3], v[126:129], v[32:47]
	s_waitcnt lgkmcnt(0)
	v_mfma_f32_32x32x16_bf16 v[32:47], v[8:11], v[118:121], v[32:47]
	ds_read_b128 v[0:3], v190
	ds_read_b128 v[122:125], v191 offset:27648
	ds_read_b128 v[8:11], v190 offset:32
	ds_read_b128 v[12:15], v190 offset:64
	ds_read_b128 v[114:117], v191 offset:27680
	ds_read_b128 v[110:113], v191 offset:27712
	s_waitcnt lgkmcnt(4)
	v_mfma_f32_32x32x16_bf16 v[32:47], v[0:3], v[122:125], v[32:47]
	s_waitcnt lgkmcnt(1)
	v_mfma_f32_32x32x16_bf16 v[32:47], v[8:11], v[114:117], v[32:47]
	s_waitcnt lgkmcnt(0)
	v_mfma_f32_32x32x16_bf16 v[32:47], v[12:15], v[110:113], v[32:47]
	ds_read_b128 v[0:3], v192
	ds_read_b128 v[106:109], v193 offset:27648
	ds_read_b128 v[8:11], v192 offset:32
	ds_read_b128 v[12:15], v192 offset:64
	ds_read_b128 v[102:105], v193 offset:27680
	ds_read_b128 v[98:101], v193 offset:27712
	s_waitcnt lgkmcnt(4)
	v_mfma_f32_32x32x16_bf16 v[32:47], v[0:3], v[106:109], v[32:47]
	s_waitcnt lgkmcnt(1)
	v_mfma_f32_32x32x16_bf16 v[32:47], v[8:11], v[102:105], v[32:47]
	ds_read_b128 v[0:3], v189 offset:4608
	ds_read_b128 v[8:11], v189 offset:4640
	s_waitcnt lgkmcnt(1)
	v_mfma_f32_32x32x16_bf16 v[16:31], v[0:3], v[4:7], 0
	s_waitcnt lgkmcnt(0)
	v_mfma_f32_32x32x16_bf16 v[16:31], v[8:11], v[130:133], v[16:31]
	ds_read_b128 v[0:3], v189 offset:4672
	ds_read_b128 v[8:11], v189 offset:4704
	s_waitcnt lgkmcnt(1)
	v_mfma_f32_32x32x16_bf16 v[16:31], v[0:3], v[126:129], v[16:31]
	s_waitcnt lgkmcnt(0)
	v_mfma_f32_32x32x16_bf16 v[16:31], v[8:11], v[118:121], v[16:31]
	ds_read_b128 v[0:3], v198
	ds_read_b128 v[8:11], v198 offset:32
	s_waitcnt lgkmcnt(1)
	v_mfma_f32_32x32x16_bf16 v[16:31], v[0:3], v[122:125], v[16:31]
	s_waitcnt lgkmcnt(0)
	v_mfma_f32_32x32x16_bf16 v[16:31], v[8:11], v[114:117], v[16:31]
	ds_read_b128 v[0:3], v198 offset:64
	ds_read_b128 v[8:11], v199
	s_waitcnt lgkmcnt(1)
	v_mfma_f32_32x32x16_bf16 v[16:31], v[0:3], v[110:113], v[16:31]
	s_waitcnt lgkmcnt(0)
	v_mfma_f32_32x32x16_bf16 v[16:31], v[8:11], v[106:109], v[16:31]
	ds_read_b128 v[0:3], v199 offset:32
	ds_read_b128 v[8:11], v199 offset:64
	s_waitcnt lgkmcnt(1)
	v_mfma_f32_32x32x16_bf16 v[16:31], v[0:3], v[102:105], v[16:31]
	ds_read_b128 v[0:3], v189 offset:9216
	ds_read_b128 v[134:137], v189 offset:9248
	v_mfma_f32_32x32x16_bf16 v[32:47], v[12:15], v[98:101], v[32:47]
	s_waitcnt lgkmcnt(2)
	v_mfma_f32_32x32x16_bf16 v[16:31], v[8:11], v[98:101], v[16:31]
	s_nop 9
	v_add_f32_e32 v202, 0, v32
	v_add_f32_e32 v202, v33, v202
	v_add_f32_e32 v202, v34, v202
	v_add_f32_e32 v202, v35, v202
	s_waitcnt lgkmcnt(1)
	v_mfma_f32_32x32x16_bf16 v[0:15], v[0:3], v[4:7], 0
	s_waitcnt lgkmcnt(0)
	v_mfma_f32_32x32x16_bf16 v[0:15], v[134:137], v[130:133], v[0:15]
	ds_read_b128 v[130:133], v189 offset:9280
	ds_read_b128 v[134:137], v189 offset:9312
	s_waitcnt lgkmcnt(1)
	v_mfma_f32_32x32x16_bf16 v[0:15], v[130:133], v[126:129], v[0:15]
	s_waitcnt lgkmcnt(0)
	v_mfma_f32_32x32x16_bf16 v[0:15], v[134:137], v[118:121], v[0:15]
	ds_read_b128 v[118:121], v200
	ds_read_b128 v[126:129], v200 offset:32
	s_waitcnt lgkmcnt(1)
	v_mfma_f32_32x32x16_bf16 v[0:15], v[118:121], v[122:125], v[0:15]
	ds_read_b128 v[118:121], v200 offset:64
	ds_read_b128 v[122:125], v201
	ds_read_b128 v[130:133], v201 offset:32
	ds_read_b128 v[134:137], v201 offset:64
	s_waitcnt lgkmcnt(4)
	v_mfma_f32_32x32x16_bf16 v[0:15], v[126:129], v[114:117], v[0:15]
	v_add_f32_e32 v114, v36, v202
	v_add_f32_e32 v114, v37, v114
	v_add_f32_e32 v114, v38, v114
	v_add_f32_e32 v114, v39, v114
	v_add_f32_e32 v114, v40, v114
	v_add_f32_e32 v114, v41, v114
	v_add_f32_e32 v114, v42, v114
	s_waitcnt lgkmcnt(3)
	v_mfma_f32_32x32x16_bf16 v[0:15], v[118:121], v[110:113], v[0:15]
	v_add_f32_e32 v110, v43, v114
	v_add_f32_e32 v110, v44, v110
	v_add_f32_e32 v110, v45, v110
	v_add_f32_e32 v110, v46, v110
	v_add_f32_e32 v110, v47, v110
	v_add_f32_e32 v110, v110, v16
	v_add_f32_e32 v110, v17, v110
	s_waitcnt lgkmcnt(2)
	v_mfma_f32_32x32x16_bf16 v[0:15], v[122:125], v[106:109], v[0:15]
	v_add_f32_e32 v106, v18, v110
	v_add_f32_e32 v106, v19, v106
	v_add_f32_e32 v106, v20, v106
	v_add_f32_e32 v106, v21, v106
	v_add_f32_e32 v106, v22, v106
	v_add_f32_e32 v106, v23, v106
	v_add_f32_e32 v106, v24, v106
	s_waitcnt lgkmcnt(1)
	v_mfma_f32_32x32x16_bf16 v[0:15], v[130:133], v[102:105], v[0:15]
	v_add_f32_e32 v102, v25, v106
	v_add_f32_e32 v102, v26, v102
	v_add_f32_e32 v102, v27, v102
	v_add_f32_e32 v102, v28, v102
	v_add_f32_e32 v102, v29, v102
	v_add_f32_e32 v102, v30, v102
	v_add_f32_e32 v102, v31, v102
	s_waitcnt lgkmcnt(0)
	v_mfma_f32_32x32x16_bf16 v[0:15], v[134:137], v[98:101], v[0:15]
	v_lshlrev_b32_e32 v121, 2, v48
	s_nop 10
	v_add_f32_e32 v98, v102, v0
	v_add_f32_e32 v98, v1, v98
	v_add_f32_e32 v98, v2, v98
	v_add_f32_e32 v98, v3, v98
	v_add_f32_e32 v98, v4, v98
	v_add_f32_e32 v98, v5, v98
	v_add_f32_e32 v98, v6, v98
	v_add_f32_e32 v98, v7, v98
	v_add_f32_e32 v98, v8, v98
	v_add_f32_e32 v98, v9, v98
	v_add_f32_e32 v98, v10, v98
	v_add_f32_e32 v98, v11, v98
	v_add_f32_e32 v98, v12, v98
	v_add_f32_e32 v98, v13, v98
	v_add_f32_e32 v98, v14, v98
	v_add_f32_e32 v98, v15, v98
	ds_bpermute_b32 v48, v121, v98
	s_waitcnt lgkmcnt(0)
	v_add_f32_e32 v48, v98, v48
	v_lshlrev_b64 v[98:99], 11, v[182:183]
	v_lshl_add_u64 v[98:99], s[0:1], 0, v[98:99]
	s_movk_i32 s0, 0x780
	s_cselect_b32 s0, 0x300, s0
	s_ashr_i32 vcc_hi, vcc_lo, 31
	s_add_i32 s0, s84, s0
	v_lshl_add_u64 v[98:99], vcc, 1, v[98:99]
	s_ashr_i32 s85, s84, 31
	s_ashr_i32 s0, s0, 3
	v_mul_f32_e32 v48, 0x3c2aaaab, v48
	v_lshl_add_u64 v[114:115], s[84:85], 1, v[98:99]
	v_mov_b32_e32 v98, s0
	s_ashr_i32 s0, s0, 31
	v_cndmask_b32_e64 v120, 0, v48, s[60:61]
	v_mov_b32_e32 v99, s0
	v_alignbit_b32 v48, v183, v182, 6
	v_mad_u64_u32 v[98:99], s[0:1], v48, s17, v[98:99]
	v_mov_b32_e32 v48, v99
	v_lshrrev_b32_e32 v99, 6, v183
	v_mad_u64_u32 v[100:101], s[0:1], v99, s17, v[48:49]
	v_mov_b32_e32 v99, v100
	v_lshlrev_b64 v[98:99], 10, v[98:99]
	v_lshlrev_b32_e32 v48, 4, v182
	v_lshl_add_u64 v[98:99], s[70:71], 0, v[98:99]
	v_and_b32_e32 v48, 0x3f0, v48
	v_lshl_add_u64 v[98:99], v[98:99], 0, v[48:49]
	v_lshlrev_b32_e32 v48, 1, v156
	v_lshl_add_u64 v[102:103], v[98:99], 0, v[48:49]
	s_waitcnt vmcnt(0)
	v_lshrrev_b32_e32 v98, 6, v224
	v_mul_u32_u24_e32 v98, 0x1400, v98
	v_and_b32_e32 v100, 63, v224
	v_lshl_add_u32 v98, v100, 4, v98
	v_add_u32_e32 v98, 0x21000, v98
	ds_write_b128 v98, v[50:53]
	ds_write_b128 v98, v[54:57] offset:1024
	ds_write_b128 v98, v[58:61] offset:2048
	ds_write_b128 v98, v[62:65] offset:3072
	ds_write_b128 v98, v[66:69] offset:4096
	v_add_co_u32_e32 v104, vcc, 0x1000, v102
	s_nop 1
	v_addc_co_u32_e32 v105, vcc, 0, v103, vcc
	v_add_co_u32_e32 v106, vcc, 0x2000, v102
	s_nop 1
	v_addc_co_u32_e32 v107, vcc, 0, v103, vcc
	global_load_dwordx2 v[98:99], v[102:103], off
	global_load_dwordx2 v[100:101], v[102:103], off offset:1024
	global_load_dwordx2 v[50:51], v[102:103], off offset:2048
	global_load_dwordx2 v[52:53], v[102:103], off offset:3072
	global_load_dwordx2 v[54:55], v[104:105], off
	global_load_dwordx2 v[56:57], v[104:105], off offset:1024
	global_load_dwordx2 v[58:59], v[104:105], off offset:2048
	global_load_dwordx2 v[60:61], v[104:105], off offset:3072
	global_load_dwordx2 v[62:63], v[106:107], off
	global_load_dwordx2 v[64:65], v[106:107], off offset:1024
	global_load_dwordx2 v[66:67], v[106:107], off offset:2048
	global_load_dwordx2 v[68:69], v[106:107], off offset:3072
	v_pk_add_f32 v[204:205], v[32:33], v[120:121] op_sel_hi:[1,0] neg_lo:[0,1] neg_hi:[0,1]
	v_pk_add_f32 v[110:111], v[38:39], v[120:121] op_sel_hi:[1,0] neg_lo:[0,1] neg_hi:[0,1]
	v_pk_mul_f32 v[206:207], v[204:205], v[204:205]
	v_pk_add_f32 v[118:119], v[36:37], v[120:121] op_sel_hi:[1,0] neg_lo:[0,1] neg_hi:[0,1]
	v_pk_add_f32 v[108:109], v[40:41], v[120:121] op_sel_hi:[1,0] neg_lo:[0,1] neg_hi:[0,1]
	v_pk_add_f32 v[46:47], v[46:47], v[120:121] op_sel_hi:[1,0] neg_lo:[0,1] neg_hi:[0,1]
	v_pk_add_f32 v[38:39], v[22:23], v[120:121] op_sel_hi:[1,0] neg_lo:[0,1] neg_hi:[0,1]
	v_pk_add_f32 v[40:41], v[20:21], v[120:121] op_sel_hi:[1,0] neg_lo:[0,1] neg_hi:[0,1]
	v_pk_add_f32 v[32:33], v[26:27], v[120:121] op_sel_hi:[1,0] neg_lo:[0,1] neg_hi:[0,1]
	v_pk_add_f32 v[30:31], v[30:31], v[120:121] op_sel_hi:[1,0] neg_lo:[0,1] neg_hi:[0,1]
	v_pk_add_f32 v[28:29], v[28:29], v[120:121] op_sel_hi:[1,0] neg_lo:[0,1] neg_hi:[0,1]
	v_pk_add_f32 v[26:27], v[0:1], v[120:121] op_sel_hi:[1,0] neg_lo:[0,1] neg_hi:[0,1]
	v_pk_add_f32 v[20:21], v[6:7], v[120:121] op_sel_hi:[1,0] neg_lo:[0,1] neg_hi:[0,1]
	v_pk_add_f32 v[22:23], v[4:5], v[120:121] op_sel_hi:[1,0] neg_lo:[0,1] neg_hi:[0,1]
	v_pk_mul_f32 v[36:37], v[118:119], v[118:119]
	v_pk_mul_f32 v[208:209], v[110:111], v[110:111]
	v_pk_mul_f32 v[212:213], v[108:109], v[108:109]
	v_pk_mul_f32 v[214:215], v[46:47], v[46:47]
	v_pk_mul_f32 v[220:221], v[40:41], v[40:41]
	v_pk_mul_f32 v[218:219], v[38:39], v[38:39]
	v_pk_mul_f32 v[222:223], v[32:33], v[32:33]
	v_pk_mul_f32 v[246:247], v[28:29], v[28:29]
	v_pk_mul_f32 v[244:245], v[30:31], v[30:31]
	v_pk_mul_f32 v[0:1], v[26:27], v[26:27]
	v_pk_mul_f32 v[4:5], v[22:23], v[22:23]
	v_pk_mul_f32 v[6:7], v[20:21], v[20:21]
	s_waitcnt vmcnt(11)
	v_lshlrev_b32_e32 v234, 16, v98
	v_and_b32_e32 v235, 0xffff0000, v98
	v_mul_f32_e32 v98, 0xbfb8aa3b, v234
	v_exp_f32_e32 v104, v98
	v_mul_f32_e32 v98, 0xbfb8aa3b, v235
	v_exp_f32_e32 v105, v98
	v_lshlrev_b32_e32 v250, 16, v99
	v_and_b32_e32 v251, 0xffff0000, v99
	v_mul_f32_e32 v99, 0xbfb8aa3b, v251
	v_pk_add_f32 v[122:123], v[104:105], 1.0 op_sel_hi:[1,0]
	v_exp_f32_e32 v99, v99
	s_waitcnt vmcnt(10)
	v_lshlrev_b32_e32 v126, 16, v100
	v_and_b32_e32 v127, 0xffff0000, v100
	v_lshlrev_b32_e32 v130, 16, v101
	v_and_b32_e32 v131, 0xffff0000, v101
	v_mul_f32_e32 v98, 0xbfb8aa3b, v250
	v_exp_f32_e32 v98, v98
	s_nop 0
	v_pk_add_f32 v[124:125], v[98:99], 1.0 op_sel_hi:[1,0]
	s_nop 0
	s_nop 0
	s_nop 0
	v_mul_f32_e32 v98, 0xbfb8aa3b, v126
	v_mul_f32_e32 v99, 0xbfb8aa3b, v127
	v_exp_f32_e32 v98, v98
	v_exp_f32_e32 v99, v99
	v_pk_add_f32 v[106:107], v[42:43], v[120:121] op_sel_hi:[1,0] neg_lo:[0,1] neg_hi:[0,1]
	v_pk_add_f32 v[42:43], v[18:19], v[120:121] op_sel_hi:[1,0] neg_lo:[0,1] neg_hi:[0,1]
	v_pk_mul_f32 v[210:211], v[106:107], v[106:107]
	v_pk_add_f32 v[112:113], v[98:99], 1.0 op_sel_hi:[1,0]
	v_pk_mul_f32 v[18:19], v[42:43], v[42:43]
	s_nop 0
	v_rcp_f32_e32 v128, v113
	s_nop 0
	v_mul_f32_e32 v127, v127, v128
	v_mul_f32_e32 v98, 0xbfb8aa3b, v130
	v_mul_f32_e32 v99, 0xbfb8aa3b, v131
	v_exp_f32_e32 v98, v98
	v_exp_f32_e32 v99, v99
	v_rcp_f32_e32 v129, v112
	s_nop 0
	v_mul_f32_e32 v126, v126, v129
	v_pk_add_f32 v[116:117], v[98:99], 1.0 op_sel_hi:[1,0]
	s_nop 0
	s_nop 0
	s_mov_b64 s[0:1], 0x2db14200
	v_rcp_f32_e32 v132, v117
	s_nop 0
	v_mul_f32_e32 v117, v131, v132
	v_pk_add_f32 v[100:101], v[10:11], v[120:121] op_sel_hi:[1,0] neg_lo:[0,1] neg_hi:[0,1]
	v_pk_add_f32 v[10:11], v[34:35], v[120:121] op_sel_hi:[1,0] neg_lo:[0,1] neg_hi:[0,1]
	v_pk_add_f32 v[98:99], v[12:13], v[120:121] op_sel_hi:[1,0] neg_lo:[0,1] neg_hi:[0,1]
	v_pk_add_f32 v[12:13], v[14:15], v[120:121] op_sel_hi:[1,0] neg_lo:[0,1] neg_hi:[0,1]
	v_pk_mul_f32 v[202:203], v[10:11], v[10:11]
	v_pk_add_f32 v[104:105], v[44:45], v[120:121] op_sel_hi:[1,0] neg_lo:[0,1] neg_hi:[0,1]
	v_pk_add_f32 v[44:45], v[16:17], v[120:121] op_sel_hi:[1,0] neg_lo:[0,1] neg_hi:[0,1]
	v_pk_add_f32 v[34:35], v[24:25], v[120:121] op_sel_hi:[1,0] neg_lo:[0,1] neg_hi:[0,1]
	v_pk_add_f32 v[24:25], v[2:3], v[120:121] op_sel_hi:[1,0] neg_lo:[0,1] neg_hi:[0,1]
	v_pk_add_f32 v[14:15], v[8:9], v[120:121] op_sel_hi:[1,0] neg_lo:[0,1] neg_hi:[0,1]
	v_add_f32_e32 v120, v206, v207
	v_add_f32_e32 v120, v202, v120
	v_add_f32_e32 v120, v203, v120
	v_add_f32_e32 v36, v36, v120
	v_add_f32_e32 v36, v37, v36
	v_add_f32_e32 v36, v208, v36
	v_add_f32_e32 v36, v209, v36
	v_add_f32_e32 v36, v212, v36
	v_add_f32_e32 v36, v213, v36
	v_add_f32_e32 v36, v210, v36
	v_pk_mul_f32 v[216:217], v[104:105], v[104:105]
	v_add_f32_e32 v36, v211, v36
	v_add_f32_e32 v36, v216, v36
	v_add_f32_e32 v36, v217, v36
	v_add_f32_e32 v36, v214, v36
	v_pk_mul_f32 v[16:17], v[44:45], v[44:45]
	v_add_f32_e32 v36, v215, v36
	v_add_f32_e32 v16, v16, v36
	v_add_f32_e32 v16, v17, v16
	v_add_f32_e32 v16, v18, v16
	v_add_f32_e32 v16, v19, v16
	v_add_f32_e32 v16, v220, v16
	v_add_f32_e32 v16, v221, v16
	v_add_f32_e32 v16, v218, v16
	v_pk_mul_f32 v[242:243], v[34:35], v[34:35]
	v_add_f32_e32 v16, v219, v16
	v_add_f32_e32 v16, v242, v16
	v_add_f32_e32 v16, v243, v16
	v_add_f32_e32 v16, v222, v16
	v_add_f32_e32 v16, v223, v16
	v_add_f32_e32 v16, v246, v16
	v_add_f32_e32 v16, v247, v16
	v_add_f32_e32 v16, v244, v16
	v_add_f32_e32 v16, v245, v16
	v_add_f32_e32 v0, v0, v16
	v_pk_mul_f32 v[2:3], v[24:25], v[24:25]
	v_add_f32_e32 v0, v1, v0
	v_add_f32_e32 v0, v2, v0
	v_add_f32_e32 v0, v3, v0
	v_add_f32_e32 v0, v4, v0
	v_add_f32_e32 v0, v5, v0
	v_add_f32_e32 v0, v6, v0
	v_pk_mul_f32 v[8:9], v[14:15], v[14:15]
	v_add_f32_e32 v0, v7, v0
	v_add_f32_e32 v0, v8, v0
	v_pk_mul_f32 v[134:135], v[100:101], v[100:101]
	v_add_f32_e32 v0, v9, v0
	v_add_f32_e32 v0, v134, v0
	v_pk_mul_f32 v[136:137], v[98:99], v[98:99]
	v_add_f32_e32 v0, v135, v0
	v_add_f32_e32 v0, v136, v0
	v_pk_mul_f32 v[182:183], v[12:13], v[12:13]
	v_add_f32_e32 v0, v137, v0
	v_add_f32_e32 v0, v182, v0
	v_add_f32_e32 v0, v183, v0
	ds_bpermute_b32 v1, v121, v0
	v_lshl_add_u32 v19, v156, 2, s16
	ds_read_b128 v[4:7], v19
	v_lshl_add_u64 v[36:37], v[114:115], 0, s[0:1]
	v_rcp_f32_e32 v248, v123
	s_nop 0
	v_mul_f32_e32 v115, v235, v248
	s_waitcnt lgkmcnt(1)
	v_add_f32_e32 v0, v0, v1
	v_fmamk_f32 v0, v0, 0x3c2aaaab, v232
	v_mul_f32_e32 v1, 0x4b800000, v0
	v_cmp_gt_f32_e32 vcc, s92, v0
	v_rcp_f32_e32 v249, v122
	s_nop 0
	v_mul_f32_e32 v114, v234, v249
	v_rcp_f32_e32 v233, v125
	s_nop 0
	v_mul_f32_e32 v9, v251, v233
	v_cndmask_b32_e32 v0, v0, v1, vcc
	v_rsq_f32_e32 v0, v0
	v_rcp_f32_e32 v238, v124
	s_nop 0
	v_mul_f32_e32 v8, v250, v238
	v_lshl_add_u64 v[16:17], v[36:37], 0, v[48:49]
	v_rcp_f32_e32 v133, v116
	s_nop 0
	v_mul_f32_e32 v116, v130, v133
	v_mul_f32_e32 v1, 0x45800000, v0
	v_cndmask_b32_e32 v18, v0, v1, vcc
	v_pk_mul_f32 v[120:121], v[204:205], v[18:19] op_sel_hi:[1,0]
	v_pk_mul_f32 v[10:11], v[10:11], v[18:19] op_sel_hi:[1,0]
	s_waitcnt lgkmcnt(0)
	v_pk_mul_f32 v[4:5], v[4:5], v[120:121]
	v_pk_mul_f32 v[6:7], v[6:7], v[10:11]
	v_pk_mul_f32 v[4:5], v[114:115], v[4:5]
	v_pk_mul_f32 v[6:7], v[8:9], v[6:7]
	v_cvt_pk_bf16_f32 v4, v4, v5
	v_cvt_pk_bf16_f32 v5, v6, v7
	global_store_dwordx2 v[16:17], v[4:5], off
	ds_read_b128 v[0:3], v19 offset:256
	v_pk_mul_f32 v[118:119], v[118:119], v[18:19] op_sel_hi:[1,0]
	v_pk_mul_f32 v[110:111], v[110:111], v[18:19] op_sel_hi:[1,0]
	v_lshlrev_b32_e32 v48, 1, v158
	v_lshl_add_u64 v[112:113], v[36:37], 0, v[48:49]
	v_pk_mul_f32 v[108:109], v[108:109], v[18:19] op_sel_hi:[1,0]
	v_pk_mul_f32 v[106:107], v[106:107], v[18:19] op_sel_hi:[1,0]
	v_pk_mul_f32 v[46:47], v[46:47], v[18:19] op_sel_hi:[1,0]
	v_pk_mul_f32 v[44:45], v[44:45], v[18:19] op_sel_hi:[1,0]
	v_pk_mul_f32 v[42:43], v[42:43], v[18:19] op_sel_hi:[1,0]
	v_pk_mul_f32 v[38:39], v[38:39], v[18:19] op_sel_hi:[1,0]
	v_pk_mul_f32 v[34:35], v[34:35], v[18:19] op_sel_hi:[1,0]
	v_pk_mul_f32 v[32:33], v[32:33], v[18:19] op_sel_hi:[1,0]
	v_pk_mul_f32 v[28:29], v[28:29], v[18:19] op_sel_hi:[1,0]
	v_pk_mul_f32 v[30:31], v[30:31], v[18:19] op_sel_hi:[1,0]
	v_pk_mul_f32 v[26:27], v[26:27], v[18:19] op_sel_hi:[1,0]
	v_pk_mul_f32 v[22:23], v[22:23], v[18:19] op_sel_hi:[1,0]
	v_pk_mul_f32 v[20:21], v[20:21], v[18:19] op_sel_hi:[1,0]
	s_waitcnt vmcnt(10)
	v_mov_b32_e32 v4, v50
	v_mov_b32_e32 v5, v51
	v_lshlrev_b32_e32 v134, 16, v4
	v_and_b32_e32 v135, 0xffff0000, v4
	v_mul_f32_e32 v4, 0xbfb8aa3b, v134
	v_exp_f32_e32 v6, v4
	v_mul_f32_e32 v4, 0xbfb8aa3b, v135
	v_exp_f32_e32 v7, v4
	v_lshlrev_b32_e32 v182, 16, v5
	v_and_b32_e32 v183, 0xffff0000, v5
	v_mul_f32_e32 v5, 0xbfb8aa3b, v183
	v_pk_add_f32 v[122:123], v[6:7], 1.0 op_sel_hi:[1,0]
	v_exp_f32_e32 v5, v5
	s_nop 0
	s_nop 0
	v_mul_f32_e32 v4, 0xbfb8aa3b, v182
	v_exp_f32_e32 v4, v4
	s_nop 0
	v_pk_add_f32 v[124:125], v[4:5], 1.0 op_sel_hi:[1,0]
	s_nop 0
	s_nop 0
	s_movk_i32 s0, 0x1000
	v_lshl_add_u32 v4, v158, 2, s16
	ds_read_b128 v[8:11], v4
	v_add_co_u32_e32 v120, vcc, s0, v102
	s_movk_i32 s0, 0x2000
	s_nop 0
	v_addc_co_u32_e32 v121, vcc, 0, v103, vcc
	s_waitcnt lgkmcnt(0)
	v_pk_mul_f32 v[8:9], v[8:9], v[118:119]
	v_pk_mul_f32 v[10:11], v[10:11], v[110:111]
	v_pk_mul_f32 v[8:9], v[126:127], v[8:9]
	v_pk_mul_f32 v[10:11], v[116:117], v[10:11]
	v_cvt_pk_bf16_f32 v8, v8, v9
	v_cvt_pk_bf16_f32 v9, v10, v11
	global_store_dwordx2 v[112:113], v[8:9], off
	v_add_co_u32_e32 v114, vcc, s0, v102
	ds_read_b128 v[4:7], v19 offset:352
	s_nop 0
	v_addc_co_u32_e32 v115, vcc, 0, v103, vcc
	v_pk_mul_f32 v[0:1], v[0:1], v[26:27]
	s_waitcnt vmcnt(10)
	v_mov_b32_e32 v8, v52
	v_mov_b32_e32 v9, v53
	v_lshlrev_b32_e32 v126, 16, v8
	v_and_b32_e32 v127, 0xffff0000, v8
	v_mul_f32_e32 v8, 0xbfb8aa3b, v126
	v_exp_f32_e32 v10, v8
	v_mul_f32_e32 v8, 0xbfb8aa3b, v127
	v_exp_f32_e32 v11, v8
	v_lshlrev_b32_e32 v130, 16, v9
	v_and_b32_e32 v131, 0xffff0000, v9
	v_mul_f32_e32 v9, 0xbfb8aa3b, v131
	v_pk_add_f32 v[102:103], v[10:11], 1.0 op_sel_hi:[1,0]
	v_exp_f32_e32 v9, v9
	s_nop 0
	v_rcp_f32_e32 v128, v103
	s_nop 0
	v_mul_f32_e32 v103, v127, v128
	v_mul_f32_e32 v8, 0xbfb8aa3b, v130
	v_exp_f32_e32 v8, v8
	v_rcp_f32_e32 v129, v102
	s_nop 0
	v_mul_f32_e32 v102, v126, v129
	v_pk_add_f32 v[116:117], v[8:9], 1.0 op_sel_hi:[1,0]
	s_nop 0
	s_nop 0
	s_nop 0
	v_lshl_add_u32 v8, v160, 2, s16
	ds_read_b128 v[8:11], v8
	v_lshlrev_b32_e32 v48, 1, v160
	v_lshl_add_u64 v[118:119], v[36:37], 0, v[48:49]
	v_lshl_add_u32 v48, v162, 2, s16
	ds_read_b128 v[110:113], v48
	s_waitcnt lgkmcnt(1)
	v_pk_mul_f32 v[8:9], v[8:9], v[108:109]
	v_rcp_f32_e32 v136, v123
	s_nop 0
	v_mul_f32_e32 v109, v135, v136
	v_rcp_f32_e32 v137, v122
	s_nop 0
	v_mul_f32_e32 v108, v134, v137
	v_pk_mul_f32 v[10:11], v[10:11], v[106:107]
	v_rcp_f32_e32 v202, v125
	s_nop 0
	v_mul_f32_e32 v107, v183, v202
	v_rcp_f32_e32 v203, v124
	s_nop 0
	v_mul_f32_e32 v106, v182, v203
	v_pk_mul_f32 v[8:9], v[108:109], v[8:9]
	v_pk_mul_f32 v[10:11], v[106:107], v[10:11]
	v_cvt_pk_bf16_f32 v8, v8, v9
	v_cvt_pk_bf16_f32 v9, v10, v11
	global_store_dwordx2 v[118:119], v[8:9], off
	s_waitcnt lgkmcnt(0)
	v_pk_mul_f32 v[46:47], v[112:113], v[46:47]
	s_waitcnt vmcnt(10)
	v_mov_b32_e32 v8, v54
	v_mov_b32_e32 v9, v55
	v_lshlrev_b32_e32 v118, 16, v8
	v_and_b32_e32 v119, 0xffff0000, v8
	v_mul_f32_e32 v8, 0xbfb8aa3b, v118
	v_exp_f32_e32 v10, v8
	v_mul_f32_e32 v8, 0xbfb8aa3b, v119
	v_exp_f32_e32 v11, v8
	v_lshlrev_b32_e32 v124, 16, v9
	v_and_b32_e32 v125, 0xffff0000, v9
	v_mul_f32_e32 v9, 0xbfb8aa3b, v125
	v_pk_add_f32 v[106:107], v[10:11], 1.0 op_sel_hi:[1,0]
	v_exp_f32_e32 v9, v9
	s_nop 0
	s_nop 0
	v_mul_f32_e32 v8, 0xbfb8aa3b, v124
	v_exp_f32_e32 v8, v8
	s_nop 0
	v_pk_add_f32 v[108:109], v[8:9], 1.0 op_sel_hi:[1,0]
	s_nop 0
	s_nop 0
	s_nop 0
	v_pk_mul_f32 v[10:11], v[104:105], v[18:19] op_sel_hi:[1,0]
	v_lshlrev_b32_e32 v48, 1, v162
	v_pk_mul_f32 v[10:11], v[110:111], v[10:11]
	v_lshl_add_u64 v[8:9], v[36:37], 0, v[48:49]
	v_pk_mul_f32 v[10:11], v[102:103], v[10:11]
	v_rcp_f32_e32 v132, v117
	s_nop 0
	v_mul_f32_e32 v103, v131, v132
	v_rcp_f32_e32 v133, v116
	s_nop 0
	v_mul_f32_e32 v102, v130, v133
	v_pk_mul_f32 v[46:47], v[102:103], v[46:47]
	v_cvt_pk_bf16_f32 v10, v10, v11
	v_cvt_pk_bf16_f32 v11, v46, v47
	global_store_dwordx2 v[8:9], v[10:11], off
	s_waitcnt vmcnt(10)
	v_mov_b32_e32 v8, v56
	v_mov_b32_e32 v9, v57
	v_lshlrev_b32_e32 v116, 16, v8
	v_and_b32_e32 v117, 0xffff0000, v8
	v_mul_f32_e32 v8, 0xbfb8aa3b, v116
	v_exp_f32_e32 v10, v8
	v_mul_f32_e32 v8, 0xbfb8aa3b, v117
	v_exp_f32_e32 v11, v8
	v_lshlrev_b32_e32 v128, 16, v9
	v_and_b32_e32 v129, 0xffff0000, v9
	v_mul_f32_e32 v9, 0xbfb8aa3b, v129
	v_pk_add_f32 v[46:47], v[10:11], 1.0 op_sel_hi:[1,0]
	v_exp_f32_e32 v9, v9
	s_nop 0
	s_nop 0
	v_mul_f32_e32 v8, 0xbfb8aa3b, v128
	v_exp_f32_e32 v8, v8
	s_nop 0
	v_pk_add_f32 v[110:111], v[8:9], 1.0 op_sel_hi:[1,0]
	s_nop 0
	s_nop 0
	s_nop 0
	v_lshl_add_u32 v8, v174, 2, s16
	ds_read_b128 v[8:11], v8
	v_lshlrev_b32_e32 v48, 1, v174
	v_lshl_add_u64 v[112:113], v[36:37], 0, v[48:49]
	v_lshl_add_u32 v48, v176, 2, s16
	ds_read_b128 v[102:105], v48
	s_waitcnt lgkmcnt(1)
	v_pk_mul_f32 v[8:9], v[8:9], v[44:45]
	v_rcp_f32_e32 v122, v107
	s_nop 0
	v_mul_f32_e32 v45, v119, v122
	v_rcp_f32_e32 v123, v106
	s_nop 0
	v_mul_f32_e32 v44, v118, v123
	v_pk_mul_f32 v[10:11], v[10:11], v[42:43]
	v_rcp_f32_e32 v134, v109
	s_nop 0
	v_mul_f32_e32 v43, v125, v134
	v_rcp_f32_e32 v135, v108
	s_nop 0
	v_mul_f32_e32 v42, v124, v135
	v_pk_mul_f32 v[8:9], v[44:45], v[8:9]
	v_pk_mul_f32 v[10:11], v[42:43], v[10:11]
	v_cvt_pk_bf16_f32 v8, v8, v9
	v_cvt_pk_bf16_f32 v9, v10, v11
	global_store_dwordx2 v[112:113], v[8:9], off
	s_waitcnt lgkmcnt(0)
	v_pk_mul_f32 v[38:39], v[104:105], v[38:39]
	s_waitcnt vmcnt(10)
	v_mov_b32_e32 v8, v58
	v_mov_b32_e32 v9, v59
	v_lshlrev_b32_e32 v106, 16, v8
	v_and_b32_e32 v107, 0xffff0000, v8
	v_mul_f32_e32 v8, 0xbfb8aa3b, v106
	v_exp_f32_e32 v10, v8
	v_mul_f32_e32 v8, 0xbfb8aa3b, v107
	v_exp_f32_e32 v11, v8
	v_lshlrev_b32_e32 v112, 16, v9
	v_and_b32_e32 v113, 0xffff0000, v9
	v_mul_f32_e32 v9, 0xbfb8aa3b, v113
	v_pk_add_f32 v[42:43], v[10:11], 1.0 op_sel_hi:[1,0]
	v_exp_f32_e32 v9, v9
	s_nop 0
	s_nop 0
	v_mul_f32_e32 v8, 0xbfb8aa3b, v112
	v_exp_f32_e32 v8, v8
	s_nop 0
	v_pk_add_f32 v[44:45], v[8:9], 1.0 op_sel_hi:[1,0]
	s_nop 0
	s_nop 0
	s_nop 0
	v_pk_mul_f32 v[10:11], v[40:41], v[18:19] op_sel_hi:[1,0]
	v_rcp_f32_e32 v126, v47
	s_nop 0
	v_mul_f32_e32 v41, v117, v126
	v_pk_mul_f32 v[10:11], v[102:103], v[10:11]
	v_rcp_f32_e32 v127, v46
	s_nop 0
	v_mul_f32_e32 v40, v116, v127
	v_pk_mul_f32 v[10:11], v[40:41], v[10:11]
	v_rcp_f32_e32 v130, v111
	s_nop 0
	v_mul_f32_e32 v41, v129, v130
	v_rcp_f32_e32 v131, v110
	s_nop 0
	v_mul_f32_e32 v40, v128, v131
	v_lshlrev_b32_e32 v48, 1, v176
	v_pk_mul_f32 v[38:39], v[40:41], v[38:39]
	v_lshl_add_u64 v[8:9], v[36:37], 0, v[48:49]
	v_cvt_pk_bf16_f32 v10, v10, v11
	v_cvt_pk_bf16_f32 v11, v38, v39
	global_store_dwordx2 v[8:9], v[10:11], off
	v_lshlrev_b32_e32 v48, 1, v178
	v_lshl_add_u64 v[104:105], v[36:37], 0, v[48:49]
	s_waitcnt vmcnt(10)
	v_mov_b32_e32 v8, v60
	v_mov_b32_e32 v9, v61
	v_lshlrev_b32_e32 v110, 16, v8
	v_and_b32_e32 v111, 0xffff0000, v8
	v_mul_f32_e32 v8, 0xbfb8aa3b, v110
	v_exp_f32_e32 v10, v8
	v_mul_f32_e32 v8, 0xbfb8aa3b, v111
	v_exp_f32_e32 v11, v8
	v_lshlrev_b32_e32 v120, 16, v9
	v_and_b32_e32 v121, 0xffff0000, v9
	v_mul_f32_e32 v9, 0xbfb8aa3b, v121
	v_pk_add_f32 v[46:47], v[10:11], 1.0 op_sel_hi:[1,0]
	v_exp_f32_e32 v9, v9
	s_nop 0
	s_nop 0
	v_mul_f32_e32 v8, 0xbfb8aa3b, v120
	v_exp_f32_e32 v8, v8
	s_nop 0
	v_pk_add_f32 v[102:103], v[8:9], 1.0 op_sel_hi:[1,0]
	s_nop 0
	s_nop 0
	s_nop 0
	v_lshl_add_u32 v8, v178, 2, s16
	ds_read_b128 v[8:11], v8
	v_lshl_add_u32 v38, v180, 2, s16
	ds_read_b128 v[38:41], v38
	s_waitcnt lgkmcnt(1)
	v_pk_mul_f32 v[8:9], v[8:9], v[34:35]
	v_rcp_f32_e32 v108, v43
	s_nop 0
	v_mul_f32_e32 v35, v107, v108
	v_rcp_f32_e32 v109, v42
	s_nop 0
	v_mul_f32_e32 v34, v106, v109
	v_pk_mul_f32 v[10:11], v[10:11], v[32:33]
	v_rcp_f32_e32 v118, v45
	s_nop 0
	v_mul_f32_e32 v33, v113, v118
	v_rcp_f32_e32 v119, v44
	s_nop 0
	v_mul_f32_e32 v32, v112, v119
	v_pk_mul_f32 v[8:9], v[34:35], v[8:9]
	v_pk_mul_f32 v[10:11], v[32:33], v[10:11]
	v_cvt_pk_bf16_f32 v8, v8, v9
	v_cvt_pk_bf16_f32 v9, v10, v11
	global_store_dwordx2 v[104:105], v[8:9], off
	s_waitcnt lgkmcnt(0)
	v_pk_mul_f32 v[28:29], v[38:39], v[28:29]
	v_pk_mul_f32 v[30:31], v[40:41], v[30:31]
	s_waitcnt vmcnt(10)
	v_mov_b32_e32 v8, v62
	v_mov_b32_e32 v9, v63
	v_lshlrev_b32_e32 v42, 16, v8
	v_and_b32_e32 v43, 0xffff0000, v8
	v_mul_f32_e32 v8, 0xbfb8aa3b, v42
	v_exp_f32_e32 v10, v8
	v_mul_f32_e32 v8, 0xbfb8aa3b, v43
	v_exp_f32_e32 v11, v8
	v_lshlrev_b32_e32 v104, 16, v9
	v_and_b32_e32 v105, 0xffff0000, v9
	v_mul_f32_e32 v9, 0xbfb8aa3b, v105
	v_pk_add_f32 v[10:11], v[10:11], 1.0 op_sel_hi:[1,0]
	v_exp_f32_e32 v9, v9
	s_nop 0
	v_rcp_f32_e32 v44, v11
	s_nop 0
	v_mul_f32_e32 v11, v43, v44
	v_mul_f32_e32 v8, 0xbfb8aa3b, v104
	v_exp_f32_e32 v8, v8
	v_rcp_f32_e32 v45, v10
	s_nop 0
	v_mul_f32_e32 v10, v42, v45
	v_pk_mul_f32 v[0:1], v[10:11], v[0:1]
	v_pk_mul_f32 v[10:11], v[24:25], v[18:19] op_sel_hi:[1,0]
	v_pk_add_f32 v[8:9], v[8:9], 1.0 op_sel_hi:[1,0]
	v_pk_mul_f32 v[2:3], v[2:3], v[10:11]
	v_cvt_pk_bf16_f32 v0, v0, v1
	v_rcp_f32_e32 v106, v9
	s_nop 0
	v_mul_f32_e32 v9, v105, v106
	v_rcp_f32_e32 v116, v47
	s_nop 0
	v_mul_f32_e32 v35, v111, v116
	v_rcp_f32_e32 v117, v46
	s_nop 0
	v_mul_f32_e32 v34, v110, v117
	v_pk_mul_f32 v[28:29], v[34:35], v[28:29]
	v_rcp_f32_e32 v122, v103
	s_nop 0
	v_mul_f32_e32 v35, v121, v122
	v_rcp_f32_e32 v123, v102
	s_nop 0
	v_mul_f32_e32 v34, v120, v123
	v_lshlrev_b32_e32 v48, 1, v180
	v_pk_mul_f32 v[30:31], v[34:35], v[30:31]
	v_lshl_add_u64 v[32:33], v[36:37], 0, v[48:49]
	v_cvt_pk_bf16_f32 v28, v28, v29
	v_cvt_pk_bf16_f32 v29, v30, v31
	global_store_dwordx2 v[32:33], v[28:29], off
	v_rcp_f32_e32 v107, v8
	s_nop 0
	v_mul_f32_e32 v8, v104, v107
	v_pk_mul_f32 v[2:3], v[8:9], v[2:3]
	s_waitcnt vmcnt(10)
	v_mov_b32_e32 v28, v64
	v_mov_b32_e32 v29, v65
	v_lshlrev_b32_e32 v32, 16, v28
	v_cvt_pk_bf16_f32 v1, v2, v3
	global_store_dwordx2 v[16:17], v[0:1], off offset:128
	v_and_b32_e32 v33, 0xffff0000, v28
	v_mul_f32_e32 v28, 0xbfb8aa3b, v32
	v_exp_f32_e32 v30, v28
	v_mul_f32_e32 v28, 0xbfb8aa3b, v33
	v_exp_f32_e32 v31, v28
	s_waitcnt vmcnt(10)
	v_mov_b32_e32 v0, v66
	v_mov_b32_e32 v1, v67
	v_lshlrev_b32_e32 v44, 16, v1
	v_pk_add_f32 v[30:31], v[30:31], 1.0 op_sel_hi:[1,0]
	v_and_b32_e32 v45, 0xffff0000, v1
	v_mul_f32_e32 v1, 0xbfb8aa3b, v45
	v_exp_f32_e32 v1, v1
	s_nop 0
	v_lshlrev_b32_e32 v36, 16, v29
	v_and_b32_e32 v37, 0xffff0000, v29
	v_mul_f32_e32 v28, 0xbfb8aa3b, v36
	v_mul_f32_e32 v29, 0xbfb8aa3b, v37
	v_exp_f32_e32 v28, v28
	v_exp_f32_e32 v29, v29
	s_nop 0
	v_pk_add_f32 v[28:29], v[28:29], 1.0 op_sel_hi:[1,0]
	s_nop 0
	s_nop 0
	s_nop 0
	v_lshlrev_b32_e32 v40, 16, v0
	v_and_b32_e32 v41, 0xffff0000, v0
	v_mul_f32_e32 v0, 0xbfb8aa3b, v40
	v_exp_f32_e32 v2, v0
	v_mul_f32_e32 v0, 0xbfb8aa3b, v41
	v_exp_f32_e32 v3, v0
	s_nop 0
	v_pk_add_f32 v[24:25], v[2:3], 1.0 op_sel_hi:[1,0]
	s_nop 0
	s_nop 0
	s_nop 0
	v_mul_f32_e32 v0, 0xbfb8aa3b, v44
	v_exp_f32_e32 v0, v0
	s_nop 0
	v_pk_add_f32 v[26:27], v[0:1], 1.0 op_sel_hi:[1,0]
	s_nop 0
	s_nop 0
	s_nop 0
	ds_read_b128 v[0:3], v19 offset:288
	ds_read_b128 v[8:11], v19 offset:320
	s_waitcnt lgkmcnt(1)
	v_pk_mul_f32 v[0:1], v[0:1], v[22:23]
	v_rcp_f32_e32 v34, v31
	s_nop 0
	v_mul_f32_e32 v23, v33, v34
	v_rcp_f32_e32 v35, v30
	s_nop 0
	v_mul_f32_e32 v22, v32, v35
	v_pk_mul_f32 v[2:3], v[2:3], v[20:21]
	v_rcp_f32_e32 v38, v29
	s_nop 0
	v_mul_f32_e32 v21, v37, v38
	v_rcp_f32_e32 v39, v28
	s_nop 0
	v_mul_f32_e32 v20, v36, v39
	v_pk_mul_f32 v[0:1], v[22:23], v[0:1]
	v_pk_mul_f32 v[2:3], v[20:21], v[2:3]
	v_cvt_pk_bf16_f32 v0, v0, v1
	v_cvt_pk_bf16_f32 v1, v2, v3
	global_store_dwordx2 v[16:17], v[0:1], off offset:144
	s_waitcnt vmcnt(10)
	v_mov_b32_e32 v0, v68
	v_mov_b32_e32 v1, v69
	v_lshrrev_b32_e32 v124, 6, v224
	v_mul_u32_u24_e32 v124, 0x1400, v124
	v_and_b32_e32 v126, 63, v224
	v_lshl_add_u32 v124, v126, 4, v124
	v_add_u32_e32 v124, 0x21000, v124
	ds_read_b128 v[50:53], v124
	ds_read_b128 v[54:57], v124 offset:1024
	ds_read_b128 v[58:61], v124 offset:2048
	ds_read_b128 v[62:65], v124 offset:3072
	ds_read_b128 v[66:69], v124 offset:4096
	v_lshlrev_b32_e32 v19, 16, v0
	v_and_b32_e32 v20, 0xffff0000, v0
	v_mul_f32_e32 v0, 0xbfb8aa3b, v19
	v_exp_f32_e32 v2, v0
	v_mul_f32_e32 v0, 0xbfb8aa3b, v20
	v_exp_f32_e32 v3, v0
	v_pk_mul_f32 v[14:15], v[14:15], v[18:19] op_sel_hi:[1,0]
	v_pk_add_f32 v[2:3], v[2:3], 1.0 op_sel_hi:[1,0]
	s_nop 0
	s_waitcnt lgkmcnt(0)
	v_pk_mul_f32 v[8:9], v[8:9], v[14:15]
	v_rcp_f32_e32 v42, v25
	s_nop 0
	v_mul_f32_e32 v15, v41, v42
	v_rcp_f32_e32 v43, v24
	s_nop 0
	v_mul_f32_e32 v14, v40, v43
	v_pk_mul_f32 v[8:9], v[14:15], v[8:9]
	v_pk_mul_f32 v[14:15], v[100:101], v[18:19] op_sel_hi:[1,0]
	v_cvt_pk_bf16_f32 v8, v8, v9
	v_lshlrev_b32_e32 v23, 16, v1
	v_and_b32_e32 v28, 0xffff0000, v1
	v_mul_f32_e32 v0, 0xbfb8aa3b, v23
	v_mul_f32_e32 v1, 0xbfb8aa3b, v28
	v_exp_f32_e32 v0, v0
	v_exp_f32_e32 v1, v1
	v_pk_mul_f32 v[10:11], v[10:11], v[14:15]
	v_rcp_f32_e32 v46, v27
	s_nop 0
	v_mul_f32_e32 v15, v45, v46
	v_rcp_f32_e32 v47, v26
	s_nop 0
	v_mul_f32_e32 v14, v44, v47
	v_pk_add_f32 v[0:1], v[0:1], 1.0 op_sel_hi:[1,0]
	v_pk_mul_f32 v[10:11], v[14:15], v[10:11]
	v_cvt_pk_bf16_f32 v9, v10, v11
	global_store_dwordx2 v[16:17], v[8:9], off offset:160
	v_pk_mul_f32 v[8:9], v[98:99], v[18:19] op_sel_hi:[1,0]
	v_pk_mul_f32 v[4:5], v[4:5], v[8:9]
	v_rcp_f32_e32 v21, v3
	s_nop 0
	v_mul_f32_e32 v3, v20, v21
	v_rcp_f32_e32 v22, v2
	s_nop 0
	v_mul_f32_e32 v2, v19, v22
	v_pk_mul_f32 v[2:3], v[2:3], v[4:5]
	v_pk_mul_f32 v[4:5], v[12:13], v[18:19] op_sel_hi:[1,0]
	v_rcp_f32_e32 v29, v1
	s_nop 0
	v_mul_f32_e32 v1, v28, v29
	v_pk_mul_f32 v[4:5], v[6:7], v[4:5]
	v_rcp_f32_e32 v30, v0
	s_nop 0
	v_mul_f32_e32 v0, v23, v30
	v_pk_mul_f32 v[0:1], v[0:1], v[4:5]
	v_cvt_pk_bf16_f32 v2, v2, v3
	v_cvt_pk_bf16_f32 v3, v0, v1
	global_store_dwordx2 v[16:17], v[2:3], off offset:176
	s_branch .LBB0_855

.LBB0_982:
	s_add_i32 s22, s7, 0x100
	s_add_u32 s7, s14, s7
	s_addc_u32 s23, s15, 0
	s_add_u32 s24, s7, 0x100
	s_addc_u32 s25, s23, 0
	s_and_b64 s[20:21], s[18:19], exec
	s_cselect_b32 s25, s11, s25
	s_cselect_b32 s24, s10, s24
	s_add_i32 s49, 0, 0x10000
	s_and_b64 s[18:19], s[18:19], exec
	s_cselect_b32 s19, 0, s22
	s_cselect_b32 s18, 0, 0
	s_add_u32 s26, s0, s19
	s_addc_u32 s27, s1, s18
	s_add_u32 s28, s7, 0x10080
	s_addc_u32 s29, s23, 0
	s_add_i32 s53, s49, s35
	s_add_i32 m0, s13, 0xc000
	s_add_i32 s54, s13, 0xe000
	s_add_i32 s52, 0, 0x14000
	s_add_i32 s51, s53, 0x2000
	s_add_u32 s22, s26, 0x10000
	v_add_u32_e32 v36, s49, v205
	s_addc_u32 s23, s27, 0
	s_add_i32 s48, s52, s35
	ds_read_b128 v[16:19], v36
	ds_read_b128 v[20:23], v36 offset:1024
	ds_read_b128 v[32:35], v36 offset:2048
	ds_read_b128 v[36:39], v36 offset:3072
	s_add_i32 s47, s48, 0x2000
	s_add_i32 s46, 0, 0x18000
	s_add_u32 s20, s24, 0x10000
	s_addc_u32 s21, s25, 0
	s_add_i32 s45, s46, s35
	s_add_i32 s44, 0, 0x1c000
	s_add_i32 s7, s45, 0x2000
	s_add_u32 s18, s26, 0x10080
	s_addc_u32 s19, s27, 0
	s_add_i32 s50, s44, s35
	s_add_i32 s49, s50, 0x2000
	v_lshl_add_u64 v[190:191], s[28:29], 0, v[48:49]
	ds_read_b128 v[98:101], v206
	ds_read_b128 v[110:113], v206 offset:1024
	ds_read_b128 v[114:117], v206 offset:2048
	ds_read_b128 v[130:133], v206 offset:3072
	ds_read_b128 v[138:141], v206 offset:4096
	ds_read_b128 v[150:153], v206 offset:5120
	ds_read_b128 v[162:165], v206 offset:6144
	ds_read_b128 v[174:177], v206 offset:7168
	global_load_lds_dwordx4 v[190:191], off
	v_lshl_add_u64 v[190:191], s[28:29], 0, v[180:181]
	s_mov_b32 m0, s54
	s_nop 0
	global_load_lds_dwordx4 v[190:191], off
	s_waitcnt lgkmcnt(8)
	s_barrier
	s_waitcnt lgkmcnt(0)
	s_setprio 1
	s_waitcnt lgkmcnt(0)
	v_mfma_f32_16x16x32_bf16 v[170:173], v[16:19], v[98:101], v[170:173]
	v_mfma_f32_16x16x32_bf16 v[166:169], v[32:35], v[98:101], v[166:169]
	v_mfma_f32_16x16x32_bf16 v[146:149], v[16:19], v[114:117], v[146:149]
	v_mfma_f32_16x16x32_bf16 v[142:145], v[32:35], v[114:117], v[142:145]
	v_mfma_f32_16x16x32_bf16 v[122:125], v[16:19], v[138:141], v[122:125]
	v_mfma_f32_16x16x32_bf16 v[118:121], v[32:35], v[138:141], v[118:121]
	v_mfma_f32_16x16x32_bf16 v[94:97], v[16:19], v[162:165], v[94:97]
	v_mfma_f32_16x16x32_bf16 v[90:93], v[32:35], v[162:165], v[90:93]
	v_mfma_f32_16x16x32_bf16 v[170:173], v[20:23], v[110:113], v[170:173]
	v_mfma_f32_16x16x32_bf16 v[166:169], v[36:39], v[110:113], v[166:169]
	v_mfma_f32_16x16x32_bf16 v[146:149], v[20:23], v[130:133], v[146:149]
	v_mfma_f32_16x16x32_bf16 v[142:145], v[36:39], v[130:133], v[142:145]
	v_mfma_f32_16x16x32_bf16 v[122:125], v[20:23], v[150:153], v[122:125]
	v_mfma_f32_16x16x32_bf16 v[118:121], v[36:39], v[150:153], v[118:121]
	v_mfma_f32_16x16x32_bf16 v[94:97], v[20:23], v[174:177], v[94:97]
	v_mfma_f32_16x16x32_bf16 v[90:93], v[36:39], v[174:177], v[90:93]
	s_setprio 0
	s_barrier
	v_add_u32_e32 v202, s52, v205
	s_mov_b32 m0, s53
	ds_read_b128 v[190:193], v202
	ds_read_b128 v[198:201], v202 offset:1024
	ds_read_b128 v[208:211], v202 offset:2048
	ds_read_b128 v[212:215], v202 offset:3072
	v_lshl_add_u64 v[202:203], s[26:27], 0, v[182:183]
	global_load_lds_dwordx4 v[202:203], off
	v_lshl_add_u64 v[242:243], s[26:27], 0, v[178:179]
	s_mov_b32 m0, s51
	s_nop 0
	global_load_lds_dwordx4 v[242:243], off
	s_barrier
	s_waitcnt lgkmcnt(0)
	s_setprio 1
	s_waitcnt lgkmcnt(0)
	v_mfma_f32_16x16x32_bf16 v[158:161], v[190:193], v[98:101], v[158:161]
	v_mfma_f32_16x16x32_bf16 v[98:101], v[208:211], v[98:101], v[154:157]
	v_mfma_f32_16x16x32_bf16 v[106:109], v[190:193], v[138:141], v[106:109]
	v_mfma_f32_16x16x32_bf16 v[102:105], v[208:211], v[138:141], v[102:105]
	v_mfma_f32_16x16x32_bf16 v[86:89], v[190:193], v[162:165], v[86:89]
	v_mfma_f32_16x16x32_bf16 v[82:85], v[208:211], v[162:165], v[82:85]
	v_mfma_f32_16x16x32_bf16 v[158:161], v[198:201], v[110:113], v[158:161]
	v_mfma_f32_16x16x32_bf16 v[98:101], v[212:215], v[110:113], v[98:101]
	v_mfma_f32_16x16x32_bf16 v[110:113], v[190:193], v[114:117], v[134:137]
	v_mfma_f32_16x16x32_bf16 v[114:117], v[208:211], v[114:117], v[126:129]
	v_mfma_f32_16x16x32_bf16 v[106:109], v[198:201], v[150:153], v[106:109]
	v_mfma_f32_16x16x32_bf16 v[102:105], v[212:215], v[150:153], v[102:105]
	v_mfma_f32_16x16x32_bf16 v[86:89], v[198:201], v[174:177], v[86:89]
	v_mfma_f32_16x16x32_bf16 v[82:85], v[212:215], v[174:177], v[82:85]
	v_mfma_f32_16x16x32_bf16 v[110:113], v[198:201], v[130:133], v[110:113]
	v_mfma_f32_16x16x32_bf16 v[114:117], v[212:215], v[130:133], v[114:117]
	s_setprio 0
	s_mov_b32 m0, s13
	v_lshl_add_u64 v[244:245], s[24:25], 0, v[48:49]
	s_barrier
	ds_read_b128 v[126:129], v206 offset:16384
	ds_read_b128 v[130:133], v206 offset:17408
	ds_read_b128 v[134:137], v206 offset:18432
	ds_read_b128 v[138:141], v206 offset:19456
	ds_read_b128 v[150:153], v206 offset:20480
	ds_read_b128 v[154:157], v206 offset:21504
	ds_read_b128 v[162:165], v206 offset:22528
	ds_read_b128 v[174:177], v206 offset:23552
	global_load_lds_dwordx4 v[244:245], off
	v_lshl_add_u64 v[246:247], s[24:25], 0, v[180:181]
	s_mov_b32 m0, s38
	s_nop 0
	global_load_lds_dwordx4 v[246:247], off
	s_barrier
	s_waitcnt lgkmcnt(0)
	s_setprio 1
	s_waitcnt lgkmcnt(0)
	v_mfma_f32_16x16x32_bf16 v[78:81], v[16:19], v[126:129], v[78:81]
	v_mfma_f32_16x16x32_bf16 v[74:77], v[32:35], v[126:129], v[74:77]
	v_mfma_f32_16x16x32_bf16 v[62:65], v[16:19], v[134:137], v[62:65]
	v_mfma_f32_16x16x32_bf16 v[58:61], v[32:35], v[134:137], v[58:61]
	v_mfma_f32_16x16x32_bf16 v[44:47], v[16:19], v[150:153], v[44:47]
	v_mfma_f32_16x16x32_bf16 v[40:43], v[32:35], v[150:153], v[40:43]
	v_mfma_f32_16x16x32_bf16 v[12:15], v[16:19], v[162:165], v[12:15]
	v_mfma_f32_16x16x32_bf16 v[8:11], v[32:35], v[162:165], v[8:11]
	v_mfma_f32_16x16x32_bf16 v[78:81], v[20:23], v[130:133], v[78:81]
	v_mfma_f32_16x16x32_bf16 v[74:77], v[36:39], v[130:133], v[74:77]
	v_mfma_f32_16x16x32_bf16 v[62:65], v[20:23], v[138:141], v[62:65]
	v_mfma_f32_16x16x32_bf16 v[58:61], v[36:39], v[138:141], v[58:61]
	v_mfma_f32_16x16x32_bf16 v[44:47], v[20:23], v[154:157], v[44:47]
	v_mfma_f32_16x16x32_bf16 v[40:43], v[36:39], v[154:157], v[40:43]
	v_mfma_f32_16x16x32_bf16 v[12:15], v[20:23], v[174:177], v[12:15]
	v_mfma_f32_16x16x32_bf16 v[8:11], v[36:39], v[174:177], v[8:11]
	s_setprio 0
	s_barrier
	s_mov_b32 m0, s48
	v_lshl_add_u64 v[16:17], s[22:23], 0, v[182:183]
	global_load_lds_dwordx4 v[16:17], off
	v_lshl_add_u64 v[16:17], s[22:23], 0, v[178:179]
	s_mov_b32 m0, s47
	s_nop 0
	global_load_lds_dwordx4 v[16:17], off
	s_waitcnt vmcnt(6)
	s_barrier
	s_setprio 1
	v_mfma_f32_16x16x32_bf16 v[28:31], v[190:193], v[150:153], v[28:31]
	v_mfma_f32_16x16x32_bf16 v[24:27], v[208:211], v[150:153], v[24:27]
	v_mfma_f32_16x16x32_bf16 v[4:7], v[190:193], v[162:165], v[4:7]
	v_mfma_f32_16x16x32_bf16 v[0:3], v[208:211], v[162:165], v[0:3]
	v_mfma_f32_16x16x32_bf16 v[16:19], v[190:193], v[126:129], v[70:73]
	v_mfma_f32_16x16x32_bf16 v[20:23], v[208:211], v[126:129], v[66:69]
	v_mfma_f32_16x16x32_bf16 v[32:35], v[190:193], v[134:137], v[54:57]
	v_mfma_f32_16x16x32_bf16 v[36:39], v[208:211], v[134:137], v[50:53]
	v_mfma_f32_16x16x32_bf16 v[28:31], v[198:201], v[154:157], v[28:31]
	v_mfma_f32_16x16x32_bf16 v[24:27], v[212:215], v[154:157], v[24:27]
	v_mfma_f32_16x16x32_bf16 v[4:7], v[198:201], v[174:177], v[4:7]
	v_mfma_f32_16x16x32_bf16 v[0:3], v[212:215], v[174:177], v[0:3]
	v_mfma_f32_16x16x32_bf16 v[16:19], v[198:201], v[130:133], v[16:19]
	v_mfma_f32_16x16x32_bf16 v[20:23], v[212:215], v[130:133], v[20:23]
	v_mfma_f32_16x16x32_bf16 v[32:35], v[198:201], v[138:141], v[32:35]
	v_mfma_f32_16x16x32_bf16 v[36:39], v[212:215], v[138:141], v[36:39]
	s_setprio 0
	v_add_u32_e32 v70, s46, v205
	s_barrier
	ds_read_b128 v[50:53], v70
	ds_read_b128 v[54:57], v70 offset:1024
	ds_read_b128 v[66:69], v70 offset:2048
	ds_read_b128 v[70:73], v70 offset:3072
	s_mov_b32 m0, s39
	v_lshl_add_u64 v[134:135], s[20:21], 0, v[48:49]
	ds_read_b128 v[126:129], v206 offset:32768
	ds_read_b128 v[130:133], v206 offset:33792
	ds_read_b128 v[138:141], v206 offset:34816
	ds_read_b128 v[150:153], v206 offset:35840
	ds_read_b128 v[162:165], v206 offset:36864
	ds_read_b128 v[174:177], v206 offset:37888
	ds_read_b128 v[190:193], v206 offset:38912
	ds_read_b128 v[198:201], v206 offset:39936
	global_load_lds_dwordx4 v[134:135], off
	v_lshl_add_u64 v[134:135], s[20:21], 0, v[180:181]
	s_mov_b32 m0, s40
	s_nop 0
	global_load_lds_dwordx4 v[134:135], off
	s_waitcnt lgkmcnt(8)
	s_barrier
	s_waitcnt lgkmcnt(0)
	s_setprio 1
	s_waitcnt lgkmcnt(0)
	v_mfma_f32_16x16x32_bf16 v[134:137], v[50:53], v[126:129], v[170:173]
	v_mfma_f32_16x16x32_bf16 v[170:173], v[54:57], v[130:133], v[134:137]
	v_mfma_f32_16x16x32_bf16 v[134:137], v[66:69], v[126:129], v[166:169]
	v_mfma_f32_16x16x32_bf16 v[166:169], v[70:73], v[130:133], v[134:137]
	v_mfma_f32_16x16x32_bf16 v[134:137], v[50:53], v[138:141], v[146:149]
	v_mfma_f32_16x16x32_bf16 v[146:149], v[54:57], v[150:153], v[134:137]
	v_mfma_f32_16x16x32_bf16 v[134:137], v[66:69], v[138:141], v[142:145]
	v_mfma_f32_16x16x32_bf16 v[122:125], v[50:53], v[162:165], v[122:125]
	v_mfma_f32_16x16x32_bf16 v[118:121], v[66:69], v[162:165], v[118:121]
	v_mfma_f32_16x16x32_bf16 v[94:97], v[50:53], v[190:193], v[94:97]
	v_mfma_f32_16x16x32_bf16 v[90:93], v[66:69], v[190:193], v[90:93]
	v_mfma_f32_16x16x32_bf16 v[142:145], v[70:73], v[150:153], v[134:137]
	v_mfma_f32_16x16x32_bf16 v[122:125], v[54:57], v[174:177], v[122:125]
	v_mfma_f32_16x16x32_bf16 v[118:121], v[70:73], v[174:177], v[118:121]
	v_mfma_f32_16x16x32_bf16 v[94:97], v[54:57], v[198:201], v[94:97]
	v_mfma_f32_16x16x32_bf16 v[90:93], v[70:73], v[198:201], v[90:93]
	s_setprio 0
	s_barrier
	v_add_u32_e32 v134, s44, v205
	s_mov_b32 m0, s45
	ds_read_b128 v[208:211], v134
	ds_read_b128 v[212:215], v134 offset:1024
	ds_read_b128 v[216:219], v134 offset:2048
	ds_read_b128 v[220:223], v134 offset:3072
	v_lshl_add_u64 v[134:135], v[202:203], 0, s[66:67]
	global_load_lds_dwordx4 v[134:135], off
	v_lshl_add_u64 v[134:135], v[242:243], 0, s[66:67]
	s_mov_b32 m0, s7
	s_nop 0
	global_load_lds_dwordx4 v[134:135], off
	s_barrier
	s_waitcnt lgkmcnt(0)
	s_setprio 1
	s_waitcnt lgkmcnt(0)
	v_mfma_f32_16x16x32_bf16 v[98:101], v[216:219], v[126:129], v[98:101]
	v_mfma_f32_16x16x32_bf16 v[134:137], v[208:211], v[126:129], v[158:161]
	v_mfma_f32_16x16x32_bf16 v[154:157], v[220:223], v[130:133], v[98:101]
	v_mfma_f32_16x16x32_bf16 v[98:101], v[208:211], v[138:141], v[110:113]
	v_mfma_f32_16x16x32_bf16 v[158:161], v[212:215], v[130:133], v[134:137]
	v_mfma_f32_16x16x32_bf16 v[134:137], v[212:215], v[150:153], v[98:101]
	v_mfma_f32_16x16x32_bf16 v[98:101], v[216:219], v[138:141], v[114:117]
	v_mfma_f32_16x16x32_bf16 v[126:129], v[220:223], v[150:153], v[98:101]
	v_mfma_f32_16x16x32_bf16 v[98:101], v[208:211], v[162:165], v[106:109]
	v_mfma_f32_16x16x32_bf16 v[106:109], v[212:215], v[174:177], v[98:101]
	v_mfma_f32_16x16x32_bf16 v[98:101], v[216:219], v[162:165], v[102:105]
	v_mfma_f32_16x16x32_bf16 v[86:89], v[208:211], v[190:193], v[86:89]
	v_mfma_f32_16x16x32_bf16 v[82:85], v[216:219], v[190:193], v[82:85]
	v_mfma_f32_16x16x32_bf16 v[102:105], v[220:223], v[174:177], v[98:101]
	v_mfma_f32_16x16x32_bf16 v[86:89], v[212:215], v[198:201], v[86:89]
	v_mfma_f32_16x16x32_bf16 v[82:85], v[220:223], v[198:201], v[82:85]
	s_setprio 0
	s_mov_b32 m0, s41
	v_lshl_add_u64 v[190:191], v[244:245], 0, s[66:67]
	s_barrier
	ds_read_b128 v[98:101], v206 offset:49152
	ds_read_b128 v[110:113], v206 offset:50176
	ds_read_b128 v[114:117], v206 offset:51200
	ds_read_b128 v[130:133], v206 offset:52224
	ds_read_b128 v[138:141], v206 offset:53248
	ds_read_b128 v[150:153], v206 offset:54272
	ds_read_b128 v[162:165], v206 offset:55296
	ds_read_b128 v[174:177], v206 offset:56320
	global_load_lds_dwordx4 v[190:191], off
	v_lshl_add_u64 v[190:191], v[246:247], 0, s[66:67]
	s_mov_b32 m0, s42
	s_nop 0
	global_load_lds_dwordx4 v[190:191], off
	s_barrier
	s_waitcnt lgkmcnt(0)
	s_setprio 1
	s_waitcnt lgkmcnt(0)
	v_mfma_f32_16x16x32_bf16 v[78:81], v[50:53], v[98:101], v[78:81]
	v_mfma_f32_16x16x32_bf16 v[74:77], v[66:69], v[98:101], v[74:77]
	v_mfma_f32_16x16x32_bf16 v[62:65], v[50:53], v[114:117], v[62:65]
	v_mfma_f32_16x16x32_bf16 v[58:61], v[66:69], v[114:117], v[58:61]
	v_mfma_f32_16x16x32_bf16 v[44:47], v[50:53], v[138:141], v[44:47]
	v_mfma_f32_16x16x32_bf16 v[40:43], v[66:69], v[138:141], v[40:43]
	v_mfma_f32_16x16x32_bf16 v[12:15], v[50:53], v[162:165], v[12:15]
	v_mfma_f32_16x16x32_bf16 v[8:11], v[66:69], v[162:165], v[8:11]
	v_mfma_f32_16x16x32_bf16 v[78:81], v[54:57], v[110:113], v[78:81]
	v_mfma_f32_16x16x32_bf16 v[74:77], v[70:73], v[110:113], v[74:77]
	v_mfma_f32_16x16x32_bf16 v[62:65], v[54:57], v[130:133], v[62:65]
	v_mfma_f32_16x16x32_bf16 v[58:61], v[70:73], v[130:133], v[58:61]
	v_mfma_f32_16x16x32_bf16 v[44:47], v[54:57], v[150:153], v[44:47]
	v_mfma_f32_16x16x32_bf16 v[40:43], v[70:73], v[150:153], v[40:43]
	v_mfma_f32_16x16x32_bf16 v[12:15], v[54:57], v[174:177], v[12:15]
	v_mfma_f32_16x16x32_bf16 v[8:11], v[70:73], v[174:177], v[8:11]
	s_setprio 0
	s_barrier
	s_mov_b32 m0, s50
	v_lshl_add_u64 v[50:51], s[18:19], 0, v[182:183]
	global_load_lds_dwordx4 v[50:51], off
	v_lshl_add_u64 v[50:51], s[18:19], 0, v[178:179]
	s_mov_b32 m0, s49
	s_nop 0
	global_load_lds_dwordx4 v[50:51], off
	s_waitcnt vmcnt(6)
	s_barrier
	s_setprio 1
	v_mfma_f32_16x16x32_bf16 v[16:19], v[208:211], v[98:101], v[16:19]
	v_mfma_f32_16x16x32_bf16 v[70:73], v[212:215], v[110:113], v[16:19]
	v_mfma_f32_16x16x32_bf16 v[16:19], v[216:219], v[98:101], v[20:23]
	v_mfma_f32_16x16x32_bf16 v[66:69], v[220:223], v[110:113], v[16:19]
	v_mfma_f32_16x16x32_bf16 v[16:19], v[208:211], v[114:117], v[32:35]
	v_mfma_f32_16x16x32_bf16 v[54:57], v[212:215], v[130:133], v[16:19]
	v_mfma_f32_16x16x32_bf16 v[16:19], v[216:219], v[114:117], v[36:39]
	v_mfma_f32_16x16x32_bf16 v[50:53], v[220:223], v[130:133], v[16:19]
	v_mfma_f32_16x16x32_bf16 v[16:19], v[208:211], v[138:141], v[28:31]
	v_mfma_f32_16x16x32_bf16 v[28:31], v[212:215], v[150:153], v[16:19]
	v_mfma_f32_16x16x32_bf16 v[16:19], v[216:219], v[138:141], v[24:27]
	v_mfma_f32_16x16x32_bf16 v[4:7], v[208:211], v[162:165], v[4:7]
	v_mfma_f32_16x16x32_bf16 v[0:3], v[216:219], v[162:165], v[0:3]
	v_mfma_f32_16x16x32_bf16 v[24:27], v[220:223], v[150:153], v[16:19]
	v_mfma_f32_16x16x32_bf16 v[4:7], v[212:215], v[174:177], v[4:7]
	v_mfma_f32_16x16x32_bf16 v[0:3], v[220:223], v[174:177], v[0:3]
	s_setprio 0
	s_andn2_b64 vcc, exec, s[16:17]
	s_mov_b64 s[18:19], -1
	s_mov_b64 s[16:17], 0
	s_movk_i32 s7, 0x100
	s_barrier
	s_cbranch_vccz .LBB0_982
	global_load_dwordx4 v[32:35], v[184:185], off offset:16
	global_load_dwordx4 v[36:39], v[184:185], off
	global_load_dwordx4 v[16:19], v[184:185], off offset:528
	global_load_dwordx4 v[20:23], v[184:185], off offset:512
	v_lshl_add_u32 v190, s12, 8, v204
	v_ashrrev_i32_e32 v191, 31, v190
	v_lshlrev_b64 v[98:99], 9, v[190:191]
	v_lshl_add_u64 v[98:99], v[186:187], 0, v[98:99]
	global_load_dwordx4 v[174:177], v[98:99], off
	global_load_dwordx4 v[162:165], v[98:99], off offset:256
	v_lshlrev_b64 v[202:203], 11, v[190:191]
	v_or_b32_e32 v200, 16, v190
	v_ashrrev_i32_e32 v201, 31, v200
	v_lshlrev_b64 v[98:99], 9, v[200:201]
	v_or_b32_e32 v198, 32, v190
	v_lshl_add_u64 v[98:99], v[186:187], 0, v[98:99]
	v_ashrrev_i32_e32 v199, 31, v198
	global_load_dwordx4 v[150:153], v[98:99], off
	global_load_dwordx4 v[138:141], v[98:99], off offset:256
	v_lshlrev_b64 v[98:99], 9, v[198:199]
	v_or_b32_e32 v192, 48, v190
	v_lshl_add_u64 v[98:99], v[186:187], 0, v[98:99]
	v_ashrrev_i32_e32 v193, 31, v192
	global_load_dwordx4 v[130:133], v[98:99], off
	global_load_dwordx4 v[114:117], v[98:99], off offset:256
	v_lshlrev_b64 v[98:99], 9, v[192:193]
	v_lshl_add_u64 v[98:99], v[186:187], 0, v[98:99]
	global_load_dwordx4 v[110:113], v[98:99], off
	s_nop 0
	global_load_dwordx4 v[98:101], v[98:99], off offset:256
	s_mov_b32 s12, s6
	s_waitcnt vmcnt(0)
	v_pk_add_f32 v[168:169], v[168:169], v[34:35]
	v_pk_add_f32 v[170:171], v[170:171], v[36:37]
	v_pk_add_f32 v[208:209], v[172:173], v[38:39]
	v_pk_add_f32 v[172:173], v[166:167], v[32:33]
	v_mul_f32_e32 v166, 0xbfb8aa3b, v170
	v_mul_f32_e32 v167, 0xbfb8aa3b, v171
	v_exp_f32_e32 v166, v166
	v_exp_f32_e32 v167, v167
	v_lshlrev_b32_e32 v170, 16, v174
	v_and_b32_e32 v171, 0xffff0000, v174
	v_mul_f32_e32 v172, 0xbfb8aa3b, v172
	v_pk_add_f32 v[166:167], v[166:167], 1.0 op_sel_hi:[1,0]
	v_mul_f32_e32 v173, 0xbfb8aa3b, v173
	v_exp_f32_e32 v172, v172
	v_exp_f32_e32 v173, v173
	v_mul_f32_e32 v168, 0xbfb8aa3b, v168
	v_rcp_f32_e32 v167, v167
	s_nop 0
	v_pk_add_f32 v[172:173], v[172:173], 1.0 op_sel_hi:[1,0]
	v_mul_f32_e32 v169, 0xbfb8aa3b, v169
	v_exp_f32_e32 v168, v168
	v_rcp_f32_e32 v166, v166
	s_nop 0
	v_pk_mul_f32 v[166:167], v[166:167], v[170:171]
	v_mul_f32_e32 v170, 0xbfb8aa3b, v208
	v_mul_f32_e32 v171, 0xbfb8aa3b, v209
	v_exp_f32_e32 v170, v170
	v_exp_f32_e32 v171, v171
	v_lshlrev_b32_e32 v174, 16, v175
	v_and_b32_e32 v175, 0xffff0000, v175
	v_exp_f32_e32 v169, v169
	v_pk_add_f32 v[170:171], v[170:171], 1.0 op_sel_hi:[1,0]
	v_pk_add_f32 v[158:159], v[158:159], v[20:21]
	v_pk_add_f32 v[168:169], v[168:169], 1.0 op_sel_hi:[1,0]
	v_pk_add_f32 v[160:161], v[160:161], v[22:23]
	v_pk_add_f32 v[156:157], v[156:157], v[18:19]
	v_rcp_f32_e32 v171, v171
	s_nop 0
	v_mul_f32_e32 v156, 0xbfb8aa3b, v156
	v_mul_f32_e32 v157, 0xbfb8aa3b, v157
	v_exp_f32_e32 v156, v156
	v_rcp_f32_e32 v170, v170
	s_nop 0
	v_pk_mul_f32 v[170:171], v[170:171], v[174:175]
	v_lshlrev_b32_e32 v174, 16, v176
	v_and_b32_e32 v175, 0xffff0000, v176
	v_exp_f32_e32 v157, v157
	v_pk_add_f32 v[146:147], v[146:147], v[36:37]
	v_pk_add_f32 v[148:149], v[148:149], v[38:39]
	v_rcp_f32_e32 v173, v173
	s_nop 0
	v_pk_add_f32 v[156:157], v[156:157], 1.0 op_sel_hi:[1,0]
	v_pk_add_f32 v[144:145], v[144:145], v[34:35]
	v_pk_add_f32 v[134:135], v[134:135], v[20:21]
	v_rcp_f32_e32 v172, v172
	s_nop 0
	v_pk_mul_f32 v[172:173], v[172:173], v[174:175]
	v_lshlrev_b32_e32 v174, 16, v177
	v_and_b32_e32 v175, 0xffff0000, v177
	v_mul_f32_e32 v144, 0xbfb8aa3b, v144
	v_mul_f32_e32 v145, 0xbfb8aa3b, v145
	v_exp_f32_e32 v144, v144
	v_rcp_f32_e32 v169, v169
	s_nop 0
	v_exp_f32_e32 v145, v145
	v_pk_add_f32 v[136:137], v[136:137], v[22:23]
	v_pk_add_f32 v[128:129], v[128:129], v[18:19]
	v_rcp_f32_e32 v168, v168
	s_nop 0
	v_pk_mul_f32 v[174:175], v[168:169], v[174:175]
	v_cvt_pk_bf16_f32 v168, v166, v167
	v_cvt_pk_bf16_f32 v169, v170, v171
	v_cvt_pk_bf16_f32 v170, v172, v173
	v_cvt_pk_bf16_f32 v171, v174, v175
	v_lshl_add_u64 v[166:167], v[188:189], 0, v[202:203]
	global_store_dwordx4 v[166:167], v[168:171], off
	v_pk_add_f32 v[144:145], v[144:145], 1.0 op_sel_hi:[1,0]
	v_mul_f32_e32 v128, 0xbfb8aa3b, v128
	v_pk_add_f32 v[168:169], v[154:155], v[16:17]
	v_mul_f32_e32 v154, 0xbfb8aa3b, v158
	v_mul_f32_e32 v155, 0xbfb8aa3b, v159
	v_exp_f32_e32 v154, v154
	v_exp_f32_e32 v155, v155
	v_lshlrev_b32_e32 v158, 16, v162
	v_and_b32_e32 v159, 0xffff0000, v162
	v_mul_f32_e32 v129, 0xbfb8aa3b, v129
	v_pk_add_f32 v[154:155], v[154:155], 1.0 op_sel_hi:[1,0]
	v_exp_f32_e32 v128, v128
	v_exp_f32_e32 v129, v129
	v_pk_add_f32 v[122:123], v[122:123], v[36:37]
	v_pk_add_f32 v[124:125], v[124:125], v[38:39]
	v_rcp_f32_e32 v155, v155
	s_nop 0
	v_pk_add_f32 v[128:129], v[128:129], 1.0 op_sel_hi:[1,0]
	v_pk_add_f32 v[120:121], v[120:121], v[34:35]
	v_pk_add_f32 v[106:107], v[106:107], v[20:21]
	v_rcp_f32_e32 v154, v154
	s_nop 0
	v_pk_mul_f32 v[154:155], v[154:155], v[158:159]
	v_mul_f32_e32 v158, 0xbfb8aa3b, v160
	v_mul_f32_e32 v159, 0xbfb8aa3b, v161
	v_exp_f32_e32 v158, v158
	v_exp_f32_e32 v159, v159
	v_lshlrev_b32_e32 v160, 16, v163
	v_and_b32_e32 v161, 0xffff0000, v163
	v_cvt_pk_bf16_f32 v154, v154, v155
	v_pk_add_f32 v[158:159], v[158:159], 1.0 op_sel_hi:[1,0]
	v_mul_f32_e32 v120, 0xbfb8aa3b, v120
	v_mul_f32_e32 v121, 0xbfb8aa3b, v121
	v_exp_f32_e32 v120, v120
	v_exp_f32_e32 v121, v121
	v_rcp_f32_e32 v159, v159
	s_nop 0
	v_pk_add_f32 v[120:121], v[120:121], 1.0 op_sel_hi:[1,0]
	v_pk_add_f32 v[108:109], v[108:109], v[22:23]
	v_pk_add_f32 v[104:105], v[104:105], v[18:19]
	v_rcp_f32_e32 v158, v158
	s_nop 0
	v_pk_mul_f32 v[158:159], v[158:159], v[160:161]
	v_mul_f32_e32 v160, 0xbfb8aa3b, v168
	v_mul_f32_e32 v161, 0xbfb8aa3b, v169
	v_exp_f32_e32 v160, v160
	v_exp_f32_e32 v161, v161
	v_lshlrev_b32_e32 v162, 16, v164
	v_and_b32_e32 v163, 0xffff0000, v164
	v_cvt_pk_bf16_f32 v155, v158, v159
	v_pk_add_f32 v[160:161], v[160:161], 1.0 op_sel_hi:[1,0]
	v_mul_f32_e32 v104, 0xbfb8aa3b, v104
	v_mul_f32_e32 v105, 0xbfb8aa3b, v105
	v_exp_f32_e32 v104, v104
	v_exp_f32_e32 v105, v105
	v_rcp_f32_e32 v161, v161
	s_nop 0
	v_pk_add_f32 v[104:105], v[104:105], 1.0 op_sel_hi:[1,0]
	v_pk_add_f32 v[94:95], v[94:95], v[36:37]
	v_pk_add_f32 v[96:97], v[96:97], v[38:39]
	v_rcp_f32_e32 v160, v160
	s_nop 0
	v_pk_mul_f32 v[160:161], v[160:161], v[162:163]
	v_lshlrev_b32_e32 v162, 16, v165
	v_and_b32_e32 v163, 0xffff0000, v165
	v_pk_add_f32 v[92:93], v[92:93], v[34:35]
	v_pk_add_f32 v[86:87], v[86:87], v[20:21]
	v_mul_f32_e32 v92, 0xbfb8aa3b, v92
	v_rcp_f32_e32 v157, v157
	s_nop 0
	v_mul_f32_e32 v93, 0xbfb8aa3b, v93
	v_exp_f32_e32 v92, v92
	v_exp_f32_e32 v93, v93
	v_rcp_f32_e32 v156, v156
	s_nop 0
	v_pk_mul_f32 v[162:163], v[156:157], v[162:163]
	v_cvt_pk_bf16_f32 v156, v160, v161
	v_cvt_pk_bf16_f32 v157, v162, v163
	global_store_dwordx4 v[166:167], v[154:157], off offset:256
	v_pk_add_f32 v[92:93], v[92:93], 1.0 op_sel_hi:[1,0]
	v_pk_add_f32 v[88:89], v[88:89], v[22:23]
	v_pk_add_f32 v[156:157], v[142:143], v[32:33]
	v_mul_f32_e32 v142, 0xbfb8aa3b, v146
	v_mul_f32_e32 v143, 0xbfb8aa3b, v147
	v_exp_f32_e32 v142, v142
	v_exp_f32_e32 v143, v143
	v_lshlrev_b32_e32 v146, 16, v150
	v_and_b32_e32 v147, 0xffff0000, v150
	v_lshlrev_b64 v[154:155], 11, v[200:201]
	v_pk_add_f32 v[142:143], v[142:143], 1.0 op_sel_hi:[1,0]
	v_pk_add_f32 v[84:85], v[84:85], v[18:19]
	v_mul_f32_e32 v84, 0xbfb8aa3b, v84
	v_mul_f32_e32 v85, 0xbfb8aa3b, v85
	v_exp_f32_e32 v84, v84
	v_rcp_f32_e32 v143, v143
	s_nop 0
	v_exp_f32_e32 v85, v85
	v_pk_add_f32 v[78:79], v[78:79], v[36:37]
	v_pk_add_f32 v[80:81], v[80:81], v[38:39]
	v_rcp_f32_e32 v142, v142
	s_nop 0
	v_pk_mul_f32 v[142:143], v[142:143], v[146:147]
	v_mul_f32_e32 v146, 0xbfb8aa3b, v148
	v_mul_f32_e32 v147, 0xbfb8aa3b, v149
	v_exp_f32_e32 v146, v146
	v_exp_f32_e32 v147, v147
	v_lshlrev_b32_e32 v148, 16, v151
	v_and_b32_e32 v149, 0xffff0000, v151
	v_pk_add_f32 v[84:85], v[84:85], 1.0 op_sel_hi:[1,0]
	v_pk_add_f32 v[146:147], v[146:147], 1.0 op_sel_hi:[1,0]
	v_pk_add_f32 v[76:77], v[76:77], v[34:35]
	v_mul_f32_e32 v76, 0xbfb8aa3b, v76
	v_mul_f32_e32 v77, 0xbfb8aa3b, v77
	v_exp_f32_e32 v76, v76
	v_rcp_f32_e32 v147, v147
	s_nop 0
	v_exp_f32_e32 v77, v77
	v_pk_add_f32 v[70:71], v[70:71], v[20:21]
	v_pk_add_f32 v[72:73], v[72:73], v[22:23]
	v_rcp_f32_e32 v146, v146
	s_nop 0
	v_pk_mul_f32 v[146:147], v[146:147], v[148:149]
	v_mul_f32_e32 v148, 0xbfb8aa3b, v156
	v_mul_f32_e32 v149, 0xbfb8aa3b, v157
	v_exp_f32_e32 v148, v148
	v_exp_f32_e32 v149, v149
	v_lshlrev_b32_e32 v150, 16, v152
	v_and_b32_e32 v151, 0xffff0000, v152
	v_pk_add_f32 v[76:77], v[76:77], 1.0 op_sel_hi:[1,0]
	v_pk_add_f32 v[148:149], v[148:149], 1.0 op_sel_hi:[1,0]
	v_pk_add_f32 v[68:69], v[68:69], v[18:19]
	v_mul_f32_e32 v68, 0xbfb8aa3b, v68
	v_mul_f32_e32 v69, 0xbfb8aa3b, v69
	v_exp_f32_e32 v68, v68
	v_rcp_f32_e32 v149, v149
	s_nop 0
	v_exp_f32_e32 v69, v69
	v_pk_add_f32 v[62:63], v[62:63], v[36:37]
	v_pk_add_f32 v[64:65], v[64:65], v[38:39]
	v_rcp_f32_e32 v148, v148
	s_nop 0
	v_pk_mul_f32 v[148:149], v[148:149], v[150:151]
	v_lshlrev_b32_e32 v150, 16, v153
	v_and_b32_e32 v151, 0xffff0000, v153
	v_pk_add_f32 v[68:69], v[68:69], 1.0 op_sel_hi:[1,0]
	v_pk_add_f32 v[60:61], v[60:61], v[34:35]
	v_pk_add_f32 v[54:55], v[54:55], v[20:21]
	v_rcp_f32_e32 v145, v145
	s_nop 0
	v_mul_f32_e32 v60, 0xbfb8aa3b, v60
	v_mul_f32_e32 v61, 0xbfb8aa3b, v61
	v_exp_f32_e32 v60, v60
	v_rcp_f32_e32 v144, v144
	s_nop 0
	v_pk_mul_f32 v[150:151], v[144:145], v[150:151]
	v_cvt_pk_bf16_f32 v144, v142, v143
	v_cvt_pk_bf16_f32 v145, v146, v147
	v_cvt_pk_bf16_f32 v146, v148, v149
	v_cvt_pk_bf16_f32 v147, v150, v151
	v_lshl_add_u64 v[142:143], v[188:189], 0, v[154:155]
	global_store_dwordx4 v[142:143], v[144:147], off
	v_exp_f32_e32 v61, v61
	v_pk_add_f32 v[56:57], v[56:57], v[22:23]
	v_pk_add_f32 v[144:145], v[126:127], v[16:17]
	v_mul_f32_e32 v126, 0xbfb8aa3b, v134
	v_mul_f32_e32 v127, 0xbfb8aa3b, v135
	v_exp_f32_e32 v126, v126
	v_exp_f32_e32 v127, v127
	v_lshlrev_b32_e32 v134, 16, v138
	v_and_b32_e32 v135, 0xffff0000, v138
	v_pk_add_f32 v[60:61], v[60:61], 1.0 op_sel_hi:[1,0]
	v_pk_add_f32 v[126:127], v[126:127], 1.0 op_sel_hi:[1,0]
	v_pk_add_f32 v[52:53], v[52:53], v[18:19]
	v_mul_f32_e32 v52, 0xbfb8aa3b, v52
	v_mul_f32_e32 v53, 0xbfb8aa3b, v53
	v_exp_f32_e32 v52, v52
	v_rcp_f32_e32 v127, v127
	s_nop 0
	v_exp_f32_e32 v53, v53
	v_pk_add_f32 v[44:45], v[44:45], v[36:37]
	v_pk_add_f32 v[46:47], v[46:47], v[38:39]
	v_rcp_f32_e32 v126, v126
	s_nop 0
	v_pk_mul_f32 v[126:127], v[126:127], v[134:135]
	v_mul_f32_e32 v134, 0xbfb8aa3b, v136
	v_mul_f32_e32 v135, 0xbfb8aa3b, v137
	v_exp_f32_e32 v134, v134
	v_exp_f32_e32 v135, v135
	v_lshlrev_b32_e32 v136, 16, v139
	v_and_b32_e32 v137, 0xffff0000, v139
	v_cvt_pk_bf16_f32 v126, v126, v127
	v_pk_add_f32 v[134:135], v[134:135], 1.0 op_sel_hi:[1,0]
	v_pk_add_f32 v[52:53], v[52:53], 1.0 op_sel_hi:[1,0]
	v_pk_add_f32 v[42:43], v[42:43], v[34:35]
	v_pk_add_f32 v[28:29], v[28:29], v[20:21]
	v_mul_f32_e32 v42, 0xbfb8aa3b, v42
	v_rcp_f32_e32 v135, v135
	s_nop 0
	v_mul_f32_e32 v43, 0xbfb8aa3b, v43
	v_exp_f32_e32 v42, v42
	v_exp_f32_e32 v43, v43
	v_rcp_f32_e32 v134, v134
	s_nop 0
	v_pk_mul_f32 v[134:135], v[134:135], v[136:137]
	v_mul_f32_e32 v136, 0xbfb8aa3b, v144
	v_mul_f32_e32 v137, 0xbfb8aa3b, v145
	v_exp_f32_e32 v136, v136
	v_exp_f32_e32 v137, v137
	v_lshlrev_b32_e32 v138, 16, v140
	v_and_b32_e32 v139, 0xffff0000, v140
	v_cvt_pk_bf16_f32 v127, v134, v135
	v_pk_add_f32 v[136:137], v[136:137], 1.0 op_sel_hi:[1,0]
	v_pk_add_f32 v[42:43], v[42:43], 1.0 op_sel_hi:[1,0]
	v_pk_add_f32 v[30:31], v[30:31], v[22:23]
	v_pk_add_f32 v[26:27], v[26:27], v[18:19]
	v_pk_add_f32 v[12:13], v[12:13], v[36:37]
	v_rcp_f32_e32 v137, v137
	s_nop 0
	v_mul_f32_e32 v26, 0xbfb8aa3b, v26
	v_mul_f32_e32 v27, 0xbfb8aa3b, v27
	v_exp_f32_e32 v26, v26
	v_rcp_f32_e32 v136, v136
	s_nop 0
	v_pk_mul_f32 v[136:137], v[136:137], v[138:139]
	v_lshlrev_b32_e32 v138, 16, v141
	v_and_b32_e32 v139, 0xffff0000, v141
	v_exp_f32_e32 v27, v27
	v_pk_add_f32 v[14:15], v[14:15], v[38:39]
	v_pk_add_f32 v[10:11], v[10:11], v[34:35]
	v_rcp_f32_e32 v129, v129
	s_nop 0
	v_pk_add_f32 v[26:27], v[26:27], 1.0 op_sel_hi:[1,0]
	v_mul_f32_e32 v10, 0xbfb8aa3b, v10
	v_mul_f32_e32 v11, 0xbfb8aa3b, v11
	v_rcp_f32_e32 v128, v128
	s_nop 0
	v_pk_mul_f32 v[138:139], v[128:129], v[138:139]
	v_cvt_pk_bf16_f32 v128, v136, v137
	v_cvt_pk_bf16_f32 v129, v138, v139
	global_store_dwordx4 v[142:143], v[126:129], off offset:256
	v_exp_f32_e32 v10, v10
	v_exp_f32_e32 v11, v11
	v_pk_add_f32 v[128:129], v[118:119], v[32:33]
	v_mul_f32_e32 v118, 0xbfb8aa3b, v122
	v_mul_f32_e32 v119, 0xbfb8aa3b, v123
	v_exp_f32_e32 v118, v118
	v_exp_f32_e32 v119, v119
	v_lshlrev_b32_e32 v122, 16, v130
	v_and_b32_e32 v123, 0xffff0000, v130
	v_lshlrev_b64 v[126:127], 11, v[198:199]
	v_pk_add_f32 v[118:119], v[118:119], 1.0 op_sel_hi:[1,0]
	v_pk_add_f32 v[10:11], v[10:11], 1.0 op_sel_hi:[1,0]
	v_pk_add_f32 v[4:5], v[4:5], v[20:21]
	v_pk_add_f32 v[6:7], v[6:7], v[22:23]
	v_pk_add_f32 v[2:3], v[2:3], v[18:19]
	v_rcp_f32_e32 v119, v119
	s_nop 0
	v_mul_f32_e32 v2, 0xbfb8aa3b, v2
	v_mul_f32_e32 v3, 0xbfb8aa3b, v3
	v_exp_f32_e32 v2, v2
	v_rcp_f32_e32 v118, v118
	s_nop 0
	v_pk_mul_f32 v[118:119], v[118:119], v[122:123]
	v_mul_f32_e32 v122, 0xbfb8aa3b, v124
	v_mul_f32_e32 v123, 0xbfb8aa3b, v125
	v_exp_f32_e32 v122, v122
	v_exp_f32_e32 v123, v123
	v_lshlrev_b32_e32 v124, 16, v131
	v_and_b32_e32 v125, 0xffff0000, v131
	v_exp_f32_e32 v3, v3
	v_pk_add_f32 v[122:123], v[122:123], 1.0 op_sel_hi:[1,0]
	v_pk_add_f32 v[2:3], v[2:3], 1.0 op_sel_hi:[1,0]
	s_nop 0
	v_rcp_f32_e32 v123, v123
	s_nop 0
	s_nop 0
	v_rcp_f32_e32 v122, v122
	s_nop 0
	v_pk_mul_f32 v[122:123], v[122:123], v[124:125]
	v_mul_f32_e32 v124, 0xbfb8aa3b, v128
	v_mul_f32_e32 v125, 0xbfb8aa3b, v129
	v_exp_f32_e32 v124, v124
	v_exp_f32_e32 v125, v125
	v_lshlrev_b32_e32 v128, 16, v132
	v_and_b32_e32 v129, 0xffff0000, v132
	v_pk_add_f32 v[124:125], v[124:125], 1.0 op_sel_hi:[1,0]
	s_nop 0
	s_nop 0
	v_rcp_f32_e32 v125, v125
	s_nop 0
	s_nop 0
	v_rcp_f32_e32 v124, v124
	s_nop 0
	v_pk_mul_f32 v[124:125], v[124:125], v[128:129]
	v_lshlrev_b32_e32 v128, 16, v133
	v_and_b32_e32 v129, 0xffff0000, v133
	v_rcp_f32_e32 v121, v121
	s_nop 0
	s_nop 0
	v_rcp_f32_e32 v120, v120
	s_nop 0
	v_pk_mul_f32 v[128:129], v[120:121], v[128:129]
	v_cvt_pk_bf16_f32 v120, v118, v119
	v_cvt_pk_bf16_f32 v121, v122, v123
	v_cvt_pk_bf16_f32 v122, v124, v125
	v_cvt_pk_bf16_f32 v123, v128, v129
	v_lshl_add_u64 v[118:119], v[188:189], 0, v[126:127]
	global_store_dwordx4 v[118:119], v[120:123], off
	s_nop 1
	v_pk_add_f32 v[120:121], v[102:103], v[16:17]
	v_mul_f32_e32 v102, 0xbfb8aa3b, v106
	v_mul_f32_e32 v103, 0xbfb8aa3b, v107
	v_exp_f32_e32 v102, v102
	v_exp_f32_e32 v103, v103
	v_lshlrev_b32_e32 v106, 16, v114
	v_and_b32_e32 v107, 0xffff0000, v114
	v_pk_add_f32 v[102:103], v[102:103], 1.0 op_sel_hi:[1,0]
	s_nop 0
	s_nop 0
	v_rcp_f32_e32 v103, v103
	s_nop 0
	s_nop 0
	v_rcp_f32_e32 v102, v102
	s_nop 0
	v_pk_mul_f32 v[102:103], v[102:103], v[106:107]
	v_mul_f32_e32 v106, 0xbfb8aa3b, v108
	v_mul_f32_e32 v107, 0xbfb8aa3b, v109
	v_exp_f32_e32 v106, v106
	v_exp_f32_e32 v107, v107
	v_lshlrev_b32_e32 v108, 16, v115
	v_and_b32_e32 v109, 0xffff0000, v115
	v_cvt_pk_bf16_f32 v102, v102, v103
	v_pk_add_f32 v[106:107], v[106:107], 1.0 op_sel_hi:[1,0]
	s_nop 0
	s_nop 0
	v_rcp_f32_e32 v107, v107
	s_nop 0
	s_nop 0
	v_rcp_f32_e32 v106, v106
	s_nop 0
	v_pk_mul_f32 v[106:107], v[106:107], v[108:109]
	v_mul_f32_e32 v108, 0xbfb8aa3b, v120
	v_mul_f32_e32 v109, 0xbfb8aa3b, v121
	v_exp_f32_e32 v108, v108
	v_exp_f32_e32 v109, v109
	v_lshlrev_b32_e32 v114, 16, v116
	v_and_b32_e32 v115, 0xffff0000, v116
	v_cvt_pk_bf16_f32 v103, v106, v107
	v_pk_add_f32 v[108:109], v[108:109], 1.0 op_sel_hi:[1,0]
	s_nop 0
	s_nop 0
	v_rcp_f32_e32 v109, v109
	s_nop 0
	s_nop 0
	v_rcp_f32_e32 v108, v108
	s_nop 0
	v_pk_mul_f32 v[108:109], v[108:109], v[114:115]
	v_lshlrev_b32_e32 v114, 16, v117
	v_and_b32_e32 v115, 0xffff0000, v117
	s_nop 0
	v_rcp_f32_e32 v105, v105
	s_nop 0
	s_nop 0
	v_rcp_f32_e32 v104, v104
	s_nop 0
	v_pk_mul_f32 v[114:115], v[104:105], v[114:115]
	v_cvt_pk_bf16_f32 v104, v108, v109
	v_cvt_pk_bf16_f32 v105, v114, v115
	global_store_dwordx4 v[118:119], v[102:105], off offset:256
	v_add_u32_e32 v120, 0x80, v190
	v_ashrrev_i32_e32 v121, 31, v120
	v_pk_add_f32 v[104:105], v[90:91], v[32:33]
	v_mul_f32_e32 v90, 0xbfb8aa3b, v94
	v_mul_f32_e32 v91, 0xbfb8aa3b, v95
	v_exp_f32_e32 v90, v90
	v_exp_f32_e32 v91, v91
	v_lshlrev_b32_e32 v94, 16, v110
	v_and_b32_e32 v95, 0xffff0000, v110
	v_lshlrev_b64 v[102:103], 11, v[192:193]
	v_pk_add_f32 v[90:91], v[90:91], 1.0 op_sel_hi:[1,0]
	v_pk_add_f32 v[122:123], v[74:75], v[32:33]
	v_mul_f32_e32 v74, 0xbfb8aa3b, v78
	v_mul_f32_e32 v75, 0xbfb8aa3b, v79
	v_exp_f32_e32 v74, v74
	v_rcp_f32_e32 v91, v91
	s_nop 0
	v_exp_f32_e32 v75, v75
	v_add_u32_e32 v118, 0x90, v190
	v_ashrrev_i32_e32 v119, 31, v118
	v_rcp_f32_e32 v90, v90
	s_nop 0
	v_pk_mul_f32 v[90:91], v[90:91], v[94:95]
	v_mul_f32_e32 v94, 0xbfb8aa3b, v96
	v_mul_f32_e32 v95, 0xbfb8aa3b, v97
	v_exp_f32_e32 v94, v94
	v_exp_f32_e32 v95, v95
	v_lshlrev_b32_e32 v96, 16, v111
	v_and_b32_e32 v97, 0xffff0000, v111
	v_pk_add_f32 v[74:75], v[74:75], 1.0 op_sel_hi:[1,0]
	v_pk_add_f32 v[94:95], v[94:95], 1.0 op_sel_hi:[1,0]
	v_add_u32_e32 v116, 0xa0, v190
	v_ashrrev_i32_e32 v117, 31, v116
	v_add_u32_e32 v114, 0xb0, v190
	v_ashrrev_i32_e32 v115, 31, v114
	v_rcp_f32_e32 v95, v95
	s_nop 0
	s_nop 0
	v_rcp_f32_e32 v94, v94
	s_nop 0
	v_pk_mul_f32 v[94:95], v[94:95], v[96:97]
	v_mul_f32_e32 v96, 0xbfb8aa3b, v104
	v_mul_f32_e32 v97, 0xbfb8aa3b, v105
	v_exp_f32_e32 v96, v96
	v_exp_f32_e32 v97, v97
	v_lshlrev_b32_e32 v104, 16, v112
	v_and_b32_e32 v105, 0xffff0000, v112
	v_pk_add_f32 v[96:97], v[96:97], 1.0 op_sel_hi:[1,0]
	s_nop 0
	s_nop 0
	v_rcp_f32_e32 v97, v97
	s_nop 0
	s_nop 0
	v_rcp_f32_e32 v96, v96
	s_nop 0
	v_pk_mul_f32 v[96:97], v[96:97], v[104:105]
	v_lshlrev_b32_e32 v104, 16, v113
	v_and_b32_e32 v105, 0xffff0000, v113
	v_rcp_f32_e32 v93, v93
	s_nop 0
	s_nop 0
	v_rcp_f32_e32 v92, v92
	s_nop 0
	v_pk_mul_f32 v[104:105], v[92:93], v[104:105]
	v_cvt_pk_bf16_f32 v92, v90, v91
	v_cvt_pk_bf16_f32 v93, v94, v95
	v_cvt_pk_bf16_f32 v94, v96, v97
	v_cvt_pk_bf16_f32 v95, v104, v105
	v_lshl_add_u64 v[90:91], v[188:189], 0, v[102:103]
	global_store_dwordx4 v[90:91], v[92:95], off
	s_nop 1
	v_pk_add_f32 v[92:93], v[82:83], v[16:17]
	v_mul_f32_e32 v82, 0xbfb8aa3b, v86
	v_mul_f32_e32 v83, 0xbfb8aa3b, v87
	v_exp_f32_e32 v82, v82
	v_exp_f32_e32 v83, v83
	v_lshlrev_b32_e32 v86, 16, v98
	v_and_b32_e32 v87, 0xffff0000, v98
	v_pk_add_f32 v[82:83], v[82:83], 1.0 op_sel_hi:[1,0]
	s_nop 0
	s_nop 0
	v_rcp_f32_e32 v83, v83
	s_nop 0
	s_nop 0
	v_rcp_f32_e32 v82, v82
	s_nop 0
	v_pk_mul_f32 v[82:83], v[82:83], v[86:87]
	v_mul_f32_e32 v86, 0xbfb8aa3b, v88
	v_mul_f32_e32 v87, 0xbfb8aa3b, v89
	v_exp_f32_e32 v86, v86
	v_exp_f32_e32 v87, v87
	v_lshlrev_b32_e32 v88, 16, v99
	v_and_b32_e32 v89, 0xffff0000, v99
	v_cvt_pk_bf16_f32 v82, v82, v83
	v_pk_add_f32 v[86:87], v[86:87], 1.0 op_sel_hi:[1,0]
	s_nop 0
	s_nop 0
	v_rcp_f32_e32 v87, v87
	s_nop 0
	s_nop 0
	v_rcp_f32_e32 v86, v86
	s_nop 0
	v_pk_mul_f32 v[86:87], v[86:87], v[88:89]
	v_mul_f32_e32 v88, 0xbfb8aa3b, v92
	v_mul_f32_e32 v89, 0xbfb8aa3b, v93
	v_exp_f32_e32 v88, v88
	v_exp_f32_e32 v89, v89
	v_lshlrev_b32_e32 v92, 16, v100
	v_and_b32_e32 v93, 0xffff0000, v100
	v_cvt_pk_bf16_f32 v83, v86, v87
	v_pk_add_f32 v[88:89], v[88:89], 1.0 op_sel_hi:[1,0]
	s_nop 0
	s_nop 0
	v_rcp_f32_e32 v89, v89
	s_nop 0
	s_nop 0
	v_rcp_f32_e32 v88, v88
	s_nop 0
	v_pk_mul_f32 v[88:89], v[88:89], v[92:93]
	v_lshlrev_b32_e32 v92, 16, v101
	v_and_b32_e32 v93, 0xffff0000, v101
	v_rcp_f32_e32 v85, v85
	s_nop 0
	s_nop 0
	v_rcp_f32_e32 v84, v84
	s_nop 0
	v_pk_mul_f32 v[92:93], v[84:85], v[92:93]
	v_cvt_pk_bf16_f32 v84, v88, v89
	v_cvt_pk_bf16_f32 v85, v92, v93
	global_store_dwordx4 v[90:91], v[82:85], off offset:256
	s_nop 1
	v_lshlrev_b64 v[82:83], 9, v[120:121]
	v_lshl_add_u64 v[82:83], v[186:187], 0, v[82:83]
	global_load_dwordx4 v[110:113], v[82:83], off
	global_load_dwordx4 v[106:109], v[82:83], off offset:256
	v_lshlrev_b64 v[82:83], 9, v[118:119]
	v_lshl_add_u64 v[82:83], v[186:187], 0, v[82:83]
	global_load_dwordx4 v[102:105], v[82:83], off
	global_load_dwordx4 v[98:101], v[82:83], off offset:256
	v_lshlrev_b64 v[82:83], 9, v[116:117]
	v_lshl_add_u64 v[82:83], v[186:187], 0, v[82:83]
	global_load_dwordx4 v[94:97], v[82:83], off
	global_load_dwordx4 v[90:93], v[82:83], off offset:256
	v_lshlrev_b64 v[82:83], 9, v[114:115]
	v_lshlrev_b64 v[120:121], 11, v[120:121]
	v_lshl_add_u64 v[82:83], v[186:187], 0, v[82:83]
	global_load_dwordx4 v[86:89], v[82:83], off
	s_nop 0
	global_load_dwordx4 v[82:85], v[82:83], off offset:256
	s_waitcnt vmcnt(0)
	v_lshlrev_b32_e32 v78, 16, v110
	v_and_b32_e32 v79, 0xffff0000, v110
	s_nop 0
	v_rcp_f32_e32 v75, v75
	s_nop 0
	s_nop 0
	v_rcp_f32_e32 v74, v74
	s_nop 0
	v_pk_mul_f32 v[74:75], v[74:75], v[78:79]
	v_mul_f32_e32 v78, 0xbfb8aa3b, v80
	v_mul_f32_e32 v79, 0xbfb8aa3b, v81
	v_exp_f32_e32 v78, v78
	v_exp_f32_e32 v79, v79
	v_lshlrev_b32_e32 v80, 16, v111
	v_and_b32_e32 v81, 0xffff0000, v111
	v_pk_add_f32 v[78:79], v[78:79], 1.0 op_sel_hi:[1,0]
	s_nop 0
	s_nop 0
	v_rcp_f32_e32 v79, v79
	s_nop 0
	s_nop 0
	v_rcp_f32_e32 v78, v78
	s_nop 0
	v_pk_mul_f32 v[78:79], v[78:79], v[80:81]
	v_mul_f32_e32 v80, 0xbfb8aa3b, v122
	v_mul_f32_e32 v81, 0xbfb8aa3b, v123
	v_exp_f32_e32 v80, v80
	v_exp_f32_e32 v81, v81
	v_lshlrev_b32_e32 v110, 16, v112
	v_and_b32_e32 v111, 0xffff0000, v112
	v_pk_add_f32 v[80:81], v[80:81], 1.0 op_sel_hi:[1,0]
	s_nop 0
	s_nop 0
	v_rcp_f32_e32 v81, v81
	s_nop 0
	s_nop 0
	v_rcp_f32_e32 v80, v80
	s_nop 0
	v_pk_mul_f32 v[80:81], v[80:81], v[110:111]
	v_lshlrev_b32_e32 v110, 16, v113
	v_and_b32_e32 v111, 0xffff0000, v113
	s_nop 0
	v_rcp_f32_e32 v77, v77
	s_nop 0
	s_nop 0
	v_rcp_f32_e32 v76, v76
	s_nop 0
	v_pk_mul_f32 v[110:111], v[76:77], v[110:111]
	v_cvt_pk_bf16_f32 v76, v74, v75
	v_cvt_pk_bf16_f32 v77, v78, v79
	v_cvt_pk_bf16_f32 v78, v80, v81
	v_cvt_pk_bf16_f32 v79, v110, v111
	v_lshl_add_u64 v[74:75], v[188:189], 0, v[120:121]
	global_store_dwordx4 v[74:75], v[76:79], off
	s_nop 1
	v_pk_add_f32 v[76:77], v[66:67], v[16:17]
	v_mul_f32_e32 v66, 0xbfb8aa3b, v70
	v_mul_f32_e32 v67, 0xbfb8aa3b, v71
	v_exp_f32_e32 v66, v66
	v_exp_f32_e32 v67, v67
	v_lshlrev_b32_e32 v70, 16, v106
	v_and_b32_e32 v71, 0xffff0000, v106
	v_pk_add_f32 v[66:67], v[66:67], 1.0 op_sel_hi:[1,0]
	s_nop 0
	s_nop 0
	v_rcp_f32_e32 v67, v67
	s_nop 0
	s_nop 0
	v_rcp_f32_e32 v66, v66
	s_nop 0
	v_pk_mul_f32 v[66:67], v[66:67], v[70:71]
	v_mul_f32_e32 v70, 0xbfb8aa3b, v72
	v_mul_f32_e32 v71, 0xbfb8aa3b, v73
	v_exp_f32_e32 v70, v70
	v_exp_f32_e32 v71, v71
	v_lshlrev_b32_e32 v72, 16, v107
	v_and_b32_e32 v73, 0xffff0000, v107
	v_cvt_pk_bf16_f32 v66, v66, v67
	v_pk_add_f32 v[70:71], v[70:71], 1.0 op_sel_hi:[1,0]
	s_nop 0
	s_nop 0
	v_rcp_f32_e32 v71, v71
	s_nop 0
	s_nop 0
	v_rcp_f32_e32 v70, v70
	s_nop 0
	v_pk_mul_f32 v[70:71], v[70:71], v[72:73]
	v_mul_f32_e32 v72, 0xbfb8aa3b, v76
	v_mul_f32_e32 v73, 0xbfb8aa3b, v77
	v_exp_f32_e32 v72, v72
	v_exp_f32_e32 v73, v73
	v_lshlrev_b32_e32 v76, 16, v108
	v_and_b32_e32 v77, 0xffff0000, v108
	v_cvt_pk_bf16_f32 v67, v70, v71
	v_pk_add_f32 v[72:73], v[72:73], 1.0 op_sel_hi:[1,0]
	s_nop 0
	s_nop 0
	v_rcp_f32_e32 v73, v73
	s_nop 0
	s_nop 0
	v_rcp_f32_e32 v72, v72
	s_nop 0
	v_pk_mul_f32 v[72:73], v[72:73], v[76:77]
	v_lshlrev_b32_e32 v76, 16, v109
	v_and_b32_e32 v77, 0xffff0000, v109
	v_rcp_f32_e32 v69, v69
	s_nop 0
	s_nop 0
	v_rcp_f32_e32 v68, v68
	s_nop 0
	v_pk_mul_f32 v[76:77], v[68:69], v[76:77]
	v_cvt_pk_bf16_f32 v68, v72, v73
	v_cvt_pk_bf16_f32 v69, v76, v77
	global_store_dwordx4 v[74:75], v[66:69], off offset:256
	s_nop 1
	v_pk_add_f32 v[68:69], v[58:59], v[32:33]
	v_mul_f32_e32 v58, 0xbfb8aa3b, v62
	v_mul_f32_e32 v59, 0xbfb8aa3b, v63
	v_exp_f32_e32 v58, v58
	v_exp_f32_e32 v59, v59
	v_lshlrev_b32_e32 v62, 16, v102
	v_and_b32_e32 v63, 0xffff0000, v102
	v_lshlrev_b64 v[66:67], 11, v[118:119]
	v_pk_add_f32 v[58:59], v[58:59], 1.0 op_sel_hi:[1,0]
	s_nop 0
	s_nop 0
	v_rcp_f32_e32 v59, v59
	s_nop 0
	s_nop 0
	v_rcp_f32_e32 v58, v58
	s_nop 0
	v_pk_mul_f32 v[58:59], v[58:59], v[62:63]
	v_mul_f32_e32 v62, 0xbfb8aa3b, v64
	v_mul_f32_e32 v63, 0xbfb8aa3b, v65
	v_exp_f32_e32 v62, v62
	v_exp_f32_e32 v63, v63
	v_lshlrev_b32_e32 v64, 16, v103
	v_and_b32_e32 v65, 0xffff0000, v103
	v_pk_add_f32 v[62:63], v[62:63], 1.0 op_sel_hi:[1,0]
	s_nop 0
	s_nop 0
	v_rcp_f32_e32 v63, v63
	s_nop 0
	s_nop 0
	v_rcp_f32_e32 v62, v62
	s_nop 0
	v_pk_mul_f32 v[62:63], v[62:63], v[64:65]
	v_mul_f32_e32 v64, 0xbfb8aa3b, v68
	v_mul_f32_e32 v65, 0xbfb8aa3b, v69
	v_exp_f32_e32 v64, v64
	v_exp_f32_e32 v65, v65
	v_lshlrev_b32_e32 v68, 16, v104
	v_and_b32_e32 v69, 0xffff0000, v104
	v_pk_add_f32 v[64:65], v[64:65], 1.0 op_sel_hi:[1,0]
	s_nop 0
	s_nop 0
	v_rcp_f32_e32 v65, v65
	s_nop 0
	s_nop 0
	v_rcp_f32_e32 v64, v64
	s_nop 0
	v_pk_mul_f32 v[64:65], v[64:65], v[68:69]
	v_lshlrev_b32_e32 v68, 16, v105
	v_and_b32_e32 v69, 0xffff0000, v105
	v_rcp_f32_e32 v61, v61
	s_nop 0
	s_nop 0
	v_rcp_f32_e32 v60, v60
	s_nop 0
	v_pk_mul_f32 v[68:69], v[60:61], v[68:69]
	v_cvt_pk_bf16_f32 v60, v58, v59
	v_cvt_pk_bf16_f32 v61, v62, v63
	v_cvt_pk_bf16_f32 v62, v64, v65
	v_cvt_pk_bf16_f32 v63, v68, v69
	v_lshl_add_u64 v[58:59], v[188:189], 0, v[66:67]
	global_store_dwordx4 v[58:59], v[60:63], off
	s_nop 1
	v_pk_add_f32 v[60:61], v[50:51], v[16:17]
	v_mul_f32_e32 v50, 0xbfb8aa3b, v54
	v_mul_f32_e32 v51, 0xbfb8aa3b, v55
	v_exp_f32_e32 v50, v50
	v_exp_f32_e32 v51, v51
	v_lshlrev_b32_e32 v54, 16, v98
	v_and_b32_e32 v55, 0xffff0000, v98
	v_pk_add_f32 v[50:51], v[50:51], 1.0 op_sel_hi:[1,0]
	s_nop 0
	s_nop 0
	v_rcp_f32_e32 v51, v51
	s_nop 0
	s_nop 0
	v_rcp_f32_e32 v50, v50
	s_nop 0
	v_pk_mul_f32 v[50:51], v[50:51], v[54:55]
	v_mul_f32_e32 v54, 0xbfb8aa3b, v56
	v_mul_f32_e32 v55, 0xbfb8aa3b, v57
	v_exp_f32_e32 v54, v54
	v_exp_f32_e32 v55, v55
	v_lshlrev_b32_e32 v56, 16, v99
	v_and_b32_e32 v57, 0xffff0000, v99
	v_cvt_pk_bf16_f32 v50, v50, v51
	v_pk_add_f32 v[54:55], v[54:55], 1.0 op_sel_hi:[1,0]
	s_nop 0
	s_nop 0
	v_rcp_f32_e32 v55, v55
	s_nop 0
	s_nop 0
	v_rcp_f32_e32 v54, v54
	s_nop 0
	v_pk_mul_f32 v[54:55], v[54:55], v[56:57]
	v_mul_f32_e32 v56, 0xbfb8aa3b, v60
	v_mul_f32_e32 v57, 0xbfb8aa3b, v61
	v_exp_f32_e32 v56, v56
	v_exp_f32_e32 v57, v57
	v_lshlrev_b32_e32 v60, 16, v100
	v_and_b32_e32 v61, 0xffff0000, v100
	v_cvt_pk_bf16_f32 v51, v54, v55
	v_pk_add_f32 v[56:57], v[56:57], 1.0 op_sel_hi:[1,0]
	s_nop 0
	s_nop 0
	v_rcp_f32_e32 v57, v57
	s_nop 0
	s_nop 0
	v_rcp_f32_e32 v56, v56
	s_nop 0
	v_pk_mul_f32 v[56:57], v[56:57], v[60:61]
	v_lshlrev_b32_e32 v60, 16, v101
	v_and_b32_e32 v61, 0xffff0000, v101
	v_rcp_f32_e32 v53, v53
	s_nop 0
	s_nop 0
	v_rcp_f32_e32 v52, v52
	s_nop 0
	v_pk_mul_f32 v[60:61], v[52:53], v[60:61]
	v_cvt_pk_bf16_f32 v52, v56, v57
	v_cvt_pk_bf16_f32 v53, v60, v61
	global_store_dwordx4 v[58:59], v[50:53], off offset:256
	s_nop 1
	v_pk_add_f32 v[52:53], v[40:41], v[32:33]
	v_mul_f32_e32 v40, 0xbfb8aa3b, v44
	v_mul_f32_e32 v41, 0xbfb8aa3b, v45
	v_exp_f32_e32 v40, v40
	v_exp_f32_e32 v41, v41
	v_lshlrev_b32_e32 v44, 16, v94
	v_and_b32_e32 v45, 0xffff0000, v94
	v_lshlrev_b64 v[50:51], 11, v[116:117]
	v_pk_add_f32 v[40:41], v[40:41], 1.0 op_sel_hi:[1,0]
	s_nop 0
	s_nop 0
	v_rcp_f32_e32 v41, v41
	s_nop 0
	s_nop 0
	v_rcp_f32_e32 v40, v40
	s_nop 0
	v_pk_mul_f32 v[40:41], v[40:41], v[44:45]
	v_mul_f32_e32 v44, 0xbfb8aa3b, v46
	v_mul_f32_e32 v45, 0xbfb8aa3b, v47
	v_exp_f32_e32 v44, v44
	v_exp_f32_e32 v45, v45
	v_lshlrev_b32_e32 v46, 16, v95
	v_and_b32_e32 v47, 0xffff0000, v95
	v_pk_add_f32 v[44:45], v[44:45], 1.0 op_sel_hi:[1,0]
	s_nop 0
	s_nop 0
	v_rcp_f32_e32 v45, v45
	s_nop 0
	s_nop 0
	v_rcp_f32_e32 v44, v44
	s_nop 0
	v_pk_mul_f32 v[44:45], v[44:45], v[46:47]
	v_mul_f32_e32 v46, 0xbfb8aa3b, v52
	v_mul_f32_e32 v47, 0xbfb8aa3b, v53
	v_exp_f32_e32 v46, v46
	v_exp_f32_e32 v47, v47
	v_lshlrev_b32_e32 v52, 16, v96
	v_and_b32_e32 v53, 0xffff0000, v96
	v_pk_add_f32 v[46:47], v[46:47], 1.0 op_sel_hi:[1,0]
	s_nop 0
	s_nop 0
	v_rcp_f32_e32 v47, v47
	s_nop 0
	s_nop 0
	v_rcp_f32_e32 v46, v46
	s_nop 0
	v_pk_mul_f32 v[46:47], v[46:47], v[52:53]
	v_lshlrev_b32_e32 v52, 16, v97
	v_and_b32_e32 v53, 0xffff0000, v97
	v_rcp_f32_e32 v43, v43
	s_nop 0
	s_nop 0
	v_rcp_f32_e32 v42, v42
	s_nop 0
	v_pk_mul_f32 v[52:53], v[42:43], v[52:53]
	v_cvt_pk_bf16_f32 v42, v40, v41
	v_cvt_pk_bf16_f32 v43, v44, v45
	v_cvt_pk_bf16_f32 v44, v46, v47
	v_cvt_pk_bf16_f32 v45, v52, v53
	v_lshl_add_u64 v[40:41], v[188:189], 0, v[50:51]
	global_store_dwordx4 v[40:41], v[42:45], off
	s_nop 1
	v_pk_add_f32 v[42:43], v[24:25], v[16:17]
	v_mul_f32_e32 v24, 0xbfb8aa3b, v28
	v_mul_f32_e32 v25, 0xbfb8aa3b, v29
	v_exp_f32_e32 v24, v24
	v_exp_f32_e32 v25, v25
	v_lshlrev_b32_e32 v28, 16, v90
	v_and_b32_e32 v29, 0xffff0000, v90
	v_pk_add_f32 v[24:25], v[24:25], 1.0 op_sel_hi:[1,0]
	s_nop 0
	s_nop 0
	v_rcp_f32_e32 v25, v25
	s_nop 0
	s_nop 0
	v_rcp_f32_e32 v24, v24
	s_nop 0
	v_pk_mul_f32 v[24:25], v[24:25], v[28:29]
	v_mul_f32_e32 v28, 0xbfb8aa3b, v30
	v_mul_f32_e32 v29, 0xbfb8aa3b, v31
	v_exp_f32_e32 v28, v28
	v_exp_f32_e32 v29, v29
	v_lshlrev_b32_e32 v30, 16, v91
	v_and_b32_e32 v31, 0xffff0000, v91
	v_cvt_pk_bf16_f32 v24, v24, v25
	v_pk_add_f32 v[28:29], v[28:29], 1.0 op_sel_hi:[1,0]
	s_nop 0
	s_nop 0
	v_rcp_f32_e32 v29, v29
	s_nop 0
	s_nop 0
	v_rcp_f32_e32 v28, v28
	s_nop 0
	v_pk_mul_f32 v[28:29], v[28:29], v[30:31]
	v_mul_f32_e32 v30, 0xbfb8aa3b, v42
	v_mul_f32_e32 v31, 0xbfb8aa3b, v43
	v_exp_f32_e32 v30, v30
	v_exp_f32_e32 v31, v31
	v_lshlrev_b32_e32 v42, 16, v92
	v_and_b32_e32 v43, 0xffff0000, v92
	v_cvt_pk_bf16_f32 v25, v28, v29
	v_pk_add_f32 v[30:31], v[30:31], 1.0 op_sel_hi:[1,0]
	s_nop 0
	s_nop 0
	v_rcp_f32_e32 v31, v31
	s_nop 0
	s_nop 0
	v_rcp_f32_e32 v30, v30
	s_nop 0
	v_pk_mul_f32 v[30:31], v[30:31], v[42:43]
	v_lshlrev_b32_e32 v42, 16, v93
	v_and_b32_e32 v43, 0xffff0000, v93
	v_rcp_f32_e32 v27, v27
	s_nop 0
	s_nop 0
	v_rcp_f32_e32 v26, v26
	s_nop 0
	v_pk_mul_f32 v[42:43], v[26:27], v[42:43]
	v_cvt_pk_bf16_f32 v26, v30, v31
	v_cvt_pk_bf16_f32 v27, v42, v43
	global_store_dwordx4 v[40:41], v[24:27], off offset:256
	s_nop 1
	v_pk_add_f32 v[26:27], v[8:9], v[32:33]
	v_mul_f32_e32 v8, 0xbfb8aa3b, v12
	v_mul_f32_e32 v9, 0xbfb8aa3b, v13
	v_exp_f32_e32 v8, v8
	v_exp_f32_e32 v9, v9
	v_lshlrev_b32_e32 v12, 16, v86
	v_and_b32_e32 v13, 0xffff0000, v86
	v_lshlrev_b64 v[24:25], 11, v[114:115]
	v_pk_add_f32 v[8:9], v[8:9], 1.0 op_sel_hi:[1,0]
	s_nop 0
	s_nop 0
	v_rcp_f32_e32 v9, v9
	s_nop 0
	s_nop 0
	v_rcp_f32_e32 v8, v8
	s_nop 0
	v_pk_mul_f32 v[8:9], v[8:9], v[12:13]
	v_mul_f32_e32 v12, 0xbfb8aa3b, v14
	v_mul_f32_e32 v13, 0xbfb8aa3b, v15
	v_exp_f32_e32 v12, v12
	v_exp_f32_e32 v13, v13
	v_lshlrev_b32_e32 v14, 16, v87
	v_and_b32_e32 v15, 0xffff0000, v87
	v_pk_add_f32 v[12:13], v[12:13], 1.0 op_sel_hi:[1,0]
	s_nop 0
	s_nop 0
	v_rcp_f32_e32 v13, v13
	s_nop 0
	s_nop 0
	v_rcp_f32_e32 v12, v12
	s_nop 0
	v_pk_mul_f32 v[12:13], v[12:13], v[14:15]
	v_mul_f32_e32 v14, 0xbfb8aa3b, v26
	v_mul_f32_e32 v15, 0xbfb8aa3b, v27
	v_exp_f32_e32 v14, v14
	v_exp_f32_e32 v15, v15
	v_lshlrev_b32_e32 v26, 16, v88
	v_and_b32_e32 v27, 0xffff0000, v88
	v_pk_add_f32 v[14:15], v[14:15], 1.0 op_sel_hi:[1,0]
	s_nop 0
	s_nop 0
	v_rcp_f32_e32 v15, v15
	s_nop 0
	s_nop 0
	v_rcp_f32_e32 v14, v14
	s_nop 0
	v_pk_mul_f32 v[14:15], v[14:15], v[26:27]
	v_lshlrev_b32_e32 v26, 16, v89
	v_and_b32_e32 v27, 0xffff0000, v89
	v_rcp_f32_e32 v11, v11
	s_nop 0
	s_nop 0
	v_rcp_f32_e32 v10, v10
	s_nop 0
	v_pk_mul_f32 v[26:27], v[10:11], v[26:27]
	v_cvt_pk_bf16_f32 v10, v8, v9
	v_cvt_pk_bf16_f32 v11, v12, v13
	v_cvt_pk_bf16_f32 v12, v14, v15
	v_cvt_pk_bf16_f32 v13, v26, v27
	v_lshl_add_u64 v[8:9], v[188:189], 0, v[24:25]
	global_store_dwordx4 v[8:9], v[10:13], off
	s_nop 1
	v_pk_add_f32 v[10:11], v[0:1], v[16:17]
	v_mul_f32_e32 v0, 0xbfb8aa3b, v4
	v_mul_f32_e32 v1, 0xbfb8aa3b, v5
	v_exp_f32_e32 v0, v0
	v_exp_f32_e32 v1, v1
	v_lshlrev_b32_e32 v4, 16, v82
	v_and_b32_e32 v5, 0xffff0000, v82
	v_pk_add_f32 v[0:1], v[0:1], 1.0 op_sel_hi:[1,0]
	s_nop 0
	s_nop 0
	v_rcp_f32_e32 v1, v1
	s_nop 0
	s_nop 0
	v_rcp_f32_e32 v0, v0
	s_nop 0
	v_pk_mul_f32 v[0:1], v[0:1], v[4:5]
	v_mul_f32_e32 v4, 0xbfb8aa3b, v6
	v_mul_f32_e32 v5, 0xbfb8aa3b, v7
	v_exp_f32_e32 v4, v4
	v_exp_f32_e32 v5, v5
	v_lshlrev_b32_e32 v6, 16, v83
	v_and_b32_e32 v7, 0xffff0000, v83
	v_cvt_pk_bf16_f32 v0, v0, v1
	v_pk_add_f32 v[4:5], v[4:5], 1.0 op_sel_hi:[1,0]
	s_nop 0
	s_nop 0
	v_rcp_f32_e32 v5, v5
	s_nop 0
	s_nop 0
	v_rcp_f32_e32 v4, v4
	s_nop 0
	v_pk_mul_f32 v[4:5], v[4:5], v[6:7]
	v_mul_f32_e32 v6, 0xbfb8aa3b, v10
	v_mul_f32_e32 v7, 0xbfb8aa3b, v11
	v_exp_f32_e32 v6, v6
	v_exp_f32_e32 v7, v7
	v_lshlrev_b32_e32 v10, 16, v84
	v_and_b32_e32 v11, 0xffff0000, v84
	v_cvt_pk_bf16_f32 v1, v4, v5
	v_pk_add_f32 v[6:7], v[6:7], 1.0 op_sel_hi:[1,0]
	s_nop 0
	s_nop 0
	v_rcp_f32_e32 v7, v7
	s_nop 0
	s_nop 0
	v_rcp_f32_e32 v6, v6
	s_nop 0
	v_pk_mul_f32 v[6:7], v[6:7], v[10:11]
	v_lshlrev_b32_e32 v10, 16, v85
	v_and_b32_e32 v11, 0xffff0000, v85
	v_rcp_f32_e32 v3, v3
	s_nop 0
	s_mov_b64 s[14:15], s[10:11]
	v_rcp_f32_e32 v2, v2
	s_nop 0
	v_pk_mul_f32 v[10:11], v[2:3], v[10:11]
	v_cvt_pk_bf16_f32 v2, v6, v7
	v_cvt_pk_bf16_f32 v3, v10, v11
	s_and_b64 vcc, exec, s[8:9]
	global_store_dwordx4 v[8:9], v[0:3], off offset:256
	s_cbranch_vccz .LBB0_979
	s_waitcnt vmcnt(0)
	s_cmpk_gt_u32 s30, 0xff
	s_cbranch_scc1 .LBB0_986
	s_barrier

.LBB0_1198:
	s_ashr_i32 s25, s24, 31
	s_lshl_b64 s[24:25], s[24:25], 18
	v_lshl_or_b32 v132, s22, 8, v171
	v_lshl_add_u64 v[130:131], s[24:25], 0, v[148:149]
	v_ashrrev_i32_e32 v133, 31, v132
	v_lshl_add_u64 v[130:131], v[130:131], 0, v[132:133]
	v_lshlrev_b64 v[154:155], 1, v[130:131]
	v_lshl_add_u64 v[156:157], s[6:7], 0, v[154:155]
	v_add_co_u32_e32 v130, vcc, s91, v156
	global_load_dwordx2 v[158:159], v[156:157], off
	global_load_dwordx2 v[160:161], v[156:157], off offset:32
	global_load_dwordx2 v[162:163], v[156:157], off offset:256
	global_load_dwordx2 v[164:165], v[156:157], off offset:288
	v_addc_co_u32_e32 v131, vcc, 0, v157, vcc
	global_load_dwordx2 v[166:167], v[130:131], off
	global_load_dwordx2 v[168:169], v[130:131], off offset:32
	global_load_dwordx2 v[174:175], v[130:131], off offset:256
	global_load_dwordx2 v[176:177], v[130:131], off offset:288
	v_add_co_u32_e32 v130, vcc, s89, v156
	s_lshl_b64 s[24:25], s[26:27], 2
	s_nop 0
	v_addc_co_u32_e32 v131, vcc, 0, v157, vcc
	global_load_dwordx2 v[178:179], v[130:131], off
	global_load_dwordx2 v[180:181], v[130:131], off offset:32
	global_load_dwordx2 v[182:183], v[130:131], off offset:256
	global_load_dwordx2 v[184:185], v[130:131], off offset:288
	v_add_co_u32_e32 v130, vcc, s83, v156
	s_add_u32 s24, s44, s24
	s_nop 0
	v_addc_co_u32_e32 v131, vcc, 0, v157, vcc
	s_addc_u32 s25, s45, s25
	global_load_dwordx2 v[186:187], v[130:131], off
	global_load_dwordx2 v[188:189], v[130:131], off offset:32
	global_load_dwordx2 v[190:191], v[130:131], off offset:256
	global_load_dwordx2 v[192:193], v[130:131], off offset:288
	v_lshl_add_u64 v[130:131], v[132:133], 2, s[24:25]
	global_load_dwordx4 v[142:145], v[130:131], off
	global_load_dwordx4 v[138:141], v[130:131], off offset:64
	global_load_dwordx4 v[134:137], v[130:131], off offset:512
	s_nop 0
	global_load_dwordx4 v[130:133], v[130:131], off offset:576
	v_lshl_add_u64 v[154:155], s[12:13], 0, v[154:155]
	s_mov_b32 s15, 0x40000
	s_mov_b32 s17, 0x48000
	s_mov_b32 s22, 0x50000
	s_mov_b32 s24, 0x58000
	s_mov_b64 s[28:29], s[20:21]
	s_mov_b64 s[26:27], s[18:19]
	s_waitcnt vmcnt(0)
	v_lshlrev_b32_e32 v198, 16, v158
	v_and_b32_e32 v199, 0xffff0000, v158
	v_lshlrev_b32_e32 v200, 16, v159
	v_lshlrev_b32_e32 v210, 16, v164
	v_and_b32_e32 v211, 0xffff0000, v164
	v_lshlrev_b32_e32 v212, 16, v165
	v_and_b32_e32 v213, 0xffff0000, v165
	v_lshlrev_b32_e32 v214, 16, v166
	v_and_b32_e32 v215, 0xffff0000, v166
	v_lshlrev_b32_e32 v216, 16, v167
	v_and_b32_e32 v217, 0xffff0000, v167
	v_lshlrev_b32_e32 v242, 16, v176
	v_and_b32_e32 v243, 0xffff0000, v176
	v_lshlrev_b32_e32 v176, 16, v177
	v_and_b32_e32 v177, 0xffff0000, v177
	v_lshlrev_b32_e32 v218, 16, v168
	v_and_b32_e32 v219, 0xffff0000, v168
	v_lshlrev_b32_e32 v220, 16, v169
	v_and_b32_e32 v221, 0xffff0000, v169
	v_pk_fma_f32 v[108:109], v[108:109], v[140:141], v[220:221]
	v_pk_fma_f32 v[106:107], v[106:107], v[138:139], v[218:219]
	v_pk_fma_f32 v[112:113], v[112:113], v[132:133], v[212:213]
	v_pk_fma_f32 v[110:111], v[110:111], v[130:131], v[210:211]
	v_pk_fma_f32 v[100:101], v[100:101], v[132:133], v[176:177]
	v_cvt_pk_bf16_f32 v110, v110, v111
	v_cvt_pk_bf16_f32 v111, v112, v113
	global_store_dwordx2 v[154:155], v[110:111], off offset:288
	v_pk_fma_f32 v[110:111], v[116:117], v[144:145], v[216:217]
	v_pk_fma_f32 v[112:113], v[114:115], v[142:143], v[214:215]
	v_pk_fma_f32 v[98:99], v[98:99], v[130:131], v[242:243]
	v_cvt_pk_bf16_f32 v112, v112, v113
	v_cvt_pk_bf16_f32 v113, v110, v111
	v_add_co_u32_e32 v110, vcc, s91, v154
	v_cvt_pk_bf16_f32 v98, v98, v99
	s_nop 0
	v_addc_co_u32_e32 v111, vcc, 0, v155, vcc
	v_cvt_pk_bf16_f32 v99, v100, v101
	global_store_dwordx2 v[110:111], v[98:99], off offset:288
	v_add_co_u32_e32 v98, vcc, s15, v156
	v_and_b32_e32 v201, 0xffff0000, v159
	v_lshlrev_b32_e32 v202, 16, v160
	v_and_b32_e32 v203, 0xffff0000, v160
	v_lshlrev_b32_e32 v204, 16, v161
	v_and_b32_e32 v205, 0xffff0000, v161
	v_lshlrev_b32_e32 v206, 16, v162
	v_and_b32_e32 v207, 0xffff0000, v162
	v_lshlrev_b32_e32 v208, 16, v163
	v_and_b32_e32 v209, 0xffff0000, v163
	v_lshlrev_b32_e32 v222, 16, v174
	v_and_b32_e32 v223, 0xffff0000, v174
	v_lshlrev_b32_e32 v174, 16, v175
	v_and_b32_e32 v175, 0xffff0000, v175
	v_cvt_pk_bf16_f32 v106, v106, v107
	v_cvt_pk_bf16_f32 v107, v108, v109
	v_addc_co_u32_e32 v99, vcc, 0, v157, vcc
	v_lshlrev_b32_e32 v244, 16, v178
	v_and_b32_e32 v245, 0xffff0000, v178
	v_lshlrev_b32_e32 v178, 16, v179
	v_and_b32_e32 v179, 0xffff0000, v179
	v_pk_fma_f32 v[128:129], v[128:129], v[144:145], v[200:201]
	v_pk_fma_f32 v[126:127], v[126:127], v[142:143], v[198:199]
	v_pk_fma_f32 v[124:125], v[124:125], v[140:141], v[204:205]
	v_pk_fma_f32 v[122:123], v[122:123], v[138:139], v[202:203]
	v_pk_fma_f32 v[120:121], v[120:121], v[136:137], v[208:209]
	v_pk_fma_f32 v[118:119], v[118:119], v[134:135], v[206:207]
	global_store_dwordx2 v[110:111], v[106:107], off offset:32
	v_pk_fma_f32 v[104:105], v[104:105], v[136:137], v[174:175]
	v_pk_fma_f32 v[102:103], v[102:103], v[134:135], v[222:223]
	v_add_co_u32_e32 v106, vcc, s17, v156
	v_lshlrev_b32_e32 v250, 16, v184
	v_and_b32_e32 v251, 0xffff0000, v184
	v_lshlrev_b32_e32 v184, 16, v185
	v_and_b32_e32 v185, 0xffff0000, v185
	v_cvt_pk_bf16_f32 v126, v126, v127
	v_cvt_pk_bf16_f32 v127, v128, v129
	v_cvt_pk_bf16_f32 v122, v122, v123
	v_cvt_pk_bf16_f32 v123, v124, v125
	v_cvt_pk_bf16_f32 v118, v118, v119
	v_cvt_pk_bf16_f32 v119, v120, v121
	v_cvt_pk_bf16_f32 v102, v102, v103
	v_cvt_pk_bf16_f32 v103, v104, v105
	v_addc_co_u32_e32 v107, vcc, 0, v157, vcc
	v_pk_fma_f32 v[96:97], v[96:97], v[144:145], v[178:179]
	v_pk_fma_f32 v[94:95], v[94:95], v[142:143], v[244:245]
	global_store_dwordx2 v[154:155], v[126:127], off
	global_store_dwordx2 v[154:155], v[122:123], off offset:32
	global_store_dwordx2 v[154:155], v[118:119], off offset:256
	global_store_dwordx2 v[110:111], v[112:113], off
	global_store_dwordx2 v[110:111], v[102:103], off offset:256
	v_cvt_pk_bf16_f32 v94, v94, v95
	v_cvt_pk_bf16_f32 v95, v96, v97
	v_add_co_u32_e32 v96, vcc, s89, v154
	v_pk_fma_f32 v[80:81], v[80:81], v[132:133], v[184:185]
	v_pk_fma_f32 v[78:79], v[78:79], v[130:131], v[250:251]
	v_lshlrev_b32_e32 v234, 16, v186
	v_and_b32_e32 v235, 0xffff0000, v186
	v_lshlrev_b32_e32 v186, 16, v187
	v_and_b32_e32 v187, 0xffff0000, v187
	global_load_dwordx2 v[100:101], v[98:99], off
	global_load_dwordx2 v[102:103], v[98:99], off offset:32
	global_load_dwordx2 v[104:105], v[98:99], off offset:256
	s_nop 0
	global_load_dwordx2 v[98:99], v[98:99], off offset:288
	v_addc_co_u32_e32 v97, vcc, 0, v155, vcc
	v_cvt_pk_bf16_f32 v78, v78, v79
	v_cvt_pk_bf16_f32 v79, v80, v81
	v_lshlrev_b32_e32 v158, 16, v192
	v_and_b32_e32 v159, 0xffff0000, v192
	v_lshlrev_b32_e32 v160, 16, v193
	v_and_b32_e32 v161, 0xffff0000, v193
	global_load_dwordx2 v[108:109], v[106:107], off
	global_load_dwordx2 v[110:111], v[106:107], off offset:32
	global_load_dwordx2 v[112:113], v[106:107], off offset:256
	s_nop 0
	global_load_dwordx2 v[106:107], v[106:107], off offset:288
	v_pk_fma_f32 v[80:81], v[82:83], v[142:143], v[234:235]
	global_store_dwordx2 v[96:97], v[78:79], off offset:288
	v_pk_fma_f32 v[78:79], v[84:85], v[144:145], v[186:187]
	v_lshlrev_b32_e32 v246, 16, v180
	v_and_b32_e32 v247, 0xffff0000, v180
	v_lshlrev_b32_e32 v180, 16, v181
	v_and_b32_e32 v181, 0xffff0000, v181
	v_lshlrev_b32_e32 v248, 16, v182
	v_and_b32_e32 v249, 0xffff0000, v182
	v_lshlrev_b32_e32 v182, 16, v183
	v_and_b32_e32 v183, 0xffff0000, v183
	v_lshlrev_b32_e32 v166, 16, v188
	v_and_b32_e32 v167, 0xffff0000, v188
	v_lshlrev_b32_e32 v168, 16, v189
	v_and_b32_e32 v169, 0xffff0000, v189
	v_lshlrev_b32_e32 v162, 16, v190
	v_and_b32_e32 v163, 0xffff0000, v190
	v_lshlrev_b32_e32 v164, 16, v191
	v_and_b32_e32 v165, 0xffff0000, v191
	v_cvt_pk_bf16_f32 v80, v80, v81
	v_cvt_pk_bf16_f32 v81, v78, v79
	v_add_co_u32_e32 v78, vcc, s83, v154
	v_pk_fma_f32 v[68:69], v[68:69], v[132:133], v[160:161]
	v_pk_fma_f32 v[66:67], v[66:67], v[130:131], v[158:159]
	v_pk_fma_f32 v[92:93], v[92:93], v[140:141], v[180:181]
	v_pk_fma_f32 v[90:91], v[90:91], v[138:139], v[246:247]
	v_pk_fma_f32 v[88:89], v[88:89], v[136:137], v[182:183]
	v_pk_fma_f32 v[86:87], v[86:87], v[134:135], v[248:249]
	v_addc_co_u32_e32 v79, vcc, 0, v155, vcc
	v_pk_fma_f32 v[76:77], v[76:77], v[140:141], v[168:169]
	v_pk_fma_f32 v[74:75], v[74:75], v[138:139], v[166:167]
	v_pk_fma_f32 v[72:73], v[72:73], v[136:137], v[164:165]
	v_pk_fma_f32 v[70:71], v[70:71], v[134:135], v[162:163]
	v_cvt_pk_bf16_f32 v66, v66, v67
	v_cvt_pk_bf16_f32 v67, v68, v69
	v_cvt_pk_bf16_f32 v90, v90, v91
	v_cvt_pk_bf16_f32 v91, v92, v93
	v_cvt_pk_bf16_f32 v86, v86, v87
	v_cvt_pk_bf16_f32 v87, v88, v89
	v_cvt_pk_bf16_f32 v74, v74, v75
	v_cvt_pk_bf16_f32 v75, v76, v77
	v_cvt_pk_bf16_f32 v70, v70, v71
	v_cvt_pk_bf16_f32 v71, v72, v73
	global_store_dwordx2 v[78:79], v[66:67], off offset:288
	v_add_co_u32_e32 v66, vcc, s22, v156
	global_store_dwordx2 v[96:97], v[94:95], off
	global_store_dwordx2 v[96:97], v[90:91], off offset:32
	global_store_dwordx2 v[96:97], v[86:87], off offset:256
	global_store_dwordx2 v[78:79], v[80:81], off
	global_store_dwordx2 v[78:79], v[74:75], off offset:32
	global_store_dwordx2 v[78:79], v[70:71], off offset:256
	v_addc_co_u32_e32 v67, vcc, 0, v157, vcc
	global_load_dwordx2 v[68:69], v[66:67], off
	global_load_dwordx2 v[70:71], v[66:67], off offset:32
	global_load_dwordx2 v[72:73], v[66:67], off offset:256
	s_nop 0
	global_load_dwordx2 v[66:67], v[66:67], off offset:288
	v_add_co_u32_e32 v74, vcc, s24, v156
	s_waitcnt vmcnt(0)
	v_lshlrev_b32_e32 v82, 16, v100
	v_addc_co_u32_e32 v75, vcc, 0, v157, vcc
	global_load_dwordx2 v[76:77], v[74:75], off
	global_load_dwordx2 v[78:79], v[74:75], off offset:32
	global_load_dwordx2 v[80:81], v[74:75], off offset:256
	s_nop 0
	global_load_dwordx2 v[74:75], v[74:75], off offset:288
	v_and_b32_e32 v83, 0xffff0000, v100
	v_lshlrev_b32_e32 v84, 16, v101
	v_and_b32_e32 v85, 0xffff0000, v101
	v_lshlrev_b32_e32 v94, 16, v98
	v_and_b32_e32 v95, 0xffff0000, v98
	v_lshlrev_b32_e32 v96, 16, v99
	v_and_b32_e32 v97, 0xffff0000, v99
	v_pk_fma_f32 v[64:65], v[64:65], v[144:145], v[84:85]
	v_pk_fma_f32 v[62:63], v[62:63], v[142:143], v[82:83]
	v_pk_fma_f32 v[46:47], v[46:47], v[132:133], v[96:97]
	v_cvt_pk_bf16_f32 v62, v62, v63
	v_cvt_pk_bf16_f32 v63, v64, v65
	v_add_co_u32_e32 v64, vcc, s15, v154
	v_pk_fma_f32 v[44:45], v[44:45], v[130:131], v[94:95]
	v_lshlrev_b32_e32 v98, 16, v108
	v_and_b32_e32 v99, 0xffff0000, v108
	v_lshlrev_b32_e32 v100, 16, v109
	v_and_b32_e32 v101, 0xffff0000, v109
	v_addc_co_u32_e32 v65, vcc, 0, v155, vcc
	v_cvt_pk_bf16_f32 v44, v44, v45
	v_cvt_pk_bf16_f32 v45, v46, v47
	v_lshlrev_b32_e32 v86, 16, v102
	v_and_b32_e32 v87, 0xffff0000, v102
	v_lshlrev_b32_e32 v88, 16, v103
	v_and_b32_e32 v89, 0xffff0000, v103
	v_lshlrev_b32_e32 v90, 16, v104
	v_and_b32_e32 v91, 0xffff0000, v104
	v_lshlrev_b32_e32 v92, 16, v105
	v_and_b32_e32 v93, 0xffff0000, v105
	v_lshlrev_b32_e32 v102, 16, v110
	v_and_b32_e32 v103, 0xffff0000, v110
	v_lshlrev_b32_e32 v104, 16, v111
	v_and_b32_e32 v105, 0xffff0000, v111
	v_lshlrev_b32_e32 v108, 16, v112
	v_and_b32_e32 v109, 0xffff0000, v112
	v_lshlrev_b32_e32 v110, 16, v113
	v_and_b32_e32 v111, 0xffff0000, v113
	v_lshlrev_b32_e32 v112, 16, v106
	v_and_b32_e32 v113, 0xffff0000, v106
	v_lshlrev_b32_e32 v106, 16, v107
	v_and_b32_e32 v107, 0xffff0000, v107
	global_store_dwordx2 v[64:65], v[44:45], off offset:288
	v_pk_fma_f32 v[44:45], v[52:53], v[144:145], v[100:101]
	v_pk_fma_f32 v[46:47], v[50:51], v[142:143], v[98:99]
	v_pk_fma_f32 v[30:31], v[30:31], v[132:133], v[106:107]
	v_cvt_pk_bf16_f32 v46, v46, v47
	v_cvt_pk_bf16_f32 v47, v44, v45
	v_add_co_u32_e32 v44, vcc, s17, v154
	v_pk_fma_f32 v[28:29], v[28:29], v[130:131], v[112:113]
	s_nop 0
	v_addc_co_u32_e32 v45, vcc, 0, v155, vcc
	v_cvt_pk_bf16_f32 v28, v28, v29
	v_cvt_pk_bf16_f32 v29, v30, v31
	global_store_dwordx2 v[44:45], v[28:29], off offset:288
	v_pk_fma_f32 v[60:61], v[60:61], v[140:141], v[88:89]
	v_pk_fma_f32 v[58:59], v[58:59], v[138:139], v[86:87]
	v_pk_fma_f32 v[56:57], v[56:57], v[136:137], v[92:93]
	v_pk_fma_f32 v[54:55], v[54:55], v[134:135], v[90:91]
	v_pk_fma_f32 v[42:43], v[42:43], v[140:141], v[104:105]
	v_lshlrev_b32_e32 v114, 16, v68
	v_and_b32_e32 v115, 0xffff0000, v68
	v_lshlrev_b32_e32 v68, 16, v69
	v_and_b32_e32 v69, 0xffff0000, v69
	v_lshlrev_b32_e32 v120, 16, v66
	v_and_b32_e32 v121, 0xffff0000, v66
	v_lshlrev_b32_e32 v66, 16, v67
	v_and_b32_e32 v67, 0xffff0000, v67
	v_pk_fma_f32 v[28:29], v[34:35], v[144:145], v[68:69]
	v_pk_fma_f32 v[30:31], v[32:33], v[142:143], v[114:115]
	v_pk_fma_f32 v[14:15], v[14:15], v[132:133], v[66:67]
	v_cvt_pk_bf16_f32 v30, v30, v31
	v_cvt_pk_bf16_f32 v31, v28, v29
	v_add_co_u32_e32 v28, vcc, s22, v154
	v_pk_fma_f32 v[12:13], v[12:13], v[130:131], v[120:121]
	s_waitcnt vmcnt(2)
	v_lshlrev_b32_e32 v122, 16, v76
	v_and_b32_e32 v123, 0xffff0000, v76
	v_lshlrev_b32_e32 v76, 16, v77
	v_and_b32_e32 v77, 0xffff0000, v77
	v_addc_co_u32_e32 v29, vcc, 0, v155, vcc
	v_cvt_pk_bf16_f32 v12, v12, v13
	v_cvt_pk_bf16_f32 v13, v14, v15
	global_store_dwordx2 v[28:29], v[12:13], off offset:288
	v_pk_fma_f32 v[12:13], v[18:19], v[144:145], v[76:77]
	v_pk_fma_f32 v[14:15], v[16:17], v[142:143], v[122:123]
	v_lshlrev_b32_e32 v116, 16, v70
	v_and_b32_e32 v117, 0xffff0000, v70
	v_lshlrev_b32_e32 v70, 16, v71
	v_and_b32_e32 v71, 0xffff0000, v71
	v_lshlrev_b32_e32 v118, 16, v72
	v_and_b32_e32 v119, 0xffff0000, v72
	v_lshlrev_b32_e32 v72, 16, v73
	v_and_b32_e32 v73, 0xffff0000, v73
	v_lshlrev_b32_e32 v124, 16, v78
	v_and_b32_e32 v125, 0xffff0000, v78
	v_lshlrev_b32_e32 v78, 16, v79
	v_and_b32_e32 v79, 0xffff0000, v79
	v_lshlrev_b32_e32 v126, 16, v80
	v_and_b32_e32 v127, 0xffff0000, v80
	v_lshlrev_b32_e32 v80, 16, v81
	v_and_b32_e32 v81, 0xffff0000, v81
	v_lshlrev_b32_e32 v128, 16, v74
	v_and_b32_e32 v129, 0xffff0000, v74
	v_lshlrev_b32_e32 v74, 16, v75
	v_and_b32_e32 v75, 0xffff0000, v75
	v_cvt_pk_bf16_f32 v14, v14, v15
	v_cvt_pk_bf16_f32 v15, v12, v13
	v_add_co_u32_e32 v12, vcc, s24, v154
	v_pk_fma_f32 v[40:41], v[40:41], v[138:139], v[102:103]
	v_pk_fma_f32 v[38:39], v[38:39], v[136:137], v[110:111]
	v_pk_fma_f32 v[36:37], v[36:37], v[134:135], v[108:109]
	v_pk_fma_f32 v[26:27], v[26:27], v[140:141], v[70:71]
	v_pk_fma_f32 v[24:25], v[24:25], v[138:139], v[116:117]
	v_pk_fma_f32 v[22:23], v[22:23], v[136:137], v[72:73]
	v_pk_fma_f32 v[20:21], v[20:21], v[134:135], v[118:119]
	v_addc_co_u32_e32 v13, vcc, 0, v155, vcc
	v_pk_fma_f32 v[10:11], v[10:11], v[140:141], v[78:79]
	v_pk_fma_f32 v[8:9], v[8:9], v[138:139], v[124:125]
	v_pk_fma_f32 v[6:7], v[6:7], v[136:137], v[80:81]
	v_pk_fma_f32 v[4:5], v[4:5], v[134:135], v[126:127]
	v_pk_fma_f32 v[2:3], v[2:3], v[132:133], v[74:75]
	v_pk_fma_f32 v[0:1], v[0:1], v[130:131], v[128:129]
	v_cvt_pk_bf16_f32 v58, v58, v59
	v_cvt_pk_bf16_f32 v59, v60, v61
	v_cvt_pk_bf16_f32 v54, v54, v55
	v_cvt_pk_bf16_f32 v55, v56, v57
	v_cvt_pk_bf16_f32 v40, v40, v41
	v_cvt_pk_bf16_f32 v41, v42, v43
	v_cvt_pk_bf16_f32 v36, v36, v37
	v_cvt_pk_bf16_f32 v37, v38, v39
	v_cvt_pk_bf16_f32 v24, v24, v25
	v_cvt_pk_bf16_f32 v25, v26, v27
	v_cvt_pk_bf16_f32 v20, v20, v21
	v_cvt_pk_bf16_f32 v21, v22, v23
	v_cvt_pk_bf16_f32 v8, v8, v9
	v_cvt_pk_bf16_f32 v9, v10, v11
	v_cvt_pk_bf16_f32 v4, v4, v5
	v_cvt_pk_bf16_f32 v5, v6, v7
	v_cvt_pk_bf16_f32 v0, v0, v1
	v_cvt_pk_bf16_f32 v1, v2, v3
	s_and_b64 vcc, exec, s[0:1]
	s_mov_b32 s22, s14
	s_mov_b32 s24, s16
	global_store_dwordx2 v[64:65], v[62:63], off
	global_store_dwordx2 v[64:65], v[58:59], off offset:32
	global_store_dwordx2 v[64:65], v[54:55], off offset:256
	global_store_dwordx2 v[44:45], v[46:47], off
	global_store_dwordx2 v[44:45], v[40:41], off offset:32
	global_store_dwordx2 v[44:45], v[36:37], off offset:256
	global_store_dwordx2 v[28:29], v[30:31], off
	global_store_dwordx2 v[28:29], v[24:25], off offset:32
	global_store_dwordx2 v[28:29], v[20:21], off offset:256
	global_store_dwordx2 v[12:13], v[14:15], off
	global_store_dwordx2 v[12:13], v[8:9], off offset:32
	global_store_dwordx2 v[12:13], v[4:5], off offset:256
	global_store_dwordx2 v[12:13], v[0:1], off offset:288
	s_cbranch_vccnz .LBB0_1205

.LBB0_1278:
	s_or_b64 exec, exec, s[0:1]
	s_mov_b64 s[0:1], s[78:79]
	s_mov_b64 s[6:7], s[78:79]
	s_mov_b64 s[12:13], s[78:79]
	s_mov_b64 s[14:15], s[78:79]
	s_waitcnt lgkmcnt(0)
	v_mov_b32_e32 v0, v224
	s_barrier
	s_mul_i32 s56, s80, 0x31800
	v_readfirstlane_b32 s5, v0
	s_ashr_i32 s5, s5, 6
	s_add_i32 s5, s5, s70
	s_and_b64 s[16:17], s[68:69], exec
	s_cselect_b32 s9, s89, 0x12000
	s_cmp_ge_i32 s5, s9
	s_cbranch_scc1 .LBB0_1297
	s_waitcnt lgkmcnt(0)
	s_load_dwordx2 s[0:1], s[78:79], 0x100
	s_load_dwordx2 s[14:15], s[78:79], 0x38
	v_readfirstlane_b32 s58, v224
	v_and_b32_e32 v51, 63, v224
	v_lshlrev_b32_e32 v108, 5, v51
	v_lshlrev_b32_e32 v51, 4, v51
	v_add_u32_e32 v109, 0x1000, v51
	v_mov_b32_e32 v50, 0x3a800000
	s_lshr_b32 s58, s58, 6
	s_add_i32 s58, s58, s70
	s_lshr_b32 s23, s58, 6
	s_and_b32 s58, s58, 63
	s_mul_i32 s59, s23, 0x900
	s_lshl_b32 s81, s58, 5
	s_add_i32 s81, s81, s59
	s_addk_i32 s81, 0x100
	s_lshl_b32 s22, s58, 2
	s_add_i32 s22, s22, s59
	s_lshl_b32 s58, s80, 12
	s_mul_i32 s59, s80, 0xc6000
	s_waitcnt lgkmcnt(0)
	s_add_u32 s14, s14, s58
	s_addc_u32 s15, s15, 0
	s_add_u32 s6, s0, 0x2db14000
	s_addc_u32 s7, s1, 0
	s_add_u32 s12, s0, 0x85b4000
	s_addc_u32 s13, s1, 0
	s_add_u32 s16, s0, 0x63cb000
	s_addc_u32 s17, s1, 0
	s_add_u32 s16, s16, s59
	s_addc_u32 s17, s17, 0
	s_and_b64 vcc, exec, s[68:69]
	s_cbranch_vccnz .Lnorm_P10_skip
	global_load_dwordx4 v[32:35], v108, s[14:15]
	global_load_dwordx4 v[36:39], v108, s[14:15] offset:16
	global_load_dwordx4 v[40:43], v108, s[14:15] offset:2048
	global_load_dwordx4 v[44:47], v108, s[14:15] offset:2064
	s_add_u32 s0, s16, 0xc0000
	s_addc_u32 s1, s17, 0
	s_add_u32 s14, s0, 0x1000
	s_addc_u32 s15, s1, 0
	global_load_dwordx4 v[124:127], v108, s[0:1]
	global_load_dwordx4 v[128:131], v108, s[0:1] offset:16
	global_load_dwordx4 v[132:135], v108, s[0:1] offset:2048
	global_load_dwordx4 v[136:139], v108, s[0:1] offset:2064
	global_load_dwordx4 v[84:87], v108, s[14:15]
	global_load_dwordx4 v[88:91], v108, s[14:15] offset:16
	global_load_dwordx4 v[92:95], v108, s[14:15] offset:2048
	global_load_dwordx4 v[96:99], v108, s[14:15] offset:2064
	s_lshl_b32 s58, s22, 11
	s_add_u32 s18, s6, s58
	s_addc_u32 s19, s7, 0
	s_add_u32 s20, s12, s58
	s_addc_u32 s21, s13, 0
	global_load_dwordx4 v[0:3], v51, s[18:19]
	global_load_dwordx4 v[4:7], v51, s[18:19] offset:1024
	global_load_dwordx4 v[8:11], v51, s[18:19] offset:2048
	global_load_dwordx4 v[12:15], v51, s[18:19] offset:3072
	global_load_dwordx4 v[16:19], v109, s[18:19]
	global_load_dwordx4 v[20:23], v109, s[18:19] offset:1024
	global_load_dwordx4 v[24:27], v109, s[18:19] offset:2048
	global_load_dwordx4 v[28:31], v109, s[18:19] offset:3072
	s_waitcnt vmcnt(0)
	v_pk_add_f32 v[84:85], v[84:85], 1.0 op_sel_hi:[1,0]
	v_pk_add_f32 v[86:87], v[86:87], 1.0 op_sel_hi:[1,0]
	v_pk_add_f32 v[88:89], v[88:89], 1.0 op_sel_hi:[1,0]
	v_pk_add_f32 v[90:91], v[90:91], 1.0 op_sel_hi:[1,0]
	v_pk_add_f32 v[92:93], v[92:93], 1.0 op_sel_hi:[1,0]
	v_pk_add_f32 v[94:95], v[94:95], 1.0 op_sel_hi:[1,0]
	v_pk_add_f32 v[96:97], v[96:97], 1.0 op_sel_hi:[1,0]
	v_pk_add_f32 v[98:99], v[98:99], 1.0 op_sel_hi:[1,0]
	v_lshlrev_b32_e32 v140, 16, v0
	v_and_b32_e32 v141, 0xffff0000, v0
	v_lshlrev_b32_e32 v142, 16, v1
	v_and_b32_e32 v143, 0xffff0000, v1
	v_lshlrev_b32_e32 v144, 16, v2
	v_and_b32_e32 v145, 0xffff0000, v2
	v_lshlrev_b32_e32 v146, 16, v3
	v_and_b32_e32 v147, 0xffff0000, v3
	v_lshlrev_b32_e32 v148, 16, v4
	v_and_b32_e32 v149, 0xffff0000, v4
	v_lshlrev_b32_e32 v150, 16, v5
	v_and_b32_e32 v151, 0xffff0000, v5
	v_lshlrev_b32_e32 v152, 16, v6
	v_and_b32_e32 v153, 0xffff0000, v6
	v_lshlrev_b32_e32 v154, 16, v7
	v_and_b32_e32 v155, 0xffff0000, v7
	v_pk_mul_f32 v[100:101], v[140:141], v[140:141]
	v_pk_fma_f32 v[100:101], v[142:143], v[142:143], v[100:101]
	v_pk_fma_f32 v[100:101], v[144:145], v[144:145], v[100:101]
	v_pk_fma_f32 v[100:101], v[146:147], v[146:147], v[100:101]
	v_pk_fma_f32 v[100:101], v[148:149], v[148:149], v[100:101]
	v_pk_fma_f32 v[100:101], v[150:151], v[150:151], v[100:101]
	v_pk_fma_f32 v[100:101], v[152:153], v[152:153], v[100:101]
	v_pk_fma_f32 v[100:101], v[154:155], v[154:155], v[100:101]
	v_lshlrev_b32_e32 v140, 16, v8
	v_and_b32_e32 v141, 0xffff0000, v8
	v_lshlrev_b32_e32 v142, 16, v9
	v_and_b32_e32 v143, 0xffff0000, v9
	v_lshlrev_b32_e32 v144, 16, v10
	v_and_b32_e32 v145, 0xffff0000, v10
	v_lshlrev_b32_e32 v146, 16, v11
	v_and_b32_e32 v147, 0xffff0000, v11
	v_lshlrev_b32_e32 v148, 16, v12
	v_and_b32_e32 v149, 0xffff0000, v12
	v_lshlrev_b32_e32 v150, 16, v13
	v_and_b32_e32 v151, 0xffff0000, v13
	v_lshlrev_b32_e32 v152, 16, v14
	v_and_b32_e32 v153, 0xffff0000, v14
	v_lshlrev_b32_e32 v154, 16, v15
	v_and_b32_e32 v155, 0xffff0000, v15
	v_pk_mul_f32 v[102:103], v[140:141], v[140:141]
	v_pk_fma_f32 v[102:103], v[142:143], v[142:143], v[102:103]
	v_pk_fma_f32 v[102:103], v[144:145], v[144:145], v[102:103]
	v_pk_fma_f32 v[102:103], v[146:147], v[146:147], v[102:103]
	v_pk_fma_f32 v[102:103], v[148:149], v[148:149], v[102:103]
	v_pk_fma_f32 v[102:103], v[150:151], v[150:151], v[102:103]
	v_pk_fma_f32 v[102:103], v[152:153], v[152:153], v[102:103]
	v_pk_fma_f32 v[102:103], v[154:155], v[154:155], v[102:103]
	v_lshlrev_b32_e32 v140, 16, v16
	v_and_b32_e32 v141, 0xffff0000, v16
	v_lshlrev_b32_e32 v142, 16, v17
	v_and_b32_e32 v143, 0xffff0000, v17
	v_lshlrev_b32_e32 v144, 16, v18
	v_and_b32_e32 v145, 0xffff0000, v18
	v_lshlrev_b32_e32 v146, 16, v19
	v_and_b32_e32 v147, 0xffff0000, v19
	v_lshlrev_b32_e32 v148, 16, v20
	v_and_b32_e32 v149, 0xffff0000, v20
	v_lshlrev_b32_e32 v150, 16, v21
	v_and_b32_e32 v151, 0xffff0000, v21
	v_lshlrev_b32_e32 v152, 16, v22
	v_and_b32_e32 v153, 0xffff0000, v22
	v_lshlrev_b32_e32 v154, 16, v23
	v_and_b32_e32 v155, 0xffff0000, v23
	v_pk_mul_f32 v[104:105], v[140:141], v[140:141]
	v_pk_fma_f32 v[104:105], v[142:143], v[142:143], v[104:105]
	v_pk_fma_f32 v[104:105], v[144:145], v[144:145], v[104:105]
	v_pk_fma_f32 v[104:105], v[146:147], v[146:147], v[104:105]
	v_pk_fma_f32 v[104:105], v[148:149], v[148:149], v[104:105]
	v_pk_fma_f32 v[104:105], v[150:151], v[150:151], v[104:105]
	v_pk_fma_f32 v[104:105], v[152:153], v[152:153], v[104:105]
	v_pk_fma_f32 v[104:105], v[154:155], v[154:155], v[104:105]
	v_lshlrev_b32_e32 v140, 16, v24
	v_and_b32_e32 v141, 0xffff0000, v24
	v_lshlrev_b32_e32 v142, 16, v25
	v_and_b32_e32 v143, 0xffff0000, v25
	v_lshlrev_b32_e32 v144, 16, v26
	v_and_b32_e32 v145, 0xffff0000, v26
	v_lshlrev_b32_e32 v146, 16, v27
	v_and_b32_e32 v147, 0xffff0000, v27
	v_lshlrev_b32_e32 v148, 16, v28
	v_and_b32_e32 v149, 0xffff0000, v28
	v_lshlrev_b32_e32 v150, 16, v29
	v_and_b32_e32 v151, 0xffff0000, v29
	v_lshlrev_b32_e32 v152, 16, v30
	v_and_b32_e32 v153, 0xffff0000, v30
	v_lshlrev_b32_e32 v154, 16, v31
	v_and_b32_e32 v155, 0xffff0000, v31
	v_pk_mul_f32 v[106:107], v[140:141], v[140:141]
	v_pk_fma_f32 v[106:107], v[142:143], v[142:143], v[106:107]
	v_pk_fma_f32 v[106:107], v[144:145], v[144:145], v[106:107]
	v_pk_fma_f32 v[106:107], v[146:147], v[146:147], v[106:107]
	v_pk_fma_f32 v[106:107], v[148:149], v[148:149], v[106:107]
	v_pk_fma_f32 v[106:107], v[150:151], v[150:151], v[106:107]
	v_pk_fma_f32 v[106:107], v[152:153], v[152:153], v[106:107]
	v_pk_fma_f32 v[106:107], v[154:155], v[154:155], v[106:107]
	v_add_f32_e32 v100, v100, v101
	v_add_f32_e32 v102, v102, v103
	v_add_f32_e32 v104, v104, v105
	v_add_f32_e32 v106, v106, v107
	s_nop 1
	v_add_f32_dpp v100, v100, v100 row_shr:1 row_mask:0xf bank_mask:0xf bound_ctrl:1
	v_add_f32_dpp v102, v102, v102 row_shr:1 row_mask:0xf bank_mask:0xf bound_ctrl:1
	v_add_f32_dpp v104, v104, v104 row_shr:1 row_mask:0xf bank_mask:0xf bound_ctrl:1
	v_add_f32_dpp v106, v106, v106 row_shr:1 row_mask:0xf bank_mask:0xf bound_ctrl:1
	v_add_f32_dpp v100, v100, v100 row_shr:2 row_mask:0xf bank_mask:0xf bound_ctrl:1
	v_add_f32_dpp v102, v102, v102 row_shr:2 row_mask:0xf bank_mask:0xf bound_ctrl:1
	v_add_f32_dpp v104, v104, v104 row_shr:2 row_mask:0xf bank_mask:0xf bound_ctrl:1
	v_add_f32_dpp v106, v106, v106 row_shr:2 row_mask:0xf bank_mask:0xf bound_ctrl:1
	v_add_f32_dpp v100, v100, v100 row_shr:4 row_mask:0xf bank_mask:0xf bound_ctrl:1
	v_add_f32_dpp v102, v102, v102 row_shr:4 row_mask:0xf bank_mask:0xf bound_ctrl:1
	v_add_f32_dpp v104, v104, v104 row_shr:4 row_mask:0xf bank_mask:0xf bound_ctrl:1
	v_add_f32_dpp v106, v106, v106 row_shr:4 row_mask:0xf bank_mask:0xf bound_ctrl:1
	v_add_f32_dpp v100, v100, v100 row_shr:8 row_mask:0xf bank_mask:0xf bound_ctrl:1
	v_add_f32_dpp v102, v102, v102 row_shr:8 row_mask:0xf bank_mask:0xf bound_ctrl:1
	v_add_f32_dpp v104, v104, v104 row_shr:8 row_mask:0xf bank_mask:0xf bound_ctrl:1
	v_add_f32_dpp v106, v106, v106 row_shr:8 row_mask:0xf bank_mask:0xf bound_ctrl:1
	v_add_f32_dpp v100, v100, v100 row_bcast:15 row_mask:0xa bank_mask:0xf
	v_add_f32_dpp v102, v102, v102 row_bcast:15 row_mask:0xa bank_mask:0xf
	v_add_f32_dpp v104, v104, v104 row_bcast:15 row_mask:0xa bank_mask:0xf
	v_add_f32_dpp v106, v106, v106 row_bcast:15 row_mask:0xa bank_mask:0xf
	v_add_f32_dpp v100, v100, v100 row_bcast:31 row_mask:0xc bank_mask:0xf
	v_add_f32_dpp v102, v102, v102 row_bcast:31 row_mask:0xc bank_mask:0xf
	v_add_f32_dpp v104, v104, v104 row_bcast:31 row_mask:0xc bank_mask:0xf
	v_add_f32_dpp v106, v106, v106 row_bcast:31 row_mask:0xc bank_mask:0xf
	s_nop 1
	v_readlane_b32 s5, v100, 63
	v_readlane_b32 s32, v102, 63
	v_readlane_b32 s54, v104, 63
	v_readlane_b32 s60, v106, 63
	s_nop 1
	v_mov_b32_e32 v156, s5
	v_mov_b32_e32 v158, s32
	v_mov_b32_e32 v160, s54
	v_mov_b32_e32 v162, s60
	v_fmaak_f32 v156, v156, v50, 0x358637bd
	v_fmaak_f32 v158, v158, v50, 0x358637bd
	v_fmaak_f32 v160, v160, v50, 0x358637bd
	v_fmaak_f32 v162, v162, v50, 0x358637bd
	v_rsq_f32_e32 v156, v156
	v_rsq_f32_e32 v158, v158
	v_rsq_f32_e32 v160, v160
	v_rsq_f32_e32 v162, v162
	s_nop 0
	v_lshlrev_b32_e32 v140, 16, v0
	v_and_b32_e32 v141, 0xffff0000, v0
	v_lshlrev_b32_e32 v142, 16, v1
	v_and_b32_e32 v143, 0xffff0000, v1
	v_lshlrev_b32_e32 v144, 16, v2
	v_and_b32_e32 v145, 0xffff0000, v2
	v_lshlrev_b32_e32 v146, 16, v3
	v_and_b32_e32 v147, 0xffff0000, v3
	v_lshlrev_b32_e32 v148, 16, v4
	v_and_b32_e32 v149, 0xffff0000, v4
	v_lshlrev_b32_e32 v150, 16, v5
	v_and_b32_e32 v151, 0xffff0000, v5
	v_lshlrev_b32_e32 v152, 16, v6
	v_and_b32_e32 v153, 0xffff0000, v6
	v_lshlrev_b32_e32 v154, 16, v7
	v_and_b32_e32 v155, 0xffff0000, v7
	v_pk_mul_f32 v[140:141], v[156:157], v[140:141] op_sel_hi:[0,1]
	v_pk_mul_f32 v[142:143], v[156:157], v[142:143] op_sel_hi:[0,1]
	v_pk_mul_f32 v[144:145], v[156:157], v[144:145] op_sel_hi:[0,1]
	v_pk_mul_f32 v[146:147], v[156:157], v[146:147] op_sel_hi:[0,1]
	v_pk_mul_f32 v[148:149], v[156:157], v[148:149] op_sel_hi:[0,1]
	v_pk_mul_f32 v[150:151], v[156:157], v[150:151] op_sel_hi:[0,1]
	v_pk_mul_f32 v[152:153], v[156:157], v[152:153] op_sel_hi:[0,1]
	v_pk_mul_f32 v[154:155], v[156:157], v[154:155] op_sel_hi:[0,1]
	v_pk_mul_f32 v[140:141], v[140:141], v[32:33]
	v_pk_mul_f32 v[142:143], v[142:143], v[34:35]
	v_pk_mul_f32 v[144:145], v[144:145], v[36:37]
	v_pk_mul_f32 v[146:147], v[146:147], v[38:39]
	v_pk_mul_f32 v[148:149], v[148:149], v[40:41]
	v_pk_mul_f32 v[150:151], v[150:151], v[42:43]
	v_pk_mul_f32 v[152:153], v[152:153], v[44:45]
	v_pk_mul_f32 v[154:155], v[154:155], v[46:47]
	v_pk_fma_f32 v[140:141], v[140:141], v[84:85], v[124:125]
	v_pk_fma_f32 v[142:143], v[142:143], v[86:87], v[126:127]
	v_pk_fma_f32 v[144:145], v[144:145], v[88:89], v[128:129]
	v_pk_fma_f32 v[146:147], v[146:147], v[90:91], v[130:131]
	v_pk_fma_f32 v[148:149], v[148:149], v[92:93], v[132:133]
	v_pk_fma_f32 v[150:151], v[150:151], v[94:95], v[134:135]
	v_pk_fma_f32 v[152:153], v[152:153], v[96:97], v[136:137]
	v_pk_fma_f32 v[154:155], v[154:155], v[98:99], v[138:139]
	v_cvt_pk_bf16_f32 v164, v140, v141
	v_cvt_pk_bf16_f32 v165, v142, v143
	v_cvt_pk_bf16_f32 v166, v144, v145
	v_cvt_pk_bf16_f32 v167, v146, v147
	v_cvt_pk_bf16_f32 v168, v148, v149
	v_cvt_pk_bf16_f32 v169, v150, v151
	v_cvt_pk_bf16_f32 v170, v152, v153
	v_cvt_pk_bf16_f32 v171, v154, v155
	global_store_dwordx4 v51, v[164:167], s[20:21]
	global_store_dwordx4 v51, v[168:171], s[20:21] offset:1024
	v_lshlrev_b32_e32 v140, 16, v8
	v_and_b32_e32 v141, 0xffff0000, v8
	v_lshlrev_b32_e32 v142, 16, v9
	v_and_b32_e32 v143, 0xffff0000, v9
	v_lshlrev_b32_e32 v144, 16, v10
	v_and_b32_e32 v145, 0xffff0000, v10
	v_lshlrev_b32_e32 v146, 16, v11
	v_and_b32_e32 v147, 0xffff0000, v11
	v_lshlrev_b32_e32 v148, 16, v12
	v_and_b32_e32 v149, 0xffff0000, v12
	v_lshlrev_b32_e32 v150, 16, v13
	v_and_b32_e32 v151, 0xffff0000, v13
	v_lshlrev_b32_e32 v152, 16, v14
	v_and_b32_e32 v153, 0xffff0000, v14
	v_lshlrev_b32_e32 v154, 16, v15
	v_and_b32_e32 v155, 0xffff0000, v15
	v_pk_mul_f32 v[140:141], v[158:159], v[140:141] op_sel_hi:[0,1]
	v_pk_mul_f32 v[142:143], v[158:159], v[142:143] op_sel_hi:[0,1]
	v_pk_mul_f32 v[144:145], v[158:159], v[144:145] op_sel_hi:[0,1]
	v_pk_mul_f32 v[146:147], v[158:159], v[146:147] op_sel_hi:[0,1]
	v_pk_mul_f32 v[148:149], v[158:159], v[148:149] op_sel_hi:[0,1]
	v_pk_mul_f32 v[150:151], v[158:159], v[150:151] op_sel_hi:[0,1]
	v_pk_mul_f32 v[152:153], v[158:159], v[152:153] op_sel_hi:[0,1]
	v_pk_mul_f32 v[154:155], v[158:159], v[154:155] op_sel_hi:[0,1]
	v_pk_mul_f32 v[140:141], v[140:141], v[32:33]
	v_pk_mul_f32 v[142:143], v[142:143], v[34:35]
	v_pk_mul_f32 v[144:145], v[144:145], v[36:37]
	v_pk_mul_f32 v[146:147], v[146:147], v[38:39]
	v_pk_mul_f32 v[148:149], v[148:149], v[40:41]
	v_pk_mul_f32 v[150:151], v[150:151], v[42:43]
	v_pk_mul_f32 v[152:153], v[152:153], v[44:45]
	v_pk_mul_f32 v[154:155], v[154:155], v[46:47]
	v_pk_fma_f32 v[140:141], v[140:141], v[84:85], v[124:125]
	v_pk_fma_f32 v[142:143], v[142:143], v[86:87], v[126:127]
	v_pk_fma_f32 v[144:145], v[144:145], v[88:89], v[128:129]
	v_pk_fma_f32 v[146:147], v[146:147], v[90:91], v[130:131]
	v_pk_fma_f32 v[148:149], v[148:149], v[92:93], v[132:133]
	v_pk_fma_f32 v[150:151], v[150:151], v[94:95], v[134:135]
	v_pk_fma_f32 v[152:153], v[152:153], v[96:97], v[136:137]
	v_pk_fma_f32 v[154:155], v[154:155], v[98:99], v[138:139]
	v_cvt_pk_bf16_f32 v172, v140, v141
	v_cvt_pk_bf16_f32 v173, v142, v143
	v_cvt_pk_bf16_f32 v174, v144, v145
	v_cvt_pk_bf16_f32 v175, v146, v147
	v_cvt_pk_bf16_f32 v176, v148, v149
	v_cvt_pk_bf16_f32 v177, v150, v151
	v_cvt_pk_bf16_f32 v178, v152, v153
	v_cvt_pk_bf16_f32 v179, v154, v155
	global_store_dwordx4 v51, v[172:175], s[20:21] offset:2048
	global_store_dwordx4 v51, v[176:179], s[20:21] offset:3072
	v_lshlrev_b32_e32 v140, 16, v16
	v_and_b32_e32 v141, 0xffff0000, v16
	v_lshlrev_b32_e32 v142, 16, v17
	v_and_b32_e32 v143, 0xffff0000, v17
	v_lshlrev_b32_e32 v144, 16, v18
	v_and_b32_e32 v145, 0xffff0000, v18
	v_lshlrev_b32_e32 v146, 16, v19
	v_and_b32_e32 v147, 0xffff0000, v19
	v_lshlrev_b32_e32 v148, 16, v20
	v_and_b32_e32 v149, 0xffff0000, v20
	v_lshlrev_b32_e32 v150, 16, v21
	v_and_b32_e32 v151, 0xffff0000, v21
	v_lshlrev_b32_e32 v152, 16, v22
	v_and_b32_e32 v153, 0xffff0000, v22
	v_lshlrev_b32_e32 v154, 16, v23
	v_and_b32_e32 v155, 0xffff0000, v23
	v_pk_mul_f32 v[140:141], v[160:161], v[140:141] op_sel_hi:[0,1]
	v_pk_mul_f32 v[142:143], v[160:161], v[142:143] op_sel_hi:[0,1]
	v_pk_mul_f32 v[144:145], v[160:161], v[144:145] op_sel_hi:[0,1]
	v_pk_mul_f32 v[146:147], v[160:161], v[146:147] op_sel_hi:[0,1]
	v_pk_mul_f32 v[148:149], v[160:161], v[148:149] op_sel_hi:[0,1]
	v_pk_mul_f32 v[150:151], v[160:161], v[150:151] op_sel_hi:[0,1]
	v_pk_mul_f32 v[152:153], v[160:161], v[152:153] op_sel_hi:[0,1]
	v_pk_mul_f32 v[154:155], v[160:161], v[154:155] op_sel_hi:[0,1]
	v_pk_mul_f32 v[140:141], v[140:141], v[32:33]
	v_pk_mul_f32 v[142:143], v[142:143], v[34:35]
	v_pk_mul_f32 v[144:145], v[144:145], v[36:37]
	v_pk_mul_f32 v[146:147], v[146:147], v[38:39]
	v_pk_mul_f32 v[148:149], v[148:149], v[40:41]
	v_pk_mul_f32 v[150:151], v[150:151], v[42:43]
	v_pk_mul_f32 v[152:153], v[152:153], v[44:45]
	v_pk_mul_f32 v[154:155], v[154:155], v[46:47]
	v_pk_fma_f32 v[140:141], v[140:141], v[84:85], v[124:125]
	v_pk_fma_f32 v[142:143], v[142:143], v[86:87], v[126:127]
	v_pk_fma_f32 v[144:145], v[144:145], v[88:89], v[128:129]
	v_pk_fma_f32 v[146:147], v[146:147], v[90:91], v[130:131]
	v_pk_fma_f32 v[148:149], v[148:149], v[92:93], v[132:133]
	v_pk_fma_f32 v[150:151], v[150:151], v[94:95], v[134:135]
	v_pk_fma_f32 v[152:153], v[152:153], v[96:97], v[136:137]
	v_pk_fma_f32 v[154:155], v[154:155], v[98:99], v[138:139]
	v_cvt_pk_bf16_f32 v164, v140, v141
	v_cvt_pk_bf16_f32 v165, v142, v143
	v_cvt_pk_bf16_f32 v166, v144, v145
	v_cvt_pk_bf16_f32 v167, v146, v147
	v_cvt_pk_bf16_f32 v168, v148, v149
	v_cvt_pk_bf16_f32 v169, v150, v151
	v_cvt_pk_bf16_f32 v170, v152, v153
	v_cvt_pk_bf16_f32 v171, v154, v155
	global_store_dwordx4 v109, v[164:167], s[20:21]
	global_store_dwordx4 v109, v[168:171], s[20:21] offset:1024
	v_lshlrev_b32_e32 v140, 16, v24
	v_and_b32_e32 v141, 0xffff0000, v24
	v_lshlrev_b32_e32 v142, 16, v25
	v_and_b32_e32 v143, 0xffff0000, v25
	v_lshlrev_b32_e32 v144, 16, v26
	v_and_b32_e32 v145, 0xffff0000, v26
	v_lshlrev_b32_e32 v146, 16, v27
	v_and_b32_e32 v147, 0xffff0000, v27
	v_lshlrev_b32_e32 v148, 16, v28
	v_and_b32_e32 v149, 0xffff0000, v28
	v_lshlrev_b32_e32 v150, 16, v29
	v_and_b32_e32 v151, 0xffff0000, v29
	v_lshlrev_b32_e32 v152, 16, v30
	v_and_b32_e32 v153, 0xffff0000, v30
	v_lshlrev_b32_e32 v154, 16, v31
	v_and_b32_e32 v155, 0xffff0000, v31
	v_pk_mul_f32 v[140:141], v[162:163], v[140:141] op_sel_hi:[0,1]
	v_pk_mul_f32 v[142:143], v[162:163], v[142:143] op_sel_hi:[0,1]
	v_pk_mul_f32 v[144:145], v[162:163], v[144:145] op_sel_hi:[0,1]
	v_pk_mul_f32 v[146:147], v[162:163], v[146:147] op_sel_hi:[0,1]
	v_pk_mul_f32 v[148:149], v[162:163], v[148:149] op_sel_hi:[0,1]
	v_pk_mul_f32 v[150:151], v[162:163], v[150:151] op_sel_hi:[0,1]
	v_pk_mul_f32 v[152:153], v[162:163], v[152:153] op_sel_hi:[0,1]
	v_pk_mul_f32 v[154:155], v[162:163], v[154:155] op_sel_hi:[0,1]
	v_pk_mul_f32 v[140:141], v[140:141], v[32:33]
	v_pk_mul_f32 v[142:143], v[142:143], v[34:35]
	v_pk_mul_f32 v[144:145], v[144:145], v[36:37]
	v_pk_mul_f32 v[146:147], v[146:147], v[38:39]
	v_pk_mul_f32 v[148:149], v[148:149], v[40:41]
	v_pk_mul_f32 v[150:151], v[150:151], v[42:43]
	v_pk_mul_f32 v[152:153], v[152:153], v[44:45]
	v_pk_mul_f32 v[154:155], v[154:155], v[46:47]
	v_pk_fma_f32 v[140:141], v[140:141], v[84:85], v[124:125]
	v_pk_fma_f32 v[142:143], v[142:143], v[86:87], v[126:127]
	v_pk_fma_f32 v[144:145], v[144:145], v[88:89], v[128:129]
	v_pk_fma_f32 v[146:147], v[146:147], v[90:91], v[130:131]
	v_pk_fma_f32 v[148:149], v[148:149], v[92:93], v[132:133]
	v_pk_fma_f32 v[150:151], v[150:151], v[94:95], v[134:135]
	v_pk_fma_f32 v[152:153], v[152:153], v[96:97], v[136:137]
	v_pk_fma_f32 v[154:155], v[154:155], v[98:99], v[138:139]
	v_cvt_pk_bf16_f32 v172, v140, v141
	v_cvt_pk_bf16_f32 v173, v142, v143
	v_cvt_pk_bf16_f32 v174, v144, v145
	v_cvt_pk_bf16_f32 v175, v146, v147
	v_cvt_pk_bf16_f32 v176, v148, v149
	v_cvt_pk_bf16_f32 v177, v150, v151
	v_cvt_pk_bf16_f32 v178, v152, v153
	v_cvt_pk_bf16_f32 v179, v154, v155
	global_store_dwordx4 v109, v[172:175], s[20:21] offset:2048
	global_store_dwordx4 v109, v[176:179], s[20:21] offset:3072
	s_mul_i32 s58, s23, 0x6000
	s_add_u32 s0, s16, s58
	s_addc_u32 s1, s17, 0
	s_add_u32 s14, s0, 0x1000
	s_addc_u32 s15, s1, 0
	global_load_dwordx4 v[124:127], v108, s[0:1]
	global_load_dwordx4 v[128:131], v108, s[0:1] offset:16
	global_load_dwordx4 v[132:135], v108, s[0:1] offset:2048
	global_load_dwordx4 v[136:139], v108, s[0:1] offset:2064
	global_load_dwordx4 v[84:87], v108, s[14:15]
	global_load_dwordx4 v[88:91], v108, s[14:15] offset:16
	global_load_dwordx4 v[92:95], v108, s[14:15] offset:2048
	global_load_dwordx4 v[96:99], v108, s[14:15] offset:2064
	s_lshl_b32 s58, s81, 11
	s_add_u32 s18, s6, s58
	s_addc_u32 s19, s7, 0
	s_add_u32 s20, s12, s58
	s_addc_u32 s21, s13, 0
	global_load_dwordx4 v[52:55], v51, s[18:19]
	global_load_dwordx4 v[56:59], v51, s[18:19] offset:1024
	global_load_dwordx4 v[60:63], v51, s[18:19] offset:2048
	global_load_dwordx4 v[64:67], v51, s[18:19] offset:3072
	global_load_dwordx4 v[68:71], v109, s[18:19]
	global_load_dwordx4 v[72:75], v109, s[18:19] offset:1024
	global_load_dwordx4 v[76:79], v109, s[18:19] offset:2048
	global_load_dwordx4 v[80:83], v109, s[18:19] offset:3072
	s_waitcnt vmcnt(0)
	v_pk_add_f32 v[84:85], v[84:85], 1.0 op_sel_hi:[1,0]
	v_pk_add_f32 v[86:87], v[86:87], 1.0 op_sel_hi:[1,0]
	v_pk_add_f32 v[88:89], v[88:89], 1.0 op_sel_hi:[1,0]
	v_pk_add_f32 v[90:91], v[90:91], 1.0 op_sel_hi:[1,0]
	v_pk_add_f32 v[92:93], v[92:93], 1.0 op_sel_hi:[1,0]
	v_pk_add_f32 v[94:95], v[94:95], 1.0 op_sel_hi:[1,0]
	v_pk_add_f32 v[96:97], v[96:97], 1.0 op_sel_hi:[1,0]
	v_pk_add_f32 v[98:99], v[98:99], 1.0 op_sel_hi:[1,0]
	s_add_u32 s18, s18, 0x2000
	s_addc_u32 s19, s19, 0
	global_load_dwordx4 v[0:3], v51, s[18:19]
	global_load_dwordx4 v[4:7], v51, s[18:19] offset:1024
	global_load_dwordx4 v[8:11], v51, s[18:19] offset:2048
	global_load_dwordx4 v[12:15], v51, s[18:19] offset:3072
	global_load_dwordx4 v[16:19], v109, s[18:19]
	global_load_dwordx4 v[20:23], v109, s[18:19] offset:1024
	global_load_dwordx4 v[24:27], v109, s[18:19] offset:2048
	global_load_dwordx4 v[28:31], v109, s[18:19] offset:3072
	v_lshlrev_b32_e32 v140, 16, v52
	v_and_b32_e32 v141, 0xffff0000, v52
	v_lshlrev_b32_e32 v142, 16, v53
	v_and_b32_e32 v143, 0xffff0000, v53
	v_lshlrev_b32_e32 v144, 16, v54
	v_and_b32_e32 v145, 0xffff0000, v54
	v_lshlrev_b32_e32 v146, 16, v55
	v_and_b32_e32 v147, 0xffff0000, v55
	v_lshlrev_b32_e32 v148, 16, v56
	v_and_b32_e32 v149, 0xffff0000, v56
	v_lshlrev_b32_e32 v150, 16, v57
	v_and_b32_e32 v151, 0xffff0000, v57
	v_lshlrev_b32_e32 v152, 16, v58
	v_and_b32_e32 v153, 0xffff0000, v58
	v_lshlrev_b32_e32 v154, 16, v59
	v_and_b32_e32 v155, 0xffff0000, v59
	v_pk_mul_f32 v[100:101], v[140:141], v[140:141]
	v_pk_fma_f32 v[100:101], v[142:143], v[142:143], v[100:101]
	v_pk_fma_f32 v[100:101], v[144:145], v[144:145], v[100:101]
	v_pk_fma_f32 v[100:101], v[146:147], v[146:147], v[100:101]
	v_pk_fma_f32 v[100:101], v[148:149], v[148:149], v[100:101]
	v_pk_fma_f32 v[100:101], v[150:151], v[150:151], v[100:101]
	v_pk_fma_f32 v[100:101], v[152:153], v[152:153], v[100:101]
	v_pk_fma_f32 v[100:101], v[154:155], v[154:155], v[100:101]
	v_lshlrev_b32_e32 v140, 16, v60
	v_and_b32_e32 v141, 0xffff0000, v60
	v_lshlrev_b32_e32 v142, 16, v61
	v_and_b32_e32 v143, 0xffff0000, v61
	v_lshlrev_b32_e32 v144, 16, v62
	v_and_b32_e32 v145, 0xffff0000, v62
	v_lshlrev_b32_e32 v146, 16, v63
	v_and_b32_e32 v147, 0xffff0000, v63
	v_lshlrev_b32_e32 v148, 16, v64
	v_and_b32_e32 v149, 0xffff0000, v64
	v_lshlrev_b32_e32 v150, 16, v65
	v_and_b32_e32 v151, 0xffff0000, v65
	v_lshlrev_b32_e32 v152, 16, v66
	v_and_b32_e32 v153, 0xffff0000, v66
	v_lshlrev_b32_e32 v154, 16, v67
	v_and_b32_e32 v155, 0xffff0000, v67
	v_pk_mul_f32 v[102:103], v[140:141], v[140:141]
	v_pk_fma_f32 v[102:103], v[142:143], v[142:143], v[102:103]
	v_pk_fma_f32 v[102:103], v[144:145], v[144:145], v[102:103]
	v_pk_fma_f32 v[102:103], v[146:147], v[146:147], v[102:103]
	v_pk_fma_f32 v[102:103], v[148:149], v[148:149], v[102:103]
	v_pk_fma_f32 v[102:103], v[150:151], v[150:151], v[102:103]
	v_pk_fma_f32 v[102:103], v[152:153], v[152:153], v[102:103]
	v_pk_fma_f32 v[102:103], v[154:155], v[154:155], v[102:103]
	v_lshlrev_b32_e32 v140, 16, v68
	v_and_b32_e32 v141, 0xffff0000, v68
	v_lshlrev_b32_e32 v142, 16, v69
	v_and_b32_e32 v143, 0xffff0000, v69
	v_lshlrev_b32_e32 v144, 16, v70
	v_and_b32_e32 v145, 0xffff0000, v70
	v_lshlrev_b32_e32 v146, 16, v71
	v_and_b32_e32 v147, 0xffff0000, v71
	v_lshlrev_b32_e32 v148, 16, v72
	v_and_b32_e32 v149, 0xffff0000, v72
	v_lshlrev_b32_e32 v150, 16, v73
	v_and_b32_e32 v151, 0xffff0000, v73
	v_lshlrev_b32_e32 v152, 16, v74
	v_and_b32_e32 v153, 0xffff0000, v74
	v_lshlrev_b32_e32 v154, 16, v75
	v_and_b32_e32 v155, 0xffff0000, v75
	v_pk_mul_f32 v[104:105], v[140:141], v[140:141]
	v_pk_fma_f32 v[104:105], v[142:143], v[142:143], v[104:105]
	v_pk_fma_f32 v[104:105], v[144:145], v[144:145], v[104:105]
	v_pk_fma_f32 v[104:105], v[146:147], v[146:147], v[104:105]
	v_pk_fma_f32 v[104:105], v[148:149], v[148:149], v[104:105]
	v_pk_fma_f32 v[104:105], v[150:151], v[150:151], v[104:105]
	v_pk_fma_f32 v[104:105], v[152:153], v[152:153], v[104:105]
	v_pk_fma_f32 v[104:105], v[154:155], v[154:155], v[104:105]
	v_lshlrev_b32_e32 v140, 16, v76
	v_and_b32_e32 v141, 0xffff0000, v76
	v_lshlrev_b32_e32 v142, 16, v77
	v_and_b32_e32 v143, 0xffff0000, v77
	v_lshlrev_b32_e32 v144, 16, v78
	v_and_b32_e32 v145, 0xffff0000, v78
	v_lshlrev_b32_e32 v146, 16, v79
	v_and_b32_e32 v147, 0xffff0000, v79
	v_lshlrev_b32_e32 v148, 16, v80
	v_and_b32_e32 v149, 0xffff0000, v80
	v_lshlrev_b32_e32 v150, 16, v81
	v_and_b32_e32 v151, 0xffff0000, v81
	v_lshlrev_b32_e32 v152, 16, v82
	v_and_b32_e32 v153, 0xffff0000, v82
	v_lshlrev_b32_e32 v154, 16, v83
	v_and_b32_e32 v155, 0xffff0000, v83
	v_pk_mul_f32 v[106:107], v[140:141], v[140:141]
	v_pk_fma_f32 v[106:107], v[142:143], v[142:143], v[106:107]
	v_pk_fma_f32 v[106:107], v[144:145], v[144:145], v[106:107]
	v_pk_fma_f32 v[106:107], v[146:147], v[146:147], v[106:107]
	v_pk_fma_f32 v[106:107], v[148:149], v[148:149], v[106:107]
	v_pk_fma_f32 v[106:107], v[150:151], v[150:151], v[106:107]
	v_pk_fma_f32 v[106:107], v[152:153], v[152:153], v[106:107]
	v_pk_fma_f32 v[106:107], v[154:155], v[154:155], v[106:107]
	v_add_f32_e32 v100, v100, v101
	v_add_f32_e32 v102, v102, v103
	v_add_f32_e32 v104, v104, v105
	v_add_f32_e32 v106, v106, v107
	s_nop 1
	v_add_f32_dpp v100, v100, v100 row_shr:1 row_mask:0xf bank_mask:0xf bound_ctrl:1
	v_add_f32_dpp v102, v102, v102 row_shr:1 row_mask:0xf bank_mask:0xf bound_ctrl:1
	v_add_f32_dpp v104, v104, v104 row_shr:1 row_mask:0xf bank_mask:0xf bound_ctrl:1
	v_add_f32_dpp v106, v106, v106 row_shr:1 row_mask:0xf bank_mask:0xf bound_ctrl:1
	v_add_f32_dpp v100, v100, v100 row_shr:2 row_mask:0xf bank_mask:0xf bound_ctrl:1
	v_add_f32_dpp v102, v102, v102 row_shr:2 row_mask:0xf bank_mask:0xf bound_ctrl:1
	v_add_f32_dpp v104, v104, v104 row_shr:2 row_mask:0xf bank_mask:0xf bound_ctrl:1
	v_add_f32_dpp v106, v106, v106 row_shr:2 row_mask:0xf bank_mask:0xf bound_ctrl:1
	v_add_f32_dpp v100, v100, v100 row_shr:4 row_mask:0xf bank_mask:0xf bound_ctrl:1
	v_add_f32_dpp v102, v102, v102 row_shr:4 row_mask:0xf bank_mask:0xf bound_ctrl:1
	v_add_f32_dpp v104, v104, v104 row_shr:4 row_mask:0xf bank_mask:0xf bound_ctrl:1
	v_add_f32_dpp v106, v106, v106 row_shr:4 row_mask:0xf bank_mask:0xf bound_ctrl:1
	v_add_f32_dpp v100, v100, v100 row_shr:8 row_mask:0xf bank_mask:0xf bound_ctrl:1
	v_add_f32_dpp v102, v102, v102 row_shr:8 row_mask:0xf bank_mask:0xf bound_ctrl:1
	v_add_f32_dpp v104, v104, v104 row_shr:8 row_mask:0xf bank_mask:0xf bound_ctrl:1
	v_add_f32_dpp v106, v106, v106 row_shr:8 row_mask:0xf bank_mask:0xf bound_ctrl:1
	v_add_f32_dpp v100, v100, v100 row_bcast:15 row_mask:0xa bank_mask:0xf
	v_add_f32_dpp v102, v102, v102 row_bcast:15 row_mask:0xa bank_mask:0xf
	v_add_f32_dpp v104, v104, v104 row_bcast:15 row_mask:0xa bank_mask:0xf
	v_add_f32_dpp v106, v106, v106 row_bcast:15 row_mask:0xa bank_mask:0xf
	v_add_f32_dpp v100, v100, v100 row_bcast:31 row_mask:0xc bank_mask:0xf
	v_add_f32_dpp v102, v102, v102 row_bcast:31 row_mask:0xc bank_mask:0xf
	v_add_f32_dpp v104, v104, v104 row_bcast:31 row_mask:0xc bank_mask:0xf
	v_add_f32_dpp v106, v106, v106 row_bcast:31 row_mask:0xc bank_mask:0xf
	s_nop 1
	v_readlane_b32 s5, v100, 63
	v_readlane_b32 s32, v102, 63
	v_readlane_b32 s54, v104, 63
	v_readlane_b32 s60, v106, 63
	s_nop 1
	v_mov_b32_e32 v156, s5
	v_mov_b32_e32 v158, s32
	v_mov_b32_e32 v160, s54
	v_mov_b32_e32 v162, s60
	v_fmaak_f32 v156, v156, v50, 0x358637bd
	v_fmaak_f32 v158, v158, v50, 0x358637bd
	v_fmaak_f32 v160, v160, v50, 0x358637bd
	v_fmaak_f32 v162, v162, v50, 0x358637bd
	v_rsq_f32_e32 v156, v156
	v_rsq_f32_e32 v158, v158
	v_rsq_f32_e32 v160, v160
	v_rsq_f32_e32 v162, v162
	s_nop 0
	v_lshlrev_b32_e32 v140, 16, v52
	v_and_b32_e32 v141, 0xffff0000, v52
	v_lshlrev_b32_e32 v142, 16, v53
	v_and_b32_e32 v143, 0xffff0000, v53
	v_lshlrev_b32_e32 v144, 16, v54
	v_and_b32_e32 v145, 0xffff0000, v54
	v_lshlrev_b32_e32 v146, 16, v55
	v_and_b32_e32 v147, 0xffff0000, v55
	v_lshlrev_b32_e32 v148, 16, v56
	v_and_b32_e32 v149, 0xffff0000, v56
	v_lshlrev_b32_e32 v150, 16, v57
	v_and_b32_e32 v151, 0xffff0000, v57
	v_lshlrev_b32_e32 v152, 16, v58
	v_and_b32_e32 v153, 0xffff0000, v58
	v_lshlrev_b32_e32 v154, 16, v59
	v_and_b32_e32 v155, 0xffff0000, v59
	v_pk_mul_f32 v[140:141], v[156:157], v[140:141] op_sel_hi:[0,1]
	v_pk_mul_f32 v[142:143], v[156:157], v[142:143] op_sel_hi:[0,1]
	v_pk_mul_f32 v[144:145], v[156:157], v[144:145] op_sel_hi:[0,1]
	v_pk_mul_f32 v[146:147], v[156:157], v[146:147] op_sel_hi:[0,1]
	v_pk_mul_f32 v[148:149], v[156:157], v[148:149] op_sel_hi:[0,1]
	v_pk_mul_f32 v[150:151], v[156:157], v[150:151] op_sel_hi:[0,1]
	v_pk_mul_f32 v[152:153], v[156:157], v[152:153] op_sel_hi:[0,1]
	v_pk_mul_f32 v[154:155], v[156:157], v[154:155] op_sel_hi:[0,1]
	v_pk_mul_f32 v[140:141], v[140:141], v[32:33]
	v_pk_mul_f32 v[142:143], v[142:143], v[34:35]
	v_pk_mul_f32 v[144:145], v[144:145], v[36:37]
	v_pk_mul_f32 v[146:147], v[146:147], v[38:39]
	v_pk_mul_f32 v[148:149], v[148:149], v[40:41]
	v_pk_mul_f32 v[150:151], v[150:151], v[42:43]
	v_pk_mul_f32 v[152:153], v[152:153], v[44:45]
	v_pk_mul_f32 v[154:155], v[154:155], v[46:47]
	v_pk_fma_f32 v[140:141], v[140:141], v[84:85], v[124:125]
	v_pk_fma_f32 v[142:143], v[142:143], v[86:87], v[126:127]
	v_pk_fma_f32 v[144:145], v[144:145], v[88:89], v[128:129]
	v_pk_fma_f32 v[146:147], v[146:147], v[90:91], v[130:131]
	v_pk_fma_f32 v[148:149], v[148:149], v[92:93], v[132:133]
	v_pk_fma_f32 v[150:151], v[150:151], v[94:95], v[134:135]
	v_pk_fma_f32 v[152:153], v[152:153], v[96:97], v[136:137]
	v_pk_fma_f32 v[154:155], v[154:155], v[98:99], v[138:139]
	v_cvt_pk_bf16_f32 v164, v140, v141
	v_cvt_pk_bf16_f32 v165, v142, v143
	v_cvt_pk_bf16_f32 v166, v144, v145
	v_cvt_pk_bf16_f32 v167, v146, v147
	v_cvt_pk_bf16_f32 v168, v148, v149
	v_cvt_pk_bf16_f32 v169, v150, v151
	v_cvt_pk_bf16_f32 v170, v152, v153
	v_cvt_pk_bf16_f32 v171, v154, v155
	global_store_dwordx4 v51, v[164:167], s[20:21]
	global_store_dwordx4 v51, v[168:171], s[20:21] offset:1024
	v_lshlrev_b32_e32 v140, 16, v60
	v_and_b32_e32 v141, 0xffff0000, v60
	v_lshlrev_b32_e32 v142, 16, v61
	v_and_b32_e32 v143, 0xffff0000, v61
	v_lshlrev_b32_e32 v144, 16, v62
	v_and_b32_e32 v145, 0xffff0000, v62
	v_lshlrev_b32_e32 v146, 16, v63
	v_and_b32_e32 v147, 0xffff0000, v63
	v_lshlrev_b32_e32 v148, 16, v64
	v_and_b32_e32 v149, 0xffff0000, v64
	v_lshlrev_b32_e32 v150, 16, v65
	v_and_b32_e32 v151, 0xffff0000, v65
	v_lshlrev_b32_e32 v152, 16, v66
	v_and_b32_e32 v153, 0xffff0000, v66
	v_lshlrev_b32_e32 v154, 16, v67
	v_and_b32_e32 v155, 0xffff0000, v67
	v_pk_mul_f32 v[140:141], v[158:159], v[140:141] op_sel_hi:[0,1]
	v_pk_mul_f32 v[142:143], v[158:159], v[142:143] op_sel_hi:[0,1]
	v_pk_mul_f32 v[144:145], v[158:159], v[144:145] op_sel_hi:[0,1]
	v_pk_mul_f32 v[146:147], v[158:159], v[146:147] op_sel_hi:[0,1]
	v_pk_mul_f32 v[148:149], v[158:159], v[148:149] op_sel_hi:[0,1]
	v_pk_mul_f32 v[150:151], v[158:159], v[150:151] op_sel_hi:[0,1]
	v_pk_mul_f32 v[152:153], v[158:159], v[152:153] op_sel_hi:[0,1]
	v_pk_mul_f32 v[154:155], v[158:159], v[154:155] op_sel_hi:[0,1]
	v_pk_mul_f32 v[140:141], v[140:141], v[32:33]
	v_pk_mul_f32 v[142:143], v[142:143], v[34:35]
	v_pk_mul_f32 v[144:145], v[144:145], v[36:37]
	v_pk_mul_f32 v[146:147], v[146:147], v[38:39]
	v_pk_mul_f32 v[148:149], v[148:149], v[40:41]
	v_pk_mul_f32 v[150:151], v[150:151], v[42:43]
	v_pk_mul_f32 v[152:153], v[152:153], v[44:45]
	v_pk_mul_f32 v[154:155], v[154:155], v[46:47]
	v_pk_fma_f32 v[140:141], v[140:141], v[84:85], v[124:125]
	v_pk_fma_f32 v[142:143], v[142:143], v[86:87], v[126:127]
	v_pk_fma_f32 v[144:145], v[144:145], v[88:89], v[128:129]
	v_pk_fma_f32 v[146:147], v[146:147], v[90:91], v[130:131]
	v_pk_fma_f32 v[148:149], v[148:149], v[92:93], v[132:133]
	v_pk_fma_f32 v[150:151], v[150:151], v[94:95], v[134:135]
	v_pk_fma_f32 v[152:153], v[152:153], v[96:97], v[136:137]
	v_pk_fma_f32 v[154:155], v[154:155], v[98:99], v[138:139]
	v_cvt_pk_bf16_f32 v172, v140, v141
	v_cvt_pk_bf16_f32 v173, v142, v143
	v_cvt_pk_bf16_f32 v174, v144, v145
	v_cvt_pk_bf16_f32 v175, v146, v147
	v_cvt_pk_bf16_f32 v176, v148, v149
	v_cvt_pk_bf16_f32 v177, v150, v151
	v_cvt_pk_bf16_f32 v178, v152, v153
	v_cvt_pk_bf16_f32 v179, v154, v155
	global_store_dwordx4 v51, v[172:175], s[20:21] offset:2048
	global_store_dwordx4 v51, v[176:179], s[20:21] offset:3072
	v_lshlrev_b32_e32 v140, 16, v68
	v_and_b32_e32 v141, 0xffff0000, v68
	v_lshlrev_b32_e32 v142, 16, v69
	v_and_b32_e32 v143, 0xffff0000, v69
	v_lshlrev_b32_e32 v144, 16, v70
	v_and_b32_e32 v145, 0xffff0000, v70
	v_lshlrev_b32_e32 v146, 16, v71
	v_and_b32_e32 v147, 0xffff0000, v71
	v_lshlrev_b32_e32 v148, 16, v72
	v_and_b32_e32 v149, 0xffff0000, v72
	v_lshlrev_b32_e32 v150, 16, v73
	v_and_b32_e32 v151, 0xffff0000, v73
	v_lshlrev_b32_e32 v152, 16, v74
	v_and_b32_e32 v153, 0xffff0000, v74
	v_lshlrev_b32_e32 v154, 16, v75
	v_and_b32_e32 v155, 0xffff0000, v75
	v_pk_mul_f32 v[140:141], v[160:161], v[140:141] op_sel_hi:[0,1]
	v_pk_mul_f32 v[142:143], v[160:161], v[142:143] op_sel_hi:[0,1]
	v_pk_mul_f32 v[144:145], v[160:161], v[144:145] op_sel_hi:[0,1]
	v_pk_mul_f32 v[146:147], v[160:161], v[146:147] op_sel_hi:[0,1]
	v_pk_mul_f32 v[148:149], v[160:161], v[148:149] op_sel_hi:[0,1]
	v_pk_mul_f32 v[150:151], v[160:161], v[150:151] op_sel_hi:[0,1]
	v_pk_mul_f32 v[152:153], v[160:161], v[152:153] op_sel_hi:[0,1]
	v_pk_mul_f32 v[154:155], v[160:161], v[154:155] op_sel_hi:[0,1]
	v_pk_mul_f32 v[140:141], v[140:141], v[32:33]
	v_pk_mul_f32 v[142:143], v[142:143], v[34:35]
	v_pk_mul_f32 v[144:145], v[144:145], v[36:37]
	v_pk_mul_f32 v[146:147], v[146:147], v[38:39]
	v_pk_mul_f32 v[148:149], v[148:149], v[40:41]
	v_pk_mul_f32 v[150:151], v[150:151], v[42:43]
	v_pk_mul_f32 v[152:153], v[152:153], v[44:45]
	v_pk_mul_f32 v[154:155], v[154:155], v[46:47]
	v_pk_fma_f32 v[140:141], v[140:141], v[84:85], v[124:125]
	v_pk_fma_f32 v[142:143], v[142:143], v[86:87], v[126:127]
	v_pk_fma_f32 v[144:145], v[144:145], v[88:89], v[128:129]
	v_pk_fma_f32 v[146:147], v[146:147], v[90:91], v[130:131]
	v_pk_fma_f32 v[148:149], v[148:149], v[92:93], v[132:133]
	v_pk_fma_f32 v[150:151], v[150:151], v[94:95], v[134:135]
	v_pk_fma_f32 v[152:153], v[152:153], v[96:97], v[136:137]
	v_pk_fma_f32 v[154:155], v[154:155], v[98:99], v[138:139]
	v_cvt_pk_bf16_f32 v164, v140, v141
	v_cvt_pk_bf16_f32 v165, v142, v143
	v_cvt_pk_bf16_f32 v166, v144, v145
	v_cvt_pk_bf16_f32 v167, v146, v147
	v_cvt_pk_bf16_f32 v168, v148, v149
	v_cvt_pk_bf16_f32 v169, v150, v151
	v_cvt_pk_bf16_f32 v170, v152, v153
	v_cvt_pk_bf16_f32 v171, v154, v155
	global_store_dwordx4 v109, v[164:167], s[20:21]
	global_store_dwordx4 v109, v[168:171], s[20:21] offset:1024
	v_lshlrev_b32_e32 v140, 16, v76
	v_and_b32_e32 v141, 0xffff0000, v76
	v_lshlrev_b32_e32 v142, 16, v77
	v_and_b32_e32 v143, 0xffff0000, v77
	v_lshlrev_b32_e32 v144, 16, v78
	v_and_b32_e32 v145, 0xffff0000, v78
	v_lshlrev_b32_e32 v146, 16, v79
	v_and_b32_e32 v147, 0xffff0000, v79
	v_lshlrev_b32_e32 v148, 16, v80
	v_and_b32_e32 v149, 0xffff0000, v80
	v_lshlrev_b32_e32 v150, 16, v81
	v_and_b32_e32 v151, 0xffff0000, v81
	v_lshlrev_b32_e32 v152, 16, v82
	v_and_b32_e32 v153, 0xffff0000, v82
	v_lshlrev_b32_e32 v154, 16, v83
	v_and_b32_e32 v155, 0xffff0000, v83
	v_pk_mul_f32 v[140:141], v[162:163], v[140:141] op_sel_hi:[0,1]
	v_pk_mul_f32 v[142:143], v[162:163], v[142:143] op_sel_hi:[0,1]
	v_pk_mul_f32 v[144:145], v[162:163], v[144:145] op_sel_hi:[0,1]
	v_pk_mul_f32 v[146:147], v[162:163], v[146:147] op_sel_hi:[0,1]
	v_pk_mul_f32 v[148:149], v[162:163], v[148:149] op_sel_hi:[0,1]
	v_pk_mul_f32 v[150:151], v[162:163], v[150:151] op_sel_hi:[0,1]
	v_pk_mul_f32 v[152:153], v[162:163], v[152:153] op_sel_hi:[0,1]
	v_pk_mul_f32 v[154:155], v[162:163], v[154:155] op_sel_hi:[0,1]
	v_pk_mul_f32 v[140:141], v[140:141], v[32:33]
	v_pk_mul_f32 v[142:143], v[142:143], v[34:35]
	v_pk_mul_f32 v[144:145], v[144:145], v[36:37]
	v_pk_mul_f32 v[146:147], v[146:147], v[38:39]
	v_pk_mul_f32 v[148:149], v[148:149], v[40:41]
	v_pk_mul_f32 v[150:151], v[150:151], v[42:43]
	v_pk_mul_f32 v[152:153], v[152:153], v[44:45]
	v_pk_mul_f32 v[154:155], v[154:155], v[46:47]
	v_pk_fma_f32 v[140:141], v[140:141], v[84:85], v[124:125]
	v_pk_fma_f32 v[142:143], v[142:143], v[86:87], v[126:127]
	v_pk_fma_f32 v[144:145], v[144:145], v[88:89], v[128:129]
	v_pk_fma_f32 v[146:147], v[146:147], v[90:91], v[130:131]
	v_pk_fma_f32 v[148:149], v[148:149], v[92:93], v[132:133]
	v_pk_fma_f32 v[150:151], v[150:151], v[94:95], v[134:135]
	v_pk_fma_f32 v[152:153], v[152:153], v[96:97], v[136:137]
	v_pk_fma_f32 v[154:155], v[154:155], v[98:99], v[138:139]
	v_cvt_pk_bf16_f32 v172, v140, v141
	v_cvt_pk_bf16_f32 v173, v142, v143
	v_cvt_pk_bf16_f32 v174, v144, v145
	v_cvt_pk_bf16_f32 v175, v146, v147
	v_cvt_pk_bf16_f32 v176, v148, v149
	v_cvt_pk_bf16_f32 v177, v150, v151
	v_cvt_pk_bf16_f32 v178, v152, v153
	v_cvt_pk_bf16_f32 v179, v154, v155
	global_store_dwordx4 v109, v[172:175], s[20:21] offset:2048
	global_store_dwordx4 v109, v[176:179], s[20:21] offset:3072
	s_add_u32 s20, s20, 0x2000
	s_addc_u32 s21, s21, 0
	s_add_u32 s18, s18, 0x2000
	s_addc_u32 s19, s19, 0
	global_load_dwordx4 v[52:55], v51, s[18:19]
	global_load_dwordx4 v[56:59], v51, s[18:19] offset:1024
	global_load_dwordx4 v[60:63], v51, s[18:19] offset:2048
	global_load_dwordx4 v[64:67], v51, s[18:19] offset:3072
	global_load_dwordx4 v[68:71], v109, s[18:19]
	global_load_dwordx4 v[72:75], v109, s[18:19] offset:1024
	global_load_dwordx4 v[76:79], v109, s[18:19] offset:2048
	global_load_dwordx4 v[80:83], v109, s[18:19] offset:3072
	s_waitcnt vmcnt(16)
	v_lshlrev_b32_e32 v140, 16, v0
	v_and_b32_e32 v141, 0xffff0000, v0
	v_lshlrev_b32_e32 v142, 16, v1
	v_and_b32_e32 v143, 0xffff0000, v1
	v_lshlrev_b32_e32 v144, 16, v2
	v_and_b32_e32 v145, 0xffff0000, v2
	v_lshlrev_b32_e32 v146, 16, v3
	v_and_b32_e32 v147, 0xffff0000, v3
	v_lshlrev_b32_e32 v148, 16, v4
	v_and_b32_e32 v149, 0xffff0000, v4
	v_lshlrev_b32_e32 v150, 16, v5
	v_and_b32_e32 v151, 0xffff0000, v5
	v_lshlrev_b32_e32 v152, 16, v6
	v_and_b32_e32 v153, 0xffff0000, v6
	v_lshlrev_b32_e32 v154, 16, v7
	v_and_b32_e32 v155, 0xffff0000, v7
	v_pk_mul_f32 v[100:101], v[140:141], v[140:141]
	v_pk_fma_f32 v[100:101], v[142:143], v[142:143], v[100:101]
	v_pk_fma_f32 v[100:101], v[144:145], v[144:145], v[100:101]
	v_pk_fma_f32 v[100:101], v[146:147], v[146:147], v[100:101]
	v_pk_fma_f32 v[100:101], v[148:149], v[148:149], v[100:101]
	v_pk_fma_f32 v[100:101], v[150:151], v[150:151], v[100:101]
	v_pk_fma_f32 v[100:101], v[152:153], v[152:153], v[100:101]
	v_pk_fma_f32 v[100:101], v[154:155], v[154:155], v[100:101]
	v_lshlrev_b32_e32 v140, 16, v8
	v_and_b32_e32 v141, 0xffff0000, v8
	v_lshlrev_b32_e32 v142, 16, v9
	v_and_b32_e32 v143, 0xffff0000, v9
	v_lshlrev_b32_e32 v144, 16, v10
	v_and_b32_e32 v145, 0xffff0000, v10
	v_lshlrev_b32_e32 v146, 16, v11
	v_and_b32_e32 v147, 0xffff0000, v11
	v_lshlrev_b32_e32 v148, 16, v12
	v_and_b32_e32 v149, 0xffff0000, v12
	v_lshlrev_b32_e32 v150, 16, v13
	v_and_b32_e32 v151, 0xffff0000, v13
	v_lshlrev_b32_e32 v152, 16, v14
	v_and_b32_e32 v153, 0xffff0000, v14
	v_lshlrev_b32_e32 v154, 16, v15
	v_and_b32_e32 v155, 0xffff0000, v15
	v_pk_mul_f32 v[102:103], v[140:141], v[140:141]
	v_pk_fma_f32 v[102:103], v[142:143], v[142:143], v[102:103]
	v_pk_fma_f32 v[102:103], v[144:145], v[144:145], v[102:103]
	v_pk_fma_f32 v[102:103], v[146:147], v[146:147], v[102:103]
	v_pk_fma_f32 v[102:103], v[148:149], v[148:149], v[102:103]
	v_pk_fma_f32 v[102:103], v[150:151], v[150:151], v[102:103]
	v_pk_fma_f32 v[102:103], v[152:153], v[152:153], v[102:103]
	v_pk_fma_f32 v[102:103], v[154:155], v[154:155], v[102:103]
	v_lshlrev_b32_e32 v140, 16, v16
	v_and_b32_e32 v141, 0xffff0000, v16
	v_lshlrev_b32_e32 v142, 16, v17
	v_and_b32_e32 v143, 0xffff0000, v17
	v_lshlrev_b32_e32 v144, 16, v18
	v_and_b32_e32 v145, 0xffff0000, v18
	v_lshlrev_b32_e32 v146, 16, v19
	v_and_b32_e32 v147, 0xffff0000, v19
	v_lshlrev_b32_e32 v148, 16, v20
	v_and_b32_e32 v149, 0xffff0000, v20
	v_lshlrev_b32_e32 v150, 16, v21
	v_and_b32_e32 v151, 0xffff0000, v21
	v_lshlrev_b32_e32 v152, 16, v22
	v_and_b32_e32 v153, 0xffff0000, v22
	v_lshlrev_b32_e32 v154, 16, v23
	v_and_b32_e32 v155, 0xffff0000, v23
	v_pk_mul_f32 v[104:105], v[140:141], v[140:141]
	v_pk_fma_f32 v[104:105], v[142:143], v[142:143], v[104:105]
	v_pk_fma_f32 v[104:105], v[144:145], v[144:145], v[104:105]
	v_pk_fma_f32 v[104:105], v[146:147], v[146:147], v[104:105]
	v_pk_fma_f32 v[104:105], v[148:149], v[148:149], v[104:105]
	v_pk_fma_f32 v[104:105], v[150:151], v[150:151], v[104:105]
	v_pk_fma_f32 v[104:105], v[152:153], v[152:153], v[104:105]
	v_pk_fma_f32 v[104:105], v[154:155], v[154:155], v[104:105]
	v_lshlrev_b32_e32 v140, 16, v24
	v_and_b32_e32 v141, 0xffff0000, v24
	v_lshlrev_b32_e32 v142, 16, v25
	v_and_b32_e32 v143, 0xffff0000, v25
	v_lshlrev_b32_e32 v144, 16, v26
	v_and_b32_e32 v145, 0xffff0000, v26
	v_lshlrev_b32_e32 v146, 16, v27
	v_and_b32_e32 v147, 0xffff0000, v27
	v_lshlrev_b32_e32 v148, 16, v28
	v_and_b32_e32 v149, 0xffff0000, v28
	v_lshlrev_b32_e32 v150, 16, v29
	v_and_b32_e32 v151, 0xffff0000, v29
	v_lshlrev_b32_e32 v152, 16, v30
	v_and_b32_e32 v153, 0xffff0000, v30
	v_lshlrev_b32_e32 v154, 16, v31
	v_and_b32_e32 v155, 0xffff0000, v31
	v_pk_mul_f32 v[106:107], v[140:141], v[140:141]
	v_pk_fma_f32 v[106:107], v[142:143], v[142:143], v[106:107]
	v_pk_fma_f32 v[106:107], v[144:145], v[144:145], v[106:107]
	v_pk_fma_f32 v[106:107], v[146:147], v[146:147], v[106:107]
	v_pk_fma_f32 v[106:107], v[148:149], v[148:149], v[106:107]
	v_pk_fma_f32 v[106:107], v[150:151], v[150:151], v[106:107]
	v_pk_fma_f32 v[106:107], v[152:153], v[152:153], v[106:107]
	v_pk_fma_f32 v[106:107], v[154:155], v[154:155], v[106:107]
	v_add_f32_e32 v100, v100, v101
	v_add_f32_e32 v102, v102, v103
	v_add_f32_e32 v104, v104, v105
	v_add_f32_e32 v106, v106, v107
	s_nop 1
	v_add_f32_dpp v100, v100, v100 row_shr:1 row_mask:0xf bank_mask:0xf bound_ctrl:1
	v_add_f32_dpp v102, v102, v102 row_shr:1 row_mask:0xf bank_mask:0xf bound_ctrl:1
	v_add_f32_dpp v104, v104, v104 row_shr:1 row_mask:0xf bank_mask:0xf bound_ctrl:1
	v_add_f32_dpp v106, v106, v106 row_shr:1 row_mask:0xf bank_mask:0xf bound_ctrl:1
	v_add_f32_dpp v100, v100, v100 row_shr:2 row_mask:0xf bank_mask:0xf bound_ctrl:1
	v_add_f32_dpp v102, v102, v102 row_shr:2 row_mask:0xf bank_mask:0xf bound_ctrl:1
	v_add_f32_dpp v104, v104, v104 row_shr:2 row_mask:0xf bank_mask:0xf bound_ctrl:1
	v_add_f32_dpp v106, v106, v106 row_shr:2 row_mask:0xf bank_mask:0xf bound_ctrl:1
	v_add_f32_dpp v100, v100, v100 row_shr:4 row_mask:0xf bank_mask:0xf bound_ctrl:1
	v_add_f32_dpp v102, v102, v102 row_shr:4 row_mask:0xf bank_mask:0xf bound_ctrl:1
	v_add_f32_dpp v104, v104, v104 row_shr:4 row_mask:0xf bank_mask:0xf bound_ctrl:1
	v_add_f32_dpp v106, v106, v106 row_shr:4 row_mask:0xf bank_mask:0xf bound_ctrl:1
	v_add_f32_dpp v100, v100, v100 row_shr:8 row_mask:0xf bank_mask:0xf bound_ctrl:1
	v_add_f32_dpp v102, v102, v102 row_shr:8 row_mask:0xf bank_mask:0xf bound_ctrl:1
	v_add_f32_dpp v104, v104, v104 row_shr:8 row_mask:0xf bank_mask:0xf bound_ctrl:1
	v_add_f32_dpp v106, v106, v106 row_shr:8 row_mask:0xf bank_mask:0xf bound_ctrl:1
	v_add_f32_dpp v100, v100, v100 row_bcast:15 row_mask:0xa bank_mask:0xf
	v_add_f32_dpp v102, v102, v102 row_bcast:15 row_mask:0xa bank_mask:0xf
	v_add_f32_dpp v104, v104, v104 row_bcast:15 row_mask:0xa bank_mask:0xf
	v_add_f32_dpp v106, v106, v106 row_bcast:15 row_mask:0xa bank_mask:0xf
	v_add_f32_dpp v100, v100, v100 row_bcast:31 row_mask:0xc bank_mask:0xf
	v_add_f32_dpp v102, v102, v102 row_bcast:31 row_mask:0xc bank_mask:0xf
	v_add_f32_dpp v104, v104, v104 row_bcast:31 row_mask:0xc bank_mask:0xf
	v_add_f32_dpp v106, v106, v106 row_bcast:31 row_mask:0xc bank_mask:0xf
	s_nop 1
	v_readlane_b32 s5, v100, 63
	v_readlane_b32 s32, v102, 63
	v_readlane_b32 s54, v104, 63
	v_readlane_b32 s60, v106, 63
	s_nop 1
	v_mov_b32_e32 v156, s5
	v_mov_b32_e32 v158, s32
	v_mov_b32_e32 v160, s54
	v_mov_b32_e32 v162, s60
	v_fmaak_f32 v156, v156, v50, 0x358637bd
	v_fmaak_f32 v158, v158, v50, 0x358637bd
	v_fmaak_f32 v160, v160, v50, 0x358637bd
	v_fmaak_f32 v162, v162, v50, 0x358637bd
	v_rsq_f32_e32 v156, v156
	v_rsq_f32_e32 v158, v158
	v_rsq_f32_e32 v160, v160
	v_rsq_f32_e32 v162, v162
	s_nop 0
	v_lshlrev_b32_e32 v140, 16, v0
	v_and_b32_e32 v141, 0xffff0000, v0
	v_lshlrev_b32_e32 v142, 16, v1
	v_and_b32_e32 v143, 0xffff0000, v1
	v_lshlrev_b32_e32 v144, 16, v2
	v_and_b32_e32 v145, 0xffff0000, v2
	v_lshlrev_b32_e32 v146, 16, v3
	v_and_b32_e32 v147, 0xffff0000, v3
	v_lshlrev_b32_e32 v148, 16, v4
	v_and_b32_e32 v149, 0xffff0000, v4
	v_lshlrev_b32_e32 v150, 16, v5
	v_and_b32_e32 v151, 0xffff0000, v5
	v_lshlrev_b32_e32 v152, 16, v6
	v_and_b32_e32 v153, 0xffff0000, v6
	v_lshlrev_b32_e32 v154, 16, v7
	v_and_b32_e32 v155, 0xffff0000, v7
	v_pk_mul_f32 v[140:141], v[156:157], v[140:141] op_sel_hi:[0,1]
	v_pk_mul_f32 v[142:143], v[156:157], v[142:143] op_sel_hi:[0,1]
	v_pk_mul_f32 v[144:145], v[156:157], v[144:145] op_sel_hi:[0,1]
	v_pk_mul_f32 v[146:147], v[156:157], v[146:147] op_sel_hi:[0,1]
	v_pk_mul_f32 v[148:149], v[156:157], v[148:149] op_sel_hi:[0,1]
	v_pk_mul_f32 v[150:151], v[156:157], v[150:151] op_sel_hi:[0,1]
	v_pk_mul_f32 v[152:153], v[156:157], v[152:153] op_sel_hi:[0,1]
	v_pk_mul_f32 v[154:155], v[156:157], v[154:155] op_sel_hi:[0,1]
	v_pk_mul_f32 v[140:141], v[140:141], v[32:33]
	v_pk_mul_f32 v[142:143], v[142:143], v[34:35]
	v_pk_mul_f32 v[144:145], v[144:145], v[36:37]
	v_pk_mul_f32 v[146:147], v[146:147], v[38:39]
	v_pk_mul_f32 v[148:149], v[148:149], v[40:41]
	v_pk_mul_f32 v[150:151], v[150:151], v[42:43]
	v_pk_mul_f32 v[152:153], v[152:153], v[44:45]
	v_pk_mul_f32 v[154:155], v[154:155], v[46:47]
	v_pk_fma_f32 v[140:141], v[140:141], v[84:85], v[124:125]
	v_pk_fma_f32 v[142:143], v[142:143], v[86:87], v[126:127]
	v_pk_fma_f32 v[144:145], v[144:145], v[88:89], v[128:129]
	v_pk_fma_f32 v[146:147], v[146:147], v[90:91], v[130:131]
	v_pk_fma_f32 v[148:149], v[148:149], v[92:93], v[132:133]
	v_pk_fma_f32 v[150:151], v[150:151], v[94:95], v[134:135]
	v_pk_fma_f32 v[152:153], v[152:153], v[96:97], v[136:137]
	v_pk_fma_f32 v[154:155], v[154:155], v[98:99], v[138:139]
	v_cvt_pk_bf16_f32 v172, v140, v141
	v_cvt_pk_bf16_f32 v173, v142, v143
	v_cvt_pk_bf16_f32 v174, v144, v145
	v_cvt_pk_bf16_f32 v175, v146, v147
	v_cvt_pk_bf16_f32 v176, v148, v149
	v_cvt_pk_bf16_f32 v177, v150, v151
	v_cvt_pk_bf16_f32 v178, v152, v153
	v_cvt_pk_bf16_f32 v179, v154, v155
	global_store_dwordx4 v51, v[172:175], s[20:21]
	global_store_dwordx4 v51, v[176:179], s[20:21] offset:1024
	v_lshlrev_b32_e32 v140, 16, v8
	v_and_b32_e32 v141, 0xffff0000, v8
	v_lshlrev_b32_e32 v142, 16, v9
	v_and_b32_e32 v143, 0xffff0000, v9
	v_lshlrev_b32_e32 v144, 16, v10
	v_and_b32_e32 v145, 0xffff0000, v10
	v_lshlrev_b32_e32 v146, 16, v11
	v_and_b32_e32 v147, 0xffff0000, v11
	v_lshlrev_b32_e32 v148, 16, v12
	v_and_b32_e32 v149, 0xffff0000, v12
	v_lshlrev_b32_e32 v150, 16, v13
	v_and_b32_e32 v151, 0xffff0000, v13
	v_lshlrev_b32_e32 v152, 16, v14
	v_and_b32_e32 v153, 0xffff0000, v14
	v_lshlrev_b32_e32 v154, 16, v15
	v_and_b32_e32 v155, 0xffff0000, v15
	v_pk_mul_f32 v[140:141], v[158:159], v[140:141] op_sel_hi:[0,1]
	v_pk_mul_f32 v[142:143], v[158:159], v[142:143] op_sel_hi:[0,1]
	v_pk_mul_f32 v[144:145], v[158:159], v[144:145] op_sel_hi:[0,1]
	v_pk_mul_f32 v[146:147], v[158:159], v[146:147] op_sel_hi:[0,1]
	v_pk_mul_f32 v[148:149], v[158:159], v[148:149] op_sel_hi:[0,1]
	v_pk_mul_f32 v[150:151], v[158:159], v[150:151] op_sel_hi:[0,1]
	v_pk_mul_f32 v[152:153], v[158:159], v[152:153] op_sel_hi:[0,1]
	v_pk_mul_f32 v[154:155], v[158:159], v[154:155] op_sel_hi:[0,1]
	v_pk_mul_f32 v[140:141], v[140:141], v[32:33]
	v_pk_mul_f32 v[142:143], v[142:143], v[34:35]
	v_pk_mul_f32 v[144:145], v[144:145], v[36:37]
	v_pk_mul_f32 v[146:147], v[146:147], v[38:39]
	v_pk_mul_f32 v[148:149], v[148:149], v[40:41]
	v_pk_mul_f32 v[150:151], v[150:151], v[42:43]
	v_pk_mul_f32 v[152:153], v[152:153], v[44:45]
	v_pk_mul_f32 v[154:155], v[154:155], v[46:47]
	v_pk_fma_f32 v[140:141], v[140:141], v[84:85], v[124:125]
	v_pk_fma_f32 v[142:143], v[142:143], v[86:87], v[126:127]
	v_pk_fma_f32 v[144:145], v[144:145], v[88:89], v[128:129]
	v_pk_fma_f32 v[146:147], v[146:147], v[90:91], v[130:131]
	v_pk_fma_f32 v[148:149], v[148:149], v[92:93], v[132:133]
	v_pk_fma_f32 v[150:151], v[150:151], v[94:95], v[134:135]
	v_pk_fma_f32 v[152:153], v[152:153], v[96:97], v[136:137]
	v_pk_fma_f32 v[154:155], v[154:155], v[98:99], v[138:139]
	v_cvt_pk_bf16_f32 v164, v140, v141
	v_cvt_pk_bf16_f32 v165, v142, v143
	v_cvt_pk_bf16_f32 v166, v144, v145
	v_cvt_pk_bf16_f32 v167, v146, v147
	v_cvt_pk_bf16_f32 v168, v148, v149
	v_cvt_pk_bf16_f32 v169, v150, v151
	v_cvt_pk_bf16_f32 v170, v152, v153
	v_cvt_pk_bf16_f32 v171, v154, v155
	global_store_dwordx4 v51, v[164:167], s[20:21] offset:2048
	global_store_dwordx4 v51, v[168:171], s[20:21] offset:3072
	v_lshlrev_b32_e32 v140, 16, v16
	v_and_b32_e32 v141, 0xffff0000, v16
	v_lshlrev_b32_e32 v142, 16, v17
	v_and_b32_e32 v143, 0xffff0000, v17
	v_lshlrev_b32_e32 v144, 16, v18
	v_and_b32_e32 v145, 0xffff0000, v18
	v_lshlrev_b32_e32 v146, 16, v19
	v_and_b32_e32 v147, 0xffff0000, v19
	v_lshlrev_b32_e32 v148, 16, v20
	v_and_b32_e32 v149, 0xffff0000, v20
	v_lshlrev_b32_e32 v150, 16, v21
	v_and_b32_e32 v151, 0xffff0000, v21
	v_lshlrev_b32_e32 v152, 16, v22
	v_and_b32_e32 v153, 0xffff0000, v22
	v_lshlrev_b32_e32 v154, 16, v23
	v_and_b32_e32 v155, 0xffff0000, v23
	v_pk_mul_f32 v[140:141], v[160:161], v[140:141] op_sel_hi:[0,1]
	v_pk_mul_f32 v[142:143], v[160:161], v[142:143] op_sel_hi:[0,1]
	v_pk_mul_f32 v[144:145], v[160:161], v[144:145] op_sel_hi:[0,1]
	v_pk_mul_f32 v[146:147], v[160:161], v[146:147] op_sel_hi:[0,1]
	v_pk_mul_f32 v[148:149], v[160:161], v[148:149] op_sel_hi:[0,1]
	v_pk_mul_f32 v[150:151], v[160:161], v[150:151] op_sel_hi:[0,1]
	v_pk_mul_f32 v[152:153], v[160:161], v[152:153] op_sel_hi:[0,1]
	v_pk_mul_f32 v[154:155], v[160:161], v[154:155] op_sel_hi:[0,1]
	v_pk_mul_f32 v[140:141], v[140:141], v[32:33]
	v_pk_mul_f32 v[142:143], v[142:143], v[34:35]
	v_pk_mul_f32 v[144:145], v[144:145], v[36:37]
	v_pk_mul_f32 v[146:147], v[146:147], v[38:39]
	v_pk_mul_f32 v[148:149], v[148:149], v[40:41]
	v_pk_mul_f32 v[150:151], v[150:151], v[42:43]
	v_pk_mul_f32 v[152:153], v[152:153], v[44:45]
	v_pk_mul_f32 v[154:155], v[154:155], v[46:47]
	v_pk_fma_f32 v[140:141], v[140:141], v[84:85], v[124:125]
	v_pk_fma_f32 v[142:143], v[142:143], v[86:87], v[126:127]
	v_pk_fma_f32 v[144:145], v[144:145], v[88:89], v[128:129]
	v_pk_fma_f32 v[146:147], v[146:147], v[90:91], v[130:131]
	v_pk_fma_f32 v[148:149], v[148:149], v[92:93], v[132:133]
	v_pk_fma_f32 v[150:151], v[150:151], v[94:95], v[134:135]
	v_pk_fma_f32 v[152:153], v[152:153], v[96:97], v[136:137]
	v_pk_fma_f32 v[154:155], v[154:155], v[98:99], v[138:139]
	v_cvt_pk_bf16_f32 v172, v140, v141
	v_cvt_pk_bf16_f32 v173, v142, v143
	v_cvt_pk_bf16_f32 v174, v144, v145
	v_cvt_pk_bf16_f32 v175, v146, v147
	v_cvt_pk_bf16_f32 v176, v148, v149
	v_cvt_pk_bf16_f32 v177, v150, v151
	v_cvt_pk_bf16_f32 v178, v152, v153
	v_cvt_pk_bf16_f32 v179, v154, v155
	global_store_dwordx4 v109, v[172:175], s[20:21]
	global_store_dwordx4 v109, v[176:179], s[20:21] offset:1024
	v_lshlrev_b32_e32 v140, 16, v24
	v_and_b32_e32 v141, 0xffff0000, v24
	v_lshlrev_b32_e32 v142, 16, v25
	v_and_b32_e32 v143, 0xffff0000, v25
	v_lshlrev_b32_e32 v144, 16, v26
	v_and_b32_e32 v145, 0xffff0000, v26
	v_lshlrev_b32_e32 v146, 16, v27
	v_and_b32_e32 v147, 0xffff0000, v27
	v_lshlrev_b32_e32 v148, 16, v28
	v_and_b32_e32 v149, 0xffff0000, v28
	v_lshlrev_b32_e32 v150, 16, v29
	v_and_b32_e32 v151, 0xffff0000, v29
	v_lshlrev_b32_e32 v152, 16, v30
	v_and_b32_e32 v153, 0xffff0000, v30
	v_lshlrev_b32_e32 v154, 16, v31
	v_and_b32_e32 v155, 0xffff0000, v31
	v_pk_mul_f32 v[140:141], v[162:163], v[140:141] op_sel_hi:[0,1]
	v_pk_mul_f32 v[142:143], v[162:163], v[142:143] op_sel_hi:[0,1]
	v_pk_mul_f32 v[144:145], v[162:163], v[144:145] op_sel_hi:[0,1]
	v_pk_mul_f32 v[146:147], v[162:163], v[146:147] op_sel_hi:[0,1]
	v_pk_mul_f32 v[148:149], v[162:163], v[148:149] op_sel_hi:[0,1]
	v_pk_mul_f32 v[150:151], v[162:163], v[150:151] op_sel_hi:[0,1]
	v_pk_mul_f32 v[152:153], v[162:163], v[152:153] op_sel_hi:[0,1]
	v_pk_mul_f32 v[154:155], v[162:163], v[154:155] op_sel_hi:[0,1]
	v_pk_mul_f32 v[140:141], v[140:141], v[32:33]
	v_pk_mul_f32 v[142:143], v[142:143], v[34:35]
	v_pk_mul_f32 v[144:145], v[144:145], v[36:37]
	v_pk_mul_f32 v[146:147], v[146:147], v[38:39]
	v_pk_mul_f32 v[148:149], v[148:149], v[40:41]
	v_pk_mul_f32 v[150:151], v[150:151], v[42:43]
	v_pk_mul_f32 v[152:153], v[152:153], v[44:45]
	v_pk_mul_f32 v[154:155], v[154:155], v[46:47]
	v_pk_fma_f32 v[140:141], v[140:141], v[84:85], v[124:125]
	v_pk_fma_f32 v[142:143], v[142:143], v[86:87], v[126:127]
	v_pk_fma_f32 v[144:145], v[144:145], v[88:89], v[128:129]
	v_pk_fma_f32 v[146:147], v[146:147], v[90:91], v[130:131]
	v_pk_fma_f32 v[148:149], v[148:149], v[92:93], v[132:133]
	v_pk_fma_f32 v[150:151], v[150:151], v[94:95], v[134:135]
	v_pk_fma_f32 v[152:153], v[152:153], v[96:97], v[136:137]
	v_pk_fma_f32 v[154:155], v[154:155], v[98:99], v[138:139]
	v_cvt_pk_bf16_f32 v164, v140, v141
	v_cvt_pk_bf16_f32 v165, v142, v143
	v_cvt_pk_bf16_f32 v166, v144, v145
	v_cvt_pk_bf16_f32 v167, v146, v147
	v_cvt_pk_bf16_f32 v168, v148, v149
	v_cvt_pk_bf16_f32 v169, v150, v151
	v_cvt_pk_bf16_f32 v170, v152, v153
	v_cvt_pk_bf16_f32 v171, v154, v155
	global_store_dwordx4 v109, v[164:167], s[20:21] offset:2048
	global_store_dwordx4 v109, v[168:171], s[20:21] offset:3072
	s_add_u32 s20, s20, 0x2000
	s_addc_u32 s21, s21, 0
	s_add_u32 s18, s18, 0x2000
	s_addc_u32 s19, s19, 0
	global_load_dwordx4 v[0:3], v51, s[18:19]
	global_load_dwordx4 v[4:7], v51, s[18:19] offset:1024
	global_load_dwordx4 v[8:11], v51, s[18:19] offset:2048
	global_load_dwordx4 v[12:15], v51, s[18:19] offset:3072
	global_load_dwordx4 v[16:19], v109, s[18:19]
	global_load_dwordx4 v[20:23], v109, s[18:19] offset:1024
	global_load_dwordx4 v[24:27], v109, s[18:19] offset:2048
	global_load_dwordx4 v[28:31], v109, s[18:19] offset:3072
	s_waitcnt vmcnt(16)
	v_lshlrev_b32_e32 v140, 16, v52
	v_and_b32_e32 v141, 0xffff0000, v52
	v_lshlrev_b32_e32 v142, 16, v53
	v_and_b32_e32 v143, 0xffff0000, v53
	v_lshlrev_b32_e32 v144, 16, v54
	v_and_b32_e32 v145, 0xffff0000, v54
	v_lshlrev_b32_e32 v146, 16, v55
	v_and_b32_e32 v147, 0xffff0000, v55
	v_lshlrev_b32_e32 v148, 16, v56
	v_and_b32_e32 v149, 0xffff0000, v56
	v_lshlrev_b32_e32 v150, 16, v57
	v_and_b32_e32 v151, 0xffff0000, v57
	v_lshlrev_b32_e32 v152, 16, v58
	v_and_b32_e32 v153, 0xffff0000, v58
	v_lshlrev_b32_e32 v154, 16, v59
	v_and_b32_e32 v155, 0xffff0000, v59
	v_pk_mul_f32 v[100:101], v[140:141], v[140:141]
	v_pk_fma_f32 v[100:101], v[142:143], v[142:143], v[100:101]
	v_pk_fma_f32 v[100:101], v[144:145], v[144:145], v[100:101]
	v_pk_fma_f32 v[100:101], v[146:147], v[146:147], v[100:101]
	v_pk_fma_f32 v[100:101], v[148:149], v[148:149], v[100:101]
	v_pk_fma_f32 v[100:101], v[150:151], v[150:151], v[100:101]
	v_pk_fma_f32 v[100:101], v[152:153], v[152:153], v[100:101]
	v_pk_fma_f32 v[100:101], v[154:155], v[154:155], v[100:101]
	v_lshlrev_b32_e32 v140, 16, v60
	v_and_b32_e32 v141, 0xffff0000, v60
	v_lshlrev_b32_e32 v142, 16, v61
	v_and_b32_e32 v143, 0xffff0000, v61
	v_lshlrev_b32_e32 v144, 16, v62
	v_and_b32_e32 v145, 0xffff0000, v62
	v_lshlrev_b32_e32 v146, 16, v63
	v_and_b32_e32 v147, 0xffff0000, v63
	v_lshlrev_b32_e32 v148, 16, v64
	v_and_b32_e32 v149, 0xffff0000, v64
	v_lshlrev_b32_e32 v150, 16, v65
	v_and_b32_e32 v151, 0xffff0000, v65
	v_lshlrev_b32_e32 v152, 16, v66
	v_and_b32_e32 v153, 0xffff0000, v66
	v_lshlrev_b32_e32 v154, 16, v67
	v_and_b32_e32 v155, 0xffff0000, v67
	v_pk_mul_f32 v[102:103], v[140:141], v[140:141]
	v_pk_fma_f32 v[102:103], v[142:143], v[142:143], v[102:103]
	v_pk_fma_f32 v[102:103], v[144:145], v[144:145], v[102:103]
	v_pk_fma_f32 v[102:103], v[146:147], v[146:147], v[102:103]
	v_pk_fma_f32 v[102:103], v[148:149], v[148:149], v[102:103]
	v_pk_fma_f32 v[102:103], v[150:151], v[150:151], v[102:103]
	v_pk_fma_f32 v[102:103], v[152:153], v[152:153], v[102:103]
	v_pk_fma_f32 v[102:103], v[154:155], v[154:155], v[102:103]
	v_lshlrev_b32_e32 v140, 16, v68
	v_and_b32_e32 v141, 0xffff0000, v68
	v_lshlrev_b32_e32 v142, 16, v69
	v_and_b32_e32 v143, 0xffff0000, v69
	v_lshlrev_b32_e32 v144, 16, v70
	v_and_b32_e32 v145, 0xffff0000, v70
	v_lshlrev_b32_e32 v146, 16, v71
	v_and_b32_e32 v147, 0xffff0000, v71
	v_lshlrev_b32_e32 v148, 16, v72
	v_and_b32_e32 v149, 0xffff0000, v72
	v_lshlrev_b32_e32 v150, 16, v73
	v_and_b32_e32 v151, 0xffff0000, v73
	v_lshlrev_b32_e32 v152, 16, v74
	v_and_b32_e32 v153, 0xffff0000, v74
	v_lshlrev_b32_e32 v154, 16, v75
	v_and_b32_e32 v155, 0xffff0000, v75
	v_pk_mul_f32 v[104:105], v[140:141], v[140:141]
	v_pk_fma_f32 v[104:105], v[142:143], v[142:143], v[104:105]
	v_pk_fma_f32 v[104:105], v[144:145], v[144:145], v[104:105]
	v_pk_fma_f32 v[104:105], v[146:147], v[146:147], v[104:105]
	v_pk_fma_f32 v[104:105], v[148:149], v[148:149], v[104:105]
	v_pk_fma_f32 v[104:105], v[150:151], v[150:151], v[104:105]
	v_pk_fma_f32 v[104:105], v[152:153], v[152:153], v[104:105]
	v_pk_fma_f32 v[104:105], v[154:155], v[154:155], v[104:105]
	v_lshlrev_b32_e32 v140, 16, v76
	v_and_b32_e32 v141, 0xffff0000, v76
	v_lshlrev_b32_e32 v142, 16, v77
	v_and_b32_e32 v143, 0xffff0000, v77
	v_lshlrev_b32_e32 v144, 16, v78
	v_and_b32_e32 v145, 0xffff0000, v78
	v_lshlrev_b32_e32 v146, 16, v79
	v_and_b32_e32 v147, 0xffff0000, v79
	v_lshlrev_b32_e32 v148, 16, v80
	v_and_b32_e32 v149, 0xffff0000, v80
	v_lshlrev_b32_e32 v150, 16, v81
	v_and_b32_e32 v151, 0xffff0000, v81
	v_lshlrev_b32_e32 v152, 16, v82
	v_and_b32_e32 v153, 0xffff0000, v82
	v_lshlrev_b32_e32 v154, 16, v83
	v_and_b32_e32 v155, 0xffff0000, v83
	v_pk_mul_f32 v[106:107], v[140:141], v[140:141]
	v_pk_fma_f32 v[106:107], v[142:143], v[142:143], v[106:107]
	v_pk_fma_f32 v[106:107], v[144:145], v[144:145], v[106:107]
	v_pk_fma_f32 v[106:107], v[146:147], v[146:147], v[106:107]
	v_pk_fma_f32 v[106:107], v[148:149], v[148:149], v[106:107]
	v_pk_fma_f32 v[106:107], v[150:151], v[150:151], v[106:107]
	v_pk_fma_f32 v[106:107], v[152:153], v[152:153], v[106:107]
	v_pk_fma_f32 v[106:107], v[154:155], v[154:155], v[106:107]
	v_add_f32_e32 v100, v100, v101
	v_add_f32_e32 v102, v102, v103
	v_add_f32_e32 v104, v104, v105
	v_add_f32_e32 v106, v106, v107
	s_nop 1
	v_add_f32_dpp v100, v100, v100 row_shr:1 row_mask:0xf bank_mask:0xf bound_ctrl:1
	v_add_f32_dpp v102, v102, v102 row_shr:1 row_mask:0xf bank_mask:0xf bound_ctrl:1
	v_add_f32_dpp v104, v104, v104 row_shr:1 row_mask:0xf bank_mask:0xf bound_ctrl:1
	v_add_f32_dpp v106, v106, v106 row_shr:1 row_mask:0xf bank_mask:0xf bound_ctrl:1
	v_add_f32_dpp v100, v100, v100 row_shr:2 row_mask:0xf bank_mask:0xf bound_ctrl:1
	v_add_f32_dpp v102, v102, v102 row_shr:2 row_mask:0xf bank_mask:0xf bound_ctrl:1
	v_add_f32_dpp v104, v104, v104 row_shr:2 row_mask:0xf bank_mask:0xf bound_ctrl:1
	v_add_f32_dpp v106, v106, v106 row_shr:2 row_mask:0xf bank_mask:0xf bound_ctrl:1
	v_add_f32_dpp v100, v100, v100 row_shr:4 row_mask:0xf bank_mask:0xf bound_ctrl:1
	v_add_f32_dpp v102, v102, v102 row_shr:4 row_mask:0xf bank_mask:0xf bound_ctrl:1
	v_add_f32_dpp v104, v104, v104 row_shr:4 row_mask:0xf bank_mask:0xf bound_ctrl:1
	v_add_f32_dpp v106, v106, v106 row_shr:4 row_mask:0xf bank_mask:0xf bound_ctrl:1
	v_add_f32_dpp v100, v100, v100 row_shr:8 row_mask:0xf bank_mask:0xf bound_ctrl:1
	v_add_f32_dpp v102, v102, v102 row_shr:8 row_mask:0xf bank_mask:0xf bound_ctrl:1
	v_add_f32_dpp v104, v104, v104 row_shr:8 row_mask:0xf bank_mask:0xf bound_ctrl:1
	v_add_f32_dpp v106, v106, v106 row_shr:8 row_mask:0xf bank_mask:0xf bound_ctrl:1
	v_add_f32_dpp v100, v100, v100 row_bcast:15 row_mask:0xa bank_mask:0xf
	v_add_f32_dpp v102, v102, v102 row_bcast:15 row_mask:0xa bank_mask:0xf
	v_add_f32_dpp v104, v104, v104 row_bcast:15 row_mask:0xa bank_mask:0xf
	v_add_f32_dpp v106, v106, v106 row_bcast:15 row_mask:0xa bank_mask:0xf
	v_add_f32_dpp v100, v100, v100 row_bcast:31 row_mask:0xc bank_mask:0xf
	v_add_f32_dpp v102, v102, v102 row_bcast:31 row_mask:0xc bank_mask:0xf
	v_add_f32_dpp v104, v104, v104 row_bcast:31 row_mask:0xc bank_mask:0xf
	v_add_f32_dpp v106, v106, v106 row_bcast:31 row_mask:0xc bank_mask:0xf
	s_nop 1
	v_readlane_b32 s5, v100, 63
	v_readlane_b32 s32, v102, 63
	v_readlane_b32 s54, v104, 63
	v_readlane_b32 s60, v106, 63
	s_nop 1
	v_mov_b32_e32 v156, s5
	v_mov_b32_e32 v158, s32
	v_mov_b32_e32 v160, s54
	v_mov_b32_e32 v162, s60
	v_fmaak_f32 v156, v156, v50, 0x358637bd
	v_fmaak_f32 v158, v158, v50, 0x358637bd
	v_fmaak_f32 v160, v160, v50, 0x358637bd
	v_fmaak_f32 v162, v162, v50, 0x358637bd
	v_rsq_f32_e32 v156, v156
	v_rsq_f32_e32 v158, v158
	v_rsq_f32_e32 v160, v160
	v_rsq_f32_e32 v162, v162
	s_nop 0
	v_lshlrev_b32_e32 v140, 16, v52
	v_and_b32_e32 v141, 0xffff0000, v52
	v_lshlrev_b32_e32 v142, 16, v53
	v_and_b32_e32 v143, 0xffff0000, v53
	v_lshlrev_b32_e32 v144, 16, v54
	v_and_b32_e32 v145, 0xffff0000, v54
	v_lshlrev_b32_e32 v146, 16, v55
	v_and_b32_e32 v147, 0xffff0000, v55
	v_lshlrev_b32_e32 v148, 16, v56
	v_and_b32_e32 v149, 0xffff0000, v56
	v_lshlrev_b32_e32 v150, 16, v57
	v_and_b32_e32 v151, 0xffff0000, v57
	v_lshlrev_b32_e32 v152, 16, v58
	v_and_b32_e32 v153, 0xffff0000, v58
	v_lshlrev_b32_e32 v154, 16, v59
	v_and_b32_e32 v155, 0xffff0000, v59
	v_pk_mul_f32 v[140:141], v[156:157], v[140:141] op_sel_hi:[0,1]
	v_pk_mul_f32 v[142:143], v[156:157], v[142:143] op_sel_hi:[0,1]
	v_pk_mul_f32 v[144:145], v[156:157], v[144:145] op_sel_hi:[0,1]
	v_pk_mul_f32 v[146:147], v[156:157], v[146:147] op_sel_hi:[0,1]
	v_pk_mul_f32 v[148:149], v[156:157], v[148:149] op_sel_hi:[0,1]
	v_pk_mul_f32 v[150:151], v[156:157], v[150:151] op_sel_hi:[0,1]
	v_pk_mul_f32 v[152:153], v[156:157], v[152:153] op_sel_hi:[0,1]
	v_pk_mul_f32 v[154:155], v[156:157], v[154:155] op_sel_hi:[0,1]
	v_pk_mul_f32 v[140:141], v[140:141], v[32:33]
	v_pk_mul_f32 v[142:143], v[142:143], v[34:35]
	v_pk_mul_f32 v[144:145], v[144:145], v[36:37]
	v_pk_mul_f32 v[146:147], v[146:147], v[38:39]
	v_pk_mul_f32 v[148:149], v[148:149], v[40:41]
	v_pk_mul_f32 v[150:151], v[150:151], v[42:43]
	v_pk_mul_f32 v[152:153], v[152:153], v[44:45]
	v_pk_mul_f32 v[154:155], v[154:155], v[46:47]
	v_pk_fma_f32 v[140:141], v[140:141], v[84:85], v[124:125]
	v_pk_fma_f32 v[142:143], v[142:143], v[86:87], v[126:127]
	v_pk_fma_f32 v[144:145], v[144:145], v[88:89], v[128:129]
	v_pk_fma_f32 v[146:147], v[146:147], v[90:91], v[130:131]
	v_pk_fma_f32 v[148:149], v[148:149], v[92:93], v[132:133]
	v_pk_fma_f32 v[150:151], v[150:151], v[94:95], v[134:135]
	v_pk_fma_f32 v[152:153], v[152:153], v[96:97], v[136:137]
	v_pk_fma_f32 v[154:155], v[154:155], v[98:99], v[138:139]
	v_cvt_pk_bf16_f32 v164, v140, v141
	v_cvt_pk_bf16_f32 v165, v142, v143
	v_cvt_pk_bf16_f32 v166, v144, v145
	v_cvt_pk_bf16_f32 v167, v146, v147
	v_cvt_pk_bf16_f32 v168, v148, v149
	v_cvt_pk_bf16_f32 v169, v150, v151
	v_cvt_pk_bf16_f32 v170, v152, v153
	v_cvt_pk_bf16_f32 v171, v154, v155
	global_store_dwordx4 v51, v[164:167], s[20:21]
	global_store_dwordx4 v51, v[168:171], s[20:21] offset:1024
	v_lshlrev_b32_e32 v140, 16, v60
	v_and_b32_e32 v141, 0xffff0000, v60
	v_lshlrev_b32_e32 v142, 16, v61
	v_and_b32_e32 v143, 0xffff0000, v61
	v_lshlrev_b32_e32 v144, 16, v62
	v_and_b32_e32 v145, 0xffff0000, v62
	v_lshlrev_b32_e32 v146, 16, v63
	v_and_b32_e32 v147, 0xffff0000, v63
	v_lshlrev_b32_e32 v148, 16, v64
	v_and_b32_e32 v149, 0xffff0000, v64
	v_lshlrev_b32_e32 v150, 16, v65
	v_and_b32_e32 v151, 0xffff0000, v65
	v_lshlrev_b32_e32 v152, 16, v66
	v_and_b32_e32 v153, 0xffff0000, v66
	v_lshlrev_b32_e32 v154, 16, v67
	v_and_b32_e32 v155, 0xffff0000, v67
	v_pk_mul_f32 v[140:141], v[158:159], v[140:141] op_sel_hi:[0,1]
	v_pk_mul_f32 v[142:143], v[158:159], v[142:143] op_sel_hi:[0,1]
	v_pk_mul_f32 v[144:145], v[158:159], v[144:145] op_sel_hi:[0,1]
	v_pk_mul_f32 v[146:147], v[158:159], v[146:147] op_sel_hi:[0,1]
	v_pk_mul_f32 v[148:149], v[158:159], v[148:149] op_sel_hi:[0,1]
	v_pk_mul_f32 v[150:151], v[158:159], v[150:151] op_sel_hi:[0,1]
	v_pk_mul_f32 v[152:153], v[158:159], v[152:153] op_sel_hi:[0,1]
	v_pk_mul_f32 v[154:155], v[158:159], v[154:155] op_sel_hi:[0,1]
	v_pk_mul_f32 v[140:141], v[140:141], v[32:33]
	v_pk_mul_f32 v[142:143], v[142:143], v[34:35]
	v_pk_mul_f32 v[144:145], v[144:145], v[36:37]
	v_pk_mul_f32 v[146:147], v[146:147], v[38:39]
	v_pk_mul_f32 v[148:149], v[148:149], v[40:41]
	v_pk_mul_f32 v[150:151], v[150:151], v[42:43]
	v_pk_mul_f32 v[152:153], v[152:153], v[44:45]
	v_pk_mul_f32 v[154:155], v[154:155], v[46:47]
	v_pk_fma_f32 v[140:141], v[140:141], v[84:85], v[124:125]
	v_pk_fma_f32 v[142:143], v[142:143], v[86:87], v[126:127]
	v_pk_fma_f32 v[144:145], v[144:145], v[88:89], v[128:129]
	v_pk_fma_f32 v[146:147], v[146:147], v[90:91], v[130:131]
	v_pk_fma_f32 v[148:149], v[148:149], v[92:93], v[132:133]
	v_pk_fma_f32 v[150:151], v[150:151], v[94:95], v[134:135]
	v_pk_fma_f32 v[152:153], v[152:153], v[96:97], v[136:137]
	v_pk_fma_f32 v[154:155], v[154:155], v[98:99], v[138:139]
	v_cvt_pk_bf16_f32 v172, v140, v141
	v_cvt_pk_bf16_f32 v173, v142, v143
	v_cvt_pk_bf16_f32 v174, v144, v145
	v_cvt_pk_bf16_f32 v175, v146, v147
	v_cvt_pk_bf16_f32 v176, v148, v149
	v_cvt_pk_bf16_f32 v177, v150, v151
	v_cvt_pk_bf16_f32 v178, v152, v153
	v_cvt_pk_bf16_f32 v179, v154, v155
	global_store_dwordx4 v51, v[172:175], s[20:21] offset:2048
	global_store_dwordx4 v51, v[176:179], s[20:21] offset:3072
	v_lshlrev_b32_e32 v140, 16, v68
	v_and_b32_e32 v141, 0xffff0000, v68
	v_lshlrev_b32_e32 v142, 16, v69
	v_and_b32_e32 v143, 0xffff0000, v69
	v_lshlrev_b32_e32 v144, 16, v70
	v_and_b32_e32 v145, 0xffff0000, v70
	v_lshlrev_b32_e32 v146, 16, v71
	v_and_b32_e32 v147, 0xffff0000, v71
	v_lshlrev_b32_e32 v148, 16, v72
	v_and_b32_e32 v149, 0xffff0000, v72
	v_lshlrev_b32_e32 v150, 16, v73
	v_and_b32_e32 v151, 0xffff0000, v73
	v_lshlrev_b32_e32 v152, 16, v74
	v_and_b32_e32 v153, 0xffff0000, v74
	v_lshlrev_b32_e32 v154, 16, v75
	v_and_b32_e32 v155, 0xffff0000, v75
	v_pk_mul_f32 v[140:141], v[160:161], v[140:141] op_sel_hi:[0,1]
	v_pk_mul_f32 v[142:143], v[160:161], v[142:143] op_sel_hi:[0,1]
	v_pk_mul_f32 v[144:145], v[160:161], v[144:145] op_sel_hi:[0,1]
	v_pk_mul_f32 v[146:147], v[160:161], v[146:147] op_sel_hi:[0,1]
	v_pk_mul_f32 v[148:149], v[160:161], v[148:149] op_sel_hi:[0,1]
	v_pk_mul_f32 v[150:151], v[160:161], v[150:151] op_sel_hi:[0,1]
	v_pk_mul_f32 v[152:153], v[160:161], v[152:153] op_sel_hi:[0,1]
	v_pk_mul_f32 v[154:155], v[160:161], v[154:155] op_sel_hi:[0,1]
	v_pk_mul_f32 v[140:141], v[140:141], v[32:33]
	v_pk_mul_f32 v[142:143], v[142:143], v[34:35]
	v_pk_mul_f32 v[144:145], v[144:145], v[36:37]
	v_pk_mul_f32 v[146:147], v[146:147], v[38:39]
	v_pk_mul_f32 v[148:149], v[148:149], v[40:41]
	v_pk_mul_f32 v[150:151], v[150:151], v[42:43]
	v_pk_mul_f32 v[152:153], v[152:153], v[44:45]
	v_pk_mul_f32 v[154:155], v[154:155], v[46:47]
	v_pk_fma_f32 v[140:141], v[140:141], v[84:85], v[124:125]
	v_pk_fma_f32 v[142:143], v[142:143], v[86:87], v[126:127]
	v_pk_fma_f32 v[144:145], v[144:145], v[88:89], v[128:129]
	v_pk_fma_f32 v[146:147], v[146:147], v[90:91], v[130:131]
	v_pk_fma_f32 v[148:149], v[148:149], v[92:93], v[132:133]
	v_pk_fma_f32 v[150:151], v[150:151], v[94:95], v[134:135]
	v_pk_fma_f32 v[152:153], v[152:153], v[96:97], v[136:137]
	v_pk_fma_f32 v[154:155], v[154:155], v[98:99], v[138:139]
	v_cvt_pk_bf16_f32 v164, v140, v141
	v_cvt_pk_bf16_f32 v165, v142, v143
	v_cvt_pk_bf16_f32 v166, v144, v145
	v_cvt_pk_bf16_f32 v167, v146, v147
	v_cvt_pk_bf16_f32 v168, v148, v149
	v_cvt_pk_bf16_f32 v169, v150, v151
	v_cvt_pk_bf16_f32 v170, v152, v153
	v_cvt_pk_bf16_f32 v171, v154, v155
	global_store_dwordx4 v109, v[164:167], s[20:21]
	global_store_dwordx4 v109, v[168:171], s[20:21] offset:1024
	v_lshlrev_b32_e32 v140, 16, v76
	v_and_b32_e32 v141, 0xffff0000, v76
	v_lshlrev_b32_e32 v142, 16, v77
	v_and_b32_e32 v143, 0xffff0000, v77
	v_lshlrev_b32_e32 v144, 16, v78
	v_and_b32_e32 v145, 0xffff0000, v78
	v_lshlrev_b32_e32 v146, 16, v79
	v_and_b32_e32 v147, 0xffff0000, v79
	v_lshlrev_b32_e32 v148, 16, v80
	v_and_b32_e32 v149, 0xffff0000, v80
	v_lshlrev_b32_e32 v150, 16, v81
	v_and_b32_e32 v151, 0xffff0000, v81
	v_lshlrev_b32_e32 v152, 16, v82
	v_and_b32_e32 v153, 0xffff0000, v82
	v_lshlrev_b32_e32 v154, 16, v83
	v_and_b32_e32 v155, 0xffff0000, v83
	v_pk_mul_f32 v[140:141], v[162:163], v[140:141] op_sel_hi:[0,1]
	v_pk_mul_f32 v[142:143], v[162:163], v[142:143] op_sel_hi:[0,1]
	v_pk_mul_f32 v[144:145], v[162:163], v[144:145] op_sel_hi:[0,1]
	v_pk_mul_f32 v[146:147], v[162:163], v[146:147] op_sel_hi:[0,1]
	v_pk_mul_f32 v[148:149], v[162:163], v[148:149] op_sel_hi:[0,1]
	v_pk_mul_f32 v[150:151], v[162:163], v[150:151] op_sel_hi:[0,1]
	v_pk_mul_f32 v[152:153], v[162:163], v[152:153] op_sel_hi:[0,1]
	v_pk_mul_f32 v[154:155], v[162:163], v[154:155] op_sel_hi:[0,1]
	v_pk_mul_f32 v[140:141], v[140:141], v[32:33]
	v_pk_mul_f32 v[142:143], v[142:143], v[34:35]
	v_pk_mul_f32 v[144:145], v[144:145], v[36:37]
	v_pk_mul_f32 v[146:147], v[146:147], v[38:39]
	v_pk_mul_f32 v[148:149], v[148:149], v[40:41]
	v_pk_mul_f32 v[150:151], v[150:151], v[42:43]
	v_pk_mul_f32 v[152:153], v[152:153], v[44:45]
	v_pk_mul_f32 v[154:155], v[154:155], v[46:47]
	v_pk_fma_f32 v[140:141], v[140:141], v[84:85], v[124:125]
	v_pk_fma_f32 v[142:143], v[142:143], v[86:87], v[126:127]
	v_pk_fma_f32 v[144:145], v[144:145], v[88:89], v[128:129]
	v_pk_fma_f32 v[146:147], v[146:147], v[90:91], v[130:131]
	v_pk_fma_f32 v[148:149], v[148:149], v[92:93], v[132:133]
	v_pk_fma_f32 v[150:151], v[150:151], v[94:95], v[134:135]
	v_pk_fma_f32 v[152:153], v[152:153], v[96:97], v[136:137]
	v_pk_fma_f32 v[154:155], v[154:155], v[98:99], v[138:139]
	v_cvt_pk_bf16_f32 v172, v140, v141
	v_cvt_pk_bf16_f32 v173, v142, v143
	v_cvt_pk_bf16_f32 v174, v144, v145
	v_cvt_pk_bf16_f32 v175, v146, v147
	v_cvt_pk_bf16_f32 v176, v148, v149
	v_cvt_pk_bf16_f32 v177, v150, v151
	v_cvt_pk_bf16_f32 v178, v152, v153
	v_cvt_pk_bf16_f32 v179, v154, v155
	global_store_dwordx4 v109, v[172:175], s[20:21] offset:2048
	global_store_dwordx4 v109, v[176:179], s[20:21] offset:3072
	s_add_u32 s20, s20, 0x2000
	s_addc_u32 s21, s21, 0
	s_add_u32 s18, s18, 0x2000
	s_addc_u32 s19, s19, 0
	global_load_dwordx4 v[52:55], v51, s[18:19]
	global_load_dwordx4 v[56:59], v51, s[18:19] offset:1024
	global_load_dwordx4 v[60:63], v51, s[18:19] offset:2048
	global_load_dwordx4 v[64:67], v51, s[18:19] offset:3072
	global_load_dwordx4 v[68:71], v109, s[18:19]
	global_load_dwordx4 v[72:75], v109, s[18:19] offset:1024
	global_load_dwordx4 v[76:79], v109, s[18:19] offset:2048
	global_load_dwordx4 v[80:83], v109, s[18:19] offset:3072
	s_waitcnt vmcnt(16)
	v_lshlrev_b32_e32 v140, 16, v0
	v_and_b32_e32 v141, 0xffff0000, v0
	v_lshlrev_b32_e32 v142, 16, v1
	v_and_b32_e32 v143, 0xffff0000, v1
	v_lshlrev_b32_e32 v144, 16, v2
	v_and_b32_e32 v145, 0xffff0000, v2
	v_lshlrev_b32_e32 v146, 16, v3
	v_and_b32_e32 v147, 0xffff0000, v3
	v_lshlrev_b32_e32 v148, 16, v4
	v_and_b32_e32 v149, 0xffff0000, v4
	v_lshlrev_b32_e32 v150, 16, v5
	v_and_b32_e32 v151, 0xffff0000, v5
	v_lshlrev_b32_e32 v152, 16, v6
	v_and_b32_e32 v153, 0xffff0000, v6
	v_lshlrev_b32_e32 v154, 16, v7
	v_and_b32_e32 v155, 0xffff0000, v7
	v_pk_mul_f32 v[100:101], v[140:141], v[140:141]
	v_pk_fma_f32 v[100:101], v[142:143], v[142:143], v[100:101]
	v_pk_fma_f32 v[100:101], v[144:145], v[144:145], v[100:101]
	v_pk_fma_f32 v[100:101], v[146:147], v[146:147], v[100:101]
	v_pk_fma_f32 v[100:101], v[148:149], v[148:149], v[100:101]
	v_pk_fma_f32 v[100:101], v[150:151], v[150:151], v[100:101]
	v_pk_fma_f32 v[100:101], v[152:153], v[152:153], v[100:101]
	v_pk_fma_f32 v[100:101], v[154:155], v[154:155], v[100:101]
	v_lshlrev_b32_e32 v140, 16, v8
	v_and_b32_e32 v141, 0xffff0000, v8
	v_lshlrev_b32_e32 v142, 16, v9
	v_and_b32_e32 v143, 0xffff0000, v9
	v_lshlrev_b32_e32 v144, 16, v10
	v_and_b32_e32 v145, 0xffff0000, v10
	v_lshlrev_b32_e32 v146, 16, v11
	v_and_b32_e32 v147, 0xffff0000, v11
	v_lshlrev_b32_e32 v148, 16, v12
	v_and_b32_e32 v149, 0xffff0000, v12
	v_lshlrev_b32_e32 v150, 16, v13
	v_and_b32_e32 v151, 0xffff0000, v13
	v_lshlrev_b32_e32 v152, 16, v14
	v_and_b32_e32 v153, 0xffff0000, v14
	v_lshlrev_b32_e32 v154, 16, v15
	v_and_b32_e32 v155, 0xffff0000, v15
	v_pk_mul_f32 v[102:103], v[140:141], v[140:141]
	v_pk_fma_f32 v[102:103], v[142:143], v[142:143], v[102:103]
	v_pk_fma_f32 v[102:103], v[144:145], v[144:145], v[102:103]
	v_pk_fma_f32 v[102:103], v[146:147], v[146:147], v[102:103]
	v_pk_fma_f32 v[102:103], v[148:149], v[148:149], v[102:103]
	v_pk_fma_f32 v[102:103], v[150:151], v[150:151], v[102:103]
	v_pk_fma_f32 v[102:103], v[152:153], v[152:153], v[102:103]
	v_pk_fma_f32 v[102:103], v[154:155], v[154:155], v[102:103]
	v_lshlrev_b32_e32 v140, 16, v16
	v_and_b32_e32 v141, 0xffff0000, v16
	v_lshlrev_b32_e32 v142, 16, v17
	v_and_b32_e32 v143, 0xffff0000, v17
	v_lshlrev_b32_e32 v144, 16, v18
	v_and_b32_e32 v145, 0xffff0000, v18
	v_lshlrev_b32_e32 v146, 16, v19
	v_and_b32_e32 v147, 0xffff0000, v19
	v_lshlrev_b32_e32 v148, 16, v20
	v_and_b32_e32 v149, 0xffff0000, v20
	v_lshlrev_b32_e32 v150, 16, v21
	v_and_b32_e32 v151, 0xffff0000, v21
	v_lshlrev_b32_e32 v152, 16, v22
	v_and_b32_e32 v153, 0xffff0000, v22
	v_lshlrev_b32_e32 v154, 16, v23
	v_and_b32_e32 v155, 0xffff0000, v23
	v_pk_mul_f32 v[104:105], v[140:141], v[140:141]
	v_pk_fma_f32 v[104:105], v[142:143], v[142:143], v[104:105]
	v_pk_fma_f32 v[104:105], v[144:145], v[144:145], v[104:105]
	v_pk_fma_f32 v[104:105], v[146:147], v[146:147], v[104:105]
	v_pk_fma_f32 v[104:105], v[148:149], v[148:149], v[104:105]
	v_pk_fma_f32 v[104:105], v[150:151], v[150:151], v[104:105]
	v_pk_fma_f32 v[104:105], v[152:153], v[152:153], v[104:105]
	v_pk_fma_f32 v[104:105], v[154:155], v[154:155], v[104:105]
	v_lshlrev_b32_e32 v140, 16, v24
	v_and_b32_e32 v141, 0xffff0000, v24
	v_lshlrev_b32_e32 v142, 16, v25
	v_and_b32_e32 v143, 0xffff0000, v25
	v_lshlrev_b32_e32 v144, 16, v26
	v_and_b32_e32 v145, 0xffff0000, v26
	v_lshlrev_b32_e32 v146, 16, v27
	v_and_b32_e32 v147, 0xffff0000, v27
	v_lshlrev_b32_e32 v148, 16, v28
	v_and_b32_e32 v149, 0xffff0000, v28
	v_lshlrev_b32_e32 v150, 16, v29
	v_and_b32_e32 v151, 0xffff0000, v29
	v_lshlrev_b32_e32 v152, 16, v30
	v_and_b32_e32 v153, 0xffff0000, v30
	v_lshlrev_b32_e32 v154, 16, v31
	v_and_b32_e32 v155, 0xffff0000, v31
	v_pk_mul_f32 v[106:107], v[140:141], v[140:141]
	v_pk_fma_f32 v[106:107], v[142:143], v[142:143], v[106:107]
	v_pk_fma_f32 v[106:107], v[144:145], v[144:145], v[106:107]
	v_pk_fma_f32 v[106:107], v[146:147], v[146:147], v[106:107]
	v_pk_fma_f32 v[106:107], v[148:149], v[148:149], v[106:107]
	v_pk_fma_f32 v[106:107], v[150:151], v[150:151], v[106:107]
	v_pk_fma_f32 v[106:107], v[152:153], v[152:153], v[106:107]
	v_pk_fma_f32 v[106:107], v[154:155], v[154:155], v[106:107]
	v_add_f32_e32 v100, v100, v101
	v_add_f32_e32 v102, v102, v103
	v_add_f32_e32 v104, v104, v105
	v_add_f32_e32 v106, v106, v107
	s_nop 1
	v_add_f32_dpp v100, v100, v100 row_shr:1 row_mask:0xf bank_mask:0xf bound_ctrl:1
	v_add_f32_dpp v102, v102, v102 row_shr:1 row_mask:0xf bank_mask:0xf bound_ctrl:1
	v_add_f32_dpp v104, v104, v104 row_shr:1 row_mask:0xf bank_mask:0xf bound_ctrl:1
	v_add_f32_dpp v106, v106, v106 row_shr:1 row_mask:0xf bank_mask:0xf bound_ctrl:1
	v_add_f32_dpp v100, v100, v100 row_shr:2 row_mask:0xf bank_mask:0xf bound_ctrl:1
	v_add_f32_dpp v102, v102, v102 row_shr:2 row_mask:0xf bank_mask:0xf bound_ctrl:1
	v_add_f32_dpp v104, v104, v104 row_shr:2 row_mask:0xf bank_mask:0xf bound_ctrl:1
	v_add_f32_dpp v106, v106, v106 row_shr:2 row_mask:0xf bank_mask:0xf bound_ctrl:1
	v_add_f32_dpp v100, v100, v100 row_shr:4 row_mask:0xf bank_mask:0xf bound_ctrl:1
	v_add_f32_dpp v102, v102, v102 row_shr:4 row_mask:0xf bank_mask:0xf bound_ctrl:1
	v_add_f32_dpp v104, v104, v104 row_shr:4 row_mask:0xf bank_mask:0xf bound_ctrl:1
	v_add_f32_dpp v106, v106, v106 row_shr:4 row_mask:0xf bank_mask:0xf bound_ctrl:1
	v_add_f32_dpp v100, v100, v100 row_shr:8 row_mask:0xf bank_mask:0xf bound_ctrl:1
	v_add_f32_dpp v102, v102, v102 row_shr:8 row_mask:0xf bank_mask:0xf bound_ctrl:1
	v_add_f32_dpp v104, v104, v104 row_shr:8 row_mask:0xf bank_mask:0xf bound_ctrl:1
	v_add_f32_dpp v106, v106, v106 row_shr:8 row_mask:0xf bank_mask:0xf bound_ctrl:1
	v_add_f32_dpp v100, v100, v100 row_bcast:15 row_mask:0xa bank_mask:0xf
	v_add_f32_dpp v102, v102, v102 row_bcast:15 row_mask:0xa bank_mask:0xf
	v_add_f32_dpp v104, v104, v104 row_bcast:15 row_mask:0xa bank_mask:0xf
	v_add_f32_dpp v106, v106, v106 row_bcast:15 row_mask:0xa bank_mask:0xf
	v_add_f32_dpp v100, v100, v100 row_bcast:31 row_mask:0xc bank_mask:0xf
	v_add_f32_dpp v102, v102, v102 row_bcast:31 row_mask:0xc bank_mask:0xf
	v_add_f32_dpp v104, v104, v104 row_bcast:31 row_mask:0xc bank_mask:0xf
	v_add_f32_dpp v106, v106, v106 row_bcast:31 row_mask:0xc bank_mask:0xf
	s_nop 1
	v_readlane_b32 s5, v100, 63
	v_readlane_b32 s32, v102, 63
	v_readlane_b32 s54, v104, 63
	v_readlane_b32 s60, v106, 63
	s_nop 1
	v_mov_b32_e32 v156, s5
	v_mov_b32_e32 v158, s32
	v_mov_b32_e32 v160, s54
	v_mov_b32_e32 v162, s60
	v_fmaak_f32 v156, v156, v50, 0x358637bd
	v_fmaak_f32 v158, v158, v50, 0x358637bd
	v_fmaak_f32 v160, v160, v50, 0x358637bd
	v_fmaak_f32 v162, v162, v50, 0x358637bd
	v_rsq_f32_e32 v156, v156
	v_rsq_f32_e32 v158, v158
	v_rsq_f32_e32 v160, v160
	v_rsq_f32_e32 v162, v162
	s_nop 0
	v_lshlrev_b32_e32 v140, 16, v0
	v_and_b32_e32 v141, 0xffff0000, v0
	v_lshlrev_b32_e32 v142, 16, v1
	v_and_b32_e32 v143, 0xffff0000, v1
	v_lshlrev_b32_e32 v144, 16, v2
	v_and_b32_e32 v145, 0xffff0000, v2
	v_lshlrev_b32_e32 v146, 16, v3
	v_and_b32_e32 v147, 0xffff0000, v3
	v_lshlrev_b32_e32 v148, 16, v4
	v_and_b32_e32 v149, 0xffff0000, v4
	v_lshlrev_b32_e32 v150, 16, v5
	v_and_b32_e32 v151, 0xffff0000, v5
	v_lshlrev_b32_e32 v152, 16, v6
	v_and_b32_e32 v153, 0xffff0000, v6
	v_lshlrev_b32_e32 v154, 16, v7
	v_and_b32_e32 v155, 0xffff0000, v7
	v_pk_mul_f32 v[140:141], v[156:157], v[140:141] op_sel_hi:[0,1]
	v_pk_mul_f32 v[142:143], v[156:157], v[142:143] op_sel_hi:[0,1]
	v_pk_mul_f32 v[144:145], v[156:157], v[144:145] op_sel_hi:[0,1]
	v_pk_mul_f32 v[146:147], v[156:157], v[146:147] op_sel_hi:[0,1]
	v_pk_mul_f32 v[148:149], v[156:157], v[148:149] op_sel_hi:[0,1]
	v_pk_mul_f32 v[150:151], v[156:157], v[150:151] op_sel_hi:[0,1]
	v_pk_mul_f32 v[152:153], v[156:157], v[152:153] op_sel_hi:[0,1]
	v_pk_mul_f32 v[154:155], v[156:157], v[154:155] op_sel_hi:[0,1]
	v_pk_mul_f32 v[140:141], v[140:141], v[32:33]
	v_pk_mul_f32 v[142:143], v[142:143], v[34:35]
	v_pk_mul_f32 v[144:145], v[144:145], v[36:37]
	v_pk_mul_f32 v[146:147], v[146:147], v[38:39]
	v_pk_mul_f32 v[148:149], v[148:149], v[40:41]
	v_pk_mul_f32 v[150:151], v[150:151], v[42:43]
	v_pk_mul_f32 v[152:153], v[152:153], v[44:45]
	v_pk_mul_f32 v[154:155], v[154:155], v[46:47]
	v_pk_fma_f32 v[140:141], v[140:141], v[84:85], v[124:125]
	v_pk_fma_f32 v[142:143], v[142:143], v[86:87], v[126:127]
	v_pk_fma_f32 v[144:145], v[144:145], v[88:89], v[128:129]
	v_pk_fma_f32 v[146:147], v[146:147], v[90:91], v[130:131]
	v_pk_fma_f32 v[148:149], v[148:149], v[92:93], v[132:133]
	v_pk_fma_f32 v[150:151], v[150:151], v[94:95], v[134:135]
	v_pk_fma_f32 v[152:153], v[152:153], v[96:97], v[136:137]
	v_pk_fma_f32 v[154:155], v[154:155], v[98:99], v[138:139]
	v_cvt_pk_bf16_f32 v172, v140, v141
	v_cvt_pk_bf16_f32 v173, v142, v143
	v_cvt_pk_bf16_f32 v174, v144, v145
	v_cvt_pk_bf16_f32 v175, v146, v147
	v_cvt_pk_bf16_f32 v176, v148, v149
	v_cvt_pk_bf16_f32 v177, v150, v151
	v_cvt_pk_bf16_f32 v178, v152, v153
	v_cvt_pk_bf16_f32 v179, v154, v155
	global_store_dwordx4 v51, v[172:175], s[20:21]
	global_store_dwordx4 v51, v[176:179], s[20:21] offset:1024
	v_lshlrev_b32_e32 v140, 16, v8
	v_and_b32_e32 v141, 0xffff0000, v8
	v_lshlrev_b32_e32 v142, 16, v9
	v_and_b32_e32 v143, 0xffff0000, v9
	v_lshlrev_b32_e32 v144, 16, v10
	v_and_b32_e32 v145, 0xffff0000, v10
	v_lshlrev_b32_e32 v146, 16, v11
	v_and_b32_e32 v147, 0xffff0000, v11
	v_lshlrev_b32_e32 v148, 16, v12
	v_and_b32_e32 v149, 0xffff0000, v12
	v_lshlrev_b32_e32 v150, 16, v13
	v_and_b32_e32 v151, 0xffff0000, v13
	v_lshlrev_b32_e32 v152, 16, v14
	v_and_b32_e32 v153, 0xffff0000, v14
	v_lshlrev_b32_e32 v154, 16, v15
	v_and_b32_e32 v155, 0xffff0000, v15
	v_pk_mul_f32 v[140:141], v[158:159], v[140:141] op_sel_hi:[0,1]
	v_pk_mul_f32 v[142:143], v[158:159], v[142:143] op_sel_hi:[0,1]
	v_pk_mul_f32 v[144:145], v[158:159], v[144:145] op_sel_hi:[0,1]
	v_pk_mul_f32 v[146:147], v[158:159], v[146:147] op_sel_hi:[0,1]
	v_pk_mul_f32 v[148:149], v[158:159], v[148:149] op_sel_hi:[0,1]
	v_pk_mul_f32 v[150:151], v[158:159], v[150:151] op_sel_hi:[0,1]
	v_pk_mul_f32 v[152:153], v[158:159], v[152:153] op_sel_hi:[0,1]
	v_pk_mul_f32 v[154:155], v[158:159], v[154:155] op_sel_hi:[0,1]
	v_pk_mul_f32 v[140:141], v[140:141], v[32:33]
	v_pk_mul_f32 v[142:143], v[142:143], v[34:35]
	v_pk_mul_f32 v[144:145], v[144:145], v[36:37]
	v_pk_mul_f32 v[146:147], v[146:147], v[38:39]
	v_pk_mul_f32 v[148:149], v[148:149], v[40:41]
	v_pk_mul_f32 v[150:151], v[150:151], v[42:43]
	v_pk_mul_f32 v[152:153], v[152:153], v[44:45]
	v_pk_mul_f32 v[154:155], v[154:155], v[46:47]
	v_pk_fma_f32 v[140:141], v[140:141], v[84:85], v[124:125]
	v_pk_fma_f32 v[142:143], v[142:143], v[86:87], v[126:127]
	v_pk_fma_f32 v[144:145], v[144:145], v[88:89], v[128:129]
	v_pk_fma_f32 v[146:147], v[146:147], v[90:91], v[130:131]
	v_pk_fma_f32 v[148:149], v[148:149], v[92:93], v[132:133]
	v_pk_fma_f32 v[150:151], v[150:151], v[94:95], v[134:135]
	v_pk_fma_f32 v[152:153], v[152:153], v[96:97], v[136:137]
	v_pk_fma_f32 v[154:155], v[154:155], v[98:99], v[138:139]
	v_cvt_pk_bf16_f32 v164, v140, v141
	v_cvt_pk_bf16_f32 v165, v142, v143
	v_cvt_pk_bf16_f32 v166, v144, v145
	v_cvt_pk_bf16_f32 v167, v146, v147
	v_cvt_pk_bf16_f32 v168, v148, v149
	v_cvt_pk_bf16_f32 v169, v150, v151
	v_cvt_pk_bf16_f32 v170, v152, v153
	v_cvt_pk_bf16_f32 v171, v154, v155
	global_store_dwordx4 v51, v[164:167], s[20:21] offset:2048
	global_store_dwordx4 v51, v[168:171], s[20:21] offset:3072
	v_lshlrev_b32_e32 v140, 16, v16
	v_and_b32_e32 v141, 0xffff0000, v16
	v_lshlrev_b32_e32 v142, 16, v17
	v_and_b32_e32 v143, 0xffff0000, v17
	v_lshlrev_b32_e32 v144, 16, v18
	v_and_b32_e32 v145, 0xffff0000, v18
	v_lshlrev_b32_e32 v146, 16, v19
	v_and_b32_e32 v147, 0xffff0000, v19
	v_lshlrev_b32_e32 v148, 16, v20
	v_and_b32_e32 v149, 0xffff0000, v20
	v_lshlrev_b32_e32 v150, 16, v21
	v_and_b32_e32 v151, 0xffff0000, v21
	v_lshlrev_b32_e32 v152, 16, v22
	v_and_b32_e32 v153, 0xffff0000, v22
	v_lshlrev_b32_e32 v154, 16, v23
	v_and_b32_e32 v155, 0xffff0000, v23
	v_pk_mul_f32 v[140:141], v[160:161], v[140:141] op_sel_hi:[0,1]
	v_pk_mul_f32 v[142:143], v[160:161], v[142:143] op_sel_hi:[0,1]
	v_pk_mul_f32 v[144:145], v[160:161], v[144:145] op_sel_hi:[0,1]
	v_pk_mul_f32 v[146:147], v[160:161], v[146:147] op_sel_hi:[0,1]
	v_pk_mul_f32 v[148:149], v[160:161], v[148:149] op_sel_hi:[0,1]
	v_pk_mul_f32 v[150:151], v[160:161], v[150:151] op_sel_hi:[0,1]
	v_pk_mul_f32 v[152:153], v[160:161], v[152:153] op_sel_hi:[0,1]
	v_pk_mul_f32 v[154:155], v[160:161], v[154:155] op_sel_hi:[0,1]
	v_pk_mul_f32 v[140:141], v[140:141], v[32:33]
	v_pk_mul_f32 v[142:143], v[142:143], v[34:35]
	v_pk_mul_f32 v[144:145], v[144:145], v[36:37]
	v_pk_mul_f32 v[146:147], v[146:147], v[38:39]
	v_pk_mul_f32 v[148:149], v[148:149], v[40:41]
	v_pk_mul_f32 v[150:151], v[150:151], v[42:43]
	v_pk_mul_f32 v[152:153], v[152:153], v[44:45]
	v_pk_mul_f32 v[154:155], v[154:155], v[46:47]
	v_pk_fma_f32 v[140:141], v[140:141], v[84:85], v[124:125]
	v_pk_fma_f32 v[142:143], v[142:143], v[86:87], v[126:127]
	v_pk_fma_f32 v[144:145], v[144:145], v[88:89], v[128:129]
	v_pk_fma_f32 v[146:147], v[146:147], v[90:91], v[130:131]
	v_pk_fma_f32 v[148:149], v[148:149], v[92:93], v[132:133]
	v_pk_fma_f32 v[150:151], v[150:151], v[94:95], v[134:135]
	v_pk_fma_f32 v[152:153], v[152:153], v[96:97], v[136:137]
	v_pk_fma_f32 v[154:155], v[154:155], v[98:99], v[138:139]
	v_cvt_pk_bf16_f32 v172, v140, v141
	v_cvt_pk_bf16_f32 v173, v142, v143
	v_cvt_pk_bf16_f32 v174, v144, v145
	v_cvt_pk_bf16_f32 v175, v146, v147
	v_cvt_pk_bf16_f32 v176, v148, v149
	v_cvt_pk_bf16_f32 v177, v150, v151
	v_cvt_pk_bf16_f32 v178, v152, v153
	v_cvt_pk_bf16_f32 v179, v154, v155
	global_store_dwordx4 v109, v[172:175], s[20:21]
	global_store_dwordx4 v109, v[176:179], s[20:21] offset:1024
	v_lshlrev_b32_e32 v140, 16, v24
	v_and_b32_e32 v141, 0xffff0000, v24
	v_lshlrev_b32_e32 v142, 16, v25
	v_and_b32_e32 v143, 0xffff0000, v25
	v_lshlrev_b32_e32 v144, 16, v26
	v_and_b32_e32 v145, 0xffff0000, v26
	v_lshlrev_b32_e32 v146, 16, v27
	v_and_b32_e32 v147, 0xffff0000, v27
	v_lshlrev_b32_e32 v148, 16, v28
	v_and_b32_e32 v149, 0xffff0000, v28
	v_lshlrev_b32_e32 v150, 16, v29
	v_and_b32_e32 v151, 0xffff0000, v29
	v_lshlrev_b32_e32 v152, 16, v30
	v_and_b32_e32 v153, 0xffff0000, v30
	v_lshlrev_b32_e32 v154, 16, v31
	v_and_b32_e32 v155, 0xffff0000, v31
	v_pk_mul_f32 v[140:141], v[162:163], v[140:141] op_sel_hi:[0,1]
	v_pk_mul_f32 v[142:143], v[162:163], v[142:143] op_sel_hi:[0,1]
	v_pk_mul_f32 v[144:145], v[162:163], v[144:145] op_sel_hi:[0,1]
	v_pk_mul_f32 v[146:147], v[162:163], v[146:147] op_sel_hi:[0,1]
	v_pk_mul_f32 v[148:149], v[162:163], v[148:149] op_sel_hi:[0,1]
	v_pk_mul_f32 v[150:151], v[162:163], v[150:151] op_sel_hi:[0,1]
	v_pk_mul_f32 v[152:153], v[162:163], v[152:153] op_sel_hi:[0,1]
	v_pk_mul_f32 v[154:155], v[162:163], v[154:155] op_sel_hi:[0,1]
	v_pk_mul_f32 v[140:141], v[140:141], v[32:33]
	v_pk_mul_f32 v[142:143], v[142:143], v[34:35]
	v_pk_mul_f32 v[144:145], v[144:145], v[36:37]
	v_pk_mul_f32 v[146:147], v[146:147], v[38:39]
	v_pk_mul_f32 v[148:149], v[148:149], v[40:41]
	v_pk_mul_f32 v[150:151], v[150:151], v[42:43]
	v_pk_mul_f32 v[152:153], v[152:153], v[44:45]
	v_pk_mul_f32 v[154:155], v[154:155], v[46:47]
	v_pk_fma_f32 v[140:141], v[140:141], v[84:85], v[124:125]
	v_pk_fma_f32 v[142:143], v[142:143], v[86:87], v[126:127]
	v_pk_fma_f32 v[144:145], v[144:145], v[88:89], v[128:129]
	v_pk_fma_f32 v[146:147], v[146:147], v[90:91], v[130:131]
	v_pk_fma_f32 v[148:149], v[148:149], v[92:93], v[132:133]
	v_pk_fma_f32 v[150:151], v[150:151], v[94:95], v[134:135]
	v_pk_fma_f32 v[152:153], v[152:153], v[96:97], v[136:137]
	v_pk_fma_f32 v[154:155], v[154:155], v[98:99], v[138:139]
	v_cvt_pk_bf16_f32 v164, v140, v141
	v_cvt_pk_bf16_f32 v165, v142, v143
	v_cvt_pk_bf16_f32 v166, v144, v145
	v_cvt_pk_bf16_f32 v167, v146, v147
	v_cvt_pk_bf16_f32 v168, v148, v149
	v_cvt_pk_bf16_f32 v169, v150, v151
	v_cvt_pk_bf16_f32 v170, v152, v153
	v_cvt_pk_bf16_f32 v171, v154, v155
	global_store_dwordx4 v109, v[164:167], s[20:21] offset:2048
	global_store_dwordx4 v109, v[168:171], s[20:21] offset:3072
	s_add_u32 s20, s20, 0x2000
	s_addc_u32 s21, s21, 0
	s_add_u32 s18, s18, 0x2000
	s_addc_u32 s19, s19, 0
	global_load_dwordx4 v[0:3], v51, s[18:19]
	global_load_dwordx4 v[4:7], v51, s[18:19] offset:1024
	global_load_dwordx4 v[8:11], v51, s[18:19] offset:2048
	global_load_dwordx4 v[12:15], v51, s[18:19] offset:3072
	global_load_dwordx4 v[16:19], v109, s[18:19]
	global_load_dwordx4 v[20:23], v109, s[18:19] offset:1024
	global_load_dwordx4 v[24:27], v109, s[18:19] offset:2048
	global_load_dwordx4 v[28:31], v109, s[18:19] offset:3072
	s_waitcnt vmcnt(16)
	v_lshlrev_b32_e32 v140, 16, v52
	v_and_b32_e32 v141, 0xffff0000, v52
	v_lshlrev_b32_e32 v142, 16, v53
	v_and_b32_e32 v143, 0xffff0000, v53
	v_lshlrev_b32_e32 v144, 16, v54
	v_and_b32_e32 v145, 0xffff0000, v54
	v_lshlrev_b32_e32 v146, 16, v55
	v_and_b32_e32 v147, 0xffff0000, v55
	v_lshlrev_b32_e32 v148, 16, v56
	v_and_b32_e32 v149, 0xffff0000, v56
	v_lshlrev_b32_e32 v150, 16, v57
	v_and_b32_e32 v151, 0xffff0000, v57
	v_lshlrev_b32_e32 v152, 16, v58
	v_and_b32_e32 v153, 0xffff0000, v58
	v_lshlrev_b32_e32 v154, 16, v59
	v_and_b32_e32 v155, 0xffff0000, v59
	v_pk_mul_f32 v[100:101], v[140:141], v[140:141]
	v_pk_fma_f32 v[100:101], v[142:143], v[142:143], v[100:101]
	v_pk_fma_f32 v[100:101], v[144:145], v[144:145], v[100:101]
	v_pk_fma_f32 v[100:101], v[146:147], v[146:147], v[100:101]
	v_pk_fma_f32 v[100:101], v[148:149], v[148:149], v[100:101]
	v_pk_fma_f32 v[100:101], v[150:151], v[150:151], v[100:101]
	v_pk_fma_f32 v[100:101], v[152:153], v[152:153], v[100:101]
	v_pk_fma_f32 v[100:101], v[154:155], v[154:155], v[100:101]
	v_lshlrev_b32_e32 v140, 16, v60
	v_and_b32_e32 v141, 0xffff0000, v60
	v_lshlrev_b32_e32 v142, 16, v61
	v_and_b32_e32 v143, 0xffff0000, v61
	v_lshlrev_b32_e32 v144, 16, v62
	v_and_b32_e32 v145, 0xffff0000, v62
	v_lshlrev_b32_e32 v146, 16, v63
	v_and_b32_e32 v147, 0xffff0000, v63
	v_lshlrev_b32_e32 v148, 16, v64
	v_and_b32_e32 v149, 0xffff0000, v64
	v_lshlrev_b32_e32 v150, 16, v65
	v_and_b32_e32 v151, 0xffff0000, v65
	v_lshlrev_b32_e32 v152, 16, v66
	v_and_b32_e32 v153, 0xffff0000, v66
	v_lshlrev_b32_e32 v154, 16, v67
	v_and_b32_e32 v155, 0xffff0000, v67
	v_pk_mul_f32 v[102:103], v[140:141], v[140:141]
	v_pk_fma_f32 v[102:103], v[142:143], v[142:143], v[102:103]
	v_pk_fma_f32 v[102:103], v[144:145], v[144:145], v[102:103]
	v_pk_fma_f32 v[102:103], v[146:147], v[146:147], v[102:103]
	v_pk_fma_f32 v[102:103], v[148:149], v[148:149], v[102:103]
	v_pk_fma_f32 v[102:103], v[150:151], v[150:151], v[102:103]
	v_pk_fma_f32 v[102:103], v[152:153], v[152:153], v[102:103]
	v_pk_fma_f32 v[102:103], v[154:155], v[154:155], v[102:103]
	v_lshlrev_b32_e32 v140, 16, v68
	v_and_b32_e32 v141, 0xffff0000, v68
	v_lshlrev_b32_e32 v142, 16, v69
	v_and_b32_e32 v143, 0xffff0000, v69
	v_lshlrev_b32_e32 v144, 16, v70
	v_and_b32_e32 v145, 0xffff0000, v70
	v_lshlrev_b32_e32 v146, 16, v71
	v_and_b32_e32 v147, 0xffff0000, v71
	v_lshlrev_b32_e32 v148, 16, v72
	v_and_b32_e32 v149, 0xffff0000, v72
	v_lshlrev_b32_e32 v150, 16, v73
	v_and_b32_e32 v151, 0xffff0000, v73
	v_lshlrev_b32_e32 v152, 16, v74
	v_and_b32_e32 v153, 0xffff0000, v74
	v_lshlrev_b32_e32 v154, 16, v75
	v_and_b32_e32 v155, 0xffff0000, v75
	v_pk_mul_f32 v[104:105], v[140:141], v[140:141]
	v_pk_fma_f32 v[104:105], v[142:143], v[142:143], v[104:105]
	v_pk_fma_f32 v[104:105], v[144:145], v[144:145], v[104:105]
	v_pk_fma_f32 v[104:105], v[146:147], v[146:147], v[104:105]
	v_pk_fma_f32 v[104:105], v[148:149], v[148:149], v[104:105]
	v_pk_fma_f32 v[104:105], v[150:151], v[150:151], v[104:105]
	v_pk_fma_f32 v[104:105], v[152:153], v[152:153], v[104:105]
	v_pk_fma_f32 v[104:105], v[154:155], v[154:155], v[104:105]
	v_lshlrev_b32_e32 v140, 16, v76
	v_and_b32_e32 v141, 0xffff0000, v76
	v_lshlrev_b32_e32 v142, 16, v77
	v_and_b32_e32 v143, 0xffff0000, v77
	v_lshlrev_b32_e32 v144, 16, v78
	v_and_b32_e32 v145, 0xffff0000, v78
	v_lshlrev_b32_e32 v146, 16, v79
	v_and_b32_e32 v147, 0xffff0000, v79
	v_lshlrev_b32_e32 v148, 16, v80
	v_and_b32_e32 v149, 0xffff0000, v80
	v_lshlrev_b32_e32 v150, 16, v81
	v_and_b32_e32 v151, 0xffff0000, v81
	v_lshlrev_b32_e32 v152, 16, v82
	v_and_b32_e32 v153, 0xffff0000, v82
	v_lshlrev_b32_e32 v154, 16, v83
	v_and_b32_e32 v155, 0xffff0000, v83
	v_pk_mul_f32 v[106:107], v[140:141], v[140:141]
	v_pk_fma_f32 v[106:107], v[142:143], v[142:143], v[106:107]
	v_pk_fma_f32 v[106:107], v[144:145], v[144:145], v[106:107]
	v_pk_fma_f32 v[106:107], v[146:147], v[146:147], v[106:107]
	v_pk_fma_f32 v[106:107], v[148:149], v[148:149], v[106:107]
	v_pk_fma_f32 v[106:107], v[150:151], v[150:151], v[106:107]
	v_pk_fma_f32 v[106:107], v[152:153], v[152:153], v[106:107]
	v_pk_fma_f32 v[106:107], v[154:155], v[154:155], v[106:107]
	v_add_f32_e32 v100, v100, v101
	v_add_f32_e32 v102, v102, v103
	v_add_f32_e32 v104, v104, v105
	v_add_f32_e32 v106, v106, v107
	s_nop 1
	v_add_f32_dpp v100, v100, v100 row_shr:1 row_mask:0xf bank_mask:0xf bound_ctrl:1
	v_add_f32_dpp v102, v102, v102 row_shr:1 row_mask:0xf bank_mask:0xf bound_ctrl:1
	v_add_f32_dpp v104, v104, v104 row_shr:1 row_mask:0xf bank_mask:0xf bound_ctrl:1
	v_add_f32_dpp v106, v106, v106 row_shr:1 row_mask:0xf bank_mask:0xf bound_ctrl:1
	v_add_f32_dpp v100, v100, v100 row_shr:2 row_mask:0xf bank_mask:0xf bound_ctrl:1
	v_add_f32_dpp v102, v102, v102 row_shr:2 row_mask:0xf bank_mask:0xf bound_ctrl:1
	v_add_f32_dpp v104, v104, v104 row_shr:2 row_mask:0xf bank_mask:0xf bound_ctrl:1
	v_add_f32_dpp v106, v106, v106 row_shr:2 row_mask:0xf bank_mask:0xf bound_ctrl:1
	v_add_f32_dpp v100, v100, v100 row_shr:4 row_mask:0xf bank_mask:0xf bound_ctrl:1
	v_add_f32_dpp v102, v102, v102 row_shr:4 row_mask:0xf bank_mask:0xf bound_ctrl:1
	v_add_f32_dpp v104, v104, v104 row_shr:4 row_mask:0xf bank_mask:0xf bound_ctrl:1
	v_add_f32_dpp v106, v106, v106 row_shr:4 row_mask:0xf bank_mask:0xf bound_ctrl:1
	v_add_f32_dpp v100, v100, v100 row_shr:8 row_mask:0xf bank_mask:0xf bound_ctrl:1
	v_add_f32_dpp v102, v102, v102 row_shr:8 row_mask:0xf bank_mask:0xf bound_ctrl:1
	v_add_f32_dpp v104, v104, v104 row_shr:8 row_mask:0xf bank_mask:0xf bound_ctrl:1
	v_add_f32_dpp v106, v106, v106 row_shr:8 row_mask:0xf bank_mask:0xf bound_ctrl:1
	v_add_f32_dpp v100, v100, v100 row_bcast:15 row_mask:0xa bank_mask:0xf
	v_add_f32_dpp v102, v102, v102 row_bcast:15 row_mask:0xa bank_mask:0xf
	v_add_f32_dpp v104, v104, v104 row_bcast:15 row_mask:0xa bank_mask:0xf
	v_add_f32_dpp v106, v106, v106 row_bcast:15 row_mask:0xa bank_mask:0xf
	v_add_f32_dpp v100, v100, v100 row_bcast:31 row_mask:0xc bank_mask:0xf
	v_add_f32_dpp v102, v102, v102 row_bcast:31 row_mask:0xc bank_mask:0xf
	v_add_f32_dpp v104, v104, v104 row_bcast:31 row_mask:0xc bank_mask:0xf
	v_add_f32_dpp v106, v106, v106 row_bcast:31 row_mask:0xc bank_mask:0xf
	s_nop 1
	v_readlane_b32 s5, v100, 63
	v_readlane_b32 s32, v102, 63
	v_readlane_b32 s54, v104, 63
	v_readlane_b32 s60, v106, 63
	s_nop 1
	v_mov_b32_e32 v156, s5
	v_mov_b32_e32 v158, s32
	v_mov_b32_e32 v160, s54
	v_mov_b32_e32 v162, s60
	v_fmaak_f32 v156, v156, v50, 0x358637bd
	v_fmaak_f32 v158, v158, v50, 0x358637bd
	v_fmaak_f32 v160, v160, v50, 0x358637bd
	v_fmaak_f32 v162, v162, v50, 0x358637bd
	v_rsq_f32_e32 v156, v156
	v_rsq_f32_e32 v158, v158
	v_rsq_f32_e32 v160, v160
	v_rsq_f32_e32 v162, v162
	s_nop 0
	v_lshlrev_b32_e32 v140, 16, v52
	v_and_b32_e32 v141, 0xffff0000, v52
	v_lshlrev_b32_e32 v142, 16, v53
	v_and_b32_e32 v143, 0xffff0000, v53
	v_lshlrev_b32_e32 v144, 16, v54
	v_and_b32_e32 v145, 0xffff0000, v54
	v_lshlrev_b32_e32 v146, 16, v55
	v_and_b32_e32 v147, 0xffff0000, v55
	v_lshlrev_b32_e32 v148, 16, v56
	v_and_b32_e32 v149, 0xffff0000, v56
	v_lshlrev_b32_e32 v150, 16, v57
	v_and_b32_e32 v151, 0xffff0000, v57
	v_lshlrev_b32_e32 v152, 16, v58
	v_and_b32_e32 v153, 0xffff0000, v58
	v_lshlrev_b32_e32 v154, 16, v59
	v_and_b32_e32 v155, 0xffff0000, v59
	v_pk_mul_f32 v[140:141], v[156:157], v[140:141] op_sel_hi:[0,1]
	v_pk_mul_f32 v[142:143], v[156:157], v[142:143] op_sel_hi:[0,1]
	v_pk_mul_f32 v[144:145], v[156:157], v[144:145] op_sel_hi:[0,1]
	v_pk_mul_f32 v[146:147], v[156:157], v[146:147] op_sel_hi:[0,1]
	v_pk_mul_f32 v[148:149], v[156:157], v[148:149] op_sel_hi:[0,1]
	v_pk_mul_f32 v[150:151], v[156:157], v[150:151] op_sel_hi:[0,1]
	v_pk_mul_f32 v[152:153], v[156:157], v[152:153] op_sel_hi:[0,1]
	v_pk_mul_f32 v[154:155], v[156:157], v[154:155] op_sel_hi:[0,1]
	v_pk_mul_f32 v[140:141], v[140:141], v[32:33]
	v_pk_mul_f32 v[142:143], v[142:143], v[34:35]
	v_pk_mul_f32 v[144:145], v[144:145], v[36:37]
	v_pk_mul_f32 v[146:147], v[146:147], v[38:39]
	v_pk_mul_f32 v[148:149], v[148:149], v[40:41]
	v_pk_mul_f32 v[150:151], v[150:151], v[42:43]
	v_pk_mul_f32 v[152:153], v[152:153], v[44:45]
	v_pk_mul_f32 v[154:155], v[154:155], v[46:47]
	v_pk_fma_f32 v[140:141], v[140:141], v[84:85], v[124:125]
	v_pk_fma_f32 v[142:143], v[142:143], v[86:87], v[126:127]
	v_pk_fma_f32 v[144:145], v[144:145], v[88:89], v[128:129]
	v_pk_fma_f32 v[146:147], v[146:147], v[90:91], v[130:131]
	v_pk_fma_f32 v[148:149], v[148:149], v[92:93], v[132:133]
	v_pk_fma_f32 v[150:151], v[150:151], v[94:95], v[134:135]
	v_pk_fma_f32 v[152:153], v[152:153], v[96:97], v[136:137]
	v_pk_fma_f32 v[154:155], v[154:155], v[98:99], v[138:139]
	v_cvt_pk_bf16_f32 v164, v140, v141
	v_cvt_pk_bf16_f32 v165, v142, v143
	v_cvt_pk_bf16_f32 v166, v144, v145
	v_cvt_pk_bf16_f32 v167, v146, v147
	v_cvt_pk_bf16_f32 v168, v148, v149
	v_cvt_pk_bf16_f32 v169, v150, v151
	v_cvt_pk_bf16_f32 v170, v152, v153
	v_cvt_pk_bf16_f32 v171, v154, v155
	global_store_dwordx4 v51, v[164:167], s[20:21]
	global_store_dwordx4 v51, v[168:171], s[20:21] offset:1024
	v_lshlrev_b32_e32 v140, 16, v60
	v_and_b32_e32 v141, 0xffff0000, v60
	v_lshlrev_b32_e32 v142, 16, v61
	v_and_b32_e32 v143, 0xffff0000, v61
	v_lshlrev_b32_e32 v144, 16, v62
	v_and_b32_e32 v145, 0xffff0000, v62
	v_lshlrev_b32_e32 v146, 16, v63
	v_and_b32_e32 v147, 0xffff0000, v63
	v_lshlrev_b32_e32 v148, 16, v64
	v_and_b32_e32 v149, 0xffff0000, v64
	v_lshlrev_b32_e32 v150, 16, v65
	v_and_b32_e32 v151, 0xffff0000, v65
	v_lshlrev_b32_e32 v152, 16, v66
	v_and_b32_e32 v153, 0xffff0000, v66
	v_lshlrev_b32_e32 v154, 16, v67
	v_and_b32_e32 v155, 0xffff0000, v67
	v_pk_mul_f32 v[140:141], v[158:159], v[140:141] op_sel_hi:[0,1]
	v_pk_mul_f32 v[142:143], v[158:159], v[142:143] op_sel_hi:[0,1]
	v_pk_mul_f32 v[144:145], v[158:159], v[144:145] op_sel_hi:[0,1]
	v_pk_mul_f32 v[146:147], v[158:159], v[146:147] op_sel_hi:[0,1]
	v_pk_mul_f32 v[148:149], v[158:159], v[148:149] op_sel_hi:[0,1]
	v_pk_mul_f32 v[150:151], v[158:159], v[150:151] op_sel_hi:[0,1]
	v_pk_mul_f32 v[152:153], v[158:159], v[152:153] op_sel_hi:[0,1]
	v_pk_mul_f32 v[154:155], v[158:159], v[154:155] op_sel_hi:[0,1]
	v_pk_mul_f32 v[140:141], v[140:141], v[32:33]
	v_pk_mul_f32 v[142:143], v[142:143], v[34:35]
	v_pk_mul_f32 v[144:145], v[144:145], v[36:37]
	v_pk_mul_f32 v[146:147], v[146:147], v[38:39]
	v_pk_mul_f32 v[148:149], v[148:149], v[40:41]
	v_pk_mul_f32 v[150:151], v[150:151], v[42:43]
	v_pk_mul_f32 v[152:153], v[152:153], v[44:45]
	v_pk_mul_f32 v[154:155], v[154:155], v[46:47]
	v_pk_fma_f32 v[140:141], v[140:141], v[84:85], v[124:125]
	v_pk_fma_f32 v[142:143], v[142:143], v[86:87], v[126:127]
	v_pk_fma_f32 v[144:145], v[144:145], v[88:89], v[128:129]
	v_pk_fma_f32 v[146:147], v[146:147], v[90:91], v[130:131]
	v_pk_fma_f32 v[148:149], v[148:149], v[92:93], v[132:133]
	v_pk_fma_f32 v[150:151], v[150:151], v[94:95], v[134:135]
	v_pk_fma_f32 v[152:153], v[152:153], v[96:97], v[136:137]
	v_pk_fma_f32 v[154:155], v[154:155], v[98:99], v[138:139]
	v_cvt_pk_bf16_f32 v172, v140, v141
	v_cvt_pk_bf16_f32 v173, v142, v143
	v_cvt_pk_bf16_f32 v174, v144, v145
	v_cvt_pk_bf16_f32 v175, v146, v147
	v_cvt_pk_bf16_f32 v176, v148, v149
	v_cvt_pk_bf16_f32 v177, v150, v151
	v_cvt_pk_bf16_f32 v178, v152, v153
	v_cvt_pk_bf16_f32 v179, v154, v155
	global_store_dwordx4 v51, v[172:175], s[20:21] offset:2048
	global_store_dwordx4 v51, v[176:179], s[20:21] offset:3072
	v_lshlrev_b32_e32 v140, 16, v68
	v_and_b32_e32 v141, 0xffff0000, v68
	v_lshlrev_b32_e32 v142, 16, v69
	v_and_b32_e32 v143, 0xffff0000, v69
	v_lshlrev_b32_e32 v144, 16, v70
	v_and_b32_e32 v145, 0xffff0000, v70
	v_lshlrev_b32_e32 v146, 16, v71
	v_and_b32_e32 v147, 0xffff0000, v71
	v_lshlrev_b32_e32 v148, 16, v72
	v_and_b32_e32 v149, 0xffff0000, v72
	v_lshlrev_b32_e32 v150, 16, v73
	v_and_b32_e32 v151, 0xffff0000, v73
	v_lshlrev_b32_e32 v152, 16, v74
	v_and_b32_e32 v153, 0xffff0000, v74
	v_lshlrev_b32_e32 v154, 16, v75
	v_and_b32_e32 v155, 0xffff0000, v75
	v_pk_mul_f32 v[140:141], v[160:161], v[140:141] op_sel_hi:[0,1]
	v_pk_mul_f32 v[142:143], v[160:161], v[142:143] op_sel_hi:[0,1]
	v_pk_mul_f32 v[144:145], v[160:161], v[144:145] op_sel_hi:[0,1]
	v_pk_mul_f32 v[146:147], v[160:161], v[146:147] op_sel_hi:[0,1]
	v_pk_mul_f32 v[148:149], v[160:161], v[148:149] op_sel_hi:[0,1]
	v_pk_mul_f32 v[150:151], v[160:161], v[150:151] op_sel_hi:[0,1]
	v_pk_mul_f32 v[152:153], v[160:161], v[152:153] op_sel_hi:[0,1]
	v_pk_mul_f32 v[154:155], v[160:161], v[154:155] op_sel_hi:[0,1]
	v_pk_mul_f32 v[140:141], v[140:141], v[32:33]
	v_pk_mul_f32 v[142:143], v[142:143], v[34:35]
	v_pk_mul_f32 v[144:145], v[144:145], v[36:37]
	v_pk_mul_f32 v[146:147], v[146:147], v[38:39]
	v_pk_mul_f32 v[148:149], v[148:149], v[40:41]
	v_pk_mul_f32 v[150:151], v[150:151], v[42:43]
	v_pk_mul_f32 v[152:153], v[152:153], v[44:45]
	v_pk_mul_f32 v[154:155], v[154:155], v[46:47]
	v_pk_fma_f32 v[140:141], v[140:141], v[84:85], v[124:125]
	v_pk_fma_f32 v[142:143], v[142:143], v[86:87], v[126:127]
	v_pk_fma_f32 v[144:145], v[144:145], v[88:89], v[128:129]
	v_pk_fma_f32 v[146:147], v[146:147], v[90:91], v[130:131]
	v_pk_fma_f32 v[148:149], v[148:149], v[92:93], v[132:133]
	v_pk_fma_f32 v[150:151], v[150:151], v[94:95], v[134:135]
	v_pk_fma_f32 v[152:153], v[152:153], v[96:97], v[136:137]
	v_pk_fma_f32 v[154:155], v[154:155], v[98:99], v[138:139]
	v_cvt_pk_bf16_f32 v164, v140, v141
	v_cvt_pk_bf16_f32 v165, v142, v143
	v_cvt_pk_bf16_f32 v166, v144, v145
	v_cvt_pk_bf16_f32 v167, v146, v147
	v_cvt_pk_bf16_f32 v168, v148, v149
	v_cvt_pk_bf16_f32 v169, v150, v151
	v_cvt_pk_bf16_f32 v170, v152, v153
	v_cvt_pk_bf16_f32 v171, v154, v155
	global_store_dwordx4 v109, v[164:167], s[20:21]
	global_store_dwordx4 v109, v[168:171], s[20:21] offset:1024
	v_lshlrev_b32_e32 v140, 16, v76
	v_and_b32_e32 v141, 0xffff0000, v76
	v_lshlrev_b32_e32 v142, 16, v77
	v_and_b32_e32 v143, 0xffff0000, v77
	v_lshlrev_b32_e32 v144, 16, v78
	v_and_b32_e32 v145, 0xffff0000, v78
	v_lshlrev_b32_e32 v146, 16, v79
	v_and_b32_e32 v147, 0xffff0000, v79
	v_lshlrev_b32_e32 v148, 16, v80
	v_and_b32_e32 v149, 0xffff0000, v80
	v_lshlrev_b32_e32 v150, 16, v81
	v_and_b32_e32 v151, 0xffff0000, v81
	v_lshlrev_b32_e32 v152, 16, v82
	v_and_b32_e32 v153, 0xffff0000, v82
	v_lshlrev_b32_e32 v154, 16, v83
	v_and_b32_e32 v155, 0xffff0000, v83
	v_pk_mul_f32 v[140:141], v[162:163], v[140:141] op_sel_hi:[0,1]
	v_pk_mul_f32 v[142:143], v[162:163], v[142:143] op_sel_hi:[0,1]
	v_pk_mul_f32 v[144:145], v[162:163], v[144:145] op_sel_hi:[0,1]
	v_pk_mul_f32 v[146:147], v[162:163], v[146:147] op_sel_hi:[0,1]
	v_pk_mul_f32 v[148:149], v[162:163], v[148:149] op_sel_hi:[0,1]
	v_pk_mul_f32 v[150:151], v[162:163], v[150:151] op_sel_hi:[0,1]
	v_pk_mul_f32 v[152:153], v[162:163], v[152:153] op_sel_hi:[0,1]
	v_pk_mul_f32 v[154:155], v[162:163], v[154:155] op_sel_hi:[0,1]
	v_pk_mul_f32 v[140:141], v[140:141], v[32:33]
	v_pk_mul_f32 v[142:143], v[142:143], v[34:35]
	v_pk_mul_f32 v[144:145], v[144:145], v[36:37]
	v_pk_mul_f32 v[146:147], v[146:147], v[38:39]
	v_pk_mul_f32 v[148:149], v[148:149], v[40:41]
	v_pk_mul_f32 v[150:151], v[150:151], v[42:43]
	v_pk_mul_f32 v[152:153], v[152:153], v[44:45]
	v_pk_mul_f32 v[154:155], v[154:155], v[46:47]
	v_pk_fma_f32 v[140:141], v[140:141], v[84:85], v[124:125]
	v_pk_fma_f32 v[142:143], v[142:143], v[86:87], v[126:127]
	v_pk_fma_f32 v[144:145], v[144:145], v[88:89], v[128:129]
	v_pk_fma_f32 v[146:147], v[146:147], v[90:91], v[130:131]
	v_pk_fma_f32 v[148:149], v[148:149], v[92:93], v[132:133]
	v_pk_fma_f32 v[150:151], v[150:151], v[94:95], v[134:135]
	v_pk_fma_f32 v[152:153], v[152:153], v[96:97], v[136:137]
	v_pk_fma_f32 v[154:155], v[154:155], v[98:99], v[138:139]
	v_cvt_pk_bf16_f32 v172, v140, v141
	v_cvt_pk_bf16_f32 v173, v142, v143
	v_cvt_pk_bf16_f32 v174, v144, v145
	v_cvt_pk_bf16_f32 v175, v146, v147
	v_cvt_pk_bf16_f32 v176, v148, v149
	v_cvt_pk_bf16_f32 v177, v150, v151
	v_cvt_pk_bf16_f32 v178, v152, v153
	v_cvt_pk_bf16_f32 v179, v154, v155
	global_store_dwordx4 v109, v[172:175], s[20:21] offset:2048
	global_store_dwordx4 v109, v[176:179], s[20:21] offset:3072
	s_add_u32 s20, s20, 0x2000
	s_addc_u32 s21, s21, 0
	s_add_u32 s18, s18, 0x2000
	s_addc_u32 s19, s19, 0
	global_load_dwordx4 v[52:55], v51, s[18:19]
	global_load_dwordx4 v[56:59], v51, s[18:19] offset:1024
	global_load_dwordx4 v[60:63], v51, s[18:19] offset:2048
	global_load_dwordx4 v[64:67], v51, s[18:19] offset:3072
	global_load_dwordx4 v[68:71], v109, s[18:19]
	global_load_dwordx4 v[72:75], v109, s[18:19] offset:1024
	global_load_dwordx4 v[76:79], v109, s[18:19] offset:2048
	global_load_dwordx4 v[80:83], v109, s[18:19] offset:3072
	s_waitcnt vmcnt(16)
	v_lshlrev_b32_e32 v140, 16, v0
	v_and_b32_e32 v141, 0xffff0000, v0
	v_lshlrev_b32_e32 v142, 16, v1
	v_and_b32_e32 v143, 0xffff0000, v1
	v_lshlrev_b32_e32 v144, 16, v2
	v_and_b32_e32 v145, 0xffff0000, v2
	v_lshlrev_b32_e32 v146, 16, v3
	v_and_b32_e32 v147, 0xffff0000, v3
	v_lshlrev_b32_e32 v148, 16, v4
	v_and_b32_e32 v149, 0xffff0000, v4
	v_lshlrev_b32_e32 v150, 16, v5
	v_and_b32_e32 v151, 0xffff0000, v5
	v_lshlrev_b32_e32 v152, 16, v6
	v_and_b32_e32 v153, 0xffff0000, v6
	v_lshlrev_b32_e32 v154, 16, v7
	v_and_b32_e32 v155, 0xffff0000, v7
	v_pk_mul_f32 v[100:101], v[140:141], v[140:141]
	v_pk_fma_f32 v[100:101], v[142:143], v[142:143], v[100:101]
	v_pk_fma_f32 v[100:101], v[144:145], v[144:145], v[100:101]
	v_pk_fma_f32 v[100:101], v[146:147], v[146:147], v[100:101]
	v_pk_fma_f32 v[100:101], v[148:149], v[148:149], v[100:101]
	v_pk_fma_f32 v[100:101], v[150:151], v[150:151], v[100:101]
	v_pk_fma_f32 v[100:101], v[152:153], v[152:153], v[100:101]
	v_pk_fma_f32 v[100:101], v[154:155], v[154:155], v[100:101]
	v_lshlrev_b32_e32 v140, 16, v8
	v_and_b32_e32 v141, 0xffff0000, v8
	v_lshlrev_b32_e32 v142, 16, v9
	v_and_b32_e32 v143, 0xffff0000, v9
	v_lshlrev_b32_e32 v144, 16, v10
	v_and_b32_e32 v145, 0xffff0000, v10
	v_lshlrev_b32_e32 v146, 16, v11
	v_and_b32_e32 v147, 0xffff0000, v11
	v_lshlrev_b32_e32 v148, 16, v12
	v_and_b32_e32 v149, 0xffff0000, v12
	v_lshlrev_b32_e32 v150, 16, v13
	v_and_b32_e32 v151, 0xffff0000, v13
	v_lshlrev_b32_e32 v152, 16, v14
	v_and_b32_e32 v153, 0xffff0000, v14
	v_lshlrev_b32_e32 v154, 16, v15
	v_and_b32_e32 v155, 0xffff0000, v15
	v_pk_mul_f32 v[102:103], v[140:141], v[140:141]
	v_pk_fma_f32 v[102:103], v[142:143], v[142:143], v[102:103]
	v_pk_fma_f32 v[102:103], v[144:145], v[144:145], v[102:103]
	v_pk_fma_f32 v[102:103], v[146:147], v[146:147], v[102:103]
	v_pk_fma_f32 v[102:103], v[148:149], v[148:149], v[102:103]
	v_pk_fma_f32 v[102:103], v[150:151], v[150:151], v[102:103]
	v_pk_fma_f32 v[102:103], v[152:153], v[152:153], v[102:103]
	v_pk_fma_f32 v[102:103], v[154:155], v[154:155], v[102:103]
	v_lshlrev_b32_e32 v140, 16, v16
	v_and_b32_e32 v141, 0xffff0000, v16
	v_lshlrev_b32_e32 v142, 16, v17
	v_and_b32_e32 v143, 0xffff0000, v17
	v_lshlrev_b32_e32 v144, 16, v18
	v_and_b32_e32 v145, 0xffff0000, v18
	v_lshlrev_b32_e32 v146, 16, v19
	v_and_b32_e32 v147, 0xffff0000, v19
	v_lshlrev_b32_e32 v148, 16, v20
	v_and_b32_e32 v149, 0xffff0000, v20
	v_lshlrev_b32_e32 v150, 16, v21
	v_and_b32_e32 v151, 0xffff0000, v21
	v_lshlrev_b32_e32 v152, 16, v22
	v_and_b32_e32 v153, 0xffff0000, v22
	v_lshlrev_b32_e32 v154, 16, v23
	v_and_b32_e32 v155, 0xffff0000, v23
	v_pk_mul_f32 v[104:105], v[140:141], v[140:141]
	v_pk_fma_f32 v[104:105], v[142:143], v[142:143], v[104:105]
	v_pk_fma_f32 v[104:105], v[144:145], v[144:145], v[104:105]
	v_pk_fma_f32 v[104:105], v[146:147], v[146:147], v[104:105]
	v_pk_fma_f32 v[104:105], v[148:149], v[148:149], v[104:105]
	v_pk_fma_f32 v[104:105], v[150:151], v[150:151], v[104:105]
	v_pk_fma_f32 v[104:105], v[152:153], v[152:153], v[104:105]
	v_pk_fma_f32 v[104:105], v[154:155], v[154:155], v[104:105]
	v_lshlrev_b32_e32 v140, 16, v24
	v_and_b32_e32 v141, 0xffff0000, v24
	v_lshlrev_b32_e32 v142, 16, v25
	v_and_b32_e32 v143, 0xffff0000, v25
	v_lshlrev_b32_e32 v144, 16, v26
	v_and_b32_e32 v145, 0xffff0000, v26
	v_lshlrev_b32_e32 v146, 16, v27
	v_and_b32_e32 v147, 0xffff0000, v27
	v_lshlrev_b32_e32 v148, 16, v28
	v_and_b32_e32 v149, 0xffff0000, v28
	v_lshlrev_b32_e32 v150, 16, v29
	v_and_b32_e32 v151, 0xffff0000, v29
	v_lshlrev_b32_e32 v152, 16, v30
	v_and_b32_e32 v153, 0xffff0000, v30
	v_lshlrev_b32_e32 v154, 16, v31
	v_and_b32_e32 v155, 0xffff0000, v31
	v_pk_mul_f32 v[106:107], v[140:141], v[140:141]
	v_pk_fma_f32 v[106:107], v[142:143], v[142:143], v[106:107]
	v_pk_fma_f32 v[106:107], v[144:145], v[144:145], v[106:107]
	v_pk_fma_f32 v[106:107], v[146:147], v[146:147], v[106:107]
	v_pk_fma_f32 v[106:107], v[148:149], v[148:149], v[106:107]
	v_pk_fma_f32 v[106:107], v[150:151], v[150:151], v[106:107]
	v_pk_fma_f32 v[106:107], v[152:153], v[152:153], v[106:107]
	v_pk_fma_f32 v[106:107], v[154:155], v[154:155], v[106:107]
	v_add_f32_e32 v100, v100, v101
	v_add_f32_e32 v102, v102, v103
	v_add_f32_e32 v104, v104, v105
	v_add_f32_e32 v106, v106, v107
	s_nop 1
	v_add_f32_dpp v100, v100, v100 row_shr:1 row_mask:0xf bank_mask:0xf bound_ctrl:1
	v_add_f32_dpp v102, v102, v102 row_shr:1 row_mask:0xf bank_mask:0xf bound_ctrl:1
	v_add_f32_dpp v104, v104, v104 row_shr:1 row_mask:0xf bank_mask:0xf bound_ctrl:1
	v_add_f32_dpp v106, v106, v106 row_shr:1 row_mask:0xf bank_mask:0xf bound_ctrl:1
	v_add_f32_dpp v100, v100, v100 row_shr:2 row_mask:0xf bank_mask:0xf bound_ctrl:1
	v_add_f32_dpp v102, v102, v102 row_shr:2 row_mask:0xf bank_mask:0xf bound_ctrl:1
	v_add_f32_dpp v104, v104, v104 row_shr:2 row_mask:0xf bank_mask:0xf bound_ctrl:1
	v_add_f32_dpp v106, v106, v106 row_shr:2 row_mask:0xf bank_mask:0xf bound_ctrl:1
	v_add_f32_dpp v100, v100, v100 row_shr:4 row_mask:0xf bank_mask:0xf bound_ctrl:1
	v_add_f32_dpp v102, v102, v102 row_shr:4 row_mask:0xf bank_mask:0xf bound_ctrl:1
	v_add_f32_dpp v104, v104, v104 row_shr:4 row_mask:0xf bank_mask:0xf bound_ctrl:1
	v_add_f32_dpp v106, v106, v106 row_shr:4 row_mask:0xf bank_mask:0xf bound_ctrl:1
	v_add_f32_dpp v100, v100, v100 row_shr:8 row_mask:0xf bank_mask:0xf bound_ctrl:1
	v_add_f32_dpp v102, v102, v102 row_shr:8 row_mask:0xf bank_mask:0xf bound_ctrl:1
	v_add_f32_dpp v104, v104, v104 row_shr:8 row_mask:0xf bank_mask:0xf bound_ctrl:1
	v_add_f32_dpp v106, v106, v106 row_shr:8 row_mask:0xf bank_mask:0xf bound_ctrl:1
	v_add_f32_dpp v100, v100, v100 row_bcast:15 row_mask:0xa bank_mask:0xf
	v_add_f32_dpp v102, v102, v102 row_bcast:15 row_mask:0xa bank_mask:0xf
	v_add_f32_dpp v104, v104, v104 row_bcast:15 row_mask:0xa bank_mask:0xf
	v_add_f32_dpp v106, v106, v106 row_bcast:15 row_mask:0xa bank_mask:0xf
	v_add_f32_dpp v100, v100, v100 row_bcast:31 row_mask:0xc bank_mask:0xf
	v_add_f32_dpp v102, v102, v102 row_bcast:31 row_mask:0xc bank_mask:0xf
	v_add_f32_dpp v104, v104, v104 row_bcast:31 row_mask:0xc bank_mask:0xf
	v_add_f32_dpp v106, v106, v106 row_bcast:31 row_mask:0xc bank_mask:0xf
	s_nop 1
	v_readlane_b32 s5, v100, 63
	v_readlane_b32 s32, v102, 63
	v_readlane_b32 s54, v104, 63
	v_readlane_b32 s60, v106, 63
	s_nop 1
	v_mov_b32_e32 v156, s5
	v_mov_b32_e32 v158, s32
	v_mov_b32_e32 v160, s54
	v_mov_b32_e32 v162, s60
	v_fmaak_f32 v156, v156, v50, 0x358637bd
	v_fmaak_f32 v158, v158, v50, 0x358637bd
	v_fmaak_f32 v160, v160, v50, 0x358637bd
	v_fmaak_f32 v162, v162, v50, 0x358637bd
	v_rsq_f32_e32 v156, v156
	v_rsq_f32_e32 v158, v158
	v_rsq_f32_e32 v160, v160
	v_rsq_f32_e32 v162, v162
	s_nop 0
	v_lshlrev_b32_e32 v140, 16, v0
	v_and_b32_e32 v141, 0xffff0000, v0
	v_lshlrev_b32_e32 v142, 16, v1
	v_and_b32_e32 v143, 0xffff0000, v1
	v_lshlrev_b32_e32 v144, 16, v2
	v_and_b32_e32 v145, 0xffff0000, v2
	v_lshlrev_b32_e32 v146, 16, v3
	v_and_b32_e32 v147, 0xffff0000, v3
	v_lshlrev_b32_e32 v148, 16, v4
	v_and_b32_e32 v149, 0xffff0000, v4
	v_lshlrev_b32_e32 v150, 16, v5
	v_and_b32_e32 v151, 0xffff0000, v5
	v_lshlrev_b32_e32 v152, 16, v6
	v_and_b32_e32 v153, 0xffff0000, v6
	v_lshlrev_b32_e32 v154, 16, v7
	v_and_b32_e32 v155, 0xffff0000, v7
	v_pk_mul_f32 v[140:141], v[156:157], v[140:141] op_sel_hi:[0,1]
	v_pk_mul_f32 v[142:143], v[156:157], v[142:143] op_sel_hi:[0,1]
	v_pk_mul_f32 v[144:145], v[156:157], v[144:145] op_sel_hi:[0,1]
	v_pk_mul_f32 v[146:147], v[156:157], v[146:147] op_sel_hi:[0,1]
	v_pk_mul_f32 v[148:149], v[156:157], v[148:149] op_sel_hi:[0,1]
	v_pk_mul_f32 v[150:151], v[156:157], v[150:151] op_sel_hi:[0,1]
	v_pk_mul_f32 v[152:153], v[156:157], v[152:153] op_sel_hi:[0,1]
	v_pk_mul_f32 v[154:155], v[156:157], v[154:155] op_sel_hi:[0,1]
	v_pk_mul_f32 v[140:141], v[140:141], v[32:33]
	v_pk_mul_f32 v[142:143], v[142:143], v[34:35]
	v_pk_mul_f32 v[144:145], v[144:145], v[36:37]
	v_pk_mul_f32 v[146:147], v[146:147], v[38:39]
	v_pk_mul_f32 v[148:149], v[148:149], v[40:41]
	v_pk_mul_f32 v[150:151], v[150:151], v[42:43]
	v_pk_mul_f32 v[152:153], v[152:153], v[44:45]
	v_pk_mul_f32 v[154:155], v[154:155], v[46:47]
	v_pk_fma_f32 v[140:141], v[140:141], v[84:85], v[124:125]
	v_pk_fma_f32 v[142:143], v[142:143], v[86:87], v[126:127]
	v_pk_fma_f32 v[144:145], v[144:145], v[88:89], v[128:129]
	v_pk_fma_f32 v[146:147], v[146:147], v[90:91], v[130:131]
	v_pk_fma_f32 v[148:149], v[148:149], v[92:93], v[132:133]
	v_pk_fma_f32 v[150:151], v[150:151], v[94:95], v[134:135]
	v_pk_fma_f32 v[152:153], v[152:153], v[96:97], v[136:137]
	v_pk_fma_f32 v[154:155], v[154:155], v[98:99], v[138:139]
	v_cvt_pk_bf16_f32 v172, v140, v141
	v_cvt_pk_bf16_f32 v173, v142, v143
	v_cvt_pk_bf16_f32 v174, v144, v145
	v_cvt_pk_bf16_f32 v175, v146, v147
	v_cvt_pk_bf16_f32 v176, v148, v149
	v_cvt_pk_bf16_f32 v177, v150, v151
	v_cvt_pk_bf16_f32 v178, v152, v153
	v_cvt_pk_bf16_f32 v179, v154, v155
	global_store_dwordx4 v51, v[172:175], s[20:21]
	global_store_dwordx4 v51, v[176:179], s[20:21] offset:1024
	v_lshlrev_b32_e32 v140, 16, v8
	v_and_b32_e32 v141, 0xffff0000, v8
	v_lshlrev_b32_e32 v142, 16, v9
	v_and_b32_e32 v143, 0xffff0000, v9
	v_lshlrev_b32_e32 v144, 16, v10
	v_and_b32_e32 v145, 0xffff0000, v10
	v_lshlrev_b32_e32 v146, 16, v11
	v_and_b32_e32 v147, 0xffff0000, v11
	v_lshlrev_b32_e32 v148, 16, v12
	v_and_b32_e32 v149, 0xffff0000, v12
	v_lshlrev_b32_e32 v150, 16, v13
	v_and_b32_e32 v151, 0xffff0000, v13
	v_lshlrev_b32_e32 v152, 16, v14
	v_and_b32_e32 v153, 0xffff0000, v14
	v_lshlrev_b32_e32 v154, 16, v15
	v_and_b32_e32 v155, 0xffff0000, v15
	v_pk_mul_f32 v[140:141], v[158:159], v[140:141] op_sel_hi:[0,1]
	v_pk_mul_f32 v[142:143], v[158:159], v[142:143] op_sel_hi:[0,1]
	v_pk_mul_f32 v[144:145], v[158:159], v[144:145] op_sel_hi:[0,1]
	v_pk_mul_f32 v[146:147], v[158:159], v[146:147] op_sel_hi:[0,1]
	v_pk_mul_f32 v[148:149], v[158:159], v[148:149] op_sel_hi:[0,1]
	v_pk_mul_f32 v[150:151], v[158:159], v[150:151] op_sel_hi:[0,1]
	v_pk_mul_f32 v[152:153], v[158:159], v[152:153] op_sel_hi:[0,1]
	v_pk_mul_f32 v[154:155], v[158:159], v[154:155] op_sel_hi:[0,1]
	v_pk_mul_f32 v[140:141], v[140:141], v[32:33]
	v_pk_mul_f32 v[142:143], v[142:143], v[34:35]
	v_pk_mul_f32 v[144:145], v[144:145], v[36:37]
	v_pk_mul_f32 v[146:147], v[146:147], v[38:39]
	v_pk_mul_f32 v[148:149], v[148:149], v[40:41]
	v_pk_mul_f32 v[150:151], v[150:151], v[42:43]
	v_pk_mul_f32 v[152:153], v[152:153], v[44:45]
	v_pk_mul_f32 v[154:155], v[154:155], v[46:47]
	v_pk_fma_f32 v[140:141], v[140:141], v[84:85], v[124:125]
	v_pk_fma_f32 v[142:143], v[142:143], v[86:87], v[126:127]
	v_pk_fma_f32 v[144:145], v[144:145], v[88:89], v[128:129]
	v_pk_fma_f32 v[146:147], v[146:147], v[90:91], v[130:131]
	v_pk_fma_f32 v[148:149], v[148:149], v[92:93], v[132:133]
	v_pk_fma_f32 v[150:151], v[150:151], v[94:95], v[134:135]
	v_pk_fma_f32 v[152:153], v[152:153], v[96:97], v[136:137]
	v_pk_fma_f32 v[154:155], v[154:155], v[98:99], v[138:139]
	v_cvt_pk_bf16_f32 v164, v140, v141
	v_cvt_pk_bf16_f32 v165, v142, v143
	v_cvt_pk_bf16_f32 v166, v144, v145
	v_cvt_pk_bf16_f32 v167, v146, v147
	v_cvt_pk_bf16_f32 v168, v148, v149
	v_cvt_pk_bf16_f32 v169, v150, v151
	v_cvt_pk_bf16_f32 v170, v152, v153
	v_cvt_pk_bf16_f32 v171, v154, v155
	global_store_dwordx4 v51, v[164:167], s[20:21] offset:2048
	global_store_dwordx4 v51, v[168:171], s[20:21] offset:3072
	v_lshlrev_b32_e32 v140, 16, v16
	v_and_b32_e32 v141, 0xffff0000, v16
	v_lshlrev_b32_e32 v142, 16, v17
	v_and_b32_e32 v143, 0xffff0000, v17
	v_lshlrev_b32_e32 v144, 16, v18
	v_and_b32_e32 v145, 0xffff0000, v18
	v_lshlrev_b32_e32 v146, 16, v19
	v_and_b32_e32 v147, 0xffff0000, v19
	v_lshlrev_b32_e32 v148, 16, v20
	v_and_b32_e32 v149, 0xffff0000, v20
	v_lshlrev_b32_e32 v150, 16, v21
	v_and_b32_e32 v151, 0xffff0000, v21
	v_lshlrev_b32_e32 v152, 16, v22
	v_and_b32_e32 v153, 0xffff0000, v22
	v_lshlrev_b32_e32 v154, 16, v23
	v_and_b32_e32 v155, 0xffff0000, v23
	v_pk_mul_f32 v[140:141], v[160:161], v[140:141] op_sel_hi:[0,1]
	v_pk_mul_f32 v[142:143], v[160:161], v[142:143] op_sel_hi:[0,1]
	v_pk_mul_f32 v[144:145], v[160:161], v[144:145] op_sel_hi:[0,1]
	v_pk_mul_f32 v[146:147], v[160:161], v[146:147] op_sel_hi:[0,1]
	v_pk_mul_f32 v[148:149], v[160:161], v[148:149] op_sel_hi:[0,1]
	v_pk_mul_f32 v[150:151], v[160:161], v[150:151] op_sel_hi:[0,1]
	v_pk_mul_f32 v[152:153], v[160:161], v[152:153] op_sel_hi:[0,1]
	v_pk_mul_f32 v[154:155], v[160:161], v[154:155] op_sel_hi:[0,1]
	v_pk_mul_f32 v[140:141], v[140:141], v[32:33]
	v_pk_mul_f32 v[142:143], v[142:143], v[34:35]
	v_pk_mul_f32 v[144:145], v[144:145], v[36:37]
	v_pk_mul_f32 v[146:147], v[146:147], v[38:39]
	v_pk_mul_f32 v[148:149], v[148:149], v[40:41]
	v_pk_mul_f32 v[150:151], v[150:151], v[42:43]
	v_pk_mul_f32 v[152:153], v[152:153], v[44:45]
	v_pk_mul_f32 v[154:155], v[154:155], v[46:47]
	v_pk_fma_f32 v[140:141], v[140:141], v[84:85], v[124:125]
	v_pk_fma_f32 v[142:143], v[142:143], v[86:87], v[126:127]
	v_pk_fma_f32 v[144:145], v[144:145], v[88:89], v[128:129]
	v_pk_fma_f32 v[146:147], v[146:147], v[90:91], v[130:131]
	v_pk_fma_f32 v[148:149], v[148:149], v[92:93], v[132:133]
	v_pk_fma_f32 v[150:151], v[150:151], v[94:95], v[134:135]
	v_pk_fma_f32 v[152:153], v[152:153], v[96:97], v[136:137]
	v_pk_fma_f32 v[154:155], v[154:155], v[98:99], v[138:139]
	v_cvt_pk_bf16_f32 v172, v140, v141
	v_cvt_pk_bf16_f32 v173, v142, v143
	v_cvt_pk_bf16_f32 v174, v144, v145
	v_cvt_pk_bf16_f32 v175, v146, v147
	v_cvt_pk_bf16_f32 v176, v148, v149
	v_cvt_pk_bf16_f32 v177, v150, v151
	v_cvt_pk_bf16_f32 v178, v152, v153
	v_cvt_pk_bf16_f32 v179, v154, v155
	global_store_dwordx4 v109, v[172:175], s[20:21]
	global_store_dwordx4 v109, v[176:179], s[20:21] offset:1024
	v_lshlrev_b32_e32 v140, 16, v24
	v_and_b32_e32 v141, 0xffff0000, v24
	v_lshlrev_b32_e32 v142, 16, v25
	v_and_b32_e32 v143, 0xffff0000, v25
	v_lshlrev_b32_e32 v144, 16, v26
	v_and_b32_e32 v145, 0xffff0000, v26
	v_lshlrev_b32_e32 v146, 16, v27
	v_and_b32_e32 v147, 0xffff0000, v27
	v_lshlrev_b32_e32 v148, 16, v28
	v_and_b32_e32 v149, 0xffff0000, v28
	v_lshlrev_b32_e32 v150, 16, v29
	v_and_b32_e32 v151, 0xffff0000, v29
	v_lshlrev_b32_e32 v152, 16, v30
	v_and_b32_e32 v153, 0xffff0000, v30
	v_lshlrev_b32_e32 v154, 16, v31
	v_and_b32_e32 v155, 0xffff0000, v31
	v_pk_mul_f32 v[140:141], v[162:163], v[140:141] op_sel_hi:[0,1]
	v_pk_mul_f32 v[142:143], v[162:163], v[142:143] op_sel_hi:[0,1]
	v_pk_mul_f32 v[144:145], v[162:163], v[144:145] op_sel_hi:[0,1]
	v_pk_mul_f32 v[146:147], v[162:163], v[146:147] op_sel_hi:[0,1]
	v_pk_mul_f32 v[148:149], v[162:163], v[148:149] op_sel_hi:[0,1]
	v_pk_mul_f32 v[150:151], v[162:163], v[150:151] op_sel_hi:[0,1]
	v_pk_mul_f32 v[152:153], v[162:163], v[152:153] op_sel_hi:[0,1]
	v_pk_mul_f32 v[154:155], v[162:163], v[154:155] op_sel_hi:[0,1]
	v_pk_mul_f32 v[140:141], v[140:141], v[32:33]
	v_pk_mul_f32 v[142:143], v[142:143], v[34:35]
	v_pk_mul_f32 v[144:145], v[144:145], v[36:37]
	v_pk_mul_f32 v[146:147], v[146:147], v[38:39]
	v_pk_mul_f32 v[148:149], v[148:149], v[40:41]
	v_pk_mul_f32 v[150:151], v[150:151], v[42:43]
	v_pk_mul_f32 v[152:153], v[152:153], v[44:45]
	v_pk_mul_f32 v[154:155], v[154:155], v[46:47]
	v_pk_fma_f32 v[140:141], v[140:141], v[84:85], v[124:125]
	v_pk_fma_f32 v[142:143], v[142:143], v[86:87], v[126:127]
	v_pk_fma_f32 v[144:145], v[144:145], v[88:89], v[128:129]
	v_pk_fma_f32 v[146:147], v[146:147], v[90:91], v[130:131]
	v_pk_fma_f32 v[148:149], v[148:149], v[92:93], v[132:133]
	v_pk_fma_f32 v[150:151], v[150:151], v[94:95], v[134:135]
	v_pk_fma_f32 v[152:153], v[152:153], v[96:97], v[136:137]
	v_pk_fma_f32 v[154:155], v[154:155], v[98:99], v[138:139]
	v_cvt_pk_bf16_f32 v164, v140, v141
	v_cvt_pk_bf16_f32 v165, v142, v143
	v_cvt_pk_bf16_f32 v166, v144, v145
	v_cvt_pk_bf16_f32 v167, v146, v147
	v_cvt_pk_bf16_f32 v168, v148, v149
	v_cvt_pk_bf16_f32 v169, v150, v151
	v_cvt_pk_bf16_f32 v170, v152, v153
	v_cvt_pk_bf16_f32 v171, v154, v155
	global_store_dwordx4 v109, v[164:167], s[20:21] offset:2048
	global_store_dwordx4 v109, v[168:171], s[20:21] offset:3072
	s_add_u32 s20, s20, 0x2000
	s_addc_u32 s21, s21, 0
	s_add_u32 s18, s18, 0x2000
	s_addc_u32 s19, s19, 0
	global_load_dwordx4 v[0:3], v51, s[18:19]
	global_load_dwordx4 v[4:7], v51, s[18:19] offset:1024
	global_load_dwordx4 v[8:11], v51, s[18:19] offset:2048
	global_load_dwordx4 v[12:15], v51, s[18:19] offset:3072
	global_load_dwordx4 v[16:19], v109, s[18:19]
	global_load_dwordx4 v[20:23], v109, s[18:19] offset:1024
	global_load_dwordx4 v[24:27], v109, s[18:19] offset:2048
	global_load_dwordx4 v[28:31], v109, s[18:19] offset:3072
	s_waitcnt vmcnt(16)
	v_lshlrev_b32_e32 v140, 16, v52
	v_and_b32_e32 v141, 0xffff0000, v52
	v_lshlrev_b32_e32 v142, 16, v53
	v_and_b32_e32 v143, 0xffff0000, v53
	v_lshlrev_b32_e32 v144, 16, v54
	v_and_b32_e32 v145, 0xffff0000, v54
	v_lshlrev_b32_e32 v146, 16, v55
	v_and_b32_e32 v147, 0xffff0000, v55
	v_lshlrev_b32_e32 v148, 16, v56
	v_and_b32_e32 v149, 0xffff0000, v56
	v_lshlrev_b32_e32 v150, 16, v57
	v_and_b32_e32 v151, 0xffff0000, v57
	v_lshlrev_b32_e32 v152, 16, v58
	v_and_b32_e32 v153, 0xffff0000, v58
	v_lshlrev_b32_e32 v154, 16, v59
	v_and_b32_e32 v155, 0xffff0000, v59
	v_pk_mul_f32 v[100:101], v[140:141], v[140:141]
	v_pk_fma_f32 v[100:101], v[142:143], v[142:143], v[100:101]
	v_pk_fma_f32 v[100:101], v[144:145], v[144:145], v[100:101]
	v_pk_fma_f32 v[100:101], v[146:147], v[146:147], v[100:101]
	v_pk_fma_f32 v[100:101], v[148:149], v[148:149], v[100:101]
	v_pk_fma_f32 v[100:101], v[150:151], v[150:151], v[100:101]
	v_pk_fma_f32 v[100:101], v[152:153], v[152:153], v[100:101]
	v_pk_fma_f32 v[100:101], v[154:155], v[154:155], v[100:101]
	v_lshlrev_b32_e32 v140, 16, v60
	v_and_b32_e32 v141, 0xffff0000, v60
	v_lshlrev_b32_e32 v142, 16, v61
	v_and_b32_e32 v143, 0xffff0000, v61
	v_lshlrev_b32_e32 v144, 16, v62
	v_and_b32_e32 v145, 0xffff0000, v62
	v_lshlrev_b32_e32 v146, 16, v63
	v_and_b32_e32 v147, 0xffff0000, v63
	v_lshlrev_b32_e32 v148, 16, v64
	v_and_b32_e32 v149, 0xffff0000, v64
	v_lshlrev_b32_e32 v150, 16, v65
	v_and_b32_e32 v151, 0xffff0000, v65
	v_lshlrev_b32_e32 v152, 16, v66
	v_and_b32_e32 v153, 0xffff0000, v66
	v_lshlrev_b32_e32 v154, 16, v67
	v_and_b32_e32 v155, 0xffff0000, v67
	v_pk_mul_f32 v[102:103], v[140:141], v[140:141]
	v_pk_fma_f32 v[102:103], v[142:143], v[142:143], v[102:103]
	v_pk_fma_f32 v[102:103], v[144:145], v[144:145], v[102:103]
	v_pk_fma_f32 v[102:103], v[146:147], v[146:147], v[102:103]
	v_pk_fma_f32 v[102:103], v[148:149], v[148:149], v[102:103]
	v_pk_fma_f32 v[102:103], v[150:151], v[150:151], v[102:103]
	v_pk_fma_f32 v[102:103], v[152:153], v[152:153], v[102:103]
	v_pk_fma_f32 v[102:103], v[154:155], v[154:155], v[102:103]
	v_lshlrev_b32_e32 v140, 16, v68
	v_and_b32_e32 v141, 0xffff0000, v68
	v_lshlrev_b32_e32 v142, 16, v69
	v_and_b32_e32 v143, 0xffff0000, v69
	v_lshlrev_b32_e32 v144, 16, v70
	v_and_b32_e32 v145, 0xffff0000, v70
	v_lshlrev_b32_e32 v146, 16, v71
	v_and_b32_e32 v147, 0xffff0000, v71
	v_lshlrev_b32_e32 v148, 16, v72
	v_and_b32_e32 v149, 0xffff0000, v72
	v_lshlrev_b32_e32 v150, 16, v73
	v_and_b32_e32 v151, 0xffff0000, v73
	v_lshlrev_b32_e32 v152, 16, v74
	v_and_b32_e32 v153, 0xffff0000, v74
	v_lshlrev_b32_e32 v154, 16, v75
	v_and_b32_e32 v155, 0xffff0000, v75
	v_pk_mul_f32 v[104:105], v[140:141], v[140:141]
	v_pk_fma_f32 v[104:105], v[142:143], v[142:143], v[104:105]
	v_pk_fma_f32 v[104:105], v[144:145], v[144:145], v[104:105]
	v_pk_fma_f32 v[104:105], v[146:147], v[146:147], v[104:105]
	v_pk_fma_f32 v[104:105], v[148:149], v[148:149], v[104:105]
	v_pk_fma_f32 v[104:105], v[150:151], v[150:151], v[104:105]
	v_pk_fma_f32 v[104:105], v[152:153], v[152:153], v[104:105]
	v_pk_fma_f32 v[104:105], v[154:155], v[154:155], v[104:105]
	v_lshlrev_b32_e32 v140, 16, v76
	v_and_b32_e32 v141, 0xffff0000, v76
	v_lshlrev_b32_e32 v142, 16, v77
	v_and_b32_e32 v143, 0xffff0000, v77
	v_lshlrev_b32_e32 v144, 16, v78
	v_and_b32_e32 v145, 0xffff0000, v78
	v_lshlrev_b32_e32 v146, 16, v79
	v_and_b32_e32 v147, 0xffff0000, v79
	v_lshlrev_b32_e32 v148, 16, v80
	v_and_b32_e32 v149, 0xffff0000, v80
	v_lshlrev_b32_e32 v150, 16, v81
	v_and_b32_e32 v151, 0xffff0000, v81
	v_lshlrev_b32_e32 v152, 16, v82
	v_and_b32_e32 v153, 0xffff0000, v82
	v_lshlrev_b32_e32 v154, 16, v83
	v_and_b32_e32 v155, 0xffff0000, v83
	v_pk_mul_f32 v[106:107], v[140:141], v[140:141]
	v_pk_fma_f32 v[106:107], v[142:143], v[142:143], v[106:107]
	v_pk_fma_f32 v[106:107], v[144:145], v[144:145], v[106:107]
	v_pk_fma_f32 v[106:107], v[146:147], v[146:147], v[106:107]
	v_pk_fma_f32 v[106:107], v[148:149], v[148:149], v[106:107]
	v_pk_fma_f32 v[106:107], v[150:151], v[150:151], v[106:107]
	v_pk_fma_f32 v[106:107], v[152:153], v[152:153], v[106:107]
	v_pk_fma_f32 v[106:107], v[154:155], v[154:155], v[106:107]
	v_add_f32_e32 v100, v100, v101
	v_add_f32_e32 v102, v102, v103
	v_add_f32_e32 v104, v104, v105
	v_add_f32_e32 v106, v106, v107
	s_nop 1
	v_add_f32_dpp v100, v100, v100 row_shr:1 row_mask:0xf bank_mask:0xf bound_ctrl:1
	v_add_f32_dpp v102, v102, v102 row_shr:1 row_mask:0xf bank_mask:0xf bound_ctrl:1
	v_add_f32_dpp v104, v104, v104 row_shr:1 row_mask:0xf bank_mask:0xf bound_ctrl:1
	v_add_f32_dpp v106, v106, v106 row_shr:1 row_mask:0xf bank_mask:0xf bound_ctrl:1
	v_add_f32_dpp v100, v100, v100 row_shr:2 row_mask:0xf bank_mask:0xf bound_ctrl:1
	v_add_f32_dpp v102, v102, v102 row_shr:2 row_mask:0xf bank_mask:0xf bound_ctrl:1
	v_add_f32_dpp v104, v104, v104 row_shr:2 row_mask:0xf bank_mask:0xf bound_ctrl:1
	v_add_f32_dpp v106, v106, v106 row_shr:2 row_mask:0xf bank_mask:0xf bound_ctrl:1
	v_add_f32_dpp v100, v100, v100 row_shr:4 row_mask:0xf bank_mask:0xf bound_ctrl:1
	v_add_f32_dpp v102, v102, v102 row_shr:4 row_mask:0xf bank_mask:0xf bound_ctrl:1
	v_add_f32_dpp v104, v104, v104 row_shr:4 row_mask:0xf bank_mask:0xf bound_ctrl:1
	v_add_f32_dpp v106, v106, v106 row_shr:4 row_mask:0xf bank_mask:0xf bound_ctrl:1
	v_add_f32_dpp v100, v100, v100 row_shr:8 row_mask:0xf bank_mask:0xf bound_ctrl:1
	v_add_f32_dpp v102, v102, v102 row_shr:8 row_mask:0xf bank_mask:0xf bound_ctrl:1
	v_add_f32_dpp v104, v104, v104 row_shr:8 row_mask:0xf bank_mask:0xf bound_ctrl:1
	v_add_f32_dpp v106, v106, v106 row_shr:8 row_mask:0xf bank_mask:0xf bound_ctrl:1
	v_add_f32_dpp v100, v100, v100 row_bcast:15 row_mask:0xa bank_mask:0xf
	v_add_f32_dpp v102, v102, v102 row_bcast:15 row_mask:0xa bank_mask:0xf
	v_add_f32_dpp v104, v104, v104 row_bcast:15 row_mask:0xa bank_mask:0xf
	v_add_f32_dpp v106, v106, v106 row_bcast:15 row_mask:0xa bank_mask:0xf
	v_add_f32_dpp v100, v100, v100 row_bcast:31 row_mask:0xc bank_mask:0xf
	v_add_f32_dpp v102, v102, v102 row_bcast:31 row_mask:0xc bank_mask:0xf
	v_add_f32_dpp v104, v104, v104 row_bcast:31 row_mask:0xc bank_mask:0xf
	v_add_f32_dpp v106, v106, v106 row_bcast:31 row_mask:0xc bank_mask:0xf
	s_nop 1
	v_readlane_b32 s5, v100, 63
	v_readlane_b32 s32, v102, 63
	v_readlane_b32 s54, v104, 63
	v_readlane_b32 s60, v106, 63
	s_nop 1
	v_mov_b32_e32 v156, s5
	v_mov_b32_e32 v158, s32
	v_mov_b32_e32 v160, s54
	v_mov_b32_e32 v162, s60
	v_fmaak_f32 v156, v156, v50, 0x358637bd
	v_fmaak_f32 v158, v158, v50, 0x358637bd
	v_fmaak_f32 v160, v160, v50, 0x358637bd
	v_fmaak_f32 v162, v162, v50, 0x358637bd
	v_rsq_f32_e32 v156, v156
	v_rsq_f32_e32 v158, v158
	v_rsq_f32_e32 v160, v160
	v_rsq_f32_e32 v162, v162
	s_nop 0
	v_lshlrev_b32_e32 v140, 16, v52
	v_and_b32_e32 v141, 0xffff0000, v52
	v_lshlrev_b32_e32 v142, 16, v53
	v_and_b32_e32 v143, 0xffff0000, v53
	v_lshlrev_b32_e32 v144, 16, v54
	v_and_b32_e32 v145, 0xffff0000, v54
	v_lshlrev_b32_e32 v146, 16, v55
	v_and_b32_e32 v147, 0xffff0000, v55
	v_lshlrev_b32_e32 v148, 16, v56
	v_and_b32_e32 v149, 0xffff0000, v56
	v_lshlrev_b32_e32 v150, 16, v57
	v_and_b32_e32 v151, 0xffff0000, v57
	v_lshlrev_b32_e32 v152, 16, v58
	v_and_b32_e32 v153, 0xffff0000, v58
	v_lshlrev_b32_e32 v154, 16, v59
	v_and_b32_e32 v155, 0xffff0000, v59
	v_pk_mul_f32 v[140:141], v[156:157], v[140:141] op_sel_hi:[0,1]
	v_pk_mul_f32 v[142:143], v[156:157], v[142:143] op_sel_hi:[0,1]
	v_pk_mul_f32 v[144:145], v[156:157], v[144:145] op_sel_hi:[0,1]
	v_pk_mul_f32 v[146:147], v[156:157], v[146:147] op_sel_hi:[0,1]
	v_pk_mul_f32 v[148:149], v[156:157], v[148:149] op_sel_hi:[0,1]
	v_pk_mul_f32 v[150:151], v[156:157], v[150:151] op_sel_hi:[0,1]
	v_pk_mul_f32 v[152:153], v[156:157], v[152:153] op_sel_hi:[0,1]
	v_pk_mul_f32 v[154:155], v[156:157], v[154:155] op_sel_hi:[0,1]
	v_pk_mul_f32 v[140:141], v[140:141], v[32:33]
	v_pk_mul_f32 v[142:143], v[142:143], v[34:35]
	v_pk_mul_f32 v[144:145], v[144:145], v[36:37]
	v_pk_mul_f32 v[146:147], v[146:147], v[38:39]
	v_pk_mul_f32 v[148:149], v[148:149], v[40:41]
	v_pk_mul_f32 v[150:151], v[150:151], v[42:43]
	v_pk_mul_f32 v[152:153], v[152:153], v[44:45]
	v_pk_mul_f32 v[154:155], v[154:155], v[46:47]
	v_pk_fma_f32 v[140:141], v[140:141], v[84:85], v[124:125]
	v_pk_fma_f32 v[142:143], v[142:143], v[86:87], v[126:127]
	v_pk_fma_f32 v[144:145], v[144:145], v[88:89], v[128:129]
	v_pk_fma_f32 v[146:147], v[146:147], v[90:91], v[130:131]
	v_pk_fma_f32 v[148:149], v[148:149], v[92:93], v[132:133]
	v_pk_fma_f32 v[150:151], v[150:151], v[94:95], v[134:135]
	v_pk_fma_f32 v[152:153], v[152:153], v[96:97], v[136:137]
	v_pk_fma_f32 v[154:155], v[154:155], v[98:99], v[138:139]
	v_cvt_pk_bf16_f32 v164, v140, v141
	v_cvt_pk_bf16_f32 v165, v142, v143
	v_cvt_pk_bf16_f32 v166, v144, v145
	v_cvt_pk_bf16_f32 v167, v146, v147
	v_cvt_pk_bf16_f32 v168, v148, v149
	v_cvt_pk_bf16_f32 v169, v150, v151
	v_cvt_pk_bf16_f32 v170, v152, v153
	v_cvt_pk_bf16_f32 v171, v154, v155
	global_store_dwordx4 v51, v[164:167], s[20:21]
	global_store_dwordx4 v51, v[168:171], s[20:21] offset:1024
	v_lshlrev_b32_e32 v140, 16, v60
	v_and_b32_e32 v141, 0xffff0000, v60
	v_lshlrev_b32_e32 v142, 16, v61
	v_and_b32_e32 v143, 0xffff0000, v61
	v_lshlrev_b32_e32 v144, 16, v62
	v_and_b32_e32 v145, 0xffff0000, v62
	v_lshlrev_b32_e32 v146, 16, v63
	v_and_b32_e32 v147, 0xffff0000, v63
	v_lshlrev_b32_e32 v148, 16, v64
	v_and_b32_e32 v149, 0xffff0000, v64
	v_lshlrev_b32_e32 v150, 16, v65
	v_and_b32_e32 v151, 0xffff0000, v65
	v_lshlrev_b32_e32 v152, 16, v66
	v_and_b32_e32 v153, 0xffff0000, v66
	v_lshlrev_b32_e32 v154, 16, v67
	v_and_b32_e32 v155, 0xffff0000, v67
	v_pk_mul_f32 v[140:141], v[158:159], v[140:141] op_sel_hi:[0,1]
	v_pk_mul_f32 v[142:143], v[158:159], v[142:143] op_sel_hi:[0,1]
	v_pk_mul_f32 v[144:145], v[158:159], v[144:145] op_sel_hi:[0,1]
	v_pk_mul_f32 v[146:147], v[158:159], v[146:147] op_sel_hi:[0,1]
	v_pk_mul_f32 v[148:149], v[158:159], v[148:149] op_sel_hi:[0,1]
	v_pk_mul_f32 v[150:151], v[158:159], v[150:151] op_sel_hi:[0,1]
	v_pk_mul_f32 v[152:153], v[158:159], v[152:153] op_sel_hi:[0,1]
	v_pk_mul_f32 v[154:155], v[158:159], v[154:155] op_sel_hi:[0,1]
	v_pk_mul_f32 v[140:141], v[140:141], v[32:33]
	v_pk_mul_f32 v[142:143], v[142:143], v[34:35]
	v_pk_mul_f32 v[144:145], v[144:145], v[36:37]
	v_pk_mul_f32 v[146:147], v[146:147], v[38:39]
	v_pk_mul_f32 v[148:149], v[148:149], v[40:41]
	v_pk_mul_f32 v[150:151], v[150:151], v[42:43]
	v_pk_mul_f32 v[152:153], v[152:153], v[44:45]
	v_pk_mul_f32 v[154:155], v[154:155], v[46:47]
	v_pk_fma_f32 v[140:141], v[140:141], v[84:85], v[124:125]
	v_pk_fma_f32 v[142:143], v[142:143], v[86:87], v[126:127]
	v_pk_fma_f32 v[144:145], v[144:145], v[88:89], v[128:129]
	v_pk_fma_f32 v[146:147], v[146:147], v[90:91], v[130:131]
	v_pk_fma_f32 v[148:149], v[148:149], v[92:93], v[132:133]
	v_pk_fma_f32 v[150:151], v[150:151], v[94:95], v[134:135]
	v_pk_fma_f32 v[152:153], v[152:153], v[96:97], v[136:137]
	v_pk_fma_f32 v[154:155], v[154:155], v[98:99], v[138:139]
	v_cvt_pk_bf16_f32 v172, v140, v141
	v_cvt_pk_bf16_f32 v173, v142, v143
	v_cvt_pk_bf16_f32 v174, v144, v145
	v_cvt_pk_bf16_f32 v175, v146, v147
	v_cvt_pk_bf16_f32 v176, v148, v149
	v_cvt_pk_bf16_f32 v177, v150, v151
	v_cvt_pk_bf16_f32 v178, v152, v153
	v_cvt_pk_bf16_f32 v179, v154, v155
	global_store_dwordx4 v51, v[172:175], s[20:21] offset:2048
	global_store_dwordx4 v51, v[176:179], s[20:21] offset:3072
	v_lshlrev_b32_e32 v140, 16, v68
	v_and_b32_e32 v141, 0xffff0000, v68
	v_lshlrev_b32_e32 v142, 16, v69
	v_and_b32_e32 v143, 0xffff0000, v69
	v_lshlrev_b32_e32 v144, 16, v70
	v_and_b32_e32 v145, 0xffff0000, v70
	v_lshlrev_b32_e32 v146, 16, v71
	v_and_b32_e32 v147, 0xffff0000, v71
	v_lshlrev_b32_e32 v148, 16, v72
	v_and_b32_e32 v149, 0xffff0000, v72
	v_lshlrev_b32_e32 v150, 16, v73
	v_and_b32_e32 v151, 0xffff0000, v73
	v_lshlrev_b32_e32 v152, 16, v74
	v_and_b32_e32 v153, 0xffff0000, v74
	v_lshlrev_b32_e32 v154, 16, v75
	v_and_b32_e32 v155, 0xffff0000, v75
	v_pk_mul_f32 v[140:141], v[160:161], v[140:141] op_sel_hi:[0,1]
	v_pk_mul_f32 v[142:143], v[160:161], v[142:143] op_sel_hi:[0,1]
	v_pk_mul_f32 v[144:145], v[160:161], v[144:145] op_sel_hi:[0,1]
	v_pk_mul_f32 v[146:147], v[160:161], v[146:147] op_sel_hi:[0,1]
	v_pk_mul_f32 v[148:149], v[160:161], v[148:149] op_sel_hi:[0,1]
	v_pk_mul_f32 v[150:151], v[160:161], v[150:151] op_sel_hi:[0,1]
	v_pk_mul_f32 v[152:153], v[160:161], v[152:153] op_sel_hi:[0,1]
	v_pk_mul_f32 v[154:155], v[160:161], v[154:155] op_sel_hi:[0,1]
	v_pk_mul_f32 v[140:141], v[140:141], v[32:33]
	v_pk_mul_f32 v[142:143], v[142:143], v[34:35]
	v_pk_mul_f32 v[144:145], v[144:145], v[36:37]
	v_pk_mul_f32 v[146:147], v[146:147], v[38:39]
	v_pk_mul_f32 v[148:149], v[148:149], v[40:41]
	v_pk_mul_f32 v[150:151], v[150:151], v[42:43]
	v_pk_mul_f32 v[152:153], v[152:153], v[44:45]
	v_pk_mul_f32 v[154:155], v[154:155], v[46:47]
	v_pk_fma_f32 v[140:141], v[140:141], v[84:85], v[124:125]
	v_pk_fma_f32 v[142:143], v[142:143], v[86:87], v[126:127]
	v_pk_fma_f32 v[144:145], v[144:145], v[88:89], v[128:129]
	v_pk_fma_f32 v[146:147], v[146:147], v[90:91], v[130:131]
	v_pk_fma_f32 v[148:149], v[148:149], v[92:93], v[132:133]
	v_pk_fma_f32 v[150:151], v[150:151], v[94:95], v[134:135]
	v_pk_fma_f32 v[152:153], v[152:153], v[96:97], v[136:137]
	v_pk_fma_f32 v[154:155], v[154:155], v[98:99], v[138:139]
	v_cvt_pk_bf16_f32 v164, v140, v141
	v_cvt_pk_bf16_f32 v165, v142, v143
	v_cvt_pk_bf16_f32 v166, v144, v145
	v_cvt_pk_bf16_f32 v167, v146, v147
	v_cvt_pk_bf16_f32 v168, v148, v149
	v_cvt_pk_bf16_f32 v169, v150, v151
	v_cvt_pk_bf16_f32 v170, v152, v153
	v_cvt_pk_bf16_f32 v171, v154, v155
	global_store_dwordx4 v109, v[164:167], s[20:21]
	global_store_dwordx4 v109, v[168:171], s[20:21] offset:1024
	v_lshlrev_b32_e32 v140, 16, v76
	v_and_b32_e32 v141, 0xffff0000, v76
	v_lshlrev_b32_e32 v142, 16, v77
	v_and_b32_e32 v143, 0xffff0000, v77
	v_lshlrev_b32_e32 v144, 16, v78
	v_and_b32_e32 v145, 0xffff0000, v78
	v_lshlrev_b32_e32 v146, 16, v79
	v_and_b32_e32 v147, 0xffff0000, v79
	v_lshlrev_b32_e32 v148, 16, v80
	v_and_b32_e32 v149, 0xffff0000, v80
	v_lshlrev_b32_e32 v150, 16, v81
	v_and_b32_e32 v151, 0xffff0000, v81
	v_lshlrev_b32_e32 v152, 16, v82
	v_and_b32_e32 v153, 0xffff0000, v82
	v_lshlrev_b32_e32 v154, 16, v83
	v_and_b32_e32 v155, 0xffff0000, v83
	v_pk_mul_f32 v[140:141], v[162:163], v[140:141] op_sel_hi:[0,1]
	v_pk_mul_f32 v[142:143], v[162:163], v[142:143] op_sel_hi:[0,1]
	v_pk_mul_f32 v[144:145], v[162:163], v[144:145] op_sel_hi:[0,1]
	v_pk_mul_f32 v[146:147], v[162:163], v[146:147] op_sel_hi:[0,1]
	v_pk_mul_f32 v[148:149], v[162:163], v[148:149] op_sel_hi:[0,1]
	v_pk_mul_f32 v[150:151], v[162:163], v[150:151] op_sel_hi:[0,1]
	v_pk_mul_f32 v[152:153], v[162:163], v[152:153] op_sel_hi:[0,1]
	v_pk_mul_f32 v[154:155], v[162:163], v[154:155] op_sel_hi:[0,1]
	v_pk_mul_f32 v[140:141], v[140:141], v[32:33]
	v_pk_mul_f32 v[142:143], v[142:143], v[34:35]
	v_pk_mul_f32 v[144:145], v[144:145], v[36:37]
	v_pk_mul_f32 v[146:147], v[146:147], v[38:39]
	v_pk_mul_f32 v[148:149], v[148:149], v[40:41]
	v_pk_mul_f32 v[150:151], v[150:151], v[42:43]
	v_pk_mul_f32 v[152:153], v[152:153], v[44:45]
	v_pk_mul_f32 v[154:155], v[154:155], v[46:47]
	v_pk_fma_f32 v[140:141], v[140:141], v[84:85], v[124:125]
	v_pk_fma_f32 v[142:143], v[142:143], v[86:87], v[126:127]
	v_pk_fma_f32 v[144:145], v[144:145], v[88:89], v[128:129]
	v_pk_fma_f32 v[146:147], v[146:147], v[90:91], v[130:131]
	v_pk_fma_f32 v[148:149], v[148:149], v[92:93], v[132:133]
	v_pk_fma_f32 v[150:151], v[150:151], v[94:95], v[134:135]
	v_pk_fma_f32 v[152:153], v[152:153], v[96:97], v[136:137]
	v_pk_fma_f32 v[154:155], v[154:155], v[98:99], v[138:139]
	v_cvt_pk_bf16_f32 v172, v140, v141
	v_cvt_pk_bf16_f32 v173, v142, v143
	v_cvt_pk_bf16_f32 v174, v144, v145
	v_cvt_pk_bf16_f32 v175, v146, v147
	v_cvt_pk_bf16_f32 v176, v148, v149
	v_cvt_pk_bf16_f32 v177, v150, v151
	v_cvt_pk_bf16_f32 v178, v152, v153
	v_cvt_pk_bf16_f32 v179, v154, v155
	global_store_dwordx4 v109, v[172:175], s[20:21] offset:2048
	global_store_dwordx4 v109, v[176:179], s[20:21] offset:3072
	s_add_u32 s20, s20, 0x2000
	s_addc_u32 s21, s21, 0
	s_waitcnt vmcnt(8)
	v_lshlrev_b32_e32 v140, 16, v0
	v_and_b32_e32 v141, 0xffff0000, v0
	v_lshlrev_b32_e32 v142, 16, v1
	v_and_b32_e32 v143, 0xffff0000, v1
	v_lshlrev_b32_e32 v144, 16, v2
	v_and_b32_e32 v145, 0xffff0000, v2
	v_lshlrev_b32_e32 v146, 16, v3
	v_and_b32_e32 v147, 0xffff0000, v3
	v_lshlrev_b32_e32 v148, 16, v4
	v_and_b32_e32 v149, 0xffff0000, v4
	v_lshlrev_b32_e32 v150, 16, v5
	v_and_b32_e32 v151, 0xffff0000, v5
	v_lshlrev_b32_e32 v152, 16, v6
	v_and_b32_e32 v153, 0xffff0000, v6
	v_lshlrev_b32_e32 v154, 16, v7
	v_and_b32_e32 v155, 0xffff0000, v7
	v_pk_mul_f32 v[100:101], v[140:141], v[140:141]
	v_pk_fma_f32 v[100:101], v[142:143], v[142:143], v[100:101]
	v_pk_fma_f32 v[100:101], v[144:145], v[144:145], v[100:101]
	v_pk_fma_f32 v[100:101], v[146:147], v[146:147], v[100:101]
	v_pk_fma_f32 v[100:101], v[148:149], v[148:149], v[100:101]
	v_pk_fma_f32 v[100:101], v[150:151], v[150:151], v[100:101]
	v_pk_fma_f32 v[100:101], v[152:153], v[152:153], v[100:101]
	v_pk_fma_f32 v[100:101], v[154:155], v[154:155], v[100:101]
	v_lshlrev_b32_e32 v140, 16, v8
	v_and_b32_e32 v141, 0xffff0000, v8
	v_lshlrev_b32_e32 v142, 16, v9
	v_and_b32_e32 v143, 0xffff0000, v9
	v_lshlrev_b32_e32 v144, 16, v10
	v_and_b32_e32 v145, 0xffff0000, v10
	v_lshlrev_b32_e32 v146, 16, v11
	v_and_b32_e32 v147, 0xffff0000, v11
	v_lshlrev_b32_e32 v148, 16, v12
	v_and_b32_e32 v149, 0xffff0000, v12
	v_lshlrev_b32_e32 v150, 16, v13
	v_and_b32_e32 v151, 0xffff0000, v13
	v_lshlrev_b32_e32 v152, 16, v14
	v_and_b32_e32 v153, 0xffff0000, v14
	v_lshlrev_b32_e32 v154, 16, v15
	v_and_b32_e32 v155, 0xffff0000, v15
	v_pk_mul_f32 v[102:103], v[140:141], v[140:141]
	v_pk_fma_f32 v[102:103], v[142:143], v[142:143], v[102:103]
	v_pk_fma_f32 v[102:103], v[144:145], v[144:145], v[102:103]
	v_pk_fma_f32 v[102:103], v[146:147], v[146:147], v[102:103]
	v_pk_fma_f32 v[102:103], v[148:149], v[148:149], v[102:103]
	v_pk_fma_f32 v[102:103], v[150:151], v[150:151], v[102:103]
	v_pk_fma_f32 v[102:103], v[152:153], v[152:153], v[102:103]
	v_pk_fma_f32 v[102:103], v[154:155], v[154:155], v[102:103]
	v_lshlrev_b32_e32 v140, 16, v16
	v_and_b32_e32 v141, 0xffff0000, v16
	v_lshlrev_b32_e32 v142, 16, v17
	v_and_b32_e32 v143, 0xffff0000, v17
	v_lshlrev_b32_e32 v144, 16, v18
	v_and_b32_e32 v145, 0xffff0000, v18
	v_lshlrev_b32_e32 v146, 16, v19
	v_and_b32_e32 v147, 0xffff0000, v19
	v_lshlrev_b32_e32 v148, 16, v20
	v_and_b32_e32 v149, 0xffff0000, v20
	v_lshlrev_b32_e32 v150, 16, v21
	v_and_b32_e32 v151, 0xffff0000, v21
	v_lshlrev_b32_e32 v152, 16, v22
	v_and_b32_e32 v153, 0xffff0000, v22
	v_lshlrev_b32_e32 v154, 16, v23
	v_and_b32_e32 v155, 0xffff0000, v23
	v_pk_mul_f32 v[104:105], v[140:141], v[140:141]
	v_pk_fma_f32 v[104:105], v[142:143], v[142:143], v[104:105]
	v_pk_fma_f32 v[104:105], v[144:145], v[144:145], v[104:105]
	v_pk_fma_f32 v[104:105], v[146:147], v[146:147], v[104:105]
	v_pk_fma_f32 v[104:105], v[148:149], v[148:149], v[104:105]
	v_pk_fma_f32 v[104:105], v[150:151], v[150:151], v[104:105]
	v_pk_fma_f32 v[104:105], v[152:153], v[152:153], v[104:105]
	v_pk_fma_f32 v[104:105], v[154:155], v[154:155], v[104:105]
	v_lshlrev_b32_e32 v140, 16, v24
	v_and_b32_e32 v141, 0xffff0000, v24
	v_lshlrev_b32_e32 v142, 16, v25
	v_and_b32_e32 v143, 0xffff0000, v25
	v_lshlrev_b32_e32 v144, 16, v26
	v_and_b32_e32 v145, 0xffff0000, v26
	v_lshlrev_b32_e32 v146, 16, v27
	v_and_b32_e32 v147, 0xffff0000, v27
	v_lshlrev_b32_e32 v148, 16, v28
	v_and_b32_e32 v149, 0xffff0000, v28
	v_lshlrev_b32_e32 v150, 16, v29
	v_and_b32_e32 v151, 0xffff0000, v29
	v_lshlrev_b32_e32 v152, 16, v30
	v_and_b32_e32 v153, 0xffff0000, v30
	v_lshlrev_b32_e32 v154, 16, v31
	v_and_b32_e32 v155, 0xffff0000, v31
	v_pk_mul_f32 v[106:107], v[140:141], v[140:141]
	v_pk_fma_f32 v[106:107], v[142:143], v[142:143], v[106:107]
	v_pk_fma_f32 v[106:107], v[144:145], v[144:145], v[106:107]
	v_pk_fma_f32 v[106:107], v[146:147], v[146:147], v[106:107]
	v_pk_fma_f32 v[106:107], v[148:149], v[148:149], v[106:107]
	v_pk_fma_f32 v[106:107], v[150:151], v[150:151], v[106:107]
	v_pk_fma_f32 v[106:107], v[152:153], v[152:153], v[106:107]
	v_pk_fma_f32 v[106:107], v[154:155], v[154:155], v[106:107]
	v_add_f32_e32 v100, v100, v101
	v_add_f32_e32 v102, v102, v103
	v_add_f32_e32 v104, v104, v105
	v_add_f32_e32 v106, v106, v107
	s_nop 1
	v_add_f32_dpp v100, v100, v100 row_shr:1 row_mask:0xf bank_mask:0xf bound_ctrl:1
	v_add_f32_dpp v102, v102, v102 row_shr:1 row_mask:0xf bank_mask:0xf bound_ctrl:1
	v_add_f32_dpp v104, v104, v104 row_shr:1 row_mask:0xf bank_mask:0xf bound_ctrl:1
	v_add_f32_dpp v106, v106, v106 row_shr:1 row_mask:0xf bank_mask:0xf bound_ctrl:1
	v_add_f32_dpp v100, v100, v100 row_shr:2 row_mask:0xf bank_mask:0xf bound_ctrl:1
	v_add_f32_dpp v102, v102, v102 row_shr:2 row_mask:0xf bank_mask:0xf bound_ctrl:1
	v_add_f32_dpp v104, v104, v104 row_shr:2 row_mask:0xf bank_mask:0xf bound_ctrl:1
	v_add_f32_dpp v106, v106, v106 row_shr:2 row_mask:0xf bank_mask:0xf bound_ctrl:1
	v_add_f32_dpp v100, v100, v100 row_shr:4 row_mask:0xf bank_mask:0xf bound_ctrl:1
	v_add_f32_dpp v102, v102, v102 row_shr:4 row_mask:0xf bank_mask:0xf bound_ctrl:1
	v_add_f32_dpp v104, v104, v104 row_shr:4 row_mask:0xf bank_mask:0xf bound_ctrl:1
	v_add_f32_dpp v106, v106, v106 row_shr:4 row_mask:0xf bank_mask:0xf bound_ctrl:1
	v_add_f32_dpp v100, v100, v100 row_shr:8 row_mask:0xf bank_mask:0xf bound_ctrl:1
	v_add_f32_dpp v102, v102, v102 row_shr:8 row_mask:0xf bank_mask:0xf bound_ctrl:1
	v_add_f32_dpp v104, v104, v104 row_shr:8 row_mask:0xf bank_mask:0xf bound_ctrl:1
	v_add_f32_dpp v106, v106, v106 row_shr:8 row_mask:0xf bank_mask:0xf bound_ctrl:1
	v_add_f32_dpp v100, v100, v100 row_bcast:15 row_mask:0xa bank_mask:0xf
	v_add_f32_dpp v102, v102, v102 row_bcast:15 row_mask:0xa bank_mask:0xf
	v_add_f32_dpp v104, v104, v104 row_bcast:15 row_mask:0xa bank_mask:0xf
	v_add_f32_dpp v106, v106, v106 row_bcast:15 row_mask:0xa bank_mask:0xf
	v_add_f32_dpp v100, v100, v100 row_bcast:31 row_mask:0xc bank_mask:0xf
	v_add_f32_dpp v102, v102, v102 row_bcast:31 row_mask:0xc bank_mask:0xf
	v_add_f32_dpp v104, v104, v104 row_bcast:31 row_mask:0xc bank_mask:0xf
	v_add_f32_dpp v106, v106, v106 row_bcast:31 row_mask:0xc bank_mask:0xf
	s_nop 1
	v_readlane_b32 s5, v100, 63
	v_readlane_b32 s32, v102, 63
	v_readlane_b32 s54, v104, 63
	v_readlane_b32 s60, v106, 63
	s_nop 1
	v_mov_b32_e32 v156, s5
	v_mov_b32_e32 v158, s32
	v_mov_b32_e32 v160, s54
	v_mov_b32_e32 v162, s60
	v_fmaak_f32 v156, v156, v50, 0x358637bd
	v_fmaak_f32 v158, v158, v50, 0x358637bd
	v_fmaak_f32 v160, v160, v50, 0x358637bd
	v_fmaak_f32 v162, v162, v50, 0x358637bd
	v_rsq_f32_e32 v156, v156
	v_rsq_f32_e32 v158, v158
	v_rsq_f32_e32 v160, v160
	v_rsq_f32_e32 v162, v162
	s_nop 0
	v_lshlrev_b32_e32 v140, 16, v0
	v_and_b32_e32 v141, 0xffff0000, v0
	v_lshlrev_b32_e32 v142, 16, v1
	v_and_b32_e32 v143, 0xffff0000, v1
	v_lshlrev_b32_e32 v144, 16, v2
	v_and_b32_e32 v145, 0xffff0000, v2
	v_lshlrev_b32_e32 v146, 16, v3
	v_and_b32_e32 v147, 0xffff0000, v3
	v_lshlrev_b32_e32 v148, 16, v4
	v_and_b32_e32 v149, 0xffff0000, v4
	v_lshlrev_b32_e32 v150, 16, v5
	v_and_b32_e32 v151, 0xffff0000, v5
	v_lshlrev_b32_e32 v152, 16, v6
	v_and_b32_e32 v153, 0xffff0000, v6
	v_lshlrev_b32_e32 v154, 16, v7
	v_and_b32_e32 v155, 0xffff0000, v7
	v_pk_mul_f32 v[140:141], v[156:157], v[140:141] op_sel_hi:[0,1]
	v_pk_mul_f32 v[142:143], v[156:157], v[142:143] op_sel_hi:[0,1]
	v_pk_mul_f32 v[144:145], v[156:157], v[144:145] op_sel_hi:[0,1]
	v_pk_mul_f32 v[146:147], v[156:157], v[146:147] op_sel_hi:[0,1]
	v_pk_mul_f32 v[148:149], v[156:157], v[148:149] op_sel_hi:[0,1]
	v_pk_mul_f32 v[150:151], v[156:157], v[150:151] op_sel_hi:[0,1]
	v_pk_mul_f32 v[152:153], v[156:157], v[152:153] op_sel_hi:[0,1]
	v_pk_mul_f32 v[154:155], v[156:157], v[154:155] op_sel_hi:[0,1]
	v_pk_mul_f32 v[140:141], v[140:141], v[32:33]
	v_pk_mul_f32 v[142:143], v[142:143], v[34:35]
	v_pk_mul_f32 v[144:145], v[144:145], v[36:37]
	v_pk_mul_f32 v[146:147], v[146:147], v[38:39]
	v_pk_mul_f32 v[148:149], v[148:149], v[40:41]
	v_pk_mul_f32 v[150:151], v[150:151], v[42:43]
	v_pk_mul_f32 v[152:153], v[152:153], v[44:45]
	v_pk_mul_f32 v[154:155], v[154:155], v[46:47]
	v_pk_fma_f32 v[140:141], v[140:141], v[84:85], v[124:125]
	v_pk_fma_f32 v[142:143], v[142:143], v[86:87], v[126:127]
	v_pk_fma_f32 v[144:145], v[144:145], v[88:89], v[128:129]
	v_pk_fma_f32 v[146:147], v[146:147], v[90:91], v[130:131]
	v_pk_fma_f32 v[148:149], v[148:149], v[92:93], v[132:133]
	v_pk_fma_f32 v[150:151], v[150:151], v[94:95], v[134:135]
	v_pk_fma_f32 v[152:153], v[152:153], v[96:97], v[136:137]
	v_pk_fma_f32 v[154:155], v[154:155], v[98:99], v[138:139]
	v_cvt_pk_bf16_f32 v172, v140, v141
	v_cvt_pk_bf16_f32 v173, v142, v143
	v_cvt_pk_bf16_f32 v174, v144, v145
	v_cvt_pk_bf16_f32 v175, v146, v147
	v_cvt_pk_bf16_f32 v176, v148, v149
	v_cvt_pk_bf16_f32 v177, v150, v151
	v_cvt_pk_bf16_f32 v178, v152, v153
	v_cvt_pk_bf16_f32 v179, v154, v155
	global_store_dwordx4 v51, v[172:175], s[20:21]
	global_store_dwordx4 v51, v[176:179], s[20:21] offset:1024
	v_lshlrev_b32_e32 v140, 16, v8
	v_and_b32_e32 v141, 0xffff0000, v8
	v_lshlrev_b32_e32 v142, 16, v9
	v_and_b32_e32 v143, 0xffff0000, v9
	v_lshlrev_b32_e32 v144, 16, v10
	v_and_b32_e32 v145, 0xffff0000, v10
	v_lshlrev_b32_e32 v146, 16, v11
	v_and_b32_e32 v147, 0xffff0000, v11
	v_lshlrev_b32_e32 v148, 16, v12
	v_and_b32_e32 v149, 0xffff0000, v12
	v_lshlrev_b32_e32 v150, 16, v13
	v_and_b32_e32 v151, 0xffff0000, v13
	v_lshlrev_b32_e32 v152, 16, v14
	v_and_b32_e32 v153, 0xffff0000, v14
	v_lshlrev_b32_e32 v154, 16, v15
	v_and_b32_e32 v155, 0xffff0000, v15
	v_pk_mul_f32 v[140:141], v[158:159], v[140:141] op_sel_hi:[0,1]
	v_pk_mul_f32 v[142:143], v[158:159], v[142:143] op_sel_hi:[0,1]
	v_pk_mul_f32 v[144:145], v[158:159], v[144:145] op_sel_hi:[0,1]
	v_pk_mul_f32 v[146:147], v[158:159], v[146:147] op_sel_hi:[0,1]
	v_pk_mul_f32 v[148:149], v[158:159], v[148:149] op_sel_hi:[0,1]
	v_pk_mul_f32 v[150:151], v[158:159], v[150:151] op_sel_hi:[0,1]
	v_pk_mul_f32 v[152:153], v[158:159], v[152:153] op_sel_hi:[0,1]
	v_pk_mul_f32 v[154:155], v[158:159], v[154:155] op_sel_hi:[0,1]
	v_pk_mul_f32 v[140:141], v[140:141], v[32:33]
	v_pk_mul_f32 v[142:143], v[142:143], v[34:35]
	v_pk_mul_f32 v[144:145], v[144:145], v[36:37]
	v_pk_mul_f32 v[146:147], v[146:147], v[38:39]
	v_pk_mul_f32 v[148:149], v[148:149], v[40:41]
	v_pk_mul_f32 v[150:151], v[150:151], v[42:43]
	v_pk_mul_f32 v[152:153], v[152:153], v[44:45]
	v_pk_mul_f32 v[154:155], v[154:155], v[46:47]
	v_pk_fma_f32 v[140:141], v[140:141], v[84:85], v[124:125]
	v_pk_fma_f32 v[142:143], v[142:143], v[86:87], v[126:127]
	v_pk_fma_f32 v[144:145], v[144:145], v[88:89], v[128:129]
	v_pk_fma_f32 v[146:147], v[146:147], v[90:91], v[130:131]
	v_pk_fma_f32 v[148:149], v[148:149], v[92:93], v[132:133]
	v_pk_fma_f32 v[150:151], v[150:151], v[94:95], v[134:135]
	v_pk_fma_f32 v[152:153], v[152:153], v[96:97], v[136:137]
	v_pk_fma_f32 v[154:155], v[154:155], v[98:99], v[138:139]
	v_cvt_pk_bf16_f32 v164, v140, v141
	v_cvt_pk_bf16_f32 v165, v142, v143
	v_cvt_pk_bf16_f32 v166, v144, v145
	v_cvt_pk_bf16_f32 v167, v146, v147
	v_cvt_pk_bf16_f32 v168, v148, v149
	v_cvt_pk_bf16_f32 v169, v150, v151
	v_cvt_pk_bf16_f32 v170, v152, v153
	v_cvt_pk_bf16_f32 v171, v154, v155
	global_store_dwordx4 v51, v[164:167], s[20:21] offset:2048
	global_store_dwordx4 v51, v[168:171], s[20:21] offset:3072
	v_lshlrev_b32_e32 v140, 16, v16
	v_and_b32_e32 v141, 0xffff0000, v16
	v_lshlrev_b32_e32 v142, 16, v17
	v_and_b32_e32 v143, 0xffff0000, v17
	v_lshlrev_b32_e32 v144, 16, v18
	v_and_b32_e32 v145, 0xffff0000, v18
	v_lshlrev_b32_e32 v146, 16, v19
	v_and_b32_e32 v147, 0xffff0000, v19
	v_lshlrev_b32_e32 v148, 16, v20
	v_and_b32_e32 v149, 0xffff0000, v20
	v_lshlrev_b32_e32 v150, 16, v21
	v_and_b32_e32 v151, 0xffff0000, v21
	v_lshlrev_b32_e32 v152, 16, v22
	v_and_b32_e32 v153, 0xffff0000, v22
	v_lshlrev_b32_e32 v154, 16, v23
	v_and_b32_e32 v155, 0xffff0000, v23
	v_pk_mul_f32 v[140:141], v[160:161], v[140:141] op_sel_hi:[0,1]
	v_pk_mul_f32 v[142:143], v[160:161], v[142:143] op_sel_hi:[0,1]
	v_pk_mul_f32 v[144:145], v[160:161], v[144:145] op_sel_hi:[0,1]
	v_pk_mul_f32 v[146:147], v[160:161], v[146:147] op_sel_hi:[0,1]
	v_pk_mul_f32 v[148:149], v[160:161], v[148:149] op_sel_hi:[0,1]
	v_pk_mul_f32 v[150:151], v[160:161], v[150:151] op_sel_hi:[0,1]
	v_pk_mul_f32 v[152:153], v[160:161], v[152:153] op_sel_hi:[0,1]
	v_pk_mul_f32 v[154:155], v[160:161], v[154:155] op_sel_hi:[0,1]
	v_pk_mul_f32 v[140:141], v[140:141], v[32:33]
	v_pk_mul_f32 v[142:143], v[142:143], v[34:35]
	v_pk_mul_f32 v[144:145], v[144:145], v[36:37]
	v_pk_mul_f32 v[146:147], v[146:147], v[38:39]
	v_pk_mul_f32 v[148:149], v[148:149], v[40:41]
	v_pk_mul_f32 v[150:151], v[150:151], v[42:43]
	v_pk_mul_f32 v[152:153], v[152:153], v[44:45]
	v_pk_mul_f32 v[154:155], v[154:155], v[46:47]
	v_pk_fma_f32 v[140:141], v[140:141], v[84:85], v[124:125]
	v_pk_fma_f32 v[142:143], v[142:143], v[86:87], v[126:127]
	v_pk_fma_f32 v[144:145], v[144:145], v[88:89], v[128:129]
	v_pk_fma_f32 v[146:147], v[146:147], v[90:91], v[130:131]
	v_pk_fma_f32 v[148:149], v[148:149], v[92:93], v[132:133]
	v_pk_fma_f32 v[150:151], v[150:151], v[94:95], v[134:135]
	v_pk_fma_f32 v[152:153], v[152:153], v[96:97], v[136:137]
	v_pk_fma_f32 v[154:155], v[154:155], v[98:99], v[138:139]
	v_cvt_pk_bf16_f32 v172, v140, v141
	v_cvt_pk_bf16_f32 v173, v142, v143
	v_cvt_pk_bf16_f32 v174, v144, v145
	v_cvt_pk_bf16_f32 v175, v146, v147
	v_cvt_pk_bf16_f32 v176, v148, v149
	v_cvt_pk_bf16_f32 v177, v150, v151
	v_cvt_pk_bf16_f32 v178, v152, v153
	v_cvt_pk_bf16_f32 v179, v154, v155
	global_store_dwordx4 v109, v[172:175], s[20:21]
	global_store_dwordx4 v109, v[176:179], s[20:21] offset:1024
	v_lshlrev_b32_e32 v140, 16, v24
	v_and_b32_e32 v141, 0xffff0000, v24
	v_lshlrev_b32_e32 v142, 16, v25
	v_and_b32_e32 v143, 0xffff0000, v25
	v_lshlrev_b32_e32 v144, 16, v26
	v_and_b32_e32 v145, 0xffff0000, v26
	v_lshlrev_b32_e32 v146, 16, v27
	v_and_b32_e32 v147, 0xffff0000, v27
	v_lshlrev_b32_e32 v148, 16, v28
	v_and_b32_e32 v149, 0xffff0000, v28
	v_lshlrev_b32_e32 v150, 16, v29
	v_and_b32_e32 v151, 0xffff0000, v29
	v_lshlrev_b32_e32 v152, 16, v30
	v_and_b32_e32 v153, 0xffff0000, v30
	v_lshlrev_b32_e32 v154, 16, v31
	v_and_b32_e32 v155, 0xffff0000, v31
	v_pk_mul_f32 v[140:141], v[162:163], v[140:141] op_sel_hi:[0,1]
	v_pk_mul_f32 v[142:143], v[162:163], v[142:143] op_sel_hi:[0,1]
	v_pk_mul_f32 v[144:145], v[162:163], v[144:145] op_sel_hi:[0,1]
	v_pk_mul_f32 v[146:147], v[162:163], v[146:147] op_sel_hi:[0,1]
	v_pk_mul_f32 v[148:149], v[162:163], v[148:149] op_sel_hi:[0,1]
	v_pk_mul_f32 v[150:151], v[162:163], v[150:151] op_sel_hi:[0,1]
	v_pk_mul_f32 v[152:153], v[162:163], v[152:153] op_sel_hi:[0,1]
	v_pk_mul_f32 v[154:155], v[162:163], v[154:155] op_sel_hi:[0,1]
	v_pk_mul_f32 v[140:141], v[140:141], v[32:33]
	v_pk_mul_f32 v[142:143], v[142:143], v[34:35]
	v_pk_mul_f32 v[144:145], v[144:145], v[36:37]
	v_pk_mul_f32 v[146:147], v[146:147], v[38:39]
	v_pk_mul_f32 v[148:149], v[148:149], v[40:41]
	v_pk_mul_f32 v[150:151], v[150:151], v[42:43]
	v_pk_mul_f32 v[152:153], v[152:153], v[44:45]
	v_pk_mul_f32 v[154:155], v[154:155], v[46:47]
	v_pk_fma_f32 v[140:141], v[140:141], v[84:85], v[124:125]
	v_pk_fma_f32 v[142:143], v[142:143], v[86:87], v[126:127]
	v_pk_fma_f32 v[144:145], v[144:145], v[88:89], v[128:129]
	v_pk_fma_f32 v[146:147], v[146:147], v[90:91], v[130:131]
	v_pk_fma_f32 v[148:149], v[148:149], v[92:93], v[132:133]
	v_pk_fma_f32 v[150:151], v[150:151], v[94:95], v[134:135]
	v_pk_fma_f32 v[152:153], v[152:153], v[96:97], v[136:137]
	v_pk_fma_f32 v[154:155], v[154:155], v[98:99], v[138:139]
	v_cvt_pk_bf16_f32 v164, v140, v141
	v_cvt_pk_bf16_f32 v165, v142, v143
	v_cvt_pk_bf16_f32 v166, v144, v145
	v_cvt_pk_bf16_f32 v167, v146, v147
	v_cvt_pk_bf16_f32 v168, v148, v149
	v_cvt_pk_bf16_f32 v169, v150, v151
	v_cvt_pk_bf16_f32 v170, v152, v153
	v_cvt_pk_bf16_f32 v171, v154, v155
	global_store_dwordx4 v109, v[164:167], s[20:21] offset:2048
	global_store_dwordx4 v109, v[168:171], s[20:21] offset:3072
	s_add_u32 s20, s20, 0x2000
	s_addc_u32 s21, s21, 0
	s_branch .LBB0_1297
.Lnorm_P10_skip:
	global_load_dwordx4 v[32:35], v108, s[14:15]
	global_load_dwordx4 v[36:39], v108, s[14:15] offset:16
	global_load_dwordx4 v[40:43], v108, s[14:15] offset:2048
	global_load_dwordx4 v[44:47], v108, s[14:15] offset:2064
	s_mul_i32 s58, s23, 0x6000
	s_add_u32 s0, s16, s58
	s_addc_u32 s1, s17, 0
	s_add_u32 s14, s0, 0x1000
	s_addc_u32 s15, s1, 0
	global_load_dwordx4 v[124:127], v108, s[0:1]
	global_load_dwordx4 v[128:131], v108, s[0:1] offset:16
	global_load_dwordx4 v[132:135], v108, s[0:1] offset:2048
	global_load_dwordx4 v[136:139], v108, s[0:1] offset:2064
	global_load_dwordx4 v[84:87], v108, s[14:15]
	global_load_dwordx4 v[88:91], v108, s[14:15] offset:16
	global_load_dwordx4 v[92:95], v108, s[14:15] offset:2048
	global_load_dwordx4 v[96:99], v108, s[14:15] offset:2064
	s_lshl_b32 s58, s81, 11
	s_add_u32 s18, s6, s58
	s_addc_u32 s19, s7, 0
	s_add_u32 s20, s12, s58
	s_addc_u32 s21, s13, 0
	global_load_dwordx4 v[0:3], v51, s[18:19]
	global_load_dwordx4 v[4:7], v51, s[18:19] offset:1024
	global_load_dwordx4 v[8:11], v51, s[18:19] offset:2048
	global_load_dwordx4 v[12:15], v51, s[18:19] offset:3072
	global_load_dwordx4 v[16:19], v109, s[18:19]
	global_load_dwordx4 v[20:23], v109, s[18:19] offset:1024
	global_load_dwordx4 v[24:27], v109, s[18:19] offset:2048
	global_load_dwordx4 v[28:31], v109, s[18:19] offset:3072
	s_waitcnt vmcnt(0)
	v_pk_add_f32 v[84:85], v[84:85], 1.0 op_sel_hi:[1,0]
	v_pk_add_f32 v[86:87], v[86:87], 1.0 op_sel_hi:[1,0]
	v_pk_add_f32 v[88:89], v[88:89], 1.0 op_sel_hi:[1,0]
	v_pk_add_f32 v[90:91], v[90:91], 1.0 op_sel_hi:[1,0]
	v_pk_add_f32 v[92:93], v[92:93], 1.0 op_sel_hi:[1,0]
	v_pk_add_f32 v[94:95], v[94:95], 1.0 op_sel_hi:[1,0]
	v_pk_add_f32 v[96:97], v[96:97], 1.0 op_sel_hi:[1,0]
	v_pk_add_f32 v[98:99], v[98:99], 1.0 op_sel_hi:[1,0]
	s_add_u32 s18, s18, 0x2000
	s_addc_u32 s19, s19, 0
	global_load_dwordx4 v[52:55], v51, s[18:19]
	global_load_dwordx4 v[56:59], v51, s[18:19] offset:1024
	global_load_dwordx4 v[60:63], v51, s[18:19] offset:2048
	global_load_dwordx4 v[64:67], v51, s[18:19] offset:3072
	global_load_dwordx4 v[68:71], v109, s[18:19]
	global_load_dwordx4 v[72:75], v109, s[18:19] offset:1024
	global_load_dwordx4 v[76:79], v109, s[18:19] offset:2048
	global_load_dwordx4 v[80:83], v109, s[18:19] offset:3072
	v_lshlrev_b32_e32 v140, 16, v0
	v_and_b32_e32 v141, 0xffff0000, v0
	v_lshlrev_b32_e32 v142, 16, v1
	v_and_b32_e32 v143, 0xffff0000, v1
	v_lshlrev_b32_e32 v144, 16, v2
	v_and_b32_e32 v145, 0xffff0000, v2
	v_lshlrev_b32_e32 v146, 16, v3
	v_and_b32_e32 v147, 0xffff0000, v3
	v_lshlrev_b32_e32 v148, 16, v4
	v_and_b32_e32 v149, 0xffff0000, v4
	v_lshlrev_b32_e32 v150, 16, v5
	v_and_b32_e32 v151, 0xffff0000, v5
	v_lshlrev_b32_e32 v152, 16, v6
	v_and_b32_e32 v153, 0xffff0000, v6
	v_lshlrev_b32_e32 v154, 16, v7
	v_and_b32_e32 v155, 0xffff0000, v7
	v_pk_mul_f32 v[100:101], v[140:141], v[140:141]
	v_pk_fma_f32 v[100:101], v[142:143], v[142:143], v[100:101]
	v_pk_fma_f32 v[100:101], v[144:145], v[144:145], v[100:101]
	v_pk_fma_f32 v[100:101], v[146:147], v[146:147], v[100:101]
	v_pk_fma_f32 v[100:101], v[148:149], v[148:149], v[100:101]
	v_pk_fma_f32 v[100:101], v[150:151], v[150:151], v[100:101]
	v_pk_fma_f32 v[100:101], v[152:153], v[152:153], v[100:101]
	v_pk_fma_f32 v[100:101], v[154:155], v[154:155], v[100:101]
	v_lshlrev_b32_e32 v140, 16, v8
	v_and_b32_e32 v141, 0xffff0000, v8
	v_lshlrev_b32_e32 v142, 16, v9
	v_and_b32_e32 v143, 0xffff0000, v9
	v_lshlrev_b32_e32 v144, 16, v10
	v_and_b32_e32 v145, 0xffff0000, v10
	v_lshlrev_b32_e32 v146, 16, v11
	v_and_b32_e32 v147, 0xffff0000, v11
	v_lshlrev_b32_e32 v148, 16, v12
	v_and_b32_e32 v149, 0xffff0000, v12
	v_lshlrev_b32_e32 v150, 16, v13
	v_and_b32_e32 v151, 0xffff0000, v13
	v_lshlrev_b32_e32 v152, 16, v14
	v_and_b32_e32 v153, 0xffff0000, v14
	v_lshlrev_b32_e32 v154, 16, v15
	v_and_b32_e32 v155, 0xffff0000, v15
	v_pk_mul_f32 v[102:103], v[140:141], v[140:141]
	v_pk_fma_f32 v[102:103], v[142:143], v[142:143], v[102:103]
	v_pk_fma_f32 v[102:103], v[144:145], v[144:145], v[102:103]
	v_pk_fma_f32 v[102:103], v[146:147], v[146:147], v[102:103]
	v_pk_fma_f32 v[102:103], v[148:149], v[148:149], v[102:103]
	v_pk_fma_f32 v[102:103], v[150:151], v[150:151], v[102:103]
	v_pk_fma_f32 v[102:103], v[152:153], v[152:153], v[102:103]
	v_pk_fma_f32 v[102:103], v[154:155], v[154:155], v[102:103]
	v_lshlrev_b32_e32 v140, 16, v16
	v_and_b32_e32 v141, 0xffff0000, v16
	v_lshlrev_b32_e32 v142, 16, v17
	v_and_b32_e32 v143, 0xffff0000, v17
	v_lshlrev_b32_e32 v144, 16, v18
	v_and_b32_e32 v145, 0xffff0000, v18
	v_lshlrev_b32_e32 v146, 16, v19
	v_and_b32_e32 v147, 0xffff0000, v19
	v_lshlrev_b32_e32 v148, 16, v20
	v_and_b32_e32 v149, 0xffff0000, v20
	v_lshlrev_b32_e32 v150, 16, v21
	v_and_b32_e32 v151, 0xffff0000, v21
	v_lshlrev_b32_e32 v152, 16, v22
	v_and_b32_e32 v153, 0xffff0000, v22
	v_lshlrev_b32_e32 v154, 16, v23
	v_and_b32_e32 v155, 0xffff0000, v23
	v_pk_mul_f32 v[104:105], v[140:141], v[140:141]
	v_pk_fma_f32 v[104:105], v[142:143], v[142:143], v[104:105]
	v_pk_fma_f32 v[104:105], v[144:145], v[144:145], v[104:105]
	v_pk_fma_f32 v[104:105], v[146:147], v[146:147], v[104:105]
	v_pk_fma_f32 v[104:105], v[148:149], v[148:149], v[104:105]
	v_pk_fma_f32 v[104:105], v[150:151], v[150:151], v[104:105]
	v_pk_fma_f32 v[104:105], v[152:153], v[152:153], v[104:105]
	v_pk_fma_f32 v[104:105], v[154:155], v[154:155], v[104:105]
	v_lshlrev_b32_e32 v140, 16, v24
	v_and_b32_e32 v141, 0xffff0000, v24
	v_lshlrev_b32_e32 v142, 16, v25
	v_and_b32_e32 v143, 0xffff0000, v25
	v_lshlrev_b32_e32 v144, 16, v26
	v_and_b32_e32 v145, 0xffff0000, v26
	v_lshlrev_b32_e32 v146, 16, v27
	v_and_b32_e32 v147, 0xffff0000, v27
	v_lshlrev_b32_e32 v148, 16, v28
	v_and_b32_e32 v149, 0xffff0000, v28
	v_lshlrev_b32_e32 v150, 16, v29
	v_and_b32_e32 v151, 0xffff0000, v29
	v_lshlrev_b32_e32 v152, 16, v30
	v_and_b32_e32 v153, 0xffff0000, v30
	v_lshlrev_b32_e32 v154, 16, v31
	v_and_b32_e32 v155, 0xffff0000, v31
	v_pk_mul_f32 v[106:107], v[140:141], v[140:141]
	v_pk_fma_f32 v[106:107], v[142:143], v[142:143], v[106:107]
	v_pk_fma_f32 v[106:107], v[144:145], v[144:145], v[106:107]
	v_pk_fma_f32 v[106:107], v[146:147], v[146:147], v[106:107]
	v_pk_fma_f32 v[106:107], v[148:149], v[148:149], v[106:107]
	v_pk_fma_f32 v[106:107], v[150:151], v[150:151], v[106:107]
	v_pk_fma_f32 v[106:107], v[152:153], v[152:153], v[106:107]
	v_pk_fma_f32 v[106:107], v[154:155], v[154:155], v[106:107]
	v_add_f32_e32 v100, v100, v101
	v_add_f32_e32 v102, v102, v103
	v_add_f32_e32 v104, v104, v105
	v_add_f32_e32 v106, v106, v107
	s_nop 1
	v_add_f32_dpp v100, v100, v100 row_shr:1 row_mask:0xf bank_mask:0xf bound_ctrl:1
	v_add_f32_dpp v102, v102, v102 row_shr:1 row_mask:0xf bank_mask:0xf bound_ctrl:1
	v_add_f32_dpp v104, v104, v104 row_shr:1 row_mask:0xf bank_mask:0xf bound_ctrl:1
	v_add_f32_dpp v106, v106, v106 row_shr:1 row_mask:0xf bank_mask:0xf bound_ctrl:1
	v_add_f32_dpp v100, v100, v100 row_shr:2 row_mask:0xf bank_mask:0xf bound_ctrl:1
	v_add_f32_dpp v102, v102, v102 row_shr:2 row_mask:0xf bank_mask:0xf bound_ctrl:1
	v_add_f32_dpp v104, v104, v104 row_shr:2 row_mask:0xf bank_mask:0xf bound_ctrl:1
	v_add_f32_dpp v106, v106, v106 row_shr:2 row_mask:0xf bank_mask:0xf bound_ctrl:1
	v_add_f32_dpp v100, v100, v100 row_shr:4 row_mask:0xf bank_mask:0xf bound_ctrl:1
	v_add_f32_dpp v102, v102, v102 row_shr:4 row_mask:0xf bank_mask:0xf bound_ctrl:1
	v_add_f32_dpp v104, v104, v104 row_shr:4 row_mask:0xf bank_mask:0xf bound_ctrl:1
	v_add_f32_dpp v106, v106, v106 row_shr:4 row_mask:0xf bank_mask:0xf bound_ctrl:1
	v_add_f32_dpp v100, v100, v100 row_shr:8 row_mask:0xf bank_mask:0xf bound_ctrl:1
	v_add_f32_dpp v102, v102, v102 row_shr:8 row_mask:0xf bank_mask:0xf bound_ctrl:1
	v_add_f32_dpp v104, v104, v104 row_shr:8 row_mask:0xf bank_mask:0xf bound_ctrl:1
	v_add_f32_dpp v106, v106, v106 row_shr:8 row_mask:0xf bank_mask:0xf bound_ctrl:1
	v_add_f32_dpp v100, v100, v100 row_bcast:15 row_mask:0xa bank_mask:0xf
	v_add_f32_dpp v102, v102, v102 row_bcast:15 row_mask:0xa bank_mask:0xf
	v_add_f32_dpp v104, v104, v104 row_bcast:15 row_mask:0xa bank_mask:0xf
	v_add_f32_dpp v106, v106, v106 row_bcast:15 row_mask:0xa bank_mask:0xf
	v_add_f32_dpp v100, v100, v100 row_bcast:31 row_mask:0xc bank_mask:0xf
	v_add_f32_dpp v102, v102, v102 row_bcast:31 row_mask:0xc bank_mask:0xf
	v_add_f32_dpp v104, v104, v104 row_bcast:31 row_mask:0xc bank_mask:0xf
	v_add_f32_dpp v106, v106, v106 row_bcast:31 row_mask:0xc bank_mask:0xf
	s_nop 1
	v_readlane_b32 s5, v100, 63
	v_readlane_b32 s32, v102, 63
	v_readlane_b32 s54, v104, 63
	v_readlane_b32 s60, v106, 63
	s_nop 1
	v_mov_b32_e32 v156, s5
	v_mov_b32_e32 v158, s32
	v_mov_b32_e32 v160, s54
	v_mov_b32_e32 v162, s60
	v_fmaak_f32 v156, v156, v50, 0x358637bd
	v_fmaak_f32 v158, v158, v50, 0x358637bd
	v_fmaak_f32 v160, v160, v50, 0x358637bd
	v_fmaak_f32 v162, v162, v50, 0x358637bd
	v_rsq_f32_e32 v156, v156
	v_rsq_f32_e32 v158, v158
	v_rsq_f32_e32 v160, v160
	v_rsq_f32_e32 v162, v162
	s_nop 0
	v_lshlrev_b32_e32 v140, 16, v0
	v_and_b32_e32 v141, 0xffff0000, v0
	v_lshlrev_b32_e32 v142, 16, v1
	v_and_b32_e32 v143, 0xffff0000, v1
	v_lshlrev_b32_e32 v144, 16, v2
	v_and_b32_e32 v145, 0xffff0000, v2
	v_lshlrev_b32_e32 v146, 16, v3
	v_and_b32_e32 v147, 0xffff0000, v3
	v_lshlrev_b32_e32 v148, 16, v4
	v_and_b32_e32 v149, 0xffff0000, v4
	v_lshlrev_b32_e32 v150, 16, v5
	v_and_b32_e32 v151, 0xffff0000, v5
	v_lshlrev_b32_e32 v152, 16, v6
	v_and_b32_e32 v153, 0xffff0000, v6
	v_lshlrev_b32_e32 v154, 16, v7
	v_and_b32_e32 v155, 0xffff0000, v7
	v_pk_mul_f32 v[140:141], v[156:157], v[140:141] op_sel_hi:[0,1]
	v_pk_mul_f32 v[142:143], v[156:157], v[142:143] op_sel_hi:[0,1]
	v_pk_mul_f32 v[144:145], v[156:157], v[144:145] op_sel_hi:[0,1]
	v_pk_mul_f32 v[146:147], v[156:157], v[146:147] op_sel_hi:[0,1]
	v_pk_mul_f32 v[148:149], v[156:157], v[148:149] op_sel_hi:[0,1]
	v_pk_mul_f32 v[150:151], v[156:157], v[150:151] op_sel_hi:[0,1]
	v_pk_mul_f32 v[152:153], v[156:157], v[152:153] op_sel_hi:[0,1]
	v_pk_mul_f32 v[154:155], v[156:157], v[154:155] op_sel_hi:[0,1]
	v_pk_mul_f32 v[140:141], v[140:141], v[32:33]
	v_pk_mul_f32 v[142:143], v[142:143], v[34:35]
	v_pk_mul_f32 v[144:145], v[144:145], v[36:37]
	v_pk_mul_f32 v[146:147], v[146:147], v[38:39]
	v_pk_mul_f32 v[148:149], v[148:149], v[40:41]
	v_pk_mul_f32 v[150:151], v[150:151], v[42:43]
	v_pk_mul_f32 v[152:153], v[152:153], v[44:45]
	v_pk_mul_f32 v[154:155], v[154:155], v[46:47]
	v_pk_fma_f32 v[140:141], v[140:141], v[84:85], v[124:125]
	v_pk_fma_f32 v[142:143], v[142:143], v[86:87], v[126:127]
	v_pk_fma_f32 v[144:145], v[144:145], v[88:89], v[128:129]
	v_pk_fma_f32 v[146:147], v[146:147], v[90:91], v[130:131]
	v_pk_fma_f32 v[148:149], v[148:149], v[92:93], v[132:133]
	v_pk_fma_f32 v[150:151], v[150:151], v[94:95], v[134:135]
	v_pk_fma_f32 v[152:153], v[152:153], v[96:97], v[136:137]
	v_pk_fma_f32 v[154:155], v[154:155], v[98:99], v[138:139]
	v_cvt_pk_bf16_f32 v164, v140, v141
	v_cvt_pk_bf16_f32 v165, v142, v143
	v_cvt_pk_bf16_f32 v166, v144, v145
	v_cvt_pk_bf16_f32 v167, v146, v147
	v_cvt_pk_bf16_f32 v168, v148, v149
	v_cvt_pk_bf16_f32 v169, v150, v151
	v_cvt_pk_bf16_f32 v170, v152, v153
	v_cvt_pk_bf16_f32 v171, v154, v155
	global_store_dwordx4 v51, v[164:167], s[20:21]
	global_store_dwordx4 v51, v[168:171], s[20:21] offset:1024
	v_lshlrev_b32_e32 v140, 16, v8
	v_and_b32_e32 v141, 0xffff0000, v8
	v_lshlrev_b32_e32 v142, 16, v9
	v_and_b32_e32 v143, 0xffff0000, v9
	v_lshlrev_b32_e32 v144, 16, v10
	v_and_b32_e32 v145, 0xffff0000, v10
	v_lshlrev_b32_e32 v146, 16, v11
	v_and_b32_e32 v147, 0xffff0000, v11
	v_lshlrev_b32_e32 v148, 16, v12
	v_and_b32_e32 v149, 0xffff0000, v12
	v_lshlrev_b32_e32 v150, 16, v13
	v_and_b32_e32 v151, 0xffff0000, v13
	v_lshlrev_b32_e32 v152, 16, v14
	v_and_b32_e32 v153, 0xffff0000, v14
	v_lshlrev_b32_e32 v154, 16, v15
	v_and_b32_e32 v155, 0xffff0000, v15
	v_pk_mul_f32 v[140:141], v[158:159], v[140:141] op_sel_hi:[0,1]
	v_pk_mul_f32 v[142:143], v[158:159], v[142:143] op_sel_hi:[0,1]
	v_pk_mul_f32 v[144:145], v[158:159], v[144:145] op_sel_hi:[0,1]
	v_pk_mul_f32 v[146:147], v[158:159], v[146:147] op_sel_hi:[0,1]
	v_pk_mul_f32 v[148:149], v[158:159], v[148:149] op_sel_hi:[0,1]
	v_pk_mul_f32 v[150:151], v[158:159], v[150:151] op_sel_hi:[0,1]
	v_pk_mul_f32 v[152:153], v[158:159], v[152:153] op_sel_hi:[0,1]
	v_pk_mul_f32 v[154:155], v[158:159], v[154:155] op_sel_hi:[0,1]
	v_pk_mul_f32 v[140:141], v[140:141], v[32:33]
	v_pk_mul_f32 v[142:143], v[142:143], v[34:35]
	v_pk_mul_f32 v[144:145], v[144:145], v[36:37]
	v_pk_mul_f32 v[146:147], v[146:147], v[38:39]
	v_pk_mul_f32 v[148:149], v[148:149], v[40:41]
	v_pk_mul_f32 v[150:151], v[150:151], v[42:43]
	v_pk_mul_f32 v[152:153], v[152:153], v[44:45]
	v_pk_mul_f32 v[154:155], v[154:155], v[46:47]
	v_pk_fma_f32 v[140:141], v[140:141], v[84:85], v[124:125]
	v_pk_fma_f32 v[142:143], v[142:143], v[86:87], v[126:127]
	v_pk_fma_f32 v[144:145], v[144:145], v[88:89], v[128:129]
	v_pk_fma_f32 v[146:147], v[146:147], v[90:91], v[130:131]
	v_pk_fma_f32 v[148:149], v[148:149], v[92:93], v[132:133]
	v_pk_fma_f32 v[150:151], v[150:151], v[94:95], v[134:135]
	v_pk_fma_f32 v[152:153], v[152:153], v[96:97], v[136:137]
	v_pk_fma_f32 v[154:155], v[154:155], v[98:99], v[138:139]
	v_cvt_pk_bf16_f32 v172, v140, v141
	v_cvt_pk_bf16_f32 v173, v142, v143
	v_cvt_pk_bf16_f32 v174, v144, v145
	v_cvt_pk_bf16_f32 v175, v146, v147
	v_cvt_pk_bf16_f32 v176, v148, v149
	v_cvt_pk_bf16_f32 v177, v150, v151
	v_cvt_pk_bf16_f32 v178, v152, v153
	v_cvt_pk_bf16_f32 v179, v154, v155
	global_store_dwordx4 v51, v[172:175], s[20:21] offset:2048
	global_store_dwordx4 v51, v[176:179], s[20:21] offset:3072
	v_lshlrev_b32_e32 v140, 16, v16
	v_and_b32_e32 v141, 0xffff0000, v16
	v_lshlrev_b32_e32 v142, 16, v17
	v_and_b32_e32 v143, 0xffff0000, v17
	v_lshlrev_b32_e32 v144, 16, v18
	v_and_b32_e32 v145, 0xffff0000, v18
	v_lshlrev_b32_e32 v146, 16, v19
	v_and_b32_e32 v147, 0xffff0000, v19
	v_lshlrev_b32_e32 v148, 16, v20
	v_and_b32_e32 v149, 0xffff0000, v20
	v_lshlrev_b32_e32 v150, 16, v21
	v_and_b32_e32 v151, 0xffff0000, v21
	v_lshlrev_b32_e32 v152, 16, v22
	v_and_b32_e32 v153, 0xffff0000, v22
	v_lshlrev_b32_e32 v154, 16, v23
	v_and_b32_e32 v155, 0xffff0000, v23
	v_pk_mul_f32 v[140:141], v[160:161], v[140:141] op_sel_hi:[0,1]
	v_pk_mul_f32 v[142:143], v[160:161], v[142:143] op_sel_hi:[0,1]
	v_pk_mul_f32 v[144:145], v[160:161], v[144:145] op_sel_hi:[0,1]
	v_pk_mul_f32 v[146:147], v[160:161], v[146:147] op_sel_hi:[0,1]
	v_pk_mul_f32 v[148:149], v[160:161], v[148:149] op_sel_hi:[0,1]
	v_pk_mul_f32 v[150:151], v[160:161], v[150:151] op_sel_hi:[0,1]
	v_pk_mul_f32 v[152:153], v[160:161], v[152:153] op_sel_hi:[0,1]
	v_pk_mul_f32 v[154:155], v[160:161], v[154:155] op_sel_hi:[0,1]
	v_pk_mul_f32 v[140:141], v[140:141], v[32:33]
	v_pk_mul_f32 v[142:143], v[142:143], v[34:35]
	v_pk_mul_f32 v[144:145], v[144:145], v[36:37]
	v_pk_mul_f32 v[146:147], v[146:147], v[38:39]
	v_pk_mul_f32 v[148:149], v[148:149], v[40:41]
	v_pk_mul_f32 v[150:151], v[150:151], v[42:43]
	v_pk_mul_f32 v[152:153], v[152:153], v[44:45]
	v_pk_mul_f32 v[154:155], v[154:155], v[46:47]
	v_pk_fma_f32 v[140:141], v[140:141], v[84:85], v[124:125]
	v_pk_fma_f32 v[142:143], v[142:143], v[86:87], v[126:127]
	v_pk_fma_f32 v[144:145], v[144:145], v[88:89], v[128:129]
	v_pk_fma_f32 v[146:147], v[146:147], v[90:91], v[130:131]
	v_pk_fma_f32 v[148:149], v[148:149], v[92:93], v[132:133]
	v_pk_fma_f32 v[150:151], v[150:151], v[94:95], v[134:135]
	v_pk_fma_f32 v[152:153], v[152:153], v[96:97], v[136:137]
	v_pk_fma_f32 v[154:155], v[154:155], v[98:99], v[138:139]
	v_cvt_pk_bf16_f32 v164, v140, v141
	v_cvt_pk_bf16_f32 v165, v142, v143
	v_cvt_pk_bf16_f32 v166, v144, v145
	v_cvt_pk_bf16_f32 v167, v146, v147
	v_cvt_pk_bf16_f32 v168, v148, v149
	v_cvt_pk_bf16_f32 v169, v150, v151
	v_cvt_pk_bf16_f32 v170, v152, v153
	v_cvt_pk_bf16_f32 v171, v154, v155
	global_store_dwordx4 v109, v[164:167], s[20:21]
	global_store_dwordx4 v109, v[168:171], s[20:21] offset:1024
	v_lshlrev_b32_e32 v140, 16, v24
	v_and_b32_e32 v141, 0xffff0000, v24
	v_lshlrev_b32_e32 v142, 16, v25
	v_and_b32_e32 v143, 0xffff0000, v25
	v_lshlrev_b32_e32 v144, 16, v26
	v_and_b32_e32 v145, 0xffff0000, v26
	v_lshlrev_b32_e32 v146, 16, v27
	v_and_b32_e32 v147, 0xffff0000, v27
	v_lshlrev_b32_e32 v148, 16, v28
	v_and_b32_e32 v149, 0xffff0000, v28
	v_lshlrev_b32_e32 v150, 16, v29
	v_and_b32_e32 v151, 0xffff0000, v29
	v_lshlrev_b32_e32 v152, 16, v30
	v_and_b32_e32 v153, 0xffff0000, v30
	v_lshlrev_b32_e32 v154, 16, v31
	v_and_b32_e32 v155, 0xffff0000, v31
	v_pk_mul_f32 v[140:141], v[162:163], v[140:141] op_sel_hi:[0,1]
	v_pk_mul_f32 v[142:143], v[162:163], v[142:143] op_sel_hi:[0,1]
	v_pk_mul_f32 v[144:145], v[162:163], v[144:145] op_sel_hi:[0,1]
	v_pk_mul_f32 v[146:147], v[162:163], v[146:147] op_sel_hi:[0,1]
	v_pk_mul_f32 v[148:149], v[162:163], v[148:149] op_sel_hi:[0,1]
	v_pk_mul_f32 v[150:151], v[162:163], v[150:151] op_sel_hi:[0,1]
	v_pk_mul_f32 v[152:153], v[162:163], v[152:153] op_sel_hi:[0,1]
	v_pk_mul_f32 v[154:155], v[162:163], v[154:155] op_sel_hi:[0,1]
	v_pk_mul_f32 v[140:141], v[140:141], v[32:33]
	v_pk_mul_f32 v[142:143], v[142:143], v[34:35]
	v_pk_mul_f32 v[144:145], v[144:145], v[36:37]
	v_pk_mul_f32 v[146:147], v[146:147], v[38:39]
	v_pk_mul_f32 v[148:149], v[148:149], v[40:41]
	v_pk_mul_f32 v[150:151], v[150:151], v[42:43]
	v_pk_mul_f32 v[152:153], v[152:153], v[44:45]
	v_pk_mul_f32 v[154:155], v[154:155], v[46:47]
	v_pk_fma_f32 v[140:141], v[140:141], v[84:85], v[124:125]
	v_pk_fma_f32 v[142:143], v[142:143], v[86:87], v[126:127]
	v_pk_fma_f32 v[144:145], v[144:145], v[88:89], v[128:129]
	v_pk_fma_f32 v[146:147], v[146:147], v[90:91], v[130:131]
	v_pk_fma_f32 v[148:149], v[148:149], v[92:93], v[132:133]
	v_pk_fma_f32 v[150:151], v[150:151], v[94:95], v[134:135]
	v_pk_fma_f32 v[152:153], v[152:153], v[96:97], v[136:137]
	v_pk_fma_f32 v[154:155], v[154:155], v[98:99], v[138:139]
	v_cvt_pk_bf16_f32 v172, v140, v141
	v_cvt_pk_bf16_f32 v173, v142, v143
	v_cvt_pk_bf16_f32 v174, v144, v145
	v_cvt_pk_bf16_f32 v175, v146, v147
	v_cvt_pk_bf16_f32 v176, v148, v149
	v_cvt_pk_bf16_f32 v177, v150, v151
	v_cvt_pk_bf16_f32 v178, v152, v153
	v_cvt_pk_bf16_f32 v179, v154, v155
	global_store_dwordx4 v109, v[172:175], s[20:21] offset:2048
	global_store_dwordx4 v109, v[176:179], s[20:21] offset:3072
	s_add_u32 s20, s20, 0x2000
	s_addc_u32 s21, s21, 0
	s_add_u32 s18, s18, 0x2000
	s_addc_u32 s19, s19, 0
	global_load_dwordx4 v[0:3], v51, s[18:19]
	global_load_dwordx4 v[4:7], v51, s[18:19] offset:1024
	global_load_dwordx4 v[8:11], v51, s[18:19] offset:2048
	global_load_dwordx4 v[12:15], v51, s[18:19] offset:3072
	global_load_dwordx4 v[16:19], v109, s[18:19]
	global_load_dwordx4 v[20:23], v109, s[18:19] offset:1024
	global_load_dwordx4 v[24:27], v109, s[18:19] offset:2048
	global_load_dwordx4 v[28:31], v109, s[18:19] offset:3072
	s_waitcnt vmcnt(16)
	v_lshlrev_b32_e32 v140, 16, v52
	v_and_b32_e32 v141, 0xffff0000, v52
	v_lshlrev_b32_e32 v142, 16, v53
	v_and_b32_e32 v143, 0xffff0000, v53
	v_lshlrev_b32_e32 v144, 16, v54
	v_and_b32_e32 v145, 0xffff0000, v54
	v_lshlrev_b32_e32 v146, 16, v55
	v_and_b32_e32 v147, 0xffff0000, v55
	v_lshlrev_b32_e32 v148, 16, v56
	v_and_b32_e32 v149, 0xffff0000, v56
	v_lshlrev_b32_e32 v150, 16, v57
	v_and_b32_e32 v151, 0xffff0000, v57
	v_lshlrev_b32_e32 v152, 16, v58
	v_and_b32_e32 v153, 0xffff0000, v58
	v_lshlrev_b32_e32 v154, 16, v59
	v_and_b32_e32 v155, 0xffff0000, v59
	v_pk_mul_f32 v[100:101], v[140:141], v[140:141]
	v_pk_fma_f32 v[100:101], v[142:143], v[142:143], v[100:101]
	v_pk_fma_f32 v[100:101], v[144:145], v[144:145], v[100:101]
	v_pk_fma_f32 v[100:101], v[146:147], v[146:147], v[100:101]
	v_pk_fma_f32 v[100:101], v[148:149], v[148:149], v[100:101]
	v_pk_fma_f32 v[100:101], v[150:151], v[150:151], v[100:101]
	v_pk_fma_f32 v[100:101], v[152:153], v[152:153], v[100:101]
	v_pk_fma_f32 v[100:101], v[154:155], v[154:155], v[100:101]
	v_lshlrev_b32_e32 v140, 16, v60
	v_and_b32_e32 v141, 0xffff0000, v60
	v_lshlrev_b32_e32 v142, 16, v61
	v_and_b32_e32 v143, 0xffff0000, v61
	v_lshlrev_b32_e32 v144, 16, v62
	v_and_b32_e32 v145, 0xffff0000, v62
	v_lshlrev_b32_e32 v146, 16, v63
	v_and_b32_e32 v147, 0xffff0000, v63
	v_lshlrev_b32_e32 v148, 16, v64
	v_and_b32_e32 v149, 0xffff0000, v64
	v_lshlrev_b32_e32 v150, 16, v65
	v_and_b32_e32 v151, 0xffff0000, v65
	v_lshlrev_b32_e32 v152, 16, v66
	v_and_b32_e32 v153, 0xffff0000, v66
	v_lshlrev_b32_e32 v154, 16, v67
	v_and_b32_e32 v155, 0xffff0000, v67
	v_pk_mul_f32 v[102:103], v[140:141], v[140:141]
	v_pk_fma_f32 v[102:103], v[142:143], v[142:143], v[102:103]
	v_pk_fma_f32 v[102:103], v[144:145], v[144:145], v[102:103]
	v_pk_fma_f32 v[102:103], v[146:147], v[146:147], v[102:103]
	v_pk_fma_f32 v[102:103], v[148:149], v[148:149], v[102:103]
	v_pk_fma_f32 v[102:103], v[150:151], v[150:151], v[102:103]
	v_pk_fma_f32 v[102:103], v[152:153], v[152:153], v[102:103]
	v_pk_fma_f32 v[102:103], v[154:155], v[154:155], v[102:103]
	v_lshlrev_b32_e32 v140, 16, v68
	v_and_b32_e32 v141, 0xffff0000, v68
	v_lshlrev_b32_e32 v142, 16, v69
	v_and_b32_e32 v143, 0xffff0000, v69
	v_lshlrev_b32_e32 v144, 16, v70
	v_and_b32_e32 v145, 0xffff0000, v70
	v_lshlrev_b32_e32 v146, 16, v71
	v_and_b32_e32 v147, 0xffff0000, v71
	v_lshlrev_b32_e32 v148, 16, v72
	v_and_b32_e32 v149, 0xffff0000, v72
	v_lshlrev_b32_e32 v150, 16, v73
	v_and_b32_e32 v151, 0xffff0000, v73
	v_lshlrev_b32_e32 v152, 16, v74
	v_and_b32_e32 v153, 0xffff0000, v74
	v_lshlrev_b32_e32 v154, 16, v75
	v_and_b32_e32 v155, 0xffff0000, v75
	v_pk_mul_f32 v[104:105], v[140:141], v[140:141]
	v_pk_fma_f32 v[104:105], v[142:143], v[142:143], v[104:105]
	v_pk_fma_f32 v[104:105], v[144:145], v[144:145], v[104:105]
	v_pk_fma_f32 v[104:105], v[146:147], v[146:147], v[104:105]
	v_pk_fma_f32 v[104:105], v[148:149], v[148:149], v[104:105]
	v_pk_fma_f32 v[104:105], v[150:151], v[150:151], v[104:105]
	v_pk_fma_f32 v[104:105], v[152:153], v[152:153], v[104:105]
	v_pk_fma_f32 v[104:105], v[154:155], v[154:155], v[104:105]
	v_lshlrev_b32_e32 v140, 16, v76
	v_and_b32_e32 v141, 0xffff0000, v76
	v_lshlrev_b32_e32 v142, 16, v77
	v_and_b32_e32 v143, 0xffff0000, v77
	v_lshlrev_b32_e32 v144, 16, v78
	v_and_b32_e32 v145, 0xffff0000, v78
	v_lshlrev_b32_e32 v146, 16, v79
	v_and_b32_e32 v147, 0xffff0000, v79
	v_lshlrev_b32_e32 v148, 16, v80
	v_and_b32_e32 v149, 0xffff0000, v80
	v_lshlrev_b32_e32 v150, 16, v81
	v_and_b32_e32 v151, 0xffff0000, v81
	v_lshlrev_b32_e32 v152, 16, v82
	v_and_b32_e32 v153, 0xffff0000, v82
	v_lshlrev_b32_e32 v154, 16, v83
	v_and_b32_e32 v155, 0xffff0000, v83
	v_pk_mul_f32 v[106:107], v[140:141], v[140:141]
	v_pk_fma_f32 v[106:107], v[142:143], v[142:143], v[106:107]
	v_pk_fma_f32 v[106:107], v[144:145], v[144:145], v[106:107]
	v_pk_fma_f32 v[106:107], v[146:147], v[146:147], v[106:107]
	v_pk_fma_f32 v[106:107], v[148:149], v[148:149], v[106:107]
	v_pk_fma_f32 v[106:107], v[150:151], v[150:151], v[106:107]
	v_pk_fma_f32 v[106:107], v[152:153], v[152:153], v[106:107]
	v_pk_fma_f32 v[106:107], v[154:155], v[154:155], v[106:107]
	v_add_f32_e32 v100, v100, v101
	v_add_f32_e32 v102, v102, v103
	v_add_f32_e32 v104, v104, v105
	v_add_f32_e32 v106, v106, v107
	s_nop 1
	v_add_f32_dpp v100, v100, v100 row_shr:1 row_mask:0xf bank_mask:0xf bound_ctrl:1
	v_add_f32_dpp v102, v102, v102 row_shr:1 row_mask:0xf bank_mask:0xf bound_ctrl:1
	v_add_f32_dpp v104, v104, v104 row_shr:1 row_mask:0xf bank_mask:0xf bound_ctrl:1
	v_add_f32_dpp v106, v106, v106 row_shr:1 row_mask:0xf bank_mask:0xf bound_ctrl:1
	v_add_f32_dpp v100, v100, v100 row_shr:2 row_mask:0xf bank_mask:0xf bound_ctrl:1
	v_add_f32_dpp v102, v102, v102 row_shr:2 row_mask:0xf bank_mask:0xf bound_ctrl:1
	v_add_f32_dpp v104, v104, v104 row_shr:2 row_mask:0xf bank_mask:0xf bound_ctrl:1
	v_add_f32_dpp v106, v106, v106 row_shr:2 row_mask:0xf bank_mask:0xf bound_ctrl:1
	v_add_f32_dpp v100, v100, v100 row_shr:4 row_mask:0xf bank_mask:0xf bound_ctrl:1
	v_add_f32_dpp v102, v102, v102 row_shr:4 row_mask:0xf bank_mask:0xf bound_ctrl:1
	v_add_f32_dpp v104, v104, v104 row_shr:4 row_mask:0xf bank_mask:0xf bound_ctrl:1
	v_add_f32_dpp v106, v106, v106 row_shr:4 row_mask:0xf bank_mask:0xf bound_ctrl:1
	v_add_f32_dpp v100, v100, v100 row_shr:8 row_mask:0xf bank_mask:0xf bound_ctrl:1
	v_add_f32_dpp v102, v102, v102 row_shr:8 row_mask:0xf bank_mask:0xf bound_ctrl:1
	v_add_f32_dpp v104, v104, v104 row_shr:8 row_mask:0xf bank_mask:0xf bound_ctrl:1
	v_add_f32_dpp v106, v106, v106 row_shr:8 row_mask:0xf bank_mask:0xf bound_ctrl:1
	v_add_f32_dpp v100, v100, v100 row_bcast:15 row_mask:0xa bank_mask:0xf
	v_add_f32_dpp v102, v102, v102 row_bcast:15 row_mask:0xa bank_mask:0xf
	v_add_f32_dpp v104, v104, v104 row_bcast:15 row_mask:0xa bank_mask:0xf
	v_add_f32_dpp v106, v106, v106 row_bcast:15 row_mask:0xa bank_mask:0xf
	v_add_f32_dpp v100, v100, v100 row_bcast:31 row_mask:0xc bank_mask:0xf
	v_add_f32_dpp v102, v102, v102 row_bcast:31 row_mask:0xc bank_mask:0xf
	v_add_f32_dpp v104, v104, v104 row_bcast:31 row_mask:0xc bank_mask:0xf
	v_add_f32_dpp v106, v106, v106 row_bcast:31 row_mask:0xc bank_mask:0xf
	s_nop 1
	v_readlane_b32 s5, v100, 63
	v_readlane_b32 s32, v102, 63
	v_readlane_b32 s54, v104, 63
	v_readlane_b32 s60, v106, 63
	s_nop 1
	v_mov_b32_e32 v156, s5
	v_mov_b32_e32 v158, s32
	v_mov_b32_e32 v160, s54
	v_mov_b32_e32 v162, s60
	v_fmaak_f32 v156, v156, v50, 0x358637bd
	v_fmaak_f32 v158, v158, v50, 0x358637bd
	v_fmaak_f32 v160, v160, v50, 0x358637bd
	v_fmaak_f32 v162, v162, v50, 0x358637bd
	v_rsq_f32_e32 v156, v156
	v_rsq_f32_e32 v158, v158
	v_rsq_f32_e32 v160, v160
	v_rsq_f32_e32 v162, v162
	s_nop 0
	v_lshlrev_b32_e32 v140, 16, v52
	v_and_b32_e32 v141, 0xffff0000, v52
	v_lshlrev_b32_e32 v142, 16, v53
	v_and_b32_e32 v143, 0xffff0000, v53
	v_lshlrev_b32_e32 v144, 16, v54
	v_and_b32_e32 v145, 0xffff0000, v54
	v_lshlrev_b32_e32 v146, 16, v55
	v_and_b32_e32 v147, 0xffff0000, v55
	v_lshlrev_b32_e32 v148, 16, v56
	v_and_b32_e32 v149, 0xffff0000, v56
	v_lshlrev_b32_e32 v150, 16, v57
	v_and_b32_e32 v151, 0xffff0000, v57
	v_lshlrev_b32_e32 v152, 16, v58
	v_and_b32_e32 v153, 0xffff0000, v58
	v_lshlrev_b32_e32 v154, 16, v59
	v_and_b32_e32 v155, 0xffff0000, v59
	v_pk_mul_f32 v[140:141], v[156:157], v[140:141] op_sel_hi:[0,1]
	v_pk_mul_f32 v[142:143], v[156:157], v[142:143] op_sel_hi:[0,1]
	v_pk_mul_f32 v[144:145], v[156:157], v[144:145] op_sel_hi:[0,1]
	v_pk_mul_f32 v[146:147], v[156:157], v[146:147] op_sel_hi:[0,1]
	v_pk_mul_f32 v[148:149], v[156:157], v[148:149] op_sel_hi:[0,1]
	v_pk_mul_f32 v[150:151], v[156:157], v[150:151] op_sel_hi:[0,1]
	v_pk_mul_f32 v[152:153], v[156:157], v[152:153] op_sel_hi:[0,1]
	v_pk_mul_f32 v[154:155], v[156:157], v[154:155] op_sel_hi:[0,1]
	v_pk_mul_f32 v[140:141], v[140:141], v[32:33]
	v_pk_mul_f32 v[142:143], v[142:143], v[34:35]
	v_pk_mul_f32 v[144:145], v[144:145], v[36:37]
	v_pk_mul_f32 v[146:147], v[146:147], v[38:39]
	v_pk_mul_f32 v[148:149], v[148:149], v[40:41]
	v_pk_mul_f32 v[150:151], v[150:151], v[42:43]
	v_pk_mul_f32 v[152:153], v[152:153], v[44:45]
	v_pk_mul_f32 v[154:155], v[154:155], v[46:47]
	v_pk_fma_f32 v[140:141], v[140:141], v[84:85], v[124:125]
	v_pk_fma_f32 v[142:143], v[142:143], v[86:87], v[126:127]
	v_pk_fma_f32 v[144:145], v[144:145], v[88:89], v[128:129]
	v_pk_fma_f32 v[146:147], v[146:147], v[90:91], v[130:131]
	v_pk_fma_f32 v[148:149], v[148:149], v[92:93], v[132:133]
	v_pk_fma_f32 v[150:151], v[150:151], v[94:95], v[134:135]
	v_pk_fma_f32 v[152:153], v[152:153], v[96:97], v[136:137]
	v_pk_fma_f32 v[154:155], v[154:155], v[98:99], v[138:139]
	v_cvt_pk_bf16_f32 v172, v140, v141
	v_cvt_pk_bf16_f32 v173, v142, v143
	v_cvt_pk_bf16_f32 v174, v144, v145
	v_cvt_pk_bf16_f32 v175, v146, v147
	v_cvt_pk_bf16_f32 v176, v148, v149
	v_cvt_pk_bf16_f32 v177, v150, v151
	v_cvt_pk_bf16_f32 v178, v152, v153
	v_cvt_pk_bf16_f32 v179, v154, v155
	global_store_dwordx4 v51, v[172:175], s[20:21]
	global_store_dwordx4 v51, v[176:179], s[20:21] offset:1024
	v_lshlrev_b32_e32 v140, 16, v60
	v_and_b32_e32 v141, 0xffff0000, v60
	v_lshlrev_b32_e32 v142, 16, v61
	v_and_b32_e32 v143, 0xffff0000, v61
	v_lshlrev_b32_e32 v144, 16, v62
	v_and_b32_e32 v145, 0xffff0000, v62
	v_lshlrev_b32_e32 v146, 16, v63
	v_and_b32_e32 v147, 0xffff0000, v63
	v_lshlrev_b32_e32 v148, 16, v64
	v_and_b32_e32 v149, 0xffff0000, v64
	v_lshlrev_b32_e32 v150, 16, v65
	v_and_b32_e32 v151, 0xffff0000, v65
	v_lshlrev_b32_e32 v152, 16, v66
	v_and_b32_e32 v153, 0xffff0000, v66
	v_lshlrev_b32_e32 v154, 16, v67
	v_and_b32_e32 v155, 0xffff0000, v67
	v_pk_mul_f32 v[140:141], v[158:159], v[140:141] op_sel_hi:[0,1]
	v_pk_mul_f32 v[142:143], v[158:159], v[142:143] op_sel_hi:[0,1]
	v_pk_mul_f32 v[144:145], v[158:159], v[144:145] op_sel_hi:[0,1]
	v_pk_mul_f32 v[146:147], v[158:159], v[146:147] op_sel_hi:[0,1]
	v_pk_mul_f32 v[148:149], v[158:159], v[148:149] op_sel_hi:[0,1]
	v_pk_mul_f32 v[150:151], v[158:159], v[150:151] op_sel_hi:[0,1]
	v_pk_mul_f32 v[152:153], v[158:159], v[152:153] op_sel_hi:[0,1]
	v_pk_mul_f32 v[154:155], v[158:159], v[154:155] op_sel_hi:[0,1]
	v_pk_mul_f32 v[140:141], v[140:141], v[32:33]
	v_pk_mul_f32 v[142:143], v[142:143], v[34:35]
	v_pk_mul_f32 v[144:145], v[144:145], v[36:37]
	v_pk_mul_f32 v[146:147], v[146:147], v[38:39]
	v_pk_mul_f32 v[148:149], v[148:149], v[40:41]
	v_pk_mul_f32 v[150:151], v[150:151], v[42:43]
	v_pk_mul_f32 v[152:153], v[152:153], v[44:45]
	v_pk_mul_f32 v[154:155], v[154:155], v[46:47]
	v_pk_fma_f32 v[140:141], v[140:141], v[84:85], v[124:125]
	v_pk_fma_f32 v[142:143], v[142:143], v[86:87], v[126:127]
	v_pk_fma_f32 v[144:145], v[144:145], v[88:89], v[128:129]
	v_pk_fma_f32 v[146:147], v[146:147], v[90:91], v[130:131]
	v_pk_fma_f32 v[148:149], v[148:149], v[92:93], v[132:133]
	v_pk_fma_f32 v[150:151], v[150:151], v[94:95], v[134:135]
	v_pk_fma_f32 v[152:153], v[152:153], v[96:97], v[136:137]
	v_pk_fma_f32 v[154:155], v[154:155], v[98:99], v[138:139]
	v_cvt_pk_bf16_f32 v164, v140, v141
	v_cvt_pk_bf16_f32 v165, v142, v143
	v_cvt_pk_bf16_f32 v166, v144, v145
	v_cvt_pk_bf16_f32 v167, v146, v147
	v_cvt_pk_bf16_f32 v168, v148, v149
	v_cvt_pk_bf16_f32 v169, v150, v151
	v_cvt_pk_bf16_f32 v170, v152, v153
	v_cvt_pk_bf16_f32 v171, v154, v155
	global_store_dwordx4 v51, v[164:167], s[20:21] offset:2048
	global_store_dwordx4 v51, v[168:171], s[20:21] offset:3072
	v_lshlrev_b32_e32 v140, 16, v68
	v_and_b32_e32 v141, 0xffff0000, v68
	v_lshlrev_b32_e32 v142, 16, v69
	v_and_b32_e32 v143, 0xffff0000, v69
	v_lshlrev_b32_e32 v144, 16, v70
	v_and_b32_e32 v145, 0xffff0000, v70
	v_lshlrev_b32_e32 v146, 16, v71
	v_and_b32_e32 v147, 0xffff0000, v71
	v_lshlrev_b32_e32 v148, 16, v72
	v_and_b32_e32 v149, 0xffff0000, v72
	v_lshlrev_b32_e32 v150, 16, v73
	v_and_b32_e32 v151, 0xffff0000, v73
	v_lshlrev_b32_e32 v152, 16, v74
	v_and_b32_e32 v153, 0xffff0000, v74
	v_lshlrev_b32_e32 v154, 16, v75
	v_and_b32_e32 v155, 0xffff0000, v75
	v_pk_mul_f32 v[140:141], v[160:161], v[140:141] op_sel_hi:[0,1]
	v_pk_mul_f32 v[142:143], v[160:161], v[142:143] op_sel_hi:[0,1]
	v_pk_mul_f32 v[144:145], v[160:161], v[144:145] op_sel_hi:[0,1]
	v_pk_mul_f32 v[146:147], v[160:161], v[146:147] op_sel_hi:[0,1]
	v_pk_mul_f32 v[148:149], v[160:161], v[148:149] op_sel_hi:[0,1]
	v_pk_mul_f32 v[150:151], v[160:161], v[150:151] op_sel_hi:[0,1]
	v_pk_mul_f32 v[152:153], v[160:161], v[152:153] op_sel_hi:[0,1]
	v_pk_mul_f32 v[154:155], v[160:161], v[154:155] op_sel_hi:[0,1]
	v_pk_mul_f32 v[140:141], v[140:141], v[32:33]
	v_pk_mul_f32 v[142:143], v[142:143], v[34:35]
	v_pk_mul_f32 v[144:145], v[144:145], v[36:37]
	v_pk_mul_f32 v[146:147], v[146:147], v[38:39]
	v_pk_mul_f32 v[148:149], v[148:149], v[40:41]
	v_pk_mul_f32 v[150:151], v[150:151], v[42:43]
	v_pk_mul_f32 v[152:153], v[152:153], v[44:45]
	v_pk_mul_f32 v[154:155], v[154:155], v[46:47]
	v_pk_fma_f32 v[140:141], v[140:141], v[84:85], v[124:125]
	v_pk_fma_f32 v[142:143], v[142:143], v[86:87], v[126:127]
	v_pk_fma_f32 v[144:145], v[144:145], v[88:89], v[128:129]
	v_pk_fma_f32 v[146:147], v[146:147], v[90:91], v[130:131]
	v_pk_fma_f32 v[148:149], v[148:149], v[92:93], v[132:133]
	v_pk_fma_f32 v[150:151], v[150:151], v[94:95], v[134:135]
	v_pk_fma_f32 v[152:153], v[152:153], v[96:97], v[136:137]
	v_pk_fma_f32 v[154:155], v[154:155], v[98:99], v[138:139]
	v_cvt_pk_bf16_f32 v172, v140, v141
	v_cvt_pk_bf16_f32 v173, v142, v143
	v_cvt_pk_bf16_f32 v174, v144, v145
	v_cvt_pk_bf16_f32 v175, v146, v147
	v_cvt_pk_bf16_f32 v176, v148, v149
	v_cvt_pk_bf16_f32 v177, v150, v151
	v_cvt_pk_bf16_f32 v178, v152, v153
	v_cvt_pk_bf16_f32 v179, v154, v155
	global_store_dwordx4 v109, v[172:175], s[20:21]
	global_store_dwordx4 v109, v[176:179], s[20:21] offset:1024
	v_lshlrev_b32_e32 v140, 16, v76
	v_and_b32_e32 v141, 0xffff0000, v76
	v_lshlrev_b32_e32 v142, 16, v77
	v_and_b32_e32 v143, 0xffff0000, v77
	v_lshlrev_b32_e32 v144, 16, v78
	v_and_b32_e32 v145, 0xffff0000, v78
	v_lshlrev_b32_e32 v146, 16, v79
	v_and_b32_e32 v147, 0xffff0000, v79
	v_lshlrev_b32_e32 v148, 16, v80
	v_and_b32_e32 v149, 0xffff0000, v80
	v_lshlrev_b32_e32 v150, 16, v81
	v_and_b32_e32 v151, 0xffff0000, v81
	v_lshlrev_b32_e32 v152, 16, v82
	v_and_b32_e32 v153, 0xffff0000, v82
	v_lshlrev_b32_e32 v154, 16, v83
	v_and_b32_e32 v155, 0xffff0000, v83
	v_pk_mul_f32 v[140:141], v[162:163], v[140:141] op_sel_hi:[0,1]
	v_pk_mul_f32 v[142:143], v[162:163], v[142:143] op_sel_hi:[0,1]
	v_pk_mul_f32 v[144:145], v[162:163], v[144:145] op_sel_hi:[0,1]
	v_pk_mul_f32 v[146:147], v[162:163], v[146:147] op_sel_hi:[0,1]
	v_pk_mul_f32 v[148:149], v[162:163], v[148:149] op_sel_hi:[0,1]
	v_pk_mul_f32 v[150:151], v[162:163], v[150:151] op_sel_hi:[0,1]
	v_pk_mul_f32 v[152:153], v[162:163], v[152:153] op_sel_hi:[0,1]
	v_pk_mul_f32 v[154:155], v[162:163], v[154:155] op_sel_hi:[0,1]
	v_pk_mul_f32 v[140:141], v[140:141], v[32:33]
	v_pk_mul_f32 v[142:143], v[142:143], v[34:35]
	v_pk_mul_f32 v[144:145], v[144:145], v[36:37]
	v_pk_mul_f32 v[146:147], v[146:147], v[38:39]
	v_pk_mul_f32 v[148:149], v[148:149], v[40:41]
	v_pk_mul_f32 v[150:151], v[150:151], v[42:43]
	v_pk_mul_f32 v[152:153], v[152:153], v[44:45]
	v_pk_mul_f32 v[154:155], v[154:155], v[46:47]
	v_pk_fma_f32 v[140:141], v[140:141], v[84:85], v[124:125]
	v_pk_fma_f32 v[142:143], v[142:143], v[86:87], v[126:127]
	v_pk_fma_f32 v[144:145], v[144:145], v[88:89], v[128:129]
	v_pk_fma_f32 v[146:147], v[146:147], v[90:91], v[130:131]
	v_pk_fma_f32 v[148:149], v[148:149], v[92:93], v[132:133]
	v_pk_fma_f32 v[150:151], v[150:151], v[94:95], v[134:135]
	v_pk_fma_f32 v[152:153], v[152:153], v[96:97], v[136:137]
	v_pk_fma_f32 v[154:155], v[154:155], v[98:99], v[138:139]
	v_cvt_pk_bf16_f32 v164, v140, v141
	v_cvt_pk_bf16_f32 v165, v142, v143
	v_cvt_pk_bf16_f32 v166, v144, v145
	v_cvt_pk_bf16_f32 v167, v146, v147
	v_cvt_pk_bf16_f32 v168, v148, v149
	v_cvt_pk_bf16_f32 v169, v150, v151
	v_cvt_pk_bf16_f32 v170, v152, v153
	v_cvt_pk_bf16_f32 v171, v154, v155
	global_store_dwordx4 v109, v[164:167], s[20:21] offset:2048
	global_store_dwordx4 v109, v[168:171], s[20:21] offset:3072
	s_add_u32 s20, s20, 0x2000
	s_addc_u32 s21, s21, 0
	s_add_u32 s18, s18, 0x2000
	s_addc_u32 s19, s19, 0
	global_load_dwordx4 v[52:55], v51, s[18:19]
	global_load_dwordx4 v[56:59], v51, s[18:19] offset:1024
	global_load_dwordx4 v[60:63], v51, s[18:19] offset:2048
	global_load_dwordx4 v[64:67], v51, s[18:19] offset:3072
	global_load_dwordx4 v[68:71], v109, s[18:19]
	global_load_dwordx4 v[72:75], v109, s[18:19] offset:1024
	global_load_dwordx4 v[76:79], v109, s[18:19] offset:2048
	global_load_dwordx4 v[80:83], v109, s[18:19] offset:3072
	s_waitcnt vmcnt(16)
	v_lshlrev_b32_e32 v140, 16, v0
	v_and_b32_e32 v141, 0xffff0000, v0
	v_lshlrev_b32_e32 v142, 16, v1
	v_and_b32_e32 v143, 0xffff0000, v1
	v_lshlrev_b32_e32 v144, 16, v2
	v_and_b32_e32 v145, 0xffff0000, v2
	v_lshlrev_b32_e32 v146, 16, v3
	v_and_b32_e32 v147, 0xffff0000, v3
	v_lshlrev_b32_e32 v148, 16, v4
	v_and_b32_e32 v149, 0xffff0000, v4
	v_lshlrev_b32_e32 v150, 16, v5
	v_and_b32_e32 v151, 0xffff0000, v5
	v_lshlrev_b32_e32 v152, 16, v6
	v_and_b32_e32 v153, 0xffff0000, v6
	v_lshlrev_b32_e32 v154, 16, v7
	v_and_b32_e32 v155, 0xffff0000, v7
	v_pk_mul_f32 v[100:101], v[140:141], v[140:141]
	v_pk_fma_f32 v[100:101], v[142:143], v[142:143], v[100:101]
	v_pk_fma_f32 v[100:101], v[144:145], v[144:145], v[100:101]
	v_pk_fma_f32 v[100:101], v[146:147], v[146:147], v[100:101]
	v_pk_fma_f32 v[100:101], v[148:149], v[148:149], v[100:101]
	v_pk_fma_f32 v[100:101], v[150:151], v[150:151], v[100:101]
	v_pk_fma_f32 v[100:101], v[152:153], v[152:153], v[100:101]
	v_pk_fma_f32 v[100:101], v[154:155], v[154:155], v[100:101]
	v_lshlrev_b32_e32 v140, 16, v8
	v_and_b32_e32 v141, 0xffff0000, v8
	v_lshlrev_b32_e32 v142, 16, v9
	v_and_b32_e32 v143, 0xffff0000, v9
	v_lshlrev_b32_e32 v144, 16, v10
	v_and_b32_e32 v145, 0xffff0000, v10
	v_lshlrev_b32_e32 v146, 16, v11
	v_and_b32_e32 v147, 0xffff0000, v11
	v_lshlrev_b32_e32 v148, 16, v12
	v_and_b32_e32 v149, 0xffff0000, v12
	v_lshlrev_b32_e32 v150, 16, v13
	v_and_b32_e32 v151, 0xffff0000, v13
	v_lshlrev_b32_e32 v152, 16, v14
	v_and_b32_e32 v153, 0xffff0000, v14
	v_lshlrev_b32_e32 v154, 16, v15
	v_and_b32_e32 v155, 0xffff0000, v15
	v_pk_mul_f32 v[102:103], v[140:141], v[140:141]
	v_pk_fma_f32 v[102:103], v[142:143], v[142:143], v[102:103]
	v_pk_fma_f32 v[102:103], v[144:145], v[144:145], v[102:103]
	v_pk_fma_f32 v[102:103], v[146:147], v[146:147], v[102:103]
	v_pk_fma_f32 v[102:103], v[148:149], v[148:149], v[102:103]
	v_pk_fma_f32 v[102:103], v[150:151], v[150:151], v[102:103]
	v_pk_fma_f32 v[102:103], v[152:153], v[152:153], v[102:103]
	v_pk_fma_f32 v[102:103], v[154:155], v[154:155], v[102:103]
	v_lshlrev_b32_e32 v140, 16, v16
	v_and_b32_e32 v141, 0xffff0000, v16
	v_lshlrev_b32_e32 v142, 16, v17
	v_and_b32_e32 v143, 0xffff0000, v17
	v_lshlrev_b32_e32 v144, 16, v18
	v_and_b32_e32 v145, 0xffff0000, v18
	v_lshlrev_b32_e32 v146, 16, v19
	v_and_b32_e32 v147, 0xffff0000, v19
	v_lshlrev_b32_e32 v148, 16, v20
	v_and_b32_e32 v149, 0xffff0000, v20
	v_lshlrev_b32_e32 v150, 16, v21
	v_and_b32_e32 v151, 0xffff0000, v21
	v_lshlrev_b32_e32 v152, 16, v22
	v_and_b32_e32 v153, 0xffff0000, v22
	v_lshlrev_b32_e32 v154, 16, v23
	v_and_b32_e32 v155, 0xffff0000, v23
	v_pk_mul_f32 v[104:105], v[140:141], v[140:141]
	v_pk_fma_f32 v[104:105], v[142:143], v[142:143], v[104:105]
	v_pk_fma_f32 v[104:105], v[144:145], v[144:145], v[104:105]
	v_pk_fma_f32 v[104:105], v[146:147], v[146:147], v[104:105]
	v_pk_fma_f32 v[104:105], v[148:149], v[148:149], v[104:105]
	v_pk_fma_f32 v[104:105], v[150:151], v[150:151], v[104:105]
	v_pk_fma_f32 v[104:105], v[152:153], v[152:153], v[104:105]
	v_pk_fma_f32 v[104:105], v[154:155], v[154:155], v[104:105]
	v_lshlrev_b32_e32 v140, 16, v24
	v_and_b32_e32 v141, 0xffff0000, v24
	v_lshlrev_b32_e32 v142, 16, v25
	v_and_b32_e32 v143, 0xffff0000, v25
	v_lshlrev_b32_e32 v144, 16, v26
	v_and_b32_e32 v145, 0xffff0000, v26
	v_lshlrev_b32_e32 v146, 16, v27
	v_and_b32_e32 v147, 0xffff0000, v27
	v_lshlrev_b32_e32 v148, 16, v28
	v_and_b32_e32 v149, 0xffff0000, v28
	v_lshlrev_b32_e32 v150, 16, v29
	v_and_b32_e32 v151, 0xffff0000, v29
	v_lshlrev_b32_e32 v152, 16, v30
	v_and_b32_e32 v153, 0xffff0000, v30
	v_lshlrev_b32_e32 v154, 16, v31
	v_and_b32_e32 v155, 0xffff0000, v31
	v_pk_mul_f32 v[106:107], v[140:141], v[140:141]
	v_pk_fma_f32 v[106:107], v[142:143], v[142:143], v[106:107]
	v_pk_fma_f32 v[106:107], v[144:145], v[144:145], v[106:107]
	v_pk_fma_f32 v[106:107], v[146:147], v[146:147], v[106:107]
	v_pk_fma_f32 v[106:107], v[148:149], v[148:149], v[106:107]
	v_pk_fma_f32 v[106:107], v[150:151], v[150:151], v[106:107]
	v_pk_fma_f32 v[106:107], v[152:153], v[152:153], v[106:107]
	v_pk_fma_f32 v[106:107], v[154:155], v[154:155], v[106:107]
	v_add_f32_e32 v100, v100, v101
	v_add_f32_e32 v102, v102, v103
	v_add_f32_e32 v104, v104, v105
	v_add_f32_e32 v106, v106, v107
	s_nop 1
	v_add_f32_dpp v100, v100, v100 row_shr:1 row_mask:0xf bank_mask:0xf bound_ctrl:1
	v_add_f32_dpp v102, v102, v102 row_shr:1 row_mask:0xf bank_mask:0xf bound_ctrl:1
	v_add_f32_dpp v104, v104, v104 row_shr:1 row_mask:0xf bank_mask:0xf bound_ctrl:1
	v_add_f32_dpp v106, v106, v106 row_shr:1 row_mask:0xf bank_mask:0xf bound_ctrl:1
	v_add_f32_dpp v100, v100, v100 row_shr:2 row_mask:0xf bank_mask:0xf bound_ctrl:1
	v_add_f32_dpp v102, v102, v102 row_shr:2 row_mask:0xf bank_mask:0xf bound_ctrl:1
	v_add_f32_dpp v104, v104, v104 row_shr:2 row_mask:0xf bank_mask:0xf bound_ctrl:1
	v_add_f32_dpp v106, v106, v106 row_shr:2 row_mask:0xf bank_mask:0xf bound_ctrl:1
	v_add_f32_dpp v100, v100, v100 row_shr:4 row_mask:0xf bank_mask:0xf bound_ctrl:1
	v_add_f32_dpp v102, v102, v102 row_shr:4 row_mask:0xf bank_mask:0xf bound_ctrl:1
	v_add_f32_dpp v104, v104, v104 row_shr:4 row_mask:0xf bank_mask:0xf bound_ctrl:1
	v_add_f32_dpp v106, v106, v106 row_shr:4 row_mask:0xf bank_mask:0xf bound_ctrl:1
	v_add_f32_dpp v100, v100, v100 row_shr:8 row_mask:0xf bank_mask:0xf bound_ctrl:1
	v_add_f32_dpp v102, v102, v102 row_shr:8 row_mask:0xf bank_mask:0xf bound_ctrl:1
	v_add_f32_dpp v104, v104, v104 row_shr:8 row_mask:0xf bank_mask:0xf bound_ctrl:1
	v_add_f32_dpp v106, v106, v106 row_shr:8 row_mask:0xf bank_mask:0xf bound_ctrl:1
	v_add_f32_dpp v100, v100, v100 row_bcast:15 row_mask:0xa bank_mask:0xf
	v_add_f32_dpp v102, v102, v102 row_bcast:15 row_mask:0xa bank_mask:0xf
	v_add_f32_dpp v104, v104, v104 row_bcast:15 row_mask:0xa bank_mask:0xf
	v_add_f32_dpp v106, v106, v106 row_bcast:15 row_mask:0xa bank_mask:0xf
	v_add_f32_dpp v100, v100, v100 row_bcast:31 row_mask:0xc bank_mask:0xf
	v_add_f32_dpp v102, v102, v102 row_bcast:31 row_mask:0xc bank_mask:0xf
	v_add_f32_dpp v104, v104, v104 row_bcast:31 row_mask:0xc bank_mask:0xf
	v_add_f32_dpp v106, v106, v106 row_bcast:31 row_mask:0xc bank_mask:0xf
	s_nop 1
	v_readlane_b32 s5, v100, 63
	v_readlane_b32 s32, v102, 63
	v_readlane_b32 s54, v104, 63
	v_readlane_b32 s60, v106, 63
	s_nop 1
	v_mov_b32_e32 v156, s5
	v_mov_b32_e32 v158, s32
	v_mov_b32_e32 v160, s54
	v_mov_b32_e32 v162, s60
	v_fmaak_f32 v156, v156, v50, 0x358637bd
	v_fmaak_f32 v158, v158, v50, 0x358637bd
	v_fmaak_f32 v160, v160, v50, 0x358637bd
	v_fmaak_f32 v162, v162, v50, 0x358637bd
	v_rsq_f32_e32 v156, v156
	v_rsq_f32_e32 v158, v158
	v_rsq_f32_e32 v160, v160
	v_rsq_f32_e32 v162, v162
	s_nop 0
	v_lshlrev_b32_e32 v140, 16, v0
	v_and_b32_e32 v141, 0xffff0000, v0
	v_lshlrev_b32_e32 v142, 16, v1
	v_and_b32_e32 v143, 0xffff0000, v1
	v_lshlrev_b32_e32 v144, 16, v2
	v_and_b32_e32 v145, 0xffff0000, v2
	v_lshlrev_b32_e32 v146, 16, v3
	v_and_b32_e32 v147, 0xffff0000, v3
	v_lshlrev_b32_e32 v148, 16, v4
	v_and_b32_e32 v149, 0xffff0000, v4
	v_lshlrev_b32_e32 v150, 16, v5
	v_and_b32_e32 v151, 0xffff0000, v5
	v_lshlrev_b32_e32 v152, 16, v6
	v_and_b32_e32 v153, 0xffff0000, v6
	v_lshlrev_b32_e32 v154, 16, v7
	v_and_b32_e32 v155, 0xffff0000, v7
	v_pk_mul_f32 v[140:141], v[156:157], v[140:141] op_sel_hi:[0,1]
	v_pk_mul_f32 v[142:143], v[156:157], v[142:143] op_sel_hi:[0,1]
	v_pk_mul_f32 v[144:145], v[156:157], v[144:145] op_sel_hi:[0,1]
	v_pk_mul_f32 v[146:147], v[156:157], v[146:147] op_sel_hi:[0,1]
	v_pk_mul_f32 v[148:149], v[156:157], v[148:149] op_sel_hi:[0,1]
	v_pk_mul_f32 v[150:151], v[156:157], v[150:151] op_sel_hi:[0,1]
	v_pk_mul_f32 v[152:153], v[156:157], v[152:153] op_sel_hi:[0,1]
	v_pk_mul_f32 v[154:155], v[156:157], v[154:155] op_sel_hi:[0,1]
	v_pk_mul_f32 v[140:141], v[140:141], v[32:33]
	v_pk_mul_f32 v[142:143], v[142:143], v[34:35]
	v_pk_mul_f32 v[144:145], v[144:145], v[36:37]
	v_pk_mul_f32 v[146:147], v[146:147], v[38:39]
	v_pk_mul_f32 v[148:149], v[148:149], v[40:41]
	v_pk_mul_f32 v[150:151], v[150:151], v[42:43]
	v_pk_mul_f32 v[152:153], v[152:153], v[44:45]
	v_pk_mul_f32 v[154:155], v[154:155], v[46:47]
	v_pk_fma_f32 v[140:141], v[140:141], v[84:85], v[124:125]
	v_pk_fma_f32 v[142:143], v[142:143], v[86:87], v[126:127]
	v_pk_fma_f32 v[144:145], v[144:145], v[88:89], v[128:129]
	v_pk_fma_f32 v[146:147], v[146:147], v[90:91], v[130:131]
	v_pk_fma_f32 v[148:149], v[148:149], v[92:93], v[132:133]
	v_pk_fma_f32 v[150:151], v[150:151], v[94:95], v[134:135]
	v_pk_fma_f32 v[152:153], v[152:153], v[96:97], v[136:137]
	v_pk_fma_f32 v[154:155], v[154:155], v[98:99], v[138:139]
	v_cvt_pk_bf16_f32 v164, v140, v141
	v_cvt_pk_bf16_f32 v165, v142, v143
	v_cvt_pk_bf16_f32 v166, v144, v145
	v_cvt_pk_bf16_f32 v167, v146, v147
	v_cvt_pk_bf16_f32 v168, v148, v149
	v_cvt_pk_bf16_f32 v169, v150, v151
	v_cvt_pk_bf16_f32 v170, v152, v153
	v_cvt_pk_bf16_f32 v171, v154, v155
	global_store_dwordx4 v51, v[164:167], s[20:21]
	global_store_dwordx4 v51, v[168:171], s[20:21] offset:1024
	v_lshlrev_b32_e32 v140, 16, v8
	v_and_b32_e32 v141, 0xffff0000, v8
	v_lshlrev_b32_e32 v142, 16, v9
	v_and_b32_e32 v143, 0xffff0000, v9
	v_lshlrev_b32_e32 v144, 16, v10
	v_and_b32_e32 v145, 0xffff0000, v10
	v_lshlrev_b32_e32 v146, 16, v11
	v_and_b32_e32 v147, 0xffff0000, v11
	v_lshlrev_b32_e32 v148, 16, v12
	v_and_b32_e32 v149, 0xffff0000, v12
	v_lshlrev_b32_e32 v150, 16, v13
	v_and_b32_e32 v151, 0xffff0000, v13
	v_lshlrev_b32_e32 v152, 16, v14
	v_and_b32_e32 v153, 0xffff0000, v14
	v_lshlrev_b32_e32 v154, 16, v15
	v_and_b32_e32 v155, 0xffff0000, v15
	v_pk_mul_f32 v[140:141], v[158:159], v[140:141] op_sel_hi:[0,1]
	v_pk_mul_f32 v[142:143], v[158:159], v[142:143] op_sel_hi:[0,1]
	v_pk_mul_f32 v[144:145], v[158:159], v[144:145] op_sel_hi:[0,1]
	v_pk_mul_f32 v[146:147], v[158:159], v[146:147] op_sel_hi:[0,1]
	v_pk_mul_f32 v[148:149], v[158:159], v[148:149] op_sel_hi:[0,1]
	v_pk_mul_f32 v[150:151], v[158:159], v[150:151] op_sel_hi:[0,1]
	v_pk_mul_f32 v[152:153], v[158:159], v[152:153] op_sel_hi:[0,1]
	v_pk_mul_f32 v[154:155], v[158:159], v[154:155] op_sel_hi:[0,1]
	v_pk_mul_f32 v[140:141], v[140:141], v[32:33]
	v_pk_mul_f32 v[142:143], v[142:143], v[34:35]
	v_pk_mul_f32 v[144:145], v[144:145], v[36:37]
	v_pk_mul_f32 v[146:147], v[146:147], v[38:39]
	v_pk_mul_f32 v[148:149], v[148:149], v[40:41]
	v_pk_mul_f32 v[150:151], v[150:151], v[42:43]
	v_pk_mul_f32 v[152:153], v[152:153], v[44:45]
	v_pk_mul_f32 v[154:155], v[154:155], v[46:47]
	v_pk_fma_f32 v[140:141], v[140:141], v[84:85], v[124:125]
	v_pk_fma_f32 v[142:143], v[142:143], v[86:87], v[126:127]
	v_pk_fma_f32 v[144:145], v[144:145], v[88:89], v[128:129]
	v_pk_fma_f32 v[146:147], v[146:147], v[90:91], v[130:131]
	v_pk_fma_f32 v[148:149], v[148:149], v[92:93], v[132:133]
	v_pk_fma_f32 v[150:151], v[150:151], v[94:95], v[134:135]
	v_pk_fma_f32 v[152:153], v[152:153], v[96:97], v[136:137]
	v_pk_fma_f32 v[154:155], v[154:155], v[98:99], v[138:139]
	v_cvt_pk_bf16_f32 v172, v140, v141
	v_cvt_pk_bf16_f32 v173, v142, v143
	v_cvt_pk_bf16_f32 v174, v144, v145
	v_cvt_pk_bf16_f32 v175, v146, v147
	v_cvt_pk_bf16_f32 v176, v148, v149
	v_cvt_pk_bf16_f32 v177, v150, v151
	v_cvt_pk_bf16_f32 v178, v152, v153
	v_cvt_pk_bf16_f32 v179, v154, v155
	global_store_dwordx4 v51, v[172:175], s[20:21] offset:2048
	global_store_dwordx4 v51, v[176:179], s[20:21] offset:3072
	v_lshlrev_b32_e32 v140, 16, v16
	v_and_b32_e32 v141, 0xffff0000, v16
	v_lshlrev_b32_e32 v142, 16, v17
	v_and_b32_e32 v143, 0xffff0000, v17
	v_lshlrev_b32_e32 v144, 16, v18
	v_and_b32_e32 v145, 0xffff0000, v18
	v_lshlrev_b32_e32 v146, 16, v19
	v_and_b32_e32 v147, 0xffff0000, v19
	v_lshlrev_b32_e32 v148, 16, v20
	v_and_b32_e32 v149, 0xffff0000, v20
	v_lshlrev_b32_e32 v150, 16, v21
	v_and_b32_e32 v151, 0xffff0000, v21
	v_lshlrev_b32_e32 v152, 16, v22
	v_and_b32_e32 v153, 0xffff0000, v22
	v_lshlrev_b32_e32 v154, 16, v23
	v_and_b32_e32 v155, 0xffff0000, v23
	v_pk_mul_f32 v[140:141], v[160:161], v[140:141] op_sel_hi:[0,1]
	v_pk_mul_f32 v[142:143], v[160:161], v[142:143] op_sel_hi:[0,1]
	v_pk_mul_f32 v[144:145], v[160:161], v[144:145] op_sel_hi:[0,1]
	v_pk_mul_f32 v[146:147], v[160:161], v[146:147] op_sel_hi:[0,1]
	v_pk_mul_f32 v[148:149], v[160:161], v[148:149] op_sel_hi:[0,1]
	v_pk_mul_f32 v[150:151], v[160:161], v[150:151] op_sel_hi:[0,1]
	v_pk_mul_f32 v[152:153], v[160:161], v[152:153] op_sel_hi:[0,1]
	v_pk_mul_f32 v[154:155], v[160:161], v[154:155] op_sel_hi:[0,1]
	v_pk_mul_f32 v[140:141], v[140:141], v[32:33]
	v_pk_mul_f32 v[142:143], v[142:143], v[34:35]
	v_pk_mul_f32 v[144:145], v[144:145], v[36:37]
	v_pk_mul_f32 v[146:147], v[146:147], v[38:39]
	v_pk_mul_f32 v[148:149], v[148:149], v[40:41]
	v_pk_mul_f32 v[150:151], v[150:151], v[42:43]
	v_pk_mul_f32 v[152:153], v[152:153], v[44:45]
	v_pk_mul_f32 v[154:155], v[154:155], v[46:47]
	v_pk_fma_f32 v[140:141], v[140:141], v[84:85], v[124:125]
	v_pk_fma_f32 v[142:143], v[142:143], v[86:87], v[126:127]
	v_pk_fma_f32 v[144:145], v[144:145], v[88:89], v[128:129]
	v_pk_fma_f32 v[146:147], v[146:147], v[90:91], v[130:131]
	v_pk_fma_f32 v[148:149], v[148:149], v[92:93], v[132:133]
	v_pk_fma_f32 v[150:151], v[150:151], v[94:95], v[134:135]
	v_pk_fma_f32 v[152:153], v[152:153], v[96:97], v[136:137]
	v_pk_fma_f32 v[154:155], v[154:155], v[98:99], v[138:139]
	v_cvt_pk_bf16_f32 v164, v140, v141
	v_cvt_pk_bf16_f32 v165, v142, v143
	v_cvt_pk_bf16_f32 v166, v144, v145
	v_cvt_pk_bf16_f32 v167, v146, v147
	v_cvt_pk_bf16_f32 v168, v148, v149
	v_cvt_pk_bf16_f32 v169, v150, v151
	v_cvt_pk_bf16_f32 v170, v152, v153
	v_cvt_pk_bf16_f32 v171, v154, v155
	global_store_dwordx4 v109, v[164:167], s[20:21]
	global_store_dwordx4 v109, v[168:171], s[20:21] offset:1024
	v_lshlrev_b32_e32 v140, 16, v24
	v_and_b32_e32 v141, 0xffff0000, v24
	v_lshlrev_b32_e32 v142, 16, v25
	v_and_b32_e32 v143, 0xffff0000, v25
	v_lshlrev_b32_e32 v144, 16, v26
	v_and_b32_e32 v145, 0xffff0000, v26
	v_lshlrev_b32_e32 v146, 16, v27
	v_and_b32_e32 v147, 0xffff0000, v27
	v_lshlrev_b32_e32 v148, 16, v28
	v_and_b32_e32 v149, 0xffff0000, v28
	v_lshlrev_b32_e32 v150, 16, v29
	v_and_b32_e32 v151, 0xffff0000, v29
	v_lshlrev_b32_e32 v152, 16, v30
	v_and_b32_e32 v153, 0xffff0000, v30
	v_lshlrev_b32_e32 v154, 16, v31
	v_and_b32_e32 v155, 0xffff0000, v31
	v_pk_mul_f32 v[140:141], v[162:163], v[140:141] op_sel_hi:[0,1]
	v_pk_mul_f32 v[142:143], v[162:163], v[142:143] op_sel_hi:[0,1]
	v_pk_mul_f32 v[144:145], v[162:163], v[144:145] op_sel_hi:[0,1]
	v_pk_mul_f32 v[146:147], v[162:163], v[146:147] op_sel_hi:[0,1]
	v_pk_mul_f32 v[148:149], v[162:163], v[148:149] op_sel_hi:[0,1]
	v_pk_mul_f32 v[150:151], v[162:163], v[150:151] op_sel_hi:[0,1]
	v_pk_mul_f32 v[152:153], v[162:163], v[152:153] op_sel_hi:[0,1]
	v_pk_mul_f32 v[154:155], v[162:163], v[154:155] op_sel_hi:[0,1]
	v_pk_mul_f32 v[140:141], v[140:141], v[32:33]
	v_pk_mul_f32 v[142:143], v[142:143], v[34:35]
	v_pk_mul_f32 v[144:145], v[144:145], v[36:37]
	v_pk_mul_f32 v[146:147], v[146:147], v[38:39]
	v_pk_mul_f32 v[148:149], v[148:149], v[40:41]
	v_pk_mul_f32 v[150:151], v[150:151], v[42:43]
	v_pk_mul_f32 v[152:153], v[152:153], v[44:45]
	v_pk_mul_f32 v[154:155], v[154:155], v[46:47]
	v_pk_fma_f32 v[140:141], v[140:141], v[84:85], v[124:125]
	v_pk_fma_f32 v[142:143], v[142:143], v[86:87], v[126:127]
	v_pk_fma_f32 v[144:145], v[144:145], v[88:89], v[128:129]
	v_pk_fma_f32 v[146:147], v[146:147], v[90:91], v[130:131]
	v_pk_fma_f32 v[148:149], v[148:149], v[92:93], v[132:133]
	v_pk_fma_f32 v[150:151], v[150:151], v[94:95], v[134:135]
	v_pk_fma_f32 v[152:153], v[152:153], v[96:97], v[136:137]
	v_pk_fma_f32 v[154:155], v[154:155], v[98:99], v[138:139]
	v_cvt_pk_bf16_f32 v172, v140, v141
	v_cvt_pk_bf16_f32 v173, v142, v143
	v_cvt_pk_bf16_f32 v174, v144, v145
	v_cvt_pk_bf16_f32 v175, v146, v147
	v_cvt_pk_bf16_f32 v176, v148, v149
	v_cvt_pk_bf16_f32 v177, v150, v151
	v_cvt_pk_bf16_f32 v178, v152, v153
	v_cvt_pk_bf16_f32 v179, v154, v155
	global_store_dwordx4 v109, v[172:175], s[20:21] offset:2048
	global_store_dwordx4 v109, v[176:179], s[20:21] offset:3072
	s_add_u32 s20, s20, 0x2000
	s_addc_u32 s21, s21, 0
	s_add_u32 s18, s18, 0x2000
	s_addc_u32 s19, s19, 0
	global_load_dwordx4 v[0:3], v51, s[18:19]
	global_load_dwordx4 v[4:7], v51, s[18:19] offset:1024
	global_load_dwordx4 v[8:11], v51, s[18:19] offset:2048
	global_load_dwordx4 v[12:15], v51, s[18:19] offset:3072
	global_load_dwordx4 v[16:19], v109, s[18:19]
	global_load_dwordx4 v[20:23], v109, s[18:19] offset:1024
	global_load_dwordx4 v[24:27], v109, s[18:19] offset:2048
	global_load_dwordx4 v[28:31], v109, s[18:19] offset:3072
	s_waitcnt vmcnt(16)
	v_lshlrev_b32_e32 v140, 16, v52
	v_and_b32_e32 v141, 0xffff0000, v52
	v_lshlrev_b32_e32 v142, 16, v53
	v_and_b32_e32 v143, 0xffff0000, v53
	v_lshlrev_b32_e32 v144, 16, v54
	v_and_b32_e32 v145, 0xffff0000, v54
	v_lshlrev_b32_e32 v146, 16, v55
	v_and_b32_e32 v147, 0xffff0000, v55
	v_lshlrev_b32_e32 v148, 16, v56
	v_and_b32_e32 v149, 0xffff0000, v56
	v_lshlrev_b32_e32 v150, 16, v57
	v_and_b32_e32 v151, 0xffff0000, v57
	v_lshlrev_b32_e32 v152, 16, v58
	v_and_b32_e32 v153, 0xffff0000, v58
	v_lshlrev_b32_e32 v154, 16, v59
	v_and_b32_e32 v155, 0xffff0000, v59
	v_pk_mul_f32 v[100:101], v[140:141], v[140:141]
	v_pk_fma_f32 v[100:101], v[142:143], v[142:143], v[100:101]
	v_pk_fma_f32 v[100:101], v[144:145], v[144:145], v[100:101]
	v_pk_fma_f32 v[100:101], v[146:147], v[146:147], v[100:101]
	v_pk_fma_f32 v[100:101], v[148:149], v[148:149], v[100:101]
	v_pk_fma_f32 v[100:101], v[150:151], v[150:151], v[100:101]
	v_pk_fma_f32 v[100:101], v[152:153], v[152:153], v[100:101]
	v_pk_fma_f32 v[100:101], v[154:155], v[154:155], v[100:101]
	v_lshlrev_b32_e32 v140, 16, v60
	v_and_b32_e32 v141, 0xffff0000, v60
	v_lshlrev_b32_e32 v142, 16, v61
	v_and_b32_e32 v143, 0xffff0000, v61
	v_lshlrev_b32_e32 v144, 16, v62
	v_and_b32_e32 v145, 0xffff0000, v62
	v_lshlrev_b32_e32 v146, 16, v63
	v_and_b32_e32 v147, 0xffff0000, v63
	v_lshlrev_b32_e32 v148, 16, v64
	v_and_b32_e32 v149, 0xffff0000, v64
	v_lshlrev_b32_e32 v150, 16, v65
	v_and_b32_e32 v151, 0xffff0000, v65
	v_lshlrev_b32_e32 v152, 16, v66
	v_and_b32_e32 v153, 0xffff0000, v66
	v_lshlrev_b32_e32 v154, 16, v67
	v_and_b32_e32 v155, 0xffff0000, v67
	v_pk_mul_f32 v[102:103], v[140:141], v[140:141]
	v_pk_fma_f32 v[102:103], v[142:143], v[142:143], v[102:103]
	v_pk_fma_f32 v[102:103], v[144:145], v[144:145], v[102:103]
	v_pk_fma_f32 v[102:103], v[146:147], v[146:147], v[102:103]
	v_pk_fma_f32 v[102:103], v[148:149], v[148:149], v[102:103]
	v_pk_fma_f32 v[102:103], v[150:151], v[150:151], v[102:103]
	v_pk_fma_f32 v[102:103], v[152:153], v[152:153], v[102:103]
	v_pk_fma_f32 v[102:103], v[154:155], v[154:155], v[102:103]
	v_lshlrev_b32_e32 v140, 16, v68
	v_and_b32_e32 v141, 0xffff0000, v68
	v_lshlrev_b32_e32 v142, 16, v69
	v_and_b32_e32 v143, 0xffff0000, v69
	v_lshlrev_b32_e32 v144, 16, v70
	v_and_b32_e32 v145, 0xffff0000, v70
	v_lshlrev_b32_e32 v146, 16, v71
	v_and_b32_e32 v147, 0xffff0000, v71
	v_lshlrev_b32_e32 v148, 16, v72
	v_and_b32_e32 v149, 0xffff0000, v72
	v_lshlrev_b32_e32 v150, 16, v73
	v_and_b32_e32 v151, 0xffff0000, v73
	v_lshlrev_b32_e32 v152, 16, v74
	v_and_b32_e32 v153, 0xffff0000, v74
	v_lshlrev_b32_e32 v154, 16, v75
	v_and_b32_e32 v155, 0xffff0000, v75
	v_pk_mul_f32 v[104:105], v[140:141], v[140:141]
	v_pk_fma_f32 v[104:105], v[142:143], v[142:143], v[104:105]
	v_pk_fma_f32 v[104:105], v[144:145], v[144:145], v[104:105]
	v_pk_fma_f32 v[104:105], v[146:147], v[146:147], v[104:105]
	v_pk_fma_f32 v[104:105], v[148:149], v[148:149], v[104:105]
	v_pk_fma_f32 v[104:105], v[150:151], v[150:151], v[104:105]
	v_pk_fma_f32 v[104:105], v[152:153], v[152:153], v[104:105]
	v_pk_fma_f32 v[104:105], v[154:155], v[154:155], v[104:105]
	v_lshlrev_b32_e32 v140, 16, v76
	v_and_b32_e32 v141, 0xffff0000, v76
	v_lshlrev_b32_e32 v142, 16, v77
	v_and_b32_e32 v143, 0xffff0000, v77
	v_lshlrev_b32_e32 v144, 16, v78
	v_and_b32_e32 v145, 0xffff0000, v78
	v_lshlrev_b32_e32 v146, 16, v79
	v_and_b32_e32 v147, 0xffff0000, v79
	v_lshlrev_b32_e32 v148, 16, v80
	v_and_b32_e32 v149, 0xffff0000, v80
	v_lshlrev_b32_e32 v150, 16, v81
	v_and_b32_e32 v151, 0xffff0000, v81
	v_lshlrev_b32_e32 v152, 16, v82
	v_and_b32_e32 v153, 0xffff0000, v82
	v_lshlrev_b32_e32 v154, 16, v83
	v_and_b32_e32 v155, 0xffff0000, v83
	v_pk_mul_f32 v[106:107], v[140:141], v[140:141]
	v_pk_fma_f32 v[106:107], v[142:143], v[142:143], v[106:107]
	v_pk_fma_f32 v[106:107], v[144:145], v[144:145], v[106:107]
	v_pk_fma_f32 v[106:107], v[146:147], v[146:147], v[106:107]
	v_pk_fma_f32 v[106:107], v[148:149], v[148:149], v[106:107]
	v_pk_fma_f32 v[106:107], v[150:151], v[150:151], v[106:107]
	v_pk_fma_f32 v[106:107], v[152:153], v[152:153], v[106:107]
	v_pk_fma_f32 v[106:107], v[154:155], v[154:155], v[106:107]
	v_add_f32_e32 v100, v100, v101
	v_add_f32_e32 v102, v102, v103
	v_add_f32_e32 v104, v104, v105
	v_add_f32_e32 v106, v106, v107
	s_nop 1
	v_add_f32_dpp v100, v100, v100 row_shr:1 row_mask:0xf bank_mask:0xf bound_ctrl:1
	v_add_f32_dpp v102, v102, v102 row_shr:1 row_mask:0xf bank_mask:0xf bound_ctrl:1
	v_add_f32_dpp v104, v104, v104 row_shr:1 row_mask:0xf bank_mask:0xf bound_ctrl:1
	v_add_f32_dpp v106, v106, v106 row_shr:1 row_mask:0xf bank_mask:0xf bound_ctrl:1
	v_add_f32_dpp v100, v100, v100 row_shr:2 row_mask:0xf bank_mask:0xf bound_ctrl:1
	v_add_f32_dpp v102, v102, v102 row_shr:2 row_mask:0xf bank_mask:0xf bound_ctrl:1
	v_add_f32_dpp v104, v104, v104 row_shr:2 row_mask:0xf bank_mask:0xf bound_ctrl:1
	v_add_f32_dpp v106, v106, v106 row_shr:2 row_mask:0xf bank_mask:0xf bound_ctrl:1
	v_add_f32_dpp v100, v100, v100 row_shr:4 row_mask:0xf bank_mask:0xf bound_ctrl:1
	v_add_f32_dpp v102, v102, v102 row_shr:4 row_mask:0xf bank_mask:0xf bound_ctrl:1
	v_add_f32_dpp v104, v104, v104 row_shr:4 row_mask:0xf bank_mask:0xf bound_ctrl:1
	v_add_f32_dpp v106, v106, v106 row_shr:4 row_mask:0xf bank_mask:0xf bound_ctrl:1
	v_add_f32_dpp v100, v100, v100 row_shr:8 row_mask:0xf bank_mask:0xf bound_ctrl:1
	v_add_f32_dpp v102, v102, v102 row_shr:8 row_mask:0xf bank_mask:0xf bound_ctrl:1
	v_add_f32_dpp v104, v104, v104 row_shr:8 row_mask:0xf bank_mask:0xf bound_ctrl:1
	v_add_f32_dpp v106, v106, v106 row_shr:8 row_mask:0xf bank_mask:0xf bound_ctrl:1
	v_add_f32_dpp v100, v100, v100 row_bcast:15 row_mask:0xa bank_mask:0xf
	v_add_f32_dpp v102, v102, v102 row_bcast:15 row_mask:0xa bank_mask:0xf
	v_add_f32_dpp v104, v104, v104 row_bcast:15 row_mask:0xa bank_mask:0xf
	v_add_f32_dpp v106, v106, v106 row_bcast:15 row_mask:0xa bank_mask:0xf
	v_add_f32_dpp v100, v100, v100 row_bcast:31 row_mask:0xc bank_mask:0xf
	v_add_f32_dpp v102, v102, v102 row_bcast:31 row_mask:0xc bank_mask:0xf
	v_add_f32_dpp v104, v104, v104 row_bcast:31 row_mask:0xc bank_mask:0xf
	v_add_f32_dpp v106, v106, v106 row_bcast:31 row_mask:0xc bank_mask:0xf
	s_nop 1
	v_readlane_b32 s5, v100, 63
	v_readlane_b32 s32, v102, 63
	v_readlane_b32 s54, v104, 63
	v_readlane_b32 s60, v106, 63
	s_nop 1
	v_mov_b32_e32 v156, s5
	v_mov_b32_e32 v158, s32
	v_mov_b32_e32 v160, s54
	v_mov_b32_e32 v162, s60
	v_fmaak_f32 v156, v156, v50, 0x358637bd
	v_fmaak_f32 v158, v158, v50, 0x358637bd
	v_fmaak_f32 v160, v160, v50, 0x358637bd
	v_fmaak_f32 v162, v162, v50, 0x358637bd
	v_rsq_f32_e32 v156, v156
	v_rsq_f32_e32 v158, v158
	v_rsq_f32_e32 v160, v160
	v_rsq_f32_e32 v162, v162
	s_nop 0
	v_lshlrev_b32_e32 v140, 16, v52
	v_and_b32_e32 v141, 0xffff0000, v52
	v_lshlrev_b32_e32 v142, 16, v53
	v_and_b32_e32 v143, 0xffff0000, v53
	v_lshlrev_b32_e32 v144, 16, v54
	v_and_b32_e32 v145, 0xffff0000, v54
	v_lshlrev_b32_e32 v146, 16, v55
	v_and_b32_e32 v147, 0xffff0000, v55
	v_lshlrev_b32_e32 v148, 16, v56
	v_and_b32_e32 v149, 0xffff0000, v56
	v_lshlrev_b32_e32 v150, 16, v57
	v_and_b32_e32 v151, 0xffff0000, v57
	v_lshlrev_b32_e32 v152, 16, v58
	v_and_b32_e32 v153, 0xffff0000, v58
	v_lshlrev_b32_e32 v154, 16, v59
	v_and_b32_e32 v155, 0xffff0000, v59
	v_pk_mul_f32 v[140:141], v[156:157], v[140:141] op_sel_hi:[0,1]
	v_pk_mul_f32 v[142:143], v[156:157], v[142:143] op_sel_hi:[0,1]
	v_pk_mul_f32 v[144:145], v[156:157], v[144:145] op_sel_hi:[0,1]
	v_pk_mul_f32 v[146:147], v[156:157], v[146:147] op_sel_hi:[0,1]
	v_pk_mul_f32 v[148:149], v[156:157], v[148:149] op_sel_hi:[0,1]
	v_pk_mul_f32 v[150:151], v[156:157], v[150:151] op_sel_hi:[0,1]
	v_pk_mul_f32 v[152:153], v[156:157], v[152:153] op_sel_hi:[0,1]
	v_pk_mul_f32 v[154:155], v[156:157], v[154:155] op_sel_hi:[0,1]
	v_pk_mul_f32 v[140:141], v[140:141], v[32:33]
	v_pk_mul_f32 v[142:143], v[142:143], v[34:35]
	v_pk_mul_f32 v[144:145], v[144:145], v[36:37]
	v_pk_mul_f32 v[146:147], v[146:147], v[38:39]
	v_pk_mul_f32 v[148:149], v[148:149], v[40:41]
	v_pk_mul_f32 v[150:151], v[150:151], v[42:43]
	v_pk_mul_f32 v[152:153], v[152:153], v[44:45]
	v_pk_mul_f32 v[154:155], v[154:155], v[46:47]
	v_pk_fma_f32 v[140:141], v[140:141], v[84:85], v[124:125]
	v_pk_fma_f32 v[142:143], v[142:143], v[86:87], v[126:127]
	v_pk_fma_f32 v[144:145], v[144:145], v[88:89], v[128:129]
	v_pk_fma_f32 v[146:147], v[146:147], v[90:91], v[130:131]
	v_pk_fma_f32 v[148:149], v[148:149], v[92:93], v[132:133]
	v_pk_fma_f32 v[150:151], v[150:151], v[94:95], v[134:135]
	v_pk_fma_f32 v[152:153], v[152:153], v[96:97], v[136:137]
	v_pk_fma_f32 v[154:155], v[154:155], v[98:99], v[138:139]
	v_cvt_pk_bf16_f32 v172, v140, v141
	v_cvt_pk_bf16_f32 v173, v142, v143
	v_cvt_pk_bf16_f32 v174, v144, v145
	v_cvt_pk_bf16_f32 v175, v146, v147
	v_cvt_pk_bf16_f32 v176, v148, v149
	v_cvt_pk_bf16_f32 v177, v150, v151
	v_cvt_pk_bf16_f32 v178, v152, v153
	v_cvt_pk_bf16_f32 v179, v154, v155
	global_store_dwordx4 v51, v[172:175], s[20:21]
	global_store_dwordx4 v51, v[176:179], s[20:21] offset:1024
	v_lshlrev_b32_e32 v140, 16, v60
	v_and_b32_e32 v141, 0xffff0000, v60
	v_lshlrev_b32_e32 v142, 16, v61
	v_and_b32_e32 v143, 0xffff0000, v61
	v_lshlrev_b32_e32 v144, 16, v62
	v_and_b32_e32 v145, 0xffff0000, v62
	v_lshlrev_b32_e32 v146, 16, v63
	v_and_b32_e32 v147, 0xffff0000, v63
	v_lshlrev_b32_e32 v148, 16, v64
	v_and_b32_e32 v149, 0xffff0000, v64
	v_lshlrev_b32_e32 v150, 16, v65
	v_and_b32_e32 v151, 0xffff0000, v65
	v_lshlrev_b32_e32 v152, 16, v66
	v_and_b32_e32 v153, 0xffff0000, v66
	v_lshlrev_b32_e32 v154, 16, v67
	v_and_b32_e32 v155, 0xffff0000, v67
	v_pk_mul_f32 v[140:141], v[158:159], v[140:141] op_sel_hi:[0,1]
	v_pk_mul_f32 v[142:143], v[158:159], v[142:143] op_sel_hi:[0,1]
	v_pk_mul_f32 v[144:145], v[158:159], v[144:145] op_sel_hi:[0,1]
	v_pk_mul_f32 v[146:147], v[158:159], v[146:147] op_sel_hi:[0,1]
	v_pk_mul_f32 v[148:149], v[158:159], v[148:149] op_sel_hi:[0,1]
	v_pk_mul_f32 v[150:151], v[158:159], v[150:151] op_sel_hi:[0,1]
	v_pk_mul_f32 v[152:153], v[158:159], v[152:153] op_sel_hi:[0,1]
	v_pk_mul_f32 v[154:155], v[158:159], v[154:155] op_sel_hi:[0,1]
	v_pk_mul_f32 v[140:141], v[140:141], v[32:33]
	v_pk_mul_f32 v[142:143], v[142:143], v[34:35]
	v_pk_mul_f32 v[144:145], v[144:145], v[36:37]
	v_pk_mul_f32 v[146:147], v[146:147], v[38:39]
	v_pk_mul_f32 v[148:149], v[148:149], v[40:41]
	v_pk_mul_f32 v[150:151], v[150:151], v[42:43]
	v_pk_mul_f32 v[152:153], v[152:153], v[44:45]
	v_pk_mul_f32 v[154:155], v[154:155], v[46:47]
	v_pk_fma_f32 v[140:141], v[140:141], v[84:85], v[124:125]
	v_pk_fma_f32 v[142:143], v[142:143], v[86:87], v[126:127]
	v_pk_fma_f32 v[144:145], v[144:145], v[88:89], v[128:129]
	v_pk_fma_f32 v[146:147], v[146:147], v[90:91], v[130:131]
	v_pk_fma_f32 v[148:149], v[148:149], v[92:93], v[132:133]
	v_pk_fma_f32 v[150:151], v[150:151], v[94:95], v[134:135]
	v_pk_fma_f32 v[152:153], v[152:153], v[96:97], v[136:137]
	v_pk_fma_f32 v[154:155], v[154:155], v[98:99], v[138:139]
	v_cvt_pk_bf16_f32 v164, v140, v141
	v_cvt_pk_bf16_f32 v165, v142, v143
	v_cvt_pk_bf16_f32 v166, v144, v145
	v_cvt_pk_bf16_f32 v167, v146, v147
	v_cvt_pk_bf16_f32 v168, v148, v149
	v_cvt_pk_bf16_f32 v169, v150, v151
	v_cvt_pk_bf16_f32 v170, v152, v153
	v_cvt_pk_bf16_f32 v171, v154, v155
	global_store_dwordx4 v51, v[164:167], s[20:21] offset:2048
	global_store_dwordx4 v51, v[168:171], s[20:21] offset:3072
	v_lshlrev_b32_e32 v140, 16, v68
	v_and_b32_e32 v141, 0xffff0000, v68
	v_lshlrev_b32_e32 v142, 16, v69
	v_and_b32_e32 v143, 0xffff0000, v69
	v_lshlrev_b32_e32 v144, 16, v70
	v_and_b32_e32 v145, 0xffff0000, v70
	v_lshlrev_b32_e32 v146, 16, v71
	v_and_b32_e32 v147, 0xffff0000, v71
	v_lshlrev_b32_e32 v148, 16, v72
	v_and_b32_e32 v149, 0xffff0000, v72
	v_lshlrev_b32_e32 v150, 16, v73
	v_and_b32_e32 v151, 0xffff0000, v73
	v_lshlrev_b32_e32 v152, 16, v74
	v_and_b32_e32 v153, 0xffff0000, v74
	v_lshlrev_b32_e32 v154, 16, v75
	v_and_b32_e32 v155, 0xffff0000, v75
	v_pk_mul_f32 v[140:141], v[160:161], v[140:141] op_sel_hi:[0,1]
	v_pk_mul_f32 v[142:143], v[160:161], v[142:143] op_sel_hi:[0,1]
	v_pk_mul_f32 v[144:145], v[160:161], v[144:145] op_sel_hi:[0,1]
	v_pk_mul_f32 v[146:147], v[160:161], v[146:147] op_sel_hi:[0,1]
	v_pk_mul_f32 v[148:149], v[160:161], v[148:149] op_sel_hi:[0,1]
	v_pk_mul_f32 v[150:151], v[160:161], v[150:151] op_sel_hi:[0,1]
	v_pk_mul_f32 v[152:153], v[160:161], v[152:153] op_sel_hi:[0,1]
	v_pk_mul_f32 v[154:155], v[160:161], v[154:155] op_sel_hi:[0,1]
	v_pk_mul_f32 v[140:141], v[140:141], v[32:33]
	v_pk_mul_f32 v[142:143], v[142:143], v[34:35]
	v_pk_mul_f32 v[144:145], v[144:145], v[36:37]
	v_pk_mul_f32 v[146:147], v[146:147], v[38:39]
	v_pk_mul_f32 v[148:149], v[148:149], v[40:41]
	v_pk_mul_f32 v[150:151], v[150:151], v[42:43]
	v_pk_mul_f32 v[152:153], v[152:153], v[44:45]
	v_pk_mul_f32 v[154:155], v[154:155], v[46:47]
	v_pk_fma_f32 v[140:141], v[140:141], v[84:85], v[124:125]
	v_pk_fma_f32 v[142:143], v[142:143], v[86:87], v[126:127]
	v_pk_fma_f32 v[144:145], v[144:145], v[88:89], v[128:129]
	v_pk_fma_f32 v[146:147], v[146:147], v[90:91], v[130:131]
	v_pk_fma_f32 v[148:149], v[148:149], v[92:93], v[132:133]
	v_pk_fma_f32 v[150:151], v[150:151], v[94:95], v[134:135]
	v_pk_fma_f32 v[152:153], v[152:153], v[96:97], v[136:137]
	v_pk_fma_f32 v[154:155], v[154:155], v[98:99], v[138:139]
	v_cvt_pk_bf16_f32 v172, v140, v141
	v_cvt_pk_bf16_f32 v173, v142, v143
	v_cvt_pk_bf16_f32 v174, v144, v145
	v_cvt_pk_bf16_f32 v175, v146, v147
	v_cvt_pk_bf16_f32 v176, v148, v149
	v_cvt_pk_bf16_f32 v177, v150, v151
	v_cvt_pk_bf16_f32 v178, v152, v153
	v_cvt_pk_bf16_f32 v179, v154, v155
	global_store_dwordx4 v109, v[172:175], s[20:21]
	global_store_dwordx4 v109, v[176:179], s[20:21] offset:1024
	v_lshlrev_b32_e32 v140, 16, v76
	v_and_b32_e32 v141, 0xffff0000, v76
	v_lshlrev_b32_e32 v142, 16, v77
	v_and_b32_e32 v143, 0xffff0000, v77
	v_lshlrev_b32_e32 v144, 16, v78
	v_and_b32_e32 v145, 0xffff0000, v78
	v_lshlrev_b32_e32 v146, 16, v79
	v_and_b32_e32 v147, 0xffff0000, v79
	v_lshlrev_b32_e32 v148, 16, v80
	v_and_b32_e32 v149, 0xffff0000, v80
	v_lshlrev_b32_e32 v150, 16, v81
	v_and_b32_e32 v151, 0xffff0000, v81
	v_lshlrev_b32_e32 v152, 16, v82
	v_and_b32_e32 v153, 0xffff0000, v82
	v_lshlrev_b32_e32 v154, 16, v83
	v_and_b32_e32 v155, 0xffff0000, v83
	v_pk_mul_f32 v[140:141], v[162:163], v[140:141] op_sel_hi:[0,1]
	v_pk_mul_f32 v[142:143], v[162:163], v[142:143] op_sel_hi:[0,1]
	v_pk_mul_f32 v[144:145], v[162:163], v[144:145] op_sel_hi:[0,1]
	v_pk_mul_f32 v[146:147], v[162:163], v[146:147] op_sel_hi:[0,1]
	v_pk_mul_f32 v[148:149], v[162:163], v[148:149] op_sel_hi:[0,1]
	v_pk_mul_f32 v[150:151], v[162:163], v[150:151] op_sel_hi:[0,1]
	v_pk_mul_f32 v[152:153], v[162:163], v[152:153] op_sel_hi:[0,1]
	v_pk_mul_f32 v[154:155], v[162:163], v[154:155] op_sel_hi:[0,1]
	v_pk_mul_f32 v[140:141], v[140:141], v[32:33]
	v_pk_mul_f32 v[142:143], v[142:143], v[34:35]
	v_pk_mul_f32 v[144:145], v[144:145], v[36:37]
	v_pk_mul_f32 v[146:147], v[146:147], v[38:39]
	v_pk_mul_f32 v[148:149], v[148:149], v[40:41]
	v_pk_mul_f32 v[150:151], v[150:151], v[42:43]
	v_pk_mul_f32 v[152:153], v[152:153], v[44:45]
	v_pk_mul_f32 v[154:155], v[154:155], v[46:47]
	v_pk_fma_f32 v[140:141], v[140:141], v[84:85], v[124:125]
	v_pk_fma_f32 v[142:143], v[142:143], v[86:87], v[126:127]
	v_pk_fma_f32 v[144:145], v[144:145], v[88:89], v[128:129]
	v_pk_fma_f32 v[146:147], v[146:147], v[90:91], v[130:131]
	v_pk_fma_f32 v[148:149], v[148:149], v[92:93], v[132:133]
	v_pk_fma_f32 v[150:151], v[150:151], v[94:95], v[134:135]
	v_pk_fma_f32 v[152:153], v[152:153], v[96:97], v[136:137]
	v_pk_fma_f32 v[154:155], v[154:155], v[98:99], v[138:139]
	v_cvt_pk_bf16_f32 v164, v140, v141
	v_cvt_pk_bf16_f32 v165, v142, v143
	v_cvt_pk_bf16_f32 v166, v144, v145
	v_cvt_pk_bf16_f32 v167, v146, v147
	v_cvt_pk_bf16_f32 v168, v148, v149
	v_cvt_pk_bf16_f32 v169, v150, v151
	v_cvt_pk_bf16_f32 v170, v152, v153
	v_cvt_pk_bf16_f32 v171, v154, v155
	global_store_dwordx4 v109, v[164:167], s[20:21] offset:2048
	global_store_dwordx4 v109, v[168:171], s[20:21] offset:3072
	s_add_u32 s20, s20, 0x2000
	s_addc_u32 s21, s21, 0
	s_add_u32 s18, s18, 0x2000
	s_addc_u32 s19, s19, 0
	global_load_dwordx4 v[52:55], v51, s[18:19]
	global_load_dwordx4 v[56:59], v51, s[18:19] offset:1024
	global_load_dwordx4 v[60:63], v51, s[18:19] offset:2048
	global_load_dwordx4 v[64:67], v51, s[18:19] offset:3072
	global_load_dwordx4 v[68:71], v109, s[18:19]
	global_load_dwordx4 v[72:75], v109, s[18:19] offset:1024
	global_load_dwordx4 v[76:79], v109, s[18:19] offset:2048
	global_load_dwordx4 v[80:83], v109, s[18:19] offset:3072
	s_waitcnt vmcnt(16)
	v_lshlrev_b32_e32 v140, 16, v0
	v_and_b32_e32 v141, 0xffff0000, v0
	v_lshlrev_b32_e32 v142, 16, v1
	v_and_b32_e32 v143, 0xffff0000, v1
	v_lshlrev_b32_e32 v144, 16, v2
	v_and_b32_e32 v145, 0xffff0000, v2
	v_lshlrev_b32_e32 v146, 16, v3
	v_and_b32_e32 v147, 0xffff0000, v3
	v_lshlrev_b32_e32 v148, 16, v4
	v_and_b32_e32 v149, 0xffff0000, v4
	v_lshlrev_b32_e32 v150, 16, v5
	v_and_b32_e32 v151, 0xffff0000, v5
	v_lshlrev_b32_e32 v152, 16, v6
	v_and_b32_e32 v153, 0xffff0000, v6
	v_lshlrev_b32_e32 v154, 16, v7
	v_and_b32_e32 v155, 0xffff0000, v7
	v_pk_mul_f32 v[100:101], v[140:141], v[140:141]
	v_pk_fma_f32 v[100:101], v[142:143], v[142:143], v[100:101]
	v_pk_fma_f32 v[100:101], v[144:145], v[144:145], v[100:101]
	v_pk_fma_f32 v[100:101], v[146:147], v[146:147], v[100:101]
	v_pk_fma_f32 v[100:101], v[148:149], v[148:149], v[100:101]
	v_pk_fma_f32 v[100:101], v[150:151], v[150:151], v[100:101]
	v_pk_fma_f32 v[100:101], v[152:153], v[152:153], v[100:101]
	v_pk_fma_f32 v[100:101], v[154:155], v[154:155], v[100:101]
	v_lshlrev_b32_e32 v140, 16, v8
	v_and_b32_e32 v141, 0xffff0000, v8
	v_lshlrev_b32_e32 v142, 16, v9
	v_and_b32_e32 v143, 0xffff0000, v9
	v_lshlrev_b32_e32 v144, 16, v10
	v_and_b32_e32 v145, 0xffff0000, v10
	v_lshlrev_b32_e32 v146, 16, v11
	v_and_b32_e32 v147, 0xffff0000, v11
	v_lshlrev_b32_e32 v148, 16, v12
	v_and_b32_e32 v149, 0xffff0000, v12
	v_lshlrev_b32_e32 v150, 16, v13
	v_and_b32_e32 v151, 0xffff0000, v13
	v_lshlrev_b32_e32 v152, 16, v14
	v_and_b32_e32 v153, 0xffff0000, v14
	v_lshlrev_b32_e32 v154, 16, v15
	v_and_b32_e32 v155, 0xffff0000, v15
	v_pk_mul_f32 v[102:103], v[140:141], v[140:141]
	v_pk_fma_f32 v[102:103], v[142:143], v[142:143], v[102:103]
	v_pk_fma_f32 v[102:103], v[144:145], v[144:145], v[102:103]
	v_pk_fma_f32 v[102:103], v[146:147], v[146:147], v[102:103]
	v_pk_fma_f32 v[102:103], v[148:149], v[148:149], v[102:103]
	v_pk_fma_f32 v[102:103], v[150:151], v[150:151], v[102:103]
	v_pk_fma_f32 v[102:103], v[152:153], v[152:153], v[102:103]
	v_pk_fma_f32 v[102:103], v[154:155], v[154:155], v[102:103]
	v_lshlrev_b32_e32 v140, 16, v16
	v_and_b32_e32 v141, 0xffff0000, v16
	v_lshlrev_b32_e32 v142, 16, v17
	v_and_b32_e32 v143, 0xffff0000, v17
	v_lshlrev_b32_e32 v144, 16, v18
	v_and_b32_e32 v145, 0xffff0000, v18
	v_lshlrev_b32_e32 v146, 16, v19
	v_and_b32_e32 v147, 0xffff0000, v19
	v_lshlrev_b32_e32 v148, 16, v20
	v_and_b32_e32 v149, 0xffff0000, v20
	v_lshlrev_b32_e32 v150, 16, v21
	v_and_b32_e32 v151, 0xffff0000, v21
	v_lshlrev_b32_e32 v152, 16, v22
	v_and_b32_e32 v153, 0xffff0000, v22
	v_lshlrev_b32_e32 v154, 16, v23
	v_and_b32_e32 v155, 0xffff0000, v23
	v_pk_mul_f32 v[104:105], v[140:141], v[140:141]
	v_pk_fma_f32 v[104:105], v[142:143], v[142:143], v[104:105]
	v_pk_fma_f32 v[104:105], v[144:145], v[144:145], v[104:105]
	v_pk_fma_f32 v[104:105], v[146:147], v[146:147], v[104:105]
	v_pk_fma_f32 v[104:105], v[148:149], v[148:149], v[104:105]
	v_pk_fma_f32 v[104:105], v[150:151], v[150:151], v[104:105]
	v_pk_fma_f32 v[104:105], v[152:153], v[152:153], v[104:105]
	v_pk_fma_f32 v[104:105], v[154:155], v[154:155], v[104:105]
	v_lshlrev_b32_e32 v140, 16, v24
	v_and_b32_e32 v141, 0xffff0000, v24
	v_lshlrev_b32_e32 v142, 16, v25
	v_and_b32_e32 v143, 0xffff0000, v25
	v_lshlrev_b32_e32 v144, 16, v26
	v_and_b32_e32 v145, 0xffff0000, v26
	v_lshlrev_b32_e32 v146, 16, v27
	v_and_b32_e32 v147, 0xffff0000, v27
	v_lshlrev_b32_e32 v148, 16, v28
	v_and_b32_e32 v149, 0xffff0000, v28
	v_lshlrev_b32_e32 v150, 16, v29
	v_and_b32_e32 v151, 0xffff0000, v29
	v_lshlrev_b32_e32 v152, 16, v30
	v_and_b32_e32 v153, 0xffff0000, v30
	v_lshlrev_b32_e32 v154, 16, v31
	v_and_b32_e32 v155, 0xffff0000, v31
	v_pk_mul_f32 v[106:107], v[140:141], v[140:141]
	v_pk_fma_f32 v[106:107], v[142:143], v[142:143], v[106:107]
	v_pk_fma_f32 v[106:107], v[144:145], v[144:145], v[106:107]
	v_pk_fma_f32 v[106:107], v[146:147], v[146:147], v[106:107]
	v_pk_fma_f32 v[106:107], v[148:149], v[148:149], v[106:107]
	v_pk_fma_f32 v[106:107], v[150:151], v[150:151], v[106:107]
	v_pk_fma_f32 v[106:107], v[152:153], v[152:153], v[106:107]
	v_pk_fma_f32 v[106:107], v[154:155], v[154:155], v[106:107]
	v_add_f32_e32 v100, v100, v101
	v_add_f32_e32 v102, v102, v103
	v_add_f32_e32 v104, v104, v105
	v_add_f32_e32 v106, v106, v107
	s_nop 1
	v_add_f32_dpp v100, v100, v100 row_shr:1 row_mask:0xf bank_mask:0xf bound_ctrl:1
	v_add_f32_dpp v102, v102, v102 row_shr:1 row_mask:0xf bank_mask:0xf bound_ctrl:1
	v_add_f32_dpp v104, v104, v104 row_shr:1 row_mask:0xf bank_mask:0xf bound_ctrl:1
	v_add_f32_dpp v106, v106, v106 row_shr:1 row_mask:0xf bank_mask:0xf bound_ctrl:1
	v_add_f32_dpp v100, v100, v100 row_shr:2 row_mask:0xf bank_mask:0xf bound_ctrl:1
	v_add_f32_dpp v102, v102, v102 row_shr:2 row_mask:0xf bank_mask:0xf bound_ctrl:1
	v_add_f32_dpp v104, v104, v104 row_shr:2 row_mask:0xf bank_mask:0xf bound_ctrl:1
	v_add_f32_dpp v106, v106, v106 row_shr:2 row_mask:0xf bank_mask:0xf bound_ctrl:1
	v_add_f32_dpp v100, v100, v100 row_shr:4 row_mask:0xf bank_mask:0xf bound_ctrl:1
	v_add_f32_dpp v102, v102, v102 row_shr:4 row_mask:0xf bank_mask:0xf bound_ctrl:1
	v_add_f32_dpp v104, v104, v104 row_shr:4 row_mask:0xf bank_mask:0xf bound_ctrl:1
	v_add_f32_dpp v106, v106, v106 row_shr:4 row_mask:0xf bank_mask:0xf bound_ctrl:1
	v_add_f32_dpp v100, v100, v100 row_shr:8 row_mask:0xf bank_mask:0xf bound_ctrl:1
	v_add_f32_dpp v102, v102, v102 row_shr:8 row_mask:0xf bank_mask:0xf bound_ctrl:1
	v_add_f32_dpp v104, v104, v104 row_shr:8 row_mask:0xf bank_mask:0xf bound_ctrl:1
	v_add_f32_dpp v106, v106, v106 row_shr:8 row_mask:0xf bank_mask:0xf bound_ctrl:1
	v_add_f32_dpp v100, v100, v100 row_bcast:15 row_mask:0xa bank_mask:0xf
	v_add_f32_dpp v102, v102, v102 row_bcast:15 row_mask:0xa bank_mask:0xf
	v_add_f32_dpp v104, v104, v104 row_bcast:15 row_mask:0xa bank_mask:0xf
	v_add_f32_dpp v106, v106, v106 row_bcast:15 row_mask:0xa bank_mask:0xf
	v_add_f32_dpp v100, v100, v100 row_bcast:31 row_mask:0xc bank_mask:0xf
	v_add_f32_dpp v102, v102, v102 row_bcast:31 row_mask:0xc bank_mask:0xf
	v_add_f32_dpp v104, v104, v104 row_bcast:31 row_mask:0xc bank_mask:0xf
	v_add_f32_dpp v106, v106, v106 row_bcast:31 row_mask:0xc bank_mask:0xf
	s_nop 1
	v_readlane_b32 s5, v100, 63
	v_readlane_b32 s32, v102, 63
	v_readlane_b32 s54, v104, 63
	v_readlane_b32 s60, v106, 63
	s_nop 1
	v_mov_b32_e32 v156, s5
	v_mov_b32_e32 v158, s32
	v_mov_b32_e32 v160, s54
	v_mov_b32_e32 v162, s60
	v_fmaak_f32 v156, v156, v50, 0x358637bd
	v_fmaak_f32 v158, v158, v50, 0x358637bd
	v_fmaak_f32 v160, v160, v50, 0x358637bd
	v_fmaak_f32 v162, v162, v50, 0x358637bd
	v_rsq_f32_e32 v156, v156
	v_rsq_f32_e32 v158, v158
	v_rsq_f32_e32 v160, v160
	v_rsq_f32_e32 v162, v162
	s_nop 0
	v_lshlrev_b32_e32 v140, 16, v0
	v_and_b32_e32 v141, 0xffff0000, v0
	v_lshlrev_b32_e32 v142, 16, v1
	v_and_b32_e32 v143, 0xffff0000, v1
	v_lshlrev_b32_e32 v144, 16, v2
	v_and_b32_e32 v145, 0xffff0000, v2
	v_lshlrev_b32_e32 v146, 16, v3
	v_and_b32_e32 v147, 0xffff0000, v3
	v_lshlrev_b32_e32 v148, 16, v4
	v_and_b32_e32 v149, 0xffff0000, v4
	v_lshlrev_b32_e32 v150, 16, v5
	v_and_b32_e32 v151, 0xffff0000, v5
	v_lshlrev_b32_e32 v152, 16, v6
	v_and_b32_e32 v153, 0xffff0000, v6
	v_lshlrev_b32_e32 v154, 16, v7
	v_and_b32_e32 v155, 0xffff0000, v7
	v_pk_mul_f32 v[140:141], v[156:157], v[140:141] op_sel_hi:[0,1]
	v_pk_mul_f32 v[142:143], v[156:157], v[142:143] op_sel_hi:[0,1]
	v_pk_mul_f32 v[144:145], v[156:157], v[144:145] op_sel_hi:[0,1]
	v_pk_mul_f32 v[146:147], v[156:157], v[146:147] op_sel_hi:[0,1]
	v_pk_mul_f32 v[148:149], v[156:157], v[148:149] op_sel_hi:[0,1]
	v_pk_mul_f32 v[150:151], v[156:157], v[150:151] op_sel_hi:[0,1]
	v_pk_mul_f32 v[152:153], v[156:157], v[152:153] op_sel_hi:[0,1]
	v_pk_mul_f32 v[154:155], v[156:157], v[154:155] op_sel_hi:[0,1]
	v_pk_mul_f32 v[140:141], v[140:141], v[32:33]
	v_pk_mul_f32 v[142:143], v[142:143], v[34:35]
	v_pk_mul_f32 v[144:145], v[144:145], v[36:37]
	v_pk_mul_f32 v[146:147], v[146:147], v[38:39]
	v_pk_mul_f32 v[148:149], v[148:149], v[40:41]
	v_pk_mul_f32 v[150:151], v[150:151], v[42:43]
	v_pk_mul_f32 v[152:153], v[152:153], v[44:45]
	v_pk_mul_f32 v[154:155], v[154:155], v[46:47]
	v_pk_fma_f32 v[140:141], v[140:141], v[84:85], v[124:125]
	v_pk_fma_f32 v[142:143], v[142:143], v[86:87], v[126:127]
	v_pk_fma_f32 v[144:145], v[144:145], v[88:89], v[128:129]
	v_pk_fma_f32 v[146:147], v[146:147], v[90:91], v[130:131]
	v_pk_fma_f32 v[148:149], v[148:149], v[92:93], v[132:133]
	v_pk_fma_f32 v[150:151], v[150:151], v[94:95], v[134:135]
	v_pk_fma_f32 v[152:153], v[152:153], v[96:97], v[136:137]
	v_pk_fma_f32 v[154:155], v[154:155], v[98:99], v[138:139]
	v_cvt_pk_bf16_f32 v164, v140, v141
	v_cvt_pk_bf16_f32 v165, v142, v143
	v_cvt_pk_bf16_f32 v166, v144, v145
	v_cvt_pk_bf16_f32 v167, v146, v147
	v_cvt_pk_bf16_f32 v168, v148, v149
	v_cvt_pk_bf16_f32 v169, v150, v151
	v_cvt_pk_bf16_f32 v170, v152, v153
	v_cvt_pk_bf16_f32 v171, v154, v155
	global_store_dwordx4 v51, v[164:167], s[20:21]
	global_store_dwordx4 v51, v[168:171], s[20:21] offset:1024
	v_lshlrev_b32_e32 v140, 16, v8
	v_and_b32_e32 v141, 0xffff0000, v8
	v_lshlrev_b32_e32 v142, 16, v9
	v_and_b32_e32 v143, 0xffff0000, v9
	v_lshlrev_b32_e32 v144, 16, v10
	v_and_b32_e32 v145, 0xffff0000, v10
	v_lshlrev_b32_e32 v146, 16, v11
	v_and_b32_e32 v147, 0xffff0000, v11
	v_lshlrev_b32_e32 v148, 16, v12
	v_and_b32_e32 v149, 0xffff0000, v12
	v_lshlrev_b32_e32 v150, 16, v13
	v_and_b32_e32 v151, 0xffff0000, v13
	v_lshlrev_b32_e32 v152, 16, v14
	v_and_b32_e32 v153, 0xffff0000, v14
	v_lshlrev_b32_e32 v154, 16, v15
	v_and_b32_e32 v155, 0xffff0000, v15
	v_pk_mul_f32 v[140:141], v[158:159], v[140:141] op_sel_hi:[0,1]
	v_pk_mul_f32 v[142:143], v[158:159], v[142:143] op_sel_hi:[0,1]
	v_pk_mul_f32 v[144:145], v[158:159], v[144:145] op_sel_hi:[0,1]
	v_pk_mul_f32 v[146:147], v[158:159], v[146:147] op_sel_hi:[0,1]
	v_pk_mul_f32 v[148:149], v[158:159], v[148:149] op_sel_hi:[0,1]
	v_pk_mul_f32 v[150:151], v[158:159], v[150:151] op_sel_hi:[0,1]
	v_pk_mul_f32 v[152:153], v[158:159], v[152:153] op_sel_hi:[0,1]
	v_pk_mul_f32 v[154:155], v[158:159], v[154:155] op_sel_hi:[0,1]
	v_pk_mul_f32 v[140:141], v[140:141], v[32:33]
	v_pk_mul_f32 v[142:143], v[142:143], v[34:35]
	v_pk_mul_f32 v[144:145], v[144:145], v[36:37]
	v_pk_mul_f32 v[146:147], v[146:147], v[38:39]
	v_pk_mul_f32 v[148:149], v[148:149], v[40:41]
	v_pk_mul_f32 v[150:151], v[150:151], v[42:43]
	v_pk_mul_f32 v[152:153], v[152:153], v[44:45]
	v_pk_mul_f32 v[154:155], v[154:155], v[46:47]
	v_pk_fma_f32 v[140:141], v[140:141], v[84:85], v[124:125]
	v_pk_fma_f32 v[142:143], v[142:143], v[86:87], v[126:127]
	v_pk_fma_f32 v[144:145], v[144:145], v[88:89], v[128:129]
	v_pk_fma_f32 v[146:147], v[146:147], v[90:91], v[130:131]
	v_pk_fma_f32 v[148:149], v[148:149], v[92:93], v[132:133]
	v_pk_fma_f32 v[150:151], v[150:151], v[94:95], v[134:135]
	v_pk_fma_f32 v[152:153], v[152:153], v[96:97], v[136:137]
	v_pk_fma_f32 v[154:155], v[154:155], v[98:99], v[138:139]
	v_cvt_pk_bf16_f32 v172, v140, v141
	v_cvt_pk_bf16_f32 v173, v142, v143
	v_cvt_pk_bf16_f32 v174, v144, v145
	v_cvt_pk_bf16_f32 v175, v146, v147
	v_cvt_pk_bf16_f32 v176, v148, v149
	v_cvt_pk_bf16_f32 v177, v150, v151
	v_cvt_pk_bf16_f32 v178, v152, v153
	v_cvt_pk_bf16_f32 v179, v154, v155
	global_store_dwordx4 v51, v[172:175], s[20:21] offset:2048
	global_store_dwordx4 v51, v[176:179], s[20:21] offset:3072
	v_lshlrev_b32_e32 v140, 16, v16
	v_and_b32_e32 v141, 0xffff0000, v16
	v_lshlrev_b32_e32 v142, 16, v17
	v_and_b32_e32 v143, 0xffff0000, v17
	v_lshlrev_b32_e32 v144, 16, v18
	v_and_b32_e32 v145, 0xffff0000, v18
	v_lshlrev_b32_e32 v146, 16, v19
	v_and_b32_e32 v147, 0xffff0000, v19
	v_lshlrev_b32_e32 v148, 16, v20
	v_and_b32_e32 v149, 0xffff0000, v20
	v_lshlrev_b32_e32 v150, 16, v21
	v_and_b32_e32 v151, 0xffff0000, v21
	v_lshlrev_b32_e32 v152, 16, v22
	v_and_b32_e32 v153, 0xffff0000, v22
	v_lshlrev_b32_e32 v154, 16, v23
	v_and_b32_e32 v155, 0xffff0000, v23
	v_pk_mul_f32 v[140:141], v[160:161], v[140:141] op_sel_hi:[0,1]
	v_pk_mul_f32 v[142:143], v[160:161], v[142:143] op_sel_hi:[0,1]
	v_pk_mul_f32 v[144:145], v[160:161], v[144:145] op_sel_hi:[0,1]
	v_pk_mul_f32 v[146:147], v[160:161], v[146:147] op_sel_hi:[0,1]
	v_pk_mul_f32 v[148:149], v[160:161], v[148:149] op_sel_hi:[0,1]
	v_pk_mul_f32 v[150:151], v[160:161], v[150:151] op_sel_hi:[0,1]
	v_pk_mul_f32 v[152:153], v[160:161], v[152:153] op_sel_hi:[0,1]
	v_pk_mul_f32 v[154:155], v[160:161], v[154:155] op_sel_hi:[0,1]
	v_pk_mul_f32 v[140:141], v[140:141], v[32:33]
	v_pk_mul_f32 v[142:143], v[142:143], v[34:35]
	v_pk_mul_f32 v[144:145], v[144:145], v[36:37]
	v_pk_mul_f32 v[146:147], v[146:147], v[38:39]
	v_pk_mul_f32 v[148:149], v[148:149], v[40:41]
	v_pk_mul_f32 v[150:151], v[150:151], v[42:43]
	v_pk_mul_f32 v[152:153], v[152:153], v[44:45]
	v_pk_mul_f32 v[154:155], v[154:155], v[46:47]
	v_pk_fma_f32 v[140:141], v[140:141], v[84:85], v[124:125]
	v_pk_fma_f32 v[142:143], v[142:143], v[86:87], v[126:127]
	v_pk_fma_f32 v[144:145], v[144:145], v[88:89], v[128:129]
	v_pk_fma_f32 v[146:147], v[146:147], v[90:91], v[130:131]
	v_pk_fma_f32 v[148:149], v[148:149], v[92:93], v[132:133]
	v_pk_fma_f32 v[150:151], v[150:151], v[94:95], v[134:135]
	v_pk_fma_f32 v[152:153], v[152:153], v[96:97], v[136:137]
	v_pk_fma_f32 v[154:155], v[154:155], v[98:99], v[138:139]
	v_cvt_pk_bf16_f32 v164, v140, v141
	v_cvt_pk_bf16_f32 v165, v142, v143
	v_cvt_pk_bf16_f32 v166, v144, v145
	v_cvt_pk_bf16_f32 v167, v146, v147
	v_cvt_pk_bf16_f32 v168, v148, v149
	v_cvt_pk_bf16_f32 v169, v150, v151
	v_cvt_pk_bf16_f32 v170, v152, v153
	v_cvt_pk_bf16_f32 v171, v154, v155
	global_store_dwordx4 v109, v[164:167], s[20:21]
	global_store_dwordx4 v109, v[168:171], s[20:21] offset:1024
	v_lshlrev_b32_e32 v140, 16, v24
	v_and_b32_e32 v141, 0xffff0000, v24
	v_lshlrev_b32_e32 v142, 16, v25
	v_and_b32_e32 v143, 0xffff0000, v25
	v_lshlrev_b32_e32 v144, 16, v26
	v_and_b32_e32 v145, 0xffff0000, v26
	v_lshlrev_b32_e32 v146, 16, v27
	v_and_b32_e32 v147, 0xffff0000, v27
	v_lshlrev_b32_e32 v148, 16, v28
	v_and_b32_e32 v149, 0xffff0000, v28
	v_lshlrev_b32_e32 v150, 16, v29
	v_and_b32_e32 v151, 0xffff0000, v29
	v_lshlrev_b32_e32 v152, 16, v30
	v_and_b32_e32 v153, 0xffff0000, v30
	v_lshlrev_b32_e32 v154, 16, v31
	v_and_b32_e32 v155, 0xffff0000, v31
	v_pk_mul_f32 v[140:141], v[162:163], v[140:141] op_sel_hi:[0,1]
	v_pk_mul_f32 v[142:143], v[162:163], v[142:143] op_sel_hi:[0,1]
	v_pk_mul_f32 v[144:145], v[162:163], v[144:145] op_sel_hi:[0,1]
	v_pk_mul_f32 v[146:147], v[162:163], v[146:147] op_sel_hi:[0,1]
	v_pk_mul_f32 v[148:149], v[162:163], v[148:149] op_sel_hi:[0,1]
	v_pk_mul_f32 v[150:151], v[162:163], v[150:151] op_sel_hi:[0,1]
	v_pk_mul_f32 v[152:153], v[162:163], v[152:153] op_sel_hi:[0,1]
	v_pk_mul_f32 v[154:155], v[162:163], v[154:155] op_sel_hi:[0,1]
	v_pk_mul_f32 v[140:141], v[140:141], v[32:33]
	v_pk_mul_f32 v[142:143], v[142:143], v[34:35]
	v_pk_mul_f32 v[144:145], v[144:145], v[36:37]
	v_pk_mul_f32 v[146:147], v[146:147], v[38:39]
	v_pk_mul_f32 v[148:149], v[148:149], v[40:41]
	v_pk_mul_f32 v[150:151], v[150:151], v[42:43]
	v_pk_mul_f32 v[152:153], v[152:153], v[44:45]
	v_pk_mul_f32 v[154:155], v[154:155], v[46:47]
	v_pk_fma_f32 v[140:141], v[140:141], v[84:85], v[124:125]
	v_pk_fma_f32 v[142:143], v[142:143], v[86:87], v[126:127]
	v_pk_fma_f32 v[144:145], v[144:145], v[88:89], v[128:129]
	v_pk_fma_f32 v[146:147], v[146:147], v[90:91], v[130:131]
	v_pk_fma_f32 v[148:149], v[148:149], v[92:93], v[132:133]
	v_pk_fma_f32 v[150:151], v[150:151], v[94:95], v[134:135]
	v_pk_fma_f32 v[152:153], v[152:153], v[96:97], v[136:137]
	v_pk_fma_f32 v[154:155], v[154:155], v[98:99], v[138:139]
	v_cvt_pk_bf16_f32 v172, v140, v141
	v_cvt_pk_bf16_f32 v173, v142, v143
	v_cvt_pk_bf16_f32 v174, v144, v145
	v_cvt_pk_bf16_f32 v175, v146, v147
	v_cvt_pk_bf16_f32 v176, v148, v149
	v_cvt_pk_bf16_f32 v177, v150, v151
	v_cvt_pk_bf16_f32 v178, v152, v153
	v_cvt_pk_bf16_f32 v179, v154, v155
	global_store_dwordx4 v109, v[172:175], s[20:21] offset:2048
	global_store_dwordx4 v109, v[176:179], s[20:21] offset:3072
	s_add_u32 s20, s20, 0x2000
	s_addc_u32 s21, s21, 0
	s_add_u32 s18, s18, 0x2000
	s_addc_u32 s19, s19, 0
	global_load_dwordx4 v[0:3], v51, s[18:19]
	global_load_dwordx4 v[4:7], v51, s[18:19] offset:1024
	global_load_dwordx4 v[8:11], v51, s[18:19] offset:2048
	global_load_dwordx4 v[12:15], v51, s[18:19] offset:3072
	global_load_dwordx4 v[16:19], v109, s[18:19]
	global_load_dwordx4 v[20:23], v109, s[18:19] offset:1024
	global_load_dwordx4 v[24:27], v109, s[18:19] offset:2048
	global_load_dwordx4 v[28:31], v109, s[18:19] offset:3072
	s_waitcnt vmcnt(16)
	v_lshlrev_b32_e32 v140, 16, v52
	v_and_b32_e32 v141, 0xffff0000, v52
	v_lshlrev_b32_e32 v142, 16, v53
	v_and_b32_e32 v143, 0xffff0000, v53
	v_lshlrev_b32_e32 v144, 16, v54
	v_and_b32_e32 v145, 0xffff0000, v54
	v_lshlrev_b32_e32 v146, 16, v55
	v_and_b32_e32 v147, 0xffff0000, v55
	v_lshlrev_b32_e32 v148, 16, v56
	v_and_b32_e32 v149, 0xffff0000, v56
	v_lshlrev_b32_e32 v150, 16, v57
	v_and_b32_e32 v151, 0xffff0000, v57
	v_lshlrev_b32_e32 v152, 16, v58
	v_and_b32_e32 v153, 0xffff0000, v58
	v_lshlrev_b32_e32 v154, 16, v59
	v_and_b32_e32 v155, 0xffff0000, v59
	v_pk_mul_f32 v[100:101], v[140:141], v[140:141]
	v_pk_fma_f32 v[100:101], v[142:143], v[142:143], v[100:101]
	v_pk_fma_f32 v[100:101], v[144:145], v[144:145], v[100:101]
	v_pk_fma_f32 v[100:101], v[146:147], v[146:147], v[100:101]
	v_pk_fma_f32 v[100:101], v[148:149], v[148:149], v[100:101]
	v_pk_fma_f32 v[100:101], v[150:151], v[150:151], v[100:101]
	v_pk_fma_f32 v[100:101], v[152:153], v[152:153], v[100:101]
	v_pk_fma_f32 v[100:101], v[154:155], v[154:155], v[100:101]
	v_lshlrev_b32_e32 v140, 16, v60
	v_and_b32_e32 v141, 0xffff0000, v60
	v_lshlrev_b32_e32 v142, 16, v61
	v_and_b32_e32 v143, 0xffff0000, v61
	v_lshlrev_b32_e32 v144, 16, v62
	v_and_b32_e32 v145, 0xffff0000, v62
	v_lshlrev_b32_e32 v146, 16, v63
	v_and_b32_e32 v147, 0xffff0000, v63
	v_lshlrev_b32_e32 v148, 16, v64
	v_and_b32_e32 v149, 0xffff0000, v64
	v_lshlrev_b32_e32 v150, 16, v65
	v_and_b32_e32 v151, 0xffff0000, v65
	v_lshlrev_b32_e32 v152, 16, v66
	v_and_b32_e32 v153, 0xffff0000, v66
	v_lshlrev_b32_e32 v154, 16, v67
	v_and_b32_e32 v155, 0xffff0000, v67
	v_pk_mul_f32 v[102:103], v[140:141], v[140:141]
	v_pk_fma_f32 v[102:103], v[142:143], v[142:143], v[102:103]
	v_pk_fma_f32 v[102:103], v[144:145], v[144:145], v[102:103]
	v_pk_fma_f32 v[102:103], v[146:147], v[146:147], v[102:103]
	v_pk_fma_f32 v[102:103], v[148:149], v[148:149], v[102:103]
	v_pk_fma_f32 v[102:103], v[150:151], v[150:151], v[102:103]
	v_pk_fma_f32 v[102:103], v[152:153], v[152:153], v[102:103]
	v_pk_fma_f32 v[102:103], v[154:155], v[154:155], v[102:103]
	v_lshlrev_b32_e32 v140, 16, v68
	v_and_b32_e32 v141, 0xffff0000, v68
	v_lshlrev_b32_e32 v142, 16, v69
	v_and_b32_e32 v143, 0xffff0000, v69
	v_lshlrev_b32_e32 v144, 16, v70
	v_and_b32_e32 v145, 0xffff0000, v70
	v_lshlrev_b32_e32 v146, 16, v71
	v_and_b32_e32 v147, 0xffff0000, v71
	v_lshlrev_b32_e32 v148, 16, v72
	v_and_b32_e32 v149, 0xffff0000, v72
	v_lshlrev_b32_e32 v150, 16, v73
	v_and_b32_e32 v151, 0xffff0000, v73
	v_lshlrev_b32_e32 v152, 16, v74
	v_and_b32_e32 v153, 0xffff0000, v74
	v_lshlrev_b32_e32 v154, 16, v75
	v_and_b32_e32 v155, 0xffff0000, v75
	v_pk_mul_f32 v[104:105], v[140:141], v[140:141]
	v_pk_fma_f32 v[104:105], v[142:143], v[142:143], v[104:105]
	v_pk_fma_f32 v[104:105], v[144:145], v[144:145], v[104:105]
	v_pk_fma_f32 v[104:105], v[146:147], v[146:147], v[104:105]
	v_pk_fma_f32 v[104:105], v[148:149], v[148:149], v[104:105]
	v_pk_fma_f32 v[104:105], v[150:151], v[150:151], v[104:105]
	v_pk_fma_f32 v[104:105], v[152:153], v[152:153], v[104:105]
	v_pk_fma_f32 v[104:105], v[154:155], v[154:155], v[104:105]
	v_lshlrev_b32_e32 v140, 16, v76
	v_and_b32_e32 v141, 0xffff0000, v76
	v_lshlrev_b32_e32 v142, 16, v77
	v_and_b32_e32 v143, 0xffff0000, v77
	v_lshlrev_b32_e32 v144, 16, v78
	v_and_b32_e32 v145, 0xffff0000, v78
	v_lshlrev_b32_e32 v146, 16, v79
	v_and_b32_e32 v147, 0xffff0000, v79
	v_lshlrev_b32_e32 v148, 16, v80
	v_and_b32_e32 v149, 0xffff0000, v80
	v_lshlrev_b32_e32 v150, 16, v81
	v_and_b32_e32 v151, 0xffff0000, v81
	v_lshlrev_b32_e32 v152, 16, v82
	v_and_b32_e32 v153, 0xffff0000, v82
	v_lshlrev_b32_e32 v154, 16, v83
	v_and_b32_e32 v155, 0xffff0000, v83
	v_pk_mul_f32 v[106:107], v[140:141], v[140:141]
	v_pk_fma_f32 v[106:107], v[142:143], v[142:143], v[106:107]
	v_pk_fma_f32 v[106:107], v[144:145], v[144:145], v[106:107]
	v_pk_fma_f32 v[106:107], v[146:147], v[146:147], v[106:107]
	v_pk_fma_f32 v[106:107], v[148:149], v[148:149], v[106:107]
	v_pk_fma_f32 v[106:107], v[150:151], v[150:151], v[106:107]
	v_pk_fma_f32 v[106:107], v[152:153], v[152:153], v[106:107]
	v_pk_fma_f32 v[106:107], v[154:155], v[154:155], v[106:107]
	v_add_f32_e32 v100, v100, v101
	v_add_f32_e32 v102, v102, v103
	v_add_f32_e32 v104, v104, v105
	v_add_f32_e32 v106, v106, v107
	s_nop 1
	v_add_f32_dpp v100, v100, v100 row_shr:1 row_mask:0xf bank_mask:0xf bound_ctrl:1
	v_add_f32_dpp v102, v102, v102 row_shr:1 row_mask:0xf bank_mask:0xf bound_ctrl:1
	v_add_f32_dpp v104, v104, v104 row_shr:1 row_mask:0xf bank_mask:0xf bound_ctrl:1
	v_add_f32_dpp v106, v106, v106 row_shr:1 row_mask:0xf bank_mask:0xf bound_ctrl:1
	v_add_f32_dpp v100, v100, v100 row_shr:2 row_mask:0xf bank_mask:0xf bound_ctrl:1
	v_add_f32_dpp v102, v102, v102 row_shr:2 row_mask:0xf bank_mask:0xf bound_ctrl:1
	v_add_f32_dpp v104, v104, v104 row_shr:2 row_mask:0xf bank_mask:0xf bound_ctrl:1
	v_add_f32_dpp v106, v106, v106 row_shr:2 row_mask:0xf bank_mask:0xf bound_ctrl:1
	v_add_f32_dpp v100, v100, v100 row_shr:4 row_mask:0xf bank_mask:0xf bound_ctrl:1
	v_add_f32_dpp v102, v102, v102 row_shr:4 row_mask:0xf bank_mask:0xf bound_ctrl:1
	v_add_f32_dpp v104, v104, v104 row_shr:4 row_mask:0xf bank_mask:0xf bound_ctrl:1
	v_add_f32_dpp v106, v106, v106 row_shr:4 row_mask:0xf bank_mask:0xf bound_ctrl:1
	v_add_f32_dpp v100, v100, v100 row_shr:8 row_mask:0xf bank_mask:0xf bound_ctrl:1
	v_add_f32_dpp v102, v102, v102 row_shr:8 row_mask:0xf bank_mask:0xf bound_ctrl:1
	v_add_f32_dpp v104, v104, v104 row_shr:8 row_mask:0xf bank_mask:0xf bound_ctrl:1
	v_add_f32_dpp v106, v106, v106 row_shr:8 row_mask:0xf bank_mask:0xf bound_ctrl:1
	v_add_f32_dpp v100, v100, v100 row_bcast:15 row_mask:0xa bank_mask:0xf
	v_add_f32_dpp v102, v102, v102 row_bcast:15 row_mask:0xa bank_mask:0xf
	v_add_f32_dpp v104, v104, v104 row_bcast:15 row_mask:0xa bank_mask:0xf
	v_add_f32_dpp v106, v106, v106 row_bcast:15 row_mask:0xa bank_mask:0xf
	v_add_f32_dpp v100, v100, v100 row_bcast:31 row_mask:0xc bank_mask:0xf
	v_add_f32_dpp v102, v102, v102 row_bcast:31 row_mask:0xc bank_mask:0xf
	v_add_f32_dpp v104, v104, v104 row_bcast:31 row_mask:0xc bank_mask:0xf
	v_add_f32_dpp v106, v106, v106 row_bcast:31 row_mask:0xc bank_mask:0xf
	s_nop 1
	v_readlane_b32 s5, v100, 63
	v_readlane_b32 s32, v102, 63
	v_readlane_b32 s54, v104, 63
	v_readlane_b32 s60, v106, 63
	s_nop 1
	v_mov_b32_e32 v156, s5
	v_mov_b32_e32 v158, s32
	v_mov_b32_e32 v160, s54
	v_mov_b32_e32 v162, s60
	v_fmaak_f32 v156, v156, v50, 0x358637bd
	v_fmaak_f32 v158, v158, v50, 0x358637bd
	v_fmaak_f32 v160, v160, v50, 0x358637bd
	v_fmaak_f32 v162, v162, v50, 0x358637bd
	v_rsq_f32_e32 v156, v156
	v_rsq_f32_e32 v158, v158
	v_rsq_f32_e32 v160, v160
	v_rsq_f32_e32 v162, v162
	s_nop 0
	v_lshlrev_b32_e32 v140, 16, v52
	v_and_b32_e32 v141, 0xffff0000, v52
	v_lshlrev_b32_e32 v142, 16, v53
	v_and_b32_e32 v143, 0xffff0000, v53
	v_lshlrev_b32_e32 v144, 16, v54
	v_and_b32_e32 v145, 0xffff0000, v54
	v_lshlrev_b32_e32 v146, 16, v55
	v_and_b32_e32 v147, 0xffff0000, v55
	v_lshlrev_b32_e32 v148, 16, v56
	v_and_b32_e32 v149, 0xffff0000, v56
	v_lshlrev_b32_e32 v150, 16, v57
	v_and_b32_e32 v151, 0xffff0000, v57
	v_lshlrev_b32_e32 v152, 16, v58
	v_and_b32_e32 v153, 0xffff0000, v58
	v_lshlrev_b32_e32 v154, 16, v59
	v_and_b32_e32 v155, 0xffff0000, v59
	v_pk_mul_f32 v[140:141], v[156:157], v[140:141] op_sel_hi:[0,1]
	v_pk_mul_f32 v[142:143], v[156:157], v[142:143] op_sel_hi:[0,1]
	v_pk_mul_f32 v[144:145], v[156:157], v[144:145] op_sel_hi:[0,1]
	v_pk_mul_f32 v[146:147], v[156:157], v[146:147] op_sel_hi:[0,1]
	v_pk_mul_f32 v[148:149], v[156:157], v[148:149] op_sel_hi:[0,1]
	v_pk_mul_f32 v[150:151], v[156:157], v[150:151] op_sel_hi:[0,1]
	v_pk_mul_f32 v[152:153], v[156:157], v[152:153] op_sel_hi:[0,1]
	v_pk_mul_f32 v[154:155], v[156:157], v[154:155] op_sel_hi:[0,1]
	v_pk_mul_f32 v[140:141], v[140:141], v[32:33]
	v_pk_mul_f32 v[142:143], v[142:143], v[34:35]
	v_pk_mul_f32 v[144:145], v[144:145], v[36:37]
	v_pk_mul_f32 v[146:147], v[146:147], v[38:39]
	v_pk_mul_f32 v[148:149], v[148:149], v[40:41]
	v_pk_mul_f32 v[150:151], v[150:151], v[42:43]
	v_pk_mul_f32 v[152:153], v[152:153], v[44:45]
	v_pk_mul_f32 v[154:155], v[154:155], v[46:47]
	v_pk_fma_f32 v[140:141], v[140:141], v[84:85], v[124:125]
	v_pk_fma_f32 v[142:143], v[142:143], v[86:87], v[126:127]
	v_pk_fma_f32 v[144:145], v[144:145], v[88:89], v[128:129]
	v_pk_fma_f32 v[146:147], v[146:147], v[90:91], v[130:131]
	v_pk_fma_f32 v[148:149], v[148:149], v[92:93], v[132:133]
	v_pk_fma_f32 v[150:151], v[150:151], v[94:95], v[134:135]
	v_pk_fma_f32 v[152:153], v[152:153], v[96:97], v[136:137]
	v_pk_fma_f32 v[154:155], v[154:155], v[98:99], v[138:139]
	v_cvt_pk_bf16_f32 v172, v140, v141
	v_cvt_pk_bf16_f32 v173, v142, v143
	v_cvt_pk_bf16_f32 v174, v144, v145
	v_cvt_pk_bf16_f32 v175, v146, v147
	v_cvt_pk_bf16_f32 v176, v148, v149
	v_cvt_pk_bf16_f32 v177, v150, v151
	v_cvt_pk_bf16_f32 v178, v152, v153
	v_cvt_pk_bf16_f32 v179, v154, v155
	global_store_dwordx4 v51, v[172:175], s[20:21]
	global_store_dwordx4 v51, v[176:179], s[20:21] offset:1024
	v_lshlrev_b32_e32 v140, 16, v60
	v_and_b32_e32 v141, 0xffff0000, v60
	v_lshlrev_b32_e32 v142, 16, v61
	v_and_b32_e32 v143, 0xffff0000, v61
	v_lshlrev_b32_e32 v144, 16, v62
	v_and_b32_e32 v145, 0xffff0000, v62
	v_lshlrev_b32_e32 v146, 16, v63
	v_and_b32_e32 v147, 0xffff0000, v63
	v_lshlrev_b32_e32 v148, 16, v64
	v_and_b32_e32 v149, 0xffff0000, v64
	v_lshlrev_b32_e32 v150, 16, v65
	v_and_b32_e32 v151, 0xffff0000, v65
	v_lshlrev_b32_e32 v152, 16, v66
	v_and_b32_e32 v153, 0xffff0000, v66
	v_lshlrev_b32_e32 v154, 16, v67
	v_and_b32_e32 v155, 0xffff0000, v67
	v_pk_mul_f32 v[140:141], v[158:159], v[140:141] op_sel_hi:[0,1]
	v_pk_mul_f32 v[142:143], v[158:159], v[142:143] op_sel_hi:[0,1]
	v_pk_mul_f32 v[144:145], v[158:159], v[144:145] op_sel_hi:[0,1]
	v_pk_mul_f32 v[146:147], v[158:159], v[146:147] op_sel_hi:[0,1]
	v_pk_mul_f32 v[148:149], v[158:159], v[148:149] op_sel_hi:[0,1]
	v_pk_mul_f32 v[150:151], v[158:159], v[150:151] op_sel_hi:[0,1]
	v_pk_mul_f32 v[152:153], v[158:159], v[152:153] op_sel_hi:[0,1]
	v_pk_mul_f32 v[154:155], v[158:159], v[154:155] op_sel_hi:[0,1]
	v_pk_mul_f32 v[140:141], v[140:141], v[32:33]
	v_pk_mul_f32 v[142:143], v[142:143], v[34:35]
	v_pk_mul_f32 v[144:145], v[144:145], v[36:37]
	v_pk_mul_f32 v[146:147], v[146:147], v[38:39]
	v_pk_mul_f32 v[148:149], v[148:149], v[40:41]
	v_pk_mul_f32 v[150:151], v[150:151], v[42:43]
	v_pk_mul_f32 v[152:153], v[152:153], v[44:45]
	v_pk_mul_f32 v[154:155], v[154:155], v[46:47]
	v_pk_fma_f32 v[140:141], v[140:141], v[84:85], v[124:125]
	v_pk_fma_f32 v[142:143], v[142:143], v[86:87], v[126:127]
	v_pk_fma_f32 v[144:145], v[144:145], v[88:89], v[128:129]
	v_pk_fma_f32 v[146:147], v[146:147], v[90:91], v[130:131]
	v_pk_fma_f32 v[148:149], v[148:149], v[92:93], v[132:133]
	v_pk_fma_f32 v[150:151], v[150:151], v[94:95], v[134:135]
	v_pk_fma_f32 v[152:153], v[152:153], v[96:97], v[136:137]
	v_pk_fma_f32 v[154:155], v[154:155], v[98:99], v[138:139]
	v_cvt_pk_bf16_f32 v164, v140, v141
	v_cvt_pk_bf16_f32 v165, v142, v143
	v_cvt_pk_bf16_f32 v166, v144, v145
	v_cvt_pk_bf16_f32 v167, v146, v147
	v_cvt_pk_bf16_f32 v168, v148, v149
	v_cvt_pk_bf16_f32 v169, v150, v151
	v_cvt_pk_bf16_f32 v170, v152, v153
	v_cvt_pk_bf16_f32 v171, v154, v155
	global_store_dwordx4 v51, v[164:167], s[20:21] offset:2048
	global_store_dwordx4 v51, v[168:171], s[20:21] offset:3072
	v_lshlrev_b32_e32 v140, 16, v68
	v_and_b32_e32 v141, 0xffff0000, v68
	v_lshlrev_b32_e32 v142, 16, v69
	v_and_b32_e32 v143, 0xffff0000, v69
	v_lshlrev_b32_e32 v144, 16, v70
	v_and_b32_e32 v145, 0xffff0000, v70
	v_lshlrev_b32_e32 v146, 16, v71
	v_and_b32_e32 v147, 0xffff0000, v71
	v_lshlrev_b32_e32 v148, 16, v72
	v_and_b32_e32 v149, 0xffff0000, v72
	v_lshlrev_b32_e32 v150, 16, v73
	v_and_b32_e32 v151, 0xffff0000, v73
	v_lshlrev_b32_e32 v152, 16, v74
	v_and_b32_e32 v153, 0xffff0000, v74
	v_lshlrev_b32_e32 v154, 16, v75
	v_and_b32_e32 v155, 0xffff0000, v75
	v_pk_mul_f32 v[140:141], v[160:161], v[140:141] op_sel_hi:[0,1]
	v_pk_mul_f32 v[142:143], v[160:161], v[142:143] op_sel_hi:[0,1]
	v_pk_mul_f32 v[144:145], v[160:161], v[144:145] op_sel_hi:[0,1]
	v_pk_mul_f32 v[146:147], v[160:161], v[146:147] op_sel_hi:[0,1]
	v_pk_mul_f32 v[148:149], v[160:161], v[148:149] op_sel_hi:[0,1]
	v_pk_mul_f32 v[150:151], v[160:161], v[150:151] op_sel_hi:[0,1]
	v_pk_mul_f32 v[152:153], v[160:161], v[152:153] op_sel_hi:[0,1]
	v_pk_mul_f32 v[154:155], v[160:161], v[154:155] op_sel_hi:[0,1]
	v_pk_mul_f32 v[140:141], v[140:141], v[32:33]
	v_pk_mul_f32 v[142:143], v[142:143], v[34:35]
	v_pk_mul_f32 v[144:145], v[144:145], v[36:37]
	v_pk_mul_f32 v[146:147], v[146:147], v[38:39]
	v_pk_mul_f32 v[148:149], v[148:149], v[40:41]
	v_pk_mul_f32 v[150:151], v[150:151], v[42:43]
	v_pk_mul_f32 v[152:153], v[152:153], v[44:45]
	v_pk_mul_f32 v[154:155], v[154:155], v[46:47]
	v_pk_fma_f32 v[140:141], v[140:141], v[84:85], v[124:125]
	v_pk_fma_f32 v[142:143], v[142:143], v[86:87], v[126:127]
	v_pk_fma_f32 v[144:145], v[144:145], v[88:89], v[128:129]
	v_pk_fma_f32 v[146:147], v[146:147], v[90:91], v[130:131]
	v_pk_fma_f32 v[148:149], v[148:149], v[92:93], v[132:133]
	v_pk_fma_f32 v[150:151], v[150:151], v[94:95], v[134:135]
	v_pk_fma_f32 v[152:153], v[152:153], v[96:97], v[136:137]
	v_pk_fma_f32 v[154:155], v[154:155], v[98:99], v[138:139]
	v_cvt_pk_bf16_f32 v172, v140, v141
	v_cvt_pk_bf16_f32 v173, v142, v143
	v_cvt_pk_bf16_f32 v174, v144, v145
	v_cvt_pk_bf16_f32 v175, v146, v147
	v_cvt_pk_bf16_f32 v176, v148, v149
	v_cvt_pk_bf16_f32 v177, v150, v151
	v_cvt_pk_bf16_f32 v178, v152, v153
	v_cvt_pk_bf16_f32 v179, v154, v155
	global_store_dwordx4 v109, v[172:175], s[20:21]
	global_store_dwordx4 v109, v[176:179], s[20:21] offset:1024
	v_lshlrev_b32_e32 v140, 16, v76
	v_and_b32_e32 v141, 0xffff0000, v76
	v_lshlrev_b32_e32 v142, 16, v77
	v_and_b32_e32 v143, 0xffff0000, v77
	v_lshlrev_b32_e32 v144, 16, v78
	v_and_b32_e32 v145, 0xffff0000, v78
	v_lshlrev_b32_e32 v146, 16, v79
	v_and_b32_e32 v147, 0xffff0000, v79
	v_lshlrev_b32_e32 v148, 16, v80
	v_and_b32_e32 v149, 0xffff0000, v80
	v_lshlrev_b32_e32 v150, 16, v81
	v_and_b32_e32 v151, 0xffff0000, v81
	v_lshlrev_b32_e32 v152, 16, v82
	v_and_b32_e32 v153, 0xffff0000, v82
	v_lshlrev_b32_e32 v154, 16, v83
	v_and_b32_e32 v155, 0xffff0000, v83
	v_pk_mul_f32 v[140:141], v[162:163], v[140:141] op_sel_hi:[0,1]
	v_pk_mul_f32 v[142:143], v[162:163], v[142:143] op_sel_hi:[0,1]
	v_pk_mul_f32 v[144:145], v[162:163], v[144:145] op_sel_hi:[0,1]
	v_pk_mul_f32 v[146:147], v[162:163], v[146:147] op_sel_hi:[0,1]
	v_pk_mul_f32 v[148:149], v[162:163], v[148:149] op_sel_hi:[0,1]
	v_pk_mul_f32 v[150:151], v[162:163], v[150:151] op_sel_hi:[0,1]
	v_pk_mul_f32 v[152:153], v[162:163], v[152:153] op_sel_hi:[0,1]
	v_pk_mul_f32 v[154:155], v[162:163], v[154:155] op_sel_hi:[0,1]
	v_pk_mul_f32 v[140:141], v[140:141], v[32:33]
	v_pk_mul_f32 v[142:143], v[142:143], v[34:35]
	v_pk_mul_f32 v[144:145], v[144:145], v[36:37]
	v_pk_mul_f32 v[146:147], v[146:147], v[38:39]
	v_pk_mul_f32 v[148:149], v[148:149], v[40:41]
	v_pk_mul_f32 v[150:151], v[150:151], v[42:43]
	v_pk_mul_f32 v[152:153], v[152:153], v[44:45]
	v_pk_mul_f32 v[154:155], v[154:155], v[46:47]
	v_pk_fma_f32 v[140:141], v[140:141], v[84:85], v[124:125]
	v_pk_fma_f32 v[142:143], v[142:143], v[86:87], v[126:127]
	v_pk_fma_f32 v[144:145], v[144:145], v[88:89], v[128:129]
	v_pk_fma_f32 v[146:147], v[146:147], v[90:91], v[130:131]
	v_pk_fma_f32 v[148:149], v[148:149], v[92:93], v[132:133]
	v_pk_fma_f32 v[150:151], v[150:151], v[94:95], v[134:135]
	v_pk_fma_f32 v[152:153], v[152:153], v[96:97], v[136:137]
	v_pk_fma_f32 v[154:155], v[154:155], v[98:99], v[138:139]
	v_cvt_pk_bf16_f32 v164, v140, v141
	v_cvt_pk_bf16_f32 v165, v142, v143
	v_cvt_pk_bf16_f32 v166, v144, v145
	v_cvt_pk_bf16_f32 v167, v146, v147
	v_cvt_pk_bf16_f32 v168, v148, v149
	v_cvt_pk_bf16_f32 v169, v150, v151
	v_cvt_pk_bf16_f32 v170, v152, v153
	v_cvt_pk_bf16_f32 v171, v154, v155
	global_store_dwordx4 v109, v[164:167], s[20:21] offset:2048
	global_store_dwordx4 v109, v[168:171], s[20:21] offset:3072
	s_add_u32 s20, s20, 0x2000
	s_addc_u32 s21, s21, 0
	s_add_u32 s18, s18, 0x2000
	s_addc_u32 s19, s19, 0
	global_load_dwordx4 v[52:55], v51, s[18:19]
	global_load_dwordx4 v[56:59], v51, s[18:19] offset:1024
	global_load_dwordx4 v[60:63], v51, s[18:19] offset:2048
	global_load_dwordx4 v[64:67], v51, s[18:19] offset:3072
	global_load_dwordx4 v[68:71], v109, s[18:19]
	global_load_dwordx4 v[72:75], v109, s[18:19] offset:1024
	global_load_dwordx4 v[76:79], v109, s[18:19] offset:2048
	global_load_dwordx4 v[80:83], v109, s[18:19] offset:3072
	s_waitcnt vmcnt(16)
	v_lshlrev_b32_e32 v140, 16, v0
	v_and_b32_e32 v141, 0xffff0000, v0
	v_lshlrev_b32_e32 v142, 16, v1
	v_and_b32_e32 v143, 0xffff0000, v1
	v_lshlrev_b32_e32 v144, 16, v2
	v_and_b32_e32 v145, 0xffff0000, v2
	v_lshlrev_b32_e32 v146, 16, v3
	v_and_b32_e32 v147, 0xffff0000, v3
	v_lshlrev_b32_e32 v148, 16, v4
	v_and_b32_e32 v149, 0xffff0000, v4
	v_lshlrev_b32_e32 v150, 16, v5
	v_and_b32_e32 v151, 0xffff0000, v5
	v_lshlrev_b32_e32 v152, 16, v6
	v_and_b32_e32 v153, 0xffff0000, v6
	v_lshlrev_b32_e32 v154, 16, v7
	v_and_b32_e32 v155, 0xffff0000, v7
	v_pk_mul_f32 v[100:101], v[140:141], v[140:141]
	v_pk_fma_f32 v[100:101], v[142:143], v[142:143], v[100:101]
	v_pk_fma_f32 v[100:101], v[144:145], v[144:145], v[100:101]
	v_pk_fma_f32 v[100:101], v[146:147], v[146:147], v[100:101]
	v_pk_fma_f32 v[100:101], v[148:149], v[148:149], v[100:101]
	v_pk_fma_f32 v[100:101], v[150:151], v[150:151], v[100:101]
	v_pk_fma_f32 v[100:101], v[152:153], v[152:153], v[100:101]
	v_pk_fma_f32 v[100:101], v[154:155], v[154:155], v[100:101]
	v_lshlrev_b32_e32 v140, 16, v8
	v_and_b32_e32 v141, 0xffff0000, v8
	v_lshlrev_b32_e32 v142, 16, v9
	v_and_b32_e32 v143, 0xffff0000, v9
	v_lshlrev_b32_e32 v144, 16, v10
	v_and_b32_e32 v145, 0xffff0000, v10
	v_lshlrev_b32_e32 v146, 16, v11
	v_and_b32_e32 v147, 0xffff0000, v11
	v_lshlrev_b32_e32 v148, 16, v12
	v_and_b32_e32 v149, 0xffff0000, v12
	v_lshlrev_b32_e32 v150, 16, v13
	v_and_b32_e32 v151, 0xffff0000, v13
	v_lshlrev_b32_e32 v152, 16, v14
	v_and_b32_e32 v153, 0xffff0000, v14
	v_lshlrev_b32_e32 v154, 16, v15
	v_and_b32_e32 v155, 0xffff0000, v15
	v_pk_mul_f32 v[102:103], v[140:141], v[140:141]
	v_pk_fma_f32 v[102:103], v[142:143], v[142:143], v[102:103]
	v_pk_fma_f32 v[102:103], v[144:145], v[144:145], v[102:103]
	v_pk_fma_f32 v[102:103], v[146:147], v[146:147], v[102:103]
	v_pk_fma_f32 v[102:103], v[148:149], v[148:149], v[102:103]
	v_pk_fma_f32 v[102:103], v[150:151], v[150:151], v[102:103]
	v_pk_fma_f32 v[102:103], v[152:153], v[152:153], v[102:103]
	v_pk_fma_f32 v[102:103], v[154:155], v[154:155], v[102:103]
	v_lshlrev_b32_e32 v140, 16, v16
	v_and_b32_e32 v141, 0xffff0000, v16
	v_lshlrev_b32_e32 v142, 16, v17
	v_and_b32_e32 v143, 0xffff0000, v17
	v_lshlrev_b32_e32 v144, 16, v18
	v_and_b32_e32 v145, 0xffff0000, v18
	v_lshlrev_b32_e32 v146, 16, v19
	v_and_b32_e32 v147, 0xffff0000, v19
	v_lshlrev_b32_e32 v148, 16, v20
	v_and_b32_e32 v149, 0xffff0000, v20
	v_lshlrev_b32_e32 v150, 16, v21
	v_and_b32_e32 v151, 0xffff0000, v21
	v_lshlrev_b32_e32 v152, 16, v22
	v_and_b32_e32 v153, 0xffff0000, v22
	v_lshlrev_b32_e32 v154, 16, v23
	v_and_b32_e32 v155, 0xffff0000, v23
	v_pk_mul_f32 v[104:105], v[140:141], v[140:141]
	v_pk_fma_f32 v[104:105], v[142:143], v[142:143], v[104:105]
	v_pk_fma_f32 v[104:105], v[144:145], v[144:145], v[104:105]
	v_pk_fma_f32 v[104:105], v[146:147], v[146:147], v[104:105]
	v_pk_fma_f32 v[104:105], v[148:149], v[148:149], v[104:105]
	v_pk_fma_f32 v[104:105], v[150:151], v[150:151], v[104:105]
	v_pk_fma_f32 v[104:105], v[152:153], v[152:153], v[104:105]
	v_pk_fma_f32 v[104:105], v[154:155], v[154:155], v[104:105]
	v_lshlrev_b32_e32 v140, 16, v24
	v_and_b32_e32 v141, 0xffff0000, v24
	v_lshlrev_b32_e32 v142, 16, v25
	v_and_b32_e32 v143, 0xffff0000, v25
	v_lshlrev_b32_e32 v144, 16, v26
	v_and_b32_e32 v145, 0xffff0000, v26
	v_lshlrev_b32_e32 v146, 16, v27
	v_and_b32_e32 v147, 0xffff0000, v27
	v_lshlrev_b32_e32 v148, 16, v28
	v_and_b32_e32 v149, 0xffff0000, v28
	v_lshlrev_b32_e32 v150, 16, v29
	v_and_b32_e32 v151, 0xffff0000, v29
	v_lshlrev_b32_e32 v152, 16, v30
	v_and_b32_e32 v153, 0xffff0000, v30
	v_lshlrev_b32_e32 v154, 16, v31
	v_and_b32_e32 v155, 0xffff0000, v31
	v_pk_mul_f32 v[106:107], v[140:141], v[140:141]
	v_pk_fma_f32 v[106:107], v[142:143], v[142:143], v[106:107]
	v_pk_fma_f32 v[106:107], v[144:145], v[144:145], v[106:107]
	v_pk_fma_f32 v[106:107], v[146:147], v[146:147], v[106:107]
	v_pk_fma_f32 v[106:107], v[148:149], v[148:149], v[106:107]
	v_pk_fma_f32 v[106:107], v[150:151], v[150:151], v[106:107]
	v_pk_fma_f32 v[106:107], v[152:153], v[152:153], v[106:107]
	v_pk_fma_f32 v[106:107], v[154:155], v[154:155], v[106:107]
	v_add_f32_e32 v100, v100, v101
	v_add_f32_e32 v102, v102, v103
	v_add_f32_e32 v104, v104, v105
	v_add_f32_e32 v106, v106, v107
	s_nop 1
	v_add_f32_dpp v100, v100, v100 row_shr:1 row_mask:0xf bank_mask:0xf bound_ctrl:1
	v_add_f32_dpp v102, v102, v102 row_shr:1 row_mask:0xf bank_mask:0xf bound_ctrl:1
	v_add_f32_dpp v104, v104, v104 row_shr:1 row_mask:0xf bank_mask:0xf bound_ctrl:1
	v_add_f32_dpp v106, v106, v106 row_shr:1 row_mask:0xf bank_mask:0xf bound_ctrl:1
	v_add_f32_dpp v100, v100, v100 row_shr:2 row_mask:0xf bank_mask:0xf bound_ctrl:1
	v_add_f32_dpp v102, v102, v102 row_shr:2 row_mask:0xf bank_mask:0xf bound_ctrl:1
	v_add_f32_dpp v104, v104, v104 row_shr:2 row_mask:0xf bank_mask:0xf bound_ctrl:1
	v_add_f32_dpp v106, v106, v106 row_shr:2 row_mask:0xf bank_mask:0xf bound_ctrl:1
	v_add_f32_dpp v100, v100, v100 row_shr:4 row_mask:0xf bank_mask:0xf bound_ctrl:1
	v_add_f32_dpp v102, v102, v102 row_shr:4 row_mask:0xf bank_mask:0xf bound_ctrl:1
	v_add_f32_dpp v104, v104, v104 row_shr:4 row_mask:0xf bank_mask:0xf bound_ctrl:1
	v_add_f32_dpp v106, v106, v106 row_shr:4 row_mask:0xf bank_mask:0xf bound_ctrl:1
	v_add_f32_dpp v100, v100, v100 row_shr:8 row_mask:0xf bank_mask:0xf bound_ctrl:1
	v_add_f32_dpp v102, v102, v102 row_shr:8 row_mask:0xf bank_mask:0xf bound_ctrl:1
	v_add_f32_dpp v104, v104, v104 row_shr:8 row_mask:0xf bank_mask:0xf bound_ctrl:1
	v_add_f32_dpp v106, v106, v106 row_shr:8 row_mask:0xf bank_mask:0xf bound_ctrl:1
	v_add_f32_dpp v100, v100, v100 row_bcast:15 row_mask:0xa bank_mask:0xf
	v_add_f32_dpp v102, v102, v102 row_bcast:15 row_mask:0xa bank_mask:0xf
	v_add_f32_dpp v104, v104, v104 row_bcast:15 row_mask:0xa bank_mask:0xf
	v_add_f32_dpp v106, v106, v106 row_bcast:15 row_mask:0xa bank_mask:0xf
	v_add_f32_dpp v100, v100, v100 row_bcast:31 row_mask:0xc bank_mask:0xf
	v_add_f32_dpp v102, v102, v102 row_bcast:31 row_mask:0xc bank_mask:0xf
	v_add_f32_dpp v104, v104, v104 row_bcast:31 row_mask:0xc bank_mask:0xf
	v_add_f32_dpp v106, v106, v106 row_bcast:31 row_mask:0xc bank_mask:0xf
	s_nop 1
	v_readlane_b32 s5, v100, 63
	v_readlane_b32 s32, v102, 63
	v_readlane_b32 s54, v104, 63
	v_readlane_b32 s60, v106, 63
	s_nop 1
	v_mov_b32_e32 v156, s5
	v_mov_b32_e32 v158, s32
	v_mov_b32_e32 v160, s54
	v_mov_b32_e32 v162, s60
	v_fmaak_f32 v156, v156, v50, 0x358637bd
	v_fmaak_f32 v158, v158, v50, 0x358637bd
	v_fmaak_f32 v160, v160, v50, 0x358637bd
	v_fmaak_f32 v162, v162, v50, 0x358637bd
	v_rsq_f32_e32 v156, v156
	v_rsq_f32_e32 v158, v158
	v_rsq_f32_e32 v160, v160
	v_rsq_f32_e32 v162, v162
	s_nop 0
	v_lshlrev_b32_e32 v140, 16, v0
	v_and_b32_e32 v141, 0xffff0000, v0
	v_lshlrev_b32_e32 v142, 16, v1
	v_and_b32_e32 v143, 0xffff0000, v1
	v_lshlrev_b32_e32 v144, 16, v2
	v_and_b32_e32 v145, 0xffff0000, v2
	v_lshlrev_b32_e32 v146, 16, v3
	v_and_b32_e32 v147, 0xffff0000, v3
	v_lshlrev_b32_e32 v148, 16, v4
	v_and_b32_e32 v149, 0xffff0000, v4
	v_lshlrev_b32_e32 v150, 16, v5
	v_and_b32_e32 v151, 0xffff0000, v5
	v_lshlrev_b32_e32 v152, 16, v6
	v_and_b32_e32 v153, 0xffff0000, v6
	v_lshlrev_b32_e32 v154, 16, v7
	v_and_b32_e32 v155, 0xffff0000, v7
	v_pk_mul_f32 v[140:141], v[156:157], v[140:141] op_sel_hi:[0,1]
	v_pk_mul_f32 v[142:143], v[156:157], v[142:143] op_sel_hi:[0,1]
	v_pk_mul_f32 v[144:145], v[156:157], v[144:145] op_sel_hi:[0,1]
	v_pk_mul_f32 v[146:147], v[156:157], v[146:147] op_sel_hi:[0,1]
	v_pk_mul_f32 v[148:149], v[156:157], v[148:149] op_sel_hi:[0,1]
	v_pk_mul_f32 v[150:151], v[156:157], v[150:151] op_sel_hi:[0,1]
	v_pk_mul_f32 v[152:153], v[156:157], v[152:153] op_sel_hi:[0,1]
	v_pk_mul_f32 v[154:155], v[156:157], v[154:155] op_sel_hi:[0,1]
	v_pk_mul_f32 v[140:141], v[140:141], v[32:33]
	v_pk_mul_f32 v[142:143], v[142:143], v[34:35]
	v_pk_mul_f32 v[144:145], v[144:145], v[36:37]
	v_pk_mul_f32 v[146:147], v[146:147], v[38:39]
	v_pk_mul_f32 v[148:149], v[148:149], v[40:41]
	v_pk_mul_f32 v[150:151], v[150:151], v[42:43]
	v_pk_mul_f32 v[152:153], v[152:153], v[44:45]
	v_pk_mul_f32 v[154:155], v[154:155], v[46:47]
	v_pk_fma_f32 v[140:141], v[140:141], v[84:85], v[124:125]
	v_pk_fma_f32 v[142:143], v[142:143], v[86:87], v[126:127]
	v_pk_fma_f32 v[144:145], v[144:145], v[88:89], v[128:129]
	v_pk_fma_f32 v[146:147], v[146:147], v[90:91], v[130:131]
	v_pk_fma_f32 v[148:149], v[148:149], v[92:93], v[132:133]
	v_pk_fma_f32 v[150:151], v[150:151], v[94:95], v[134:135]
	v_pk_fma_f32 v[152:153], v[152:153], v[96:97], v[136:137]
	v_pk_fma_f32 v[154:155], v[154:155], v[98:99], v[138:139]
	v_cvt_pk_bf16_f32 v164, v140, v141
	v_cvt_pk_bf16_f32 v165, v142, v143
	v_cvt_pk_bf16_f32 v166, v144, v145
	v_cvt_pk_bf16_f32 v167, v146, v147
	v_cvt_pk_bf16_f32 v168, v148, v149
	v_cvt_pk_bf16_f32 v169, v150, v151
	v_cvt_pk_bf16_f32 v170, v152, v153
	v_cvt_pk_bf16_f32 v171, v154, v155
	global_store_dwordx4 v51, v[164:167], s[20:21]
	global_store_dwordx4 v51, v[168:171], s[20:21] offset:1024
	v_lshlrev_b32_e32 v140, 16, v8
	v_and_b32_e32 v141, 0xffff0000, v8
	v_lshlrev_b32_e32 v142, 16, v9
	v_and_b32_e32 v143, 0xffff0000, v9
	v_lshlrev_b32_e32 v144, 16, v10
	v_and_b32_e32 v145, 0xffff0000, v10
	v_lshlrev_b32_e32 v146, 16, v11
	v_and_b32_e32 v147, 0xffff0000, v11
	v_lshlrev_b32_e32 v148, 16, v12
	v_and_b32_e32 v149, 0xffff0000, v12
	v_lshlrev_b32_e32 v150, 16, v13
	v_and_b32_e32 v151, 0xffff0000, v13
	v_lshlrev_b32_e32 v152, 16, v14
	v_and_b32_e32 v153, 0xffff0000, v14
	v_lshlrev_b32_e32 v154, 16, v15
	v_and_b32_e32 v155, 0xffff0000, v15
	v_pk_mul_f32 v[140:141], v[158:159], v[140:141] op_sel_hi:[0,1]
	v_pk_mul_f32 v[142:143], v[158:159], v[142:143] op_sel_hi:[0,1]
	v_pk_mul_f32 v[144:145], v[158:159], v[144:145] op_sel_hi:[0,1]
	v_pk_mul_f32 v[146:147], v[158:159], v[146:147] op_sel_hi:[0,1]
	v_pk_mul_f32 v[148:149], v[158:159], v[148:149] op_sel_hi:[0,1]
	v_pk_mul_f32 v[150:151], v[158:159], v[150:151] op_sel_hi:[0,1]
	v_pk_mul_f32 v[152:153], v[158:159], v[152:153] op_sel_hi:[0,1]
	v_pk_mul_f32 v[154:155], v[158:159], v[154:155] op_sel_hi:[0,1]
	v_pk_mul_f32 v[140:141], v[140:141], v[32:33]
	v_pk_mul_f32 v[142:143], v[142:143], v[34:35]
	v_pk_mul_f32 v[144:145], v[144:145], v[36:37]
	v_pk_mul_f32 v[146:147], v[146:147], v[38:39]
	v_pk_mul_f32 v[148:149], v[148:149], v[40:41]
	v_pk_mul_f32 v[150:151], v[150:151], v[42:43]
	v_pk_mul_f32 v[152:153], v[152:153], v[44:45]
	v_pk_mul_f32 v[154:155], v[154:155], v[46:47]
	v_pk_fma_f32 v[140:141], v[140:141], v[84:85], v[124:125]
	v_pk_fma_f32 v[142:143], v[142:143], v[86:87], v[126:127]
	v_pk_fma_f32 v[144:145], v[144:145], v[88:89], v[128:129]
	v_pk_fma_f32 v[146:147], v[146:147], v[90:91], v[130:131]
	v_pk_fma_f32 v[148:149], v[148:149], v[92:93], v[132:133]
	v_pk_fma_f32 v[150:151], v[150:151], v[94:95], v[134:135]
	v_pk_fma_f32 v[152:153], v[152:153], v[96:97], v[136:137]
	v_pk_fma_f32 v[154:155], v[154:155], v[98:99], v[138:139]
	v_cvt_pk_bf16_f32 v172, v140, v141
	v_cvt_pk_bf16_f32 v173, v142, v143
	v_cvt_pk_bf16_f32 v174, v144, v145
	v_cvt_pk_bf16_f32 v175, v146, v147
	v_cvt_pk_bf16_f32 v176, v148, v149
	v_cvt_pk_bf16_f32 v177, v150, v151
	v_cvt_pk_bf16_f32 v178, v152, v153
	v_cvt_pk_bf16_f32 v179, v154, v155
	global_store_dwordx4 v51, v[172:175], s[20:21] offset:2048
	global_store_dwordx4 v51, v[176:179], s[20:21] offset:3072
	v_lshlrev_b32_e32 v140, 16, v16
	v_and_b32_e32 v141, 0xffff0000, v16
	v_lshlrev_b32_e32 v142, 16, v17
	v_and_b32_e32 v143, 0xffff0000, v17
	v_lshlrev_b32_e32 v144, 16, v18
	v_and_b32_e32 v145, 0xffff0000, v18
	v_lshlrev_b32_e32 v146, 16, v19
	v_and_b32_e32 v147, 0xffff0000, v19
	v_lshlrev_b32_e32 v148, 16, v20
	v_and_b32_e32 v149, 0xffff0000, v20
	v_lshlrev_b32_e32 v150, 16, v21
	v_and_b32_e32 v151, 0xffff0000, v21
	v_lshlrev_b32_e32 v152, 16, v22
	v_and_b32_e32 v153, 0xffff0000, v22
	v_lshlrev_b32_e32 v154, 16, v23
	v_and_b32_e32 v155, 0xffff0000, v23
	v_pk_mul_f32 v[140:141], v[160:161], v[140:141] op_sel_hi:[0,1]
	v_pk_mul_f32 v[142:143], v[160:161], v[142:143] op_sel_hi:[0,1]
	v_pk_mul_f32 v[144:145], v[160:161], v[144:145] op_sel_hi:[0,1]
	v_pk_mul_f32 v[146:147], v[160:161], v[146:147] op_sel_hi:[0,1]
	v_pk_mul_f32 v[148:149], v[160:161], v[148:149] op_sel_hi:[0,1]
	v_pk_mul_f32 v[150:151], v[160:161], v[150:151] op_sel_hi:[0,1]
	v_pk_mul_f32 v[152:153], v[160:161], v[152:153] op_sel_hi:[0,1]
	v_pk_mul_f32 v[154:155], v[160:161], v[154:155] op_sel_hi:[0,1]
	v_pk_mul_f32 v[140:141], v[140:141], v[32:33]
	v_pk_mul_f32 v[142:143], v[142:143], v[34:35]
	v_pk_mul_f32 v[144:145], v[144:145], v[36:37]
	v_pk_mul_f32 v[146:147], v[146:147], v[38:39]
	v_pk_mul_f32 v[148:149], v[148:149], v[40:41]
	v_pk_mul_f32 v[150:151], v[150:151], v[42:43]
	v_pk_mul_f32 v[152:153], v[152:153], v[44:45]
	v_pk_mul_f32 v[154:155], v[154:155], v[46:47]
	v_pk_fma_f32 v[140:141], v[140:141], v[84:85], v[124:125]
	v_pk_fma_f32 v[142:143], v[142:143], v[86:87], v[126:127]
	v_pk_fma_f32 v[144:145], v[144:145], v[88:89], v[128:129]
	v_pk_fma_f32 v[146:147], v[146:147], v[90:91], v[130:131]
	v_pk_fma_f32 v[148:149], v[148:149], v[92:93], v[132:133]
	v_pk_fma_f32 v[150:151], v[150:151], v[94:95], v[134:135]
	v_pk_fma_f32 v[152:153], v[152:153], v[96:97], v[136:137]
	v_pk_fma_f32 v[154:155], v[154:155], v[98:99], v[138:139]
	v_cvt_pk_bf16_f32 v164, v140, v141
	v_cvt_pk_bf16_f32 v165, v142, v143
	v_cvt_pk_bf16_f32 v166, v144, v145
	v_cvt_pk_bf16_f32 v167, v146, v147
	v_cvt_pk_bf16_f32 v168, v148, v149
	v_cvt_pk_bf16_f32 v169, v150, v151
	v_cvt_pk_bf16_f32 v170, v152, v153
	v_cvt_pk_bf16_f32 v171, v154, v155
	global_store_dwordx4 v109, v[164:167], s[20:21]
	global_store_dwordx4 v109, v[168:171], s[20:21] offset:1024
	v_lshlrev_b32_e32 v140, 16, v24
	v_and_b32_e32 v141, 0xffff0000, v24
	v_lshlrev_b32_e32 v142, 16, v25
	v_and_b32_e32 v143, 0xffff0000, v25
	v_lshlrev_b32_e32 v144, 16, v26
	v_and_b32_e32 v145, 0xffff0000, v26
	v_lshlrev_b32_e32 v146, 16, v27
	v_and_b32_e32 v147, 0xffff0000, v27
	v_lshlrev_b32_e32 v148, 16, v28
	v_and_b32_e32 v149, 0xffff0000, v28
	v_lshlrev_b32_e32 v150, 16, v29
	v_and_b32_e32 v151, 0xffff0000, v29
	v_lshlrev_b32_e32 v152, 16, v30
	v_and_b32_e32 v153, 0xffff0000, v30
	v_lshlrev_b32_e32 v154, 16, v31
	v_and_b32_e32 v155, 0xffff0000, v31
	v_pk_mul_f32 v[140:141], v[162:163], v[140:141] op_sel_hi:[0,1]
	v_pk_mul_f32 v[142:143], v[162:163], v[142:143] op_sel_hi:[0,1]
	v_pk_mul_f32 v[144:145], v[162:163], v[144:145] op_sel_hi:[0,1]
	v_pk_mul_f32 v[146:147], v[162:163], v[146:147] op_sel_hi:[0,1]
	v_pk_mul_f32 v[148:149], v[162:163], v[148:149] op_sel_hi:[0,1]
	v_pk_mul_f32 v[150:151], v[162:163], v[150:151] op_sel_hi:[0,1]
	v_pk_mul_f32 v[152:153], v[162:163], v[152:153] op_sel_hi:[0,1]
	v_pk_mul_f32 v[154:155], v[162:163], v[154:155] op_sel_hi:[0,1]
	v_pk_mul_f32 v[140:141], v[140:141], v[32:33]
	v_pk_mul_f32 v[142:143], v[142:143], v[34:35]
	v_pk_mul_f32 v[144:145], v[144:145], v[36:37]
	v_pk_mul_f32 v[146:147], v[146:147], v[38:39]
	v_pk_mul_f32 v[148:149], v[148:149], v[40:41]
	v_pk_mul_f32 v[150:151], v[150:151], v[42:43]
	v_pk_mul_f32 v[152:153], v[152:153], v[44:45]
	v_pk_mul_f32 v[154:155], v[154:155], v[46:47]
	v_pk_fma_f32 v[140:141], v[140:141], v[84:85], v[124:125]
	v_pk_fma_f32 v[142:143], v[142:143], v[86:87], v[126:127]
	v_pk_fma_f32 v[144:145], v[144:145], v[88:89], v[128:129]
	v_pk_fma_f32 v[146:147], v[146:147], v[90:91], v[130:131]
	v_pk_fma_f32 v[148:149], v[148:149], v[92:93], v[132:133]
	v_pk_fma_f32 v[150:151], v[150:151], v[94:95], v[134:135]
	v_pk_fma_f32 v[152:153], v[152:153], v[96:97], v[136:137]
	v_pk_fma_f32 v[154:155], v[154:155], v[98:99], v[138:139]
	v_cvt_pk_bf16_f32 v172, v140, v141
	v_cvt_pk_bf16_f32 v173, v142, v143
	v_cvt_pk_bf16_f32 v174, v144, v145
	v_cvt_pk_bf16_f32 v175, v146, v147
	v_cvt_pk_bf16_f32 v176, v148, v149
	v_cvt_pk_bf16_f32 v177, v150, v151
	v_cvt_pk_bf16_f32 v178, v152, v153
	v_cvt_pk_bf16_f32 v179, v154, v155
	global_store_dwordx4 v109, v[172:175], s[20:21] offset:2048
	global_store_dwordx4 v109, v[176:179], s[20:21] offset:3072
	s_add_u32 s20, s20, 0x2000
	s_addc_u32 s21, s21, 0
	s_waitcnt vmcnt(8)
	v_lshlrev_b32_e32 v140, 16, v52
	v_and_b32_e32 v141, 0xffff0000, v52
	v_lshlrev_b32_e32 v142, 16, v53
	v_and_b32_e32 v143, 0xffff0000, v53
	v_lshlrev_b32_e32 v144, 16, v54
	v_and_b32_e32 v145, 0xffff0000, v54
	v_lshlrev_b32_e32 v146, 16, v55
	v_and_b32_e32 v147, 0xffff0000, v55
	v_lshlrev_b32_e32 v148, 16, v56
	v_and_b32_e32 v149, 0xffff0000, v56
	v_lshlrev_b32_e32 v150, 16, v57
	v_and_b32_e32 v151, 0xffff0000, v57
	v_lshlrev_b32_e32 v152, 16, v58
	v_and_b32_e32 v153, 0xffff0000, v58
	v_lshlrev_b32_e32 v154, 16, v59
	v_and_b32_e32 v155, 0xffff0000, v59
	v_pk_mul_f32 v[100:101], v[140:141], v[140:141]
	v_pk_fma_f32 v[100:101], v[142:143], v[142:143], v[100:101]
	v_pk_fma_f32 v[100:101], v[144:145], v[144:145], v[100:101]
	v_pk_fma_f32 v[100:101], v[146:147], v[146:147], v[100:101]
	v_pk_fma_f32 v[100:101], v[148:149], v[148:149], v[100:101]
	v_pk_fma_f32 v[100:101], v[150:151], v[150:151], v[100:101]
	v_pk_fma_f32 v[100:101], v[152:153], v[152:153], v[100:101]
	v_pk_fma_f32 v[100:101], v[154:155], v[154:155], v[100:101]
	v_lshlrev_b32_e32 v140, 16, v60
	v_and_b32_e32 v141, 0xffff0000, v60
	v_lshlrev_b32_e32 v142, 16, v61
	v_and_b32_e32 v143, 0xffff0000, v61
	v_lshlrev_b32_e32 v144, 16, v62
	v_and_b32_e32 v145, 0xffff0000, v62
	v_lshlrev_b32_e32 v146, 16, v63
	v_and_b32_e32 v147, 0xffff0000, v63
	v_lshlrev_b32_e32 v148, 16, v64
	v_and_b32_e32 v149, 0xffff0000, v64
	v_lshlrev_b32_e32 v150, 16, v65
	v_and_b32_e32 v151, 0xffff0000, v65
	v_lshlrev_b32_e32 v152, 16, v66
	v_and_b32_e32 v153, 0xffff0000, v66
	v_lshlrev_b32_e32 v154, 16, v67
	v_and_b32_e32 v155, 0xffff0000, v67
	v_pk_mul_f32 v[102:103], v[140:141], v[140:141]
	v_pk_fma_f32 v[102:103], v[142:143], v[142:143], v[102:103]
	v_pk_fma_f32 v[102:103], v[144:145], v[144:145], v[102:103]
	v_pk_fma_f32 v[102:103], v[146:147], v[146:147], v[102:103]
	v_pk_fma_f32 v[102:103], v[148:149], v[148:149], v[102:103]
	v_pk_fma_f32 v[102:103], v[150:151], v[150:151], v[102:103]
	v_pk_fma_f32 v[102:103], v[152:153], v[152:153], v[102:103]
	v_pk_fma_f32 v[102:103], v[154:155], v[154:155], v[102:103]
	v_lshlrev_b32_e32 v140, 16, v68
	v_and_b32_e32 v141, 0xffff0000, v68
	v_lshlrev_b32_e32 v142, 16, v69
	v_and_b32_e32 v143, 0xffff0000, v69
	v_lshlrev_b32_e32 v144, 16, v70
	v_and_b32_e32 v145, 0xffff0000, v70
	v_lshlrev_b32_e32 v146, 16, v71
	v_and_b32_e32 v147, 0xffff0000, v71
	v_lshlrev_b32_e32 v148, 16, v72
	v_and_b32_e32 v149, 0xffff0000, v72
	v_lshlrev_b32_e32 v150, 16, v73
	v_and_b32_e32 v151, 0xffff0000, v73
	v_lshlrev_b32_e32 v152, 16, v74
	v_and_b32_e32 v153, 0xffff0000, v74
	v_lshlrev_b32_e32 v154, 16, v75
	v_and_b32_e32 v155, 0xffff0000, v75
	v_pk_mul_f32 v[104:105], v[140:141], v[140:141]
	v_pk_fma_f32 v[104:105], v[142:143], v[142:143], v[104:105]
	v_pk_fma_f32 v[104:105], v[144:145], v[144:145], v[104:105]
	v_pk_fma_f32 v[104:105], v[146:147], v[146:147], v[104:105]
	v_pk_fma_f32 v[104:105], v[148:149], v[148:149], v[104:105]
	v_pk_fma_f32 v[104:105], v[150:151], v[150:151], v[104:105]
	v_pk_fma_f32 v[104:105], v[152:153], v[152:153], v[104:105]
	v_pk_fma_f32 v[104:105], v[154:155], v[154:155], v[104:105]
	v_lshlrev_b32_e32 v140, 16, v76
	v_and_b32_e32 v141, 0xffff0000, v76
	v_lshlrev_b32_e32 v142, 16, v77
	v_and_b32_e32 v143, 0xffff0000, v77
	v_lshlrev_b32_e32 v144, 16, v78
	v_and_b32_e32 v145, 0xffff0000, v78
	v_lshlrev_b32_e32 v146, 16, v79
	v_and_b32_e32 v147, 0xffff0000, v79
	v_lshlrev_b32_e32 v148, 16, v80
	v_and_b32_e32 v149, 0xffff0000, v80
	v_lshlrev_b32_e32 v150, 16, v81
	v_and_b32_e32 v151, 0xffff0000, v81
	v_lshlrev_b32_e32 v152, 16, v82
	v_and_b32_e32 v153, 0xffff0000, v82
	v_lshlrev_b32_e32 v154, 16, v83
	v_and_b32_e32 v155, 0xffff0000, v83
	v_pk_mul_f32 v[106:107], v[140:141], v[140:141]
	v_pk_fma_f32 v[106:107], v[142:143], v[142:143], v[106:107]
	v_pk_fma_f32 v[106:107], v[144:145], v[144:145], v[106:107]
	v_pk_fma_f32 v[106:107], v[146:147], v[146:147], v[106:107]
	v_pk_fma_f32 v[106:107], v[148:149], v[148:149], v[106:107]
	v_pk_fma_f32 v[106:107], v[150:151], v[150:151], v[106:107]
	v_pk_fma_f32 v[106:107], v[152:153], v[152:153], v[106:107]
	v_pk_fma_f32 v[106:107], v[154:155], v[154:155], v[106:107]
	v_add_f32_e32 v100, v100, v101
	v_add_f32_e32 v102, v102, v103
	v_add_f32_e32 v104, v104, v105
	v_add_f32_e32 v106, v106, v107
	s_nop 1
	v_add_f32_dpp v100, v100, v100 row_shr:1 row_mask:0xf bank_mask:0xf bound_ctrl:1
	v_add_f32_dpp v102, v102, v102 row_shr:1 row_mask:0xf bank_mask:0xf bound_ctrl:1
	v_add_f32_dpp v104, v104, v104 row_shr:1 row_mask:0xf bank_mask:0xf bound_ctrl:1
	v_add_f32_dpp v106, v106, v106 row_shr:1 row_mask:0xf bank_mask:0xf bound_ctrl:1
	v_add_f32_dpp v100, v100, v100 row_shr:2 row_mask:0xf bank_mask:0xf bound_ctrl:1
	v_add_f32_dpp v102, v102, v102 row_shr:2 row_mask:0xf bank_mask:0xf bound_ctrl:1
	v_add_f32_dpp v104, v104, v104 row_shr:2 row_mask:0xf bank_mask:0xf bound_ctrl:1
	v_add_f32_dpp v106, v106, v106 row_shr:2 row_mask:0xf bank_mask:0xf bound_ctrl:1
	v_add_f32_dpp v100, v100, v100 row_shr:4 row_mask:0xf bank_mask:0xf bound_ctrl:1
	v_add_f32_dpp v102, v102, v102 row_shr:4 row_mask:0xf bank_mask:0xf bound_ctrl:1
	v_add_f32_dpp v104, v104, v104 row_shr:4 row_mask:0xf bank_mask:0xf bound_ctrl:1
	v_add_f32_dpp v106, v106, v106 row_shr:4 row_mask:0xf bank_mask:0xf bound_ctrl:1
	v_add_f32_dpp v100, v100, v100 row_shr:8 row_mask:0xf bank_mask:0xf bound_ctrl:1
	v_add_f32_dpp v102, v102, v102 row_shr:8 row_mask:0xf bank_mask:0xf bound_ctrl:1
	v_add_f32_dpp v104, v104, v104 row_shr:8 row_mask:0xf bank_mask:0xf bound_ctrl:1
	v_add_f32_dpp v106, v106, v106 row_shr:8 row_mask:0xf bank_mask:0xf bound_ctrl:1
	v_add_f32_dpp v100, v100, v100 row_bcast:15 row_mask:0xa bank_mask:0xf
	v_add_f32_dpp v102, v102, v102 row_bcast:15 row_mask:0xa bank_mask:0xf
	v_add_f32_dpp v104, v104, v104 row_bcast:15 row_mask:0xa bank_mask:0xf
	v_add_f32_dpp v106, v106, v106 row_bcast:15 row_mask:0xa bank_mask:0xf
	v_add_f32_dpp v100, v100, v100 row_bcast:31 row_mask:0xc bank_mask:0xf
	v_add_f32_dpp v102, v102, v102 row_bcast:31 row_mask:0xc bank_mask:0xf
	v_add_f32_dpp v104, v104, v104 row_bcast:31 row_mask:0xc bank_mask:0xf
	v_add_f32_dpp v106, v106, v106 row_bcast:31 row_mask:0xc bank_mask:0xf
	s_nop 1
	v_readlane_b32 s5, v100, 63
	v_readlane_b32 s32, v102, 63
	v_readlane_b32 s54, v104, 63
	v_readlane_b32 s60, v106, 63
	s_nop 1
	v_mov_b32_e32 v156, s5
	v_mov_b32_e32 v158, s32
	v_mov_b32_e32 v160, s54
	v_mov_b32_e32 v162, s60
	v_fmaak_f32 v156, v156, v50, 0x358637bd
	v_fmaak_f32 v158, v158, v50, 0x358637bd
	v_fmaak_f32 v160, v160, v50, 0x358637bd
	v_fmaak_f32 v162, v162, v50, 0x358637bd
	v_rsq_f32_e32 v156, v156
	v_rsq_f32_e32 v158, v158
	v_rsq_f32_e32 v160, v160
	v_rsq_f32_e32 v162, v162
	s_nop 0
	v_lshlrev_b32_e32 v140, 16, v52
	v_and_b32_e32 v141, 0xffff0000, v52
	v_lshlrev_b32_e32 v142, 16, v53
	v_and_b32_e32 v143, 0xffff0000, v53
	v_lshlrev_b32_e32 v144, 16, v54
	v_and_b32_e32 v145, 0xffff0000, v54
	v_lshlrev_b32_e32 v146, 16, v55
	v_and_b32_e32 v147, 0xffff0000, v55
	v_lshlrev_b32_e32 v148, 16, v56
	v_and_b32_e32 v149, 0xffff0000, v56
	v_lshlrev_b32_e32 v150, 16, v57
	v_and_b32_e32 v151, 0xffff0000, v57
	v_lshlrev_b32_e32 v152, 16, v58
	v_and_b32_e32 v153, 0xffff0000, v58
	v_lshlrev_b32_e32 v154, 16, v59
	v_and_b32_e32 v155, 0xffff0000, v59
	v_pk_mul_f32 v[140:141], v[156:157], v[140:141] op_sel_hi:[0,1]
	v_pk_mul_f32 v[142:143], v[156:157], v[142:143] op_sel_hi:[0,1]
	v_pk_mul_f32 v[144:145], v[156:157], v[144:145] op_sel_hi:[0,1]
	v_pk_mul_f32 v[146:147], v[156:157], v[146:147] op_sel_hi:[0,1]
	v_pk_mul_f32 v[148:149], v[156:157], v[148:149] op_sel_hi:[0,1]
	v_pk_mul_f32 v[150:151], v[156:157], v[150:151] op_sel_hi:[0,1]
	v_pk_mul_f32 v[152:153], v[156:157], v[152:153] op_sel_hi:[0,1]
	v_pk_mul_f32 v[154:155], v[156:157], v[154:155] op_sel_hi:[0,1]
	v_pk_mul_f32 v[140:141], v[140:141], v[32:33]
	v_pk_mul_f32 v[142:143], v[142:143], v[34:35]
	v_pk_mul_f32 v[144:145], v[144:145], v[36:37]
	v_pk_mul_f32 v[146:147], v[146:147], v[38:39]
	v_pk_mul_f32 v[148:149], v[148:149], v[40:41]
	v_pk_mul_f32 v[150:151], v[150:151], v[42:43]
	v_pk_mul_f32 v[152:153], v[152:153], v[44:45]
	v_pk_mul_f32 v[154:155], v[154:155], v[46:47]
	v_pk_fma_f32 v[140:141], v[140:141], v[84:85], v[124:125]
	v_pk_fma_f32 v[142:143], v[142:143], v[86:87], v[126:127]
	v_pk_fma_f32 v[144:145], v[144:145], v[88:89], v[128:129]
	v_pk_fma_f32 v[146:147], v[146:147], v[90:91], v[130:131]
	v_pk_fma_f32 v[148:149], v[148:149], v[92:93], v[132:133]
	v_pk_fma_f32 v[150:151], v[150:151], v[94:95], v[134:135]
	v_pk_fma_f32 v[152:153], v[152:153], v[96:97], v[136:137]
	v_pk_fma_f32 v[154:155], v[154:155], v[98:99], v[138:139]
	v_cvt_pk_bf16_f32 v172, v140, v141
	v_cvt_pk_bf16_f32 v173, v142, v143
	v_cvt_pk_bf16_f32 v174, v144, v145
	v_cvt_pk_bf16_f32 v175, v146, v147
	v_cvt_pk_bf16_f32 v176, v148, v149
	v_cvt_pk_bf16_f32 v177, v150, v151
	v_cvt_pk_bf16_f32 v178, v152, v153
	v_cvt_pk_bf16_f32 v179, v154, v155
	global_store_dwordx4 v51, v[172:175], s[20:21]
	global_store_dwordx4 v51, v[176:179], s[20:21] offset:1024
	v_lshlrev_b32_e32 v140, 16, v60
	v_and_b32_e32 v141, 0xffff0000, v60
	v_lshlrev_b32_e32 v142, 16, v61
	v_and_b32_e32 v143, 0xffff0000, v61
	v_lshlrev_b32_e32 v144, 16, v62
	v_and_b32_e32 v145, 0xffff0000, v62
	v_lshlrev_b32_e32 v146, 16, v63
	v_and_b32_e32 v147, 0xffff0000, v63
	v_lshlrev_b32_e32 v148, 16, v64
	v_and_b32_e32 v149, 0xffff0000, v64
	v_lshlrev_b32_e32 v150, 16, v65
	v_and_b32_e32 v151, 0xffff0000, v65
	v_lshlrev_b32_e32 v152, 16, v66
	v_and_b32_e32 v153, 0xffff0000, v66
	v_lshlrev_b32_e32 v154, 16, v67
	v_and_b32_e32 v155, 0xffff0000, v67
	v_pk_mul_f32 v[140:141], v[158:159], v[140:141] op_sel_hi:[0,1]
	v_pk_mul_f32 v[142:143], v[158:159], v[142:143] op_sel_hi:[0,1]
	v_pk_mul_f32 v[144:145], v[158:159], v[144:145] op_sel_hi:[0,1]
	v_pk_mul_f32 v[146:147], v[158:159], v[146:147] op_sel_hi:[0,1]
	v_pk_mul_f32 v[148:149], v[158:159], v[148:149] op_sel_hi:[0,1]
	v_pk_mul_f32 v[150:151], v[158:159], v[150:151] op_sel_hi:[0,1]
	v_pk_mul_f32 v[152:153], v[158:159], v[152:153] op_sel_hi:[0,1]
	v_pk_mul_f32 v[154:155], v[158:159], v[154:155] op_sel_hi:[0,1]
	v_pk_mul_f32 v[140:141], v[140:141], v[32:33]
	v_pk_mul_f32 v[142:143], v[142:143], v[34:35]
	v_pk_mul_f32 v[144:145], v[144:145], v[36:37]
	v_pk_mul_f32 v[146:147], v[146:147], v[38:39]
	v_pk_mul_f32 v[148:149], v[148:149], v[40:41]
	v_pk_mul_f32 v[150:151], v[150:151], v[42:43]
	v_pk_mul_f32 v[152:153], v[152:153], v[44:45]
	v_pk_mul_f32 v[154:155], v[154:155], v[46:47]
	v_pk_fma_f32 v[140:141], v[140:141], v[84:85], v[124:125]
	v_pk_fma_f32 v[142:143], v[142:143], v[86:87], v[126:127]
	v_pk_fma_f32 v[144:145], v[144:145], v[88:89], v[128:129]
	v_pk_fma_f32 v[146:147], v[146:147], v[90:91], v[130:131]
	v_pk_fma_f32 v[148:149], v[148:149], v[92:93], v[132:133]
	v_pk_fma_f32 v[150:151], v[150:151], v[94:95], v[134:135]
	v_pk_fma_f32 v[152:153], v[152:153], v[96:97], v[136:137]
	v_pk_fma_f32 v[154:155], v[154:155], v[98:99], v[138:139]
	v_cvt_pk_bf16_f32 v164, v140, v141
	v_cvt_pk_bf16_f32 v165, v142, v143
	v_cvt_pk_bf16_f32 v166, v144, v145
	v_cvt_pk_bf16_f32 v167, v146, v147
	v_cvt_pk_bf16_f32 v168, v148, v149
	v_cvt_pk_bf16_f32 v169, v150, v151
	v_cvt_pk_bf16_f32 v170, v152, v153
	v_cvt_pk_bf16_f32 v171, v154, v155
	global_store_dwordx4 v51, v[164:167], s[20:21] offset:2048
	global_store_dwordx4 v51, v[168:171], s[20:21] offset:3072
	v_lshlrev_b32_e32 v140, 16, v68
	v_and_b32_e32 v141, 0xffff0000, v68
	v_lshlrev_b32_e32 v142, 16, v69
	v_and_b32_e32 v143, 0xffff0000, v69
	v_lshlrev_b32_e32 v144, 16, v70
	v_and_b32_e32 v145, 0xffff0000, v70
	v_lshlrev_b32_e32 v146, 16, v71
	v_and_b32_e32 v147, 0xffff0000, v71
	v_lshlrev_b32_e32 v148, 16, v72
	v_and_b32_e32 v149, 0xffff0000, v72
	v_lshlrev_b32_e32 v150, 16, v73
	v_and_b32_e32 v151, 0xffff0000, v73
	v_lshlrev_b32_e32 v152, 16, v74
	v_and_b32_e32 v153, 0xffff0000, v74
	v_lshlrev_b32_e32 v154, 16, v75
	v_and_b32_e32 v155, 0xffff0000, v75
	v_pk_mul_f32 v[140:141], v[160:161], v[140:141] op_sel_hi:[0,1]
	v_pk_mul_f32 v[142:143], v[160:161], v[142:143] op_sel_hi:[0,1]
	v_pk_mul_f32 v[144:145], v[160:161], v[144:145] op_sel_hi:[0,1]
	v_pk_mul_f32 v[146:147], v[160:161], v[146:147] op_sel_hi:[0,1]
	v_pk_mul_f32 v[148:149], v[160:161], v[148:149] op_sel_hi:[0,1]
	v_pk_mul_f32 v[150:151], v[160:161], v[150:151] op_sel_hi:[0,1]
	v_pk_mul_f32 v[152:153], v[160:161], v[152:153] op_sel_hi:[0,1]
	v_pk_mul_f32 v[154:155], v[160:161], v[154:155] op_sel_hi:[0,1]
	v_pk_mul_f32 v[140:141], v[140:141], v[32:33]
	v_pk_mul_f32 v[142:143], v[142:143], v[34:35]
	v_pk_mul_f32 v[144:145], v[144:145], v[36:37]
	v_pk_mul_f32 v[146:147], v[146:147], v[38:39]
	v_pk_mul_f32 v[148:149], v[148:149], v[40:41]
	v_pk_mul_f32 v[150:151], v[150:151], v[42:43]
	v_pk_mul_f32 v[152:153], v[152:153], v[44:45]
	v_pk_mul_f32 v[154:155], v[154:155], v[46:47]
	v_pk_fma_f32 v[140:141], v[140:141], v[84:85], v[124:125]
	v_pk_fma_f32 v[142:143], v[142:143], v[86:87], v[126:127]
	v_pk_fma_f32 v[144:145], v[144:145], v[88:89], v[128:129]
	v_pk_fma_f32 v[146:147], v[146:147], v[90:91], v[130:131]
	v_pk_fma_f32 v[148:149], v[148:149], v[92:93], v[132:133]
	v_pk_fma_f32 v[150:151], v[150:151], v[94:95], v[134:135]
	v_pk_fma_f32 v[152:153], v[152:153], v[96:97], v[136:137]
	v_pk_fma_f32 v[154:155], v[154:155], v[98:99], v[138:139]
	v_cvt_pk_bf16_f32 v172, v140, v141
	v_cvt_pk_bf16_f32 v173, v142, v143
	v_cvt_pk_bf16_f32 v174, v144, v145
	v_cvt_pk_bf16_f32 v175, v146, v147
	v_cvt_pk_bf16_f32 v176, v148, v149
	v_cvt_pk_bf16_f32 v177, v150, v151
	v_cvt_pk_bf16_f32 v178, v152, v153
	v_cvt_pk_bf16_f32 v179, v154, v155
	global_store_dwordx4 v109, v[172:175], s[20:21]
	global_store_dwordx4 v109, v[176:179], s[20:21] offset:1024
	v_lshlrev_b32_e32 v140, 16, v76
	v_and_b32_e32 v141, 0xffff0000, v76
	v_lshlrev_b32_e32 v142, 16, v77
	v_and_b32_e32 v143, 0xffff0000, v77
	v_lshlrev_b32_e32 v144, 16, v78
	v_and_b32_e32 v145, 0xffff0000, v78
	v_lshlrev_b32_e32 v146, 16, v79
	v_and_b32_e32 v147, 0xffff0000, v79
	v_lshlrev_b32_e32 v148, 16, v80
	v_and_b32_e32 v149, 0xffff0000, v80
	v_lshlrev_b32_e32 v150, 16, v81
	v_and_b32_e32 v151, 0xffff0000, v81
	v_lshlrev_b32_e32 v152, 16, v82
	v_and_b32_e32 v153, 0xffff0000, v82
	v_lshlrev_b32_e32 v154, 16, v83
	v_and_b32_e32 v155, 0xffff0000, v83
	v_pk_mul_f32 v[140:141], v[162:163], v[140:141] op_sel_hi:[0,1]
	v_pk_mul_f32 v[142:143], v[162:163], v[142:143] op_sel_hi:[0,1]
	v_pk_mul_f32 v[144:145], v[162:163], v[144:145] op_sel_hi:[0,1]
	v_pk_mul_f32 v[146:147], v[162:163], v[146:147] op_sel_hi:[0,1]
	v_pk_mul_f32 v[148:149], v[162:163], v[148:149] op_sel_hi:[0,1]
	v_pk_mul_f32 v[150:151], v[162:163], v[150:151] op_sel_hi:[0,1]
	v_pk_mul_f32 v[152:153], v[162:163], v[152:153] op_sel_hi:[0,1]
	v_pk_mul_f32 v[154:155], v[162:163], v[154:155] op_sel_hi:[0,1]
	v_pk_mul_f32 v[140:141], v[140:141], v[32:33]
	v_pk_mul_f32 v[142:143], v[142:143], v[34:35]
	v_pk_mul_f32 v[144:145], v[144:145], v[36:37]
	v_pk_mul_f32 v[146:147], v[146:147], v[38:39]
	v_pk_mul_f32 v[148:149], v[148:149], v[40:41]
	v_pk_mul_f32 v[150:151], v[150:151], v[42:43]
	v_pk_mul_f32 v[152:153], v[152:153], v[44:45]
	v_pk_mul_f32 v[154:155], v[154:155], v[46:47]
	v_pk_fma_f32 v[140:141], v[140:141], v[84:85], v[124:125]
	v_pk_fma_f32 v[142:143], v[142:143], v[86:87], v[126:127]
	v_pk_fma_f32 v[144:145], v[144:145], v[88:89], v[128:129]
	v_pk_fma_f32 v[146:147], v[146:147], v[90:91], v[130:131]
	v_pk_fma_f32 v[148:149], v[148:149], v[92:93], v[132:133]
	v_pk_fma_f32 v[150:151], v[150:151], v[94:95], v[134:135]
	v_pk_fma_f32 v[152:153], v[152:153], v[96:97], v[136:137]
	v_pk_fma_f32 v[154:155], v[154:155], v[98:99], v[138:139]
	v_cvt_pk_bf16_f32 v164, v140, v141
	v_cvt_pk_bf16_f32 v165, v142, v143
	v_cvt_pk_bf16_f32 v166, v144, v145
	v_cvt_pk_bf16_f32 v167, v146, v147
	v_cvt_pk_bf16_f32 v168, v148, v149
	v_cvt_pk_bf16_f32 v169, v150, v151
	v_cvt_pk_bf16_f32 v170, v152, v153
	v_cvt_pk_bf16_f32 v171, v154, v155
	global_store_dwordx4 v109, v[164:167], s[20:21] offset:2048
	global_store_dwordx4 v109, v[168:171], s[20:21] offset:3072
	s_add_u32 s20, s20, 0x2000
	s_addc_u32 s21, s21, 0
	s_branch .LBB0_1297

.LBB0_1435:
	s_add_u32 s20, s18, 0x100
	s_addc_u32 s21, s19, 0
	s_add_i32 s47, 0, 0x10000
	v_add_u32_e32 v142, s47, v242
	ds_read_b128 v[130:133], v142
	ds_read_b128 v[134:137], v142 offset:1024
	ds_read_b128 v[138:141], v142 offset:2048
	ds_read_b128 v[142:145], v142 offset:3072
	s_cmp_eq_u32 s46, 40
	s_cselect_b32 s25, s13, s21
	s_cselect_b32 s24, s12, s20
	s_cselect_b32 s23, s15, s45
	s_cselect_b32 s22, s14, s44
	v_lshl_add_u64 v[186:187], s[18:19], 0, v[150:151]
	s_add_i32 m0, s31, 0xc000
	ds_read_b128 v[154:157], v244
	ds_read_b128 v[158:161], v244 offset:1024
	ds_read_b128 v[162:165], v244 offset:2048
	ds_read_b128 v[166:169], v244 offset:3072
	ds_read_b128 v[170:173], v244 offset:4096
	ds_read_b128 v[174:177], v244 offset:5120
	ds_read_b128 v[178:181], v244 offset:6144
	ds_read_b128 v[182:185], v244 offset:7168
	global_load_lds_dwordx4 v[186:187], off
	v_lshl_add_u64 v[186:187], s[18:19], 0, v[152:153]
	s_add_i32 m0, s31, 0xe000
	s_nop 0
	global_load_lds_dwordx4 v[186:187], off
	s_waitcnt lgkmcnt(8)
	s_barrier
	s_waitcnt lgkmcnt(0)
	s_setprio 1
	s_waitcnt lgkmcnt(0)
	v_mfma_f32_16x16x32_bf16 v[126:129], v[130:133], v[154:157], v[126:129]
	v_mfma_f32_16x16x32_bf16 v[122:125], v[138:141], v[154:157], v[122:125]
	v_mfma_f32_16x16x32_bf16 v[114:117], v[130:133], v[162:165], v[114:117]
	v_mfma_f32_16x16x32_bf16 v[106:109], v[138:141], v[162:165], v[106:109]
	v_mfma_f32_16x16x32_bf16 v[98:101], v[130:133], v[170:173], v[98:101]
	v_mfma_f32_16x16x32_bf16 v[90:93], v[138:141], v[170:173], v[90:93]
	v_mfma_f32_16x16x32_bf16 v[82:85], v[130:133], v[178:181], v[82:85]
	v_mfma_f32_16x16x32_bf16 v[74:77], v[138:141], v[178:181], v[74:77]
	v_mfma_f32_16x16x32_bf16 v[126:129], v[134:137], v[158:161], v[126:129]
	v_mfma_f32_16x16x32_bf16 v[122:125], v[142:145], v[158:161], v[122:125]
	v_mfma_f32_16x16x32_bf16 v[114:117], v[134:137], v[166:169], v[114:117]
	v_mfma_f32_16x16x32_bf16 v[106:109], v[142:145], v[166:169], v[106:109]
	v_mfma_f32_16x16x32_bf16 v[98:101], v[134:137], v[174:177], v[98:101]
	v_mfma_f32_16x16x32_bf16 v[90:93], v[142:145], v[174:177], v[90:93]
	v_mfma_f32_16x16x32_bf16 v[82:85], v[134:137], v[182:185], v[82:85]
	v_mfma_f32_16x16x32_bf16 v[74:77], v[142:145], v[182:185], v[74:77]
	s_setprio 0
	s_barrier
	s_add_i32 s48, 0, 0x14000
	s_add_i32 s18, s47, s30
	v_add_u32_e32 v202, s48, v242
	v_lshl_add_u64 v[206:207], s[22:23], 0, v[48:49]
	s_mov_b32 m0, s18
	ds_read_b128 v[186:189], v202
	ds_read_b128 v[190:193], v202 offset:1024
	ds_read_b128 v[198:201], v202 offset:2048
	ds_read_b128 v[202:205], v202 offset:3072
	global_load_lds_dwordx4 v[206:207], off
	v_lshl_add_u64 v[208:209], s[22:23], 0, v[146:147]
	s_add_i32 m0, s18, 0x2000
	s_nop 0
	global_load_lds_dwordx4 v[208:209], off
	s_barrier
	s_waitcnt lgkmcnt(0)
	s_setprio 1
	s_waitcnt lgkmcnt(0)
	v_mfma_f32_16x16x32_bf16 v[118:121], v[186:189], v[154:157], v[118:121]
	v_mfma_f32_16x16x32_bf16 v[110:113], v[198:201], v[154:157], v[110:113]
	v_mfma_f32_16x16x32_bf16 v[102:105], v[186:189], v[162:165], v[102:105]
	v_mfma_f32_16x16x32_bf16 v[94:97], v[198:201], v[162:165], v[94:97]
	v_mfma_f32_16x16x32_bf16 v[86:89], v[186:189], v[170:173], v[86:89]
	v_mfma_f32_16x16x32_bf16 v[78:81], v[198:201], v[170:173], v[78:81]
	v_mfma_f32_16x16x32_bf16 v[70:73], v[186:189], v[178:181], v[70:73]
	v_mfma_f32_16x16x32_bf16 v[66:69], v[198:201], v[178:181], v[66:69]
	v_mfma_f32_16x16x32_bf16 v[118:121], v[190:193], v[158:161], v[118:121]
	v_mfma_f32_16x16x32_bf16 v[110:113], v[202:205], v[158:161], v[110:113]
	v_mfma_f32_16x16x32_bf16 v[102:105], v[190:193], v[166:169], v[102:105]
	v_mfma_f32_16x16x32_bf16 v[94:97], v[202:205], v[166:169], v[94:97]
	v_mfma_f32_16x16x32_bf16 v[86:89], v[190:193], v[174:177], v[86:89]
	v_mfma_f32_16x16x32_bf16 v[78:81], v[202:205], v[174:177], v[78:81]
	v_mfma_f32_16x16x32_bf16 v[70:73], v[190:193], v[182:185], v[70:73]
	v_mfma_f32_16x16x32_bf16 v[66:69], v[202:205], v[182:185], v[66:69]
	s_setprio 0
	s_mov_b32 m0, s31
	v_lshl_add_u64 v[210:211], s[24:25], 0, v[48:49]
	s_barrier
	ds_read_b128 v[154:157], v244 offset:16384
	ds_read_b128 v[158:161], v244 offset:17408
	ds_read_b128 v[162:165], v244 offset:18432
	ds_read_b128 v[166:169], v244 offset:19456
	ds_read_b128 v[170:173], v244 offset:20480
	ds_read_b128 v[174:177], v244 offset:21504
	ds_read_b128 v[178:181], v244 offset:22528
	ds_read_b128 v[182:185], v244 offset:23552
	global_load_lds_dwordx4 v[210:211], off
	v_lshl_add_u64 v[212:213], s[24:25], 0, v[146:147]
	s_mov_b32 m0, s34
	s_nop 0
	global_load_lds_dwordx4 v[212:213], off
	s_barrier
	s_waitcnt lgkmcnt(0)
	s_setprio 1
	s_waitcnt lgkmcnt(0)
	v_mfma_f32_16x16x32_bf16 v[62:65], v[130:133], v[154:157], v[62:65]
	v_mfma_f32_16x16x32_bf16 v[58:61], v[138:141], v[154:157], v[58:61]
	v_mfma_f32_16x16x32_bf16 v[50:53], v[130:133], v[162:165], v[50:53]
	v_mfma_f32_16x16x32_bf16 v[40:43], v[138:141], v[162:165], v[40:43]
	v_mfma_f32_16x16x32_bf16 v[32:35], v[130:133], v[170:173], v[32:35]
	v_mfma_f32_16x16x32_bf16 v[24:27], v[138:141], v[170:173], v[24:27]
	v_mfma_f32_16x16x32_bf16 v[16:19], v[130:133], v[178:181], v[16:19]
	v_mfma_f32_16x16x32_bf16 v[8:11], v[138:141], v[178:181], v[8:11]
	v_mfma_f32_16x16x32_bf16 v[62:65], v[134:137], v[158:161], v[62:65]
	v_mfma_f32_16x16x32_bf16 v[58:61], v[142:145], v[158:161], v[58:61]
	v_mfma_f32_16x16x32_bf16 v[50:53], v[134:137], v[166:169], v[50:53]
	v_mfma_f32_16x16x32_bf16 v[40:43], v[142:145], v[166:169], v[40:43]
	v_mfma_f32_16x16x32_bf16 v[32:35], v[134:137], v[174:177], v[32:35]
	v_mfma_f32_16x16x32_bf16 v[24:27], v[142:145], v[174:177], v[24:27]
	v_mfma_f32_16x16x32_bf16 v[16:19], v[134:137], v[182:185], v[16:19]
	v_mfma_f32_16x16x32_bf16 v[8:11], v[142:145], v[182:185], v[8:11]
	s_setprio 0
	s_barrier
	s_add_u32 s18, s22, 0xb0000
	s_addc_u32 s19, s23, 0
	s_add_i32 s47, s48, s30
	v_lshl_add_u64 v[130:131], s[18:19], 0, v[48:49]
	s_mov_b32 m0, s47
	s_nop 0
	global_load_lds_dwordx4 v[130:131], off
	v_lshl_add_u64 v[130:131], s[18:19], 0, v[146:147]
	s_add_i32 m0, s47, 0x2000
	s_nop 0
	global_load_lds_dwordx4 v[130:131], off
	s_waitcnt vmcnt(6)
	s_barrier
	s_setprio 1
	v_mfma_f32_16x16x32_bf16 v[54:57], v[186:189], v[154:157], v[54:57]
	v_mfma_f32_16x16x32_bf16 v[44:47], v[198:201], v[154:157], v[44:47]
	v_mfma_f32_16x16x32_bf16 v[36:39], v[186:189], v[162:165], v[36:39]
	v_mfma_f32_16x16x32_bf16 v[28:31], v[198:201], v[162:165], v[28:31]
	v_mfma_f32_16x16x32_bf16 v[20:23], v[186:189], v[170:173], v[20:23]
	v_mfma_f32_16x16x32_bf16 v[12:15], v[198:201], v[170:173], v[12:15]
	v_mfma_f32_16x16x32_bf16 v[4:7], v[186:189], v[178:181], v[4:7]
	v_mfma_f32_16x16x32_bf16 v[0:3], v[198:201], v[178:181], v[0:3]
	v_mfma_f32_16x16x32_bf16 v[54:57], v[190:193], v[158:161], v[54:57]
	v_mfma_f32_16x16x32_bf16 v[44:47], v[202:205], v[158:161], v[44:47]
	v_mfma_f32_16x16x32_bf16 v[36:39], v[190:193], v[166:169], v[36:39]
	v_mfma_f32_16x16x32_bf16 v[28:31], v[202:205], v[166:169], v[28:31]
	v_mfma_f32_16x16x32_bf16 v[20:23], v[190:193], v[174:177], v[20:23]
	v_mfma_f32_16x16x32_bf16 v[12:15], v[202:205], v[174:177], v[12:15]
	v_mfma_f32_16x16x32_bf16 v[4:7], v[190:193], v[182:185], v[4:7]
	v_mfma_f32_16x16x32_bf16 v[0:3], v[202:205], v[182:185], v[0:3]
	s_setprio 0
	s_add_i32 s47, 0, 0x18000
	v_add_u32_e32 v142, s47, v242
	s_barrier
	ds_read_b128 v[130:133], v142
	ds_read_b128 v[134:137], v142 offset:1024
	ds_read_b128 v[138:141], v142 offset:2048
	ds_read_b128 v[142:145], v142 offset:3072
	s_add_u32 s18, s24, 0xb0000
	s_addc_u32 s19, s25, 0
	s_mov_b32 m0, s35
	v_lshl_add_u64 v[186:187], s[18:19], 0, v[48:49]
	ds_read_b128 v[154:157], v244 offset:32768
	ds_read_b128 v[158:161], v244 offset:33792
	ds_read_b128 v[162:165], v244 offset:34816
	ds_read_b128 v[166:169], v244 offset:35840
	ds_read_b128 v[170:173], v244 offset:36864
	ds_read_b128 v[174:177], v244 offset:37888
	ds_read_b128 v[178:181], v244 offset:38912
	ds_read_b128 v[182:185], v244 offset:39936
	global_load_lds_dwordx4 v[186:187], off
	v_lshl_add_u64 v[186:187], s[18:19], 0, v[146:147]
	s_mov_b32 m0, s36
	s_nop 0
	global_load_lds_dwordx4 v[186:187], off
	s_waitcnt lgkmcnt(8)
	s_barrier
	s_waitcnt lgkmcnt(0)
	s_setprio 1
	s_waitcnt lgkmcnt(0)
	v_mfma_f32_16x16x32_bf16 v[126:129], v[130:133], v[154:157], v[126:129]
	v_mfma_f32_16x16x32_bf16 v[122:125], v[138:141], v[154:157], v[122:125]
	v_mfma_f32_16x16x32_bf16 v[114:117], v[130:133], v[162:165], v[114:117]
	v_mfma_f32_16x16x32_bf16 v[106:109], v[138:141], v[162:165], v[106:109]
	v_mfma_f32_16x16x32_bf16 v[98:101], v[130:133], v[170:173], v[98:101]
	v_mfma_f32_16x16x32_bf16 v[90:93], v[138:141], v[170:173], v[90:93]
	v_mfma_f32_16x16x32_bf16 v[82:85], v[130:133], v[178:181], v[82:85]
	v_mfma_f32_16x16x32_bf16 v[74:77], v[138:141], v[178:181], v[74:77]
	v_mfma_f32_16x16x32_bf16 v[126:129], v[134:137], v[158:161], v[126:129]
	v_mfma_f32_16x16x32_bf16 v[122:125], v[142:145], v[158:161], v[122:125]
	v_mfma_f32_16x16x32_bf16 v[114:117], v[134:137], v[166:169], v[114:117]
	v_mfma_f32_16x16x32_bf16 v[106:109], v[142:145], v[166:169], v[106:109]
	v_mfma_f32_16x16x32_bf16 v[98:101], v[134:137], v[174:177], v[98:101]
	v_mfma_f32_16x16x32_bf16 v[90:93], v[142:145], v[174:177], v[90:93]
	v_mfma_f32_16x16x32_bf16 v[82:85], v[134:137], v[182:185], v[82:85]
	v_mfma_f32_16x16x32_bf16 v[74:77], v[142:145], v[182:185], v[74:77]
	s_setprio 0
	s_barrier
	s_add_i32 s24, 0, 0x1c000
	s_add_i32 s18, s47, s30
	v_add_u32_e32 v202, s24, v242
	v_lshl_add_u64 v[206:207], v[206:207], 0, s[66:67]
	s_mov_b32 m0, s18
	ds_read_b128 v[186:189], v202
	ds_read_b128 v[190:193], v202 offset:1024
	ds_read_b128 v[198:201], v202 offset:2048
	ds_read_b128 v[202:205], v202 offset:3072
	global_load_lds_dwordx4 v[206:207], off
	v_lshl_add_u64 v[206:207], v[208:209], 0, s[66:67]
	s_add_i32 m0, s18, 0x2000
	s_nop 0
	global_load_lds_dwordx4 v[206:207], off
	s_barrier
	s_waitcnt lgkmcnt(0)
	s_setprio 1
	s_waitcnt lgkmcnt(0)
	v_mfma_f32_16x16x32_bf16 v[118:121], v[186:189], v[154:157], v[118:121]
	v_mfma_f32_16x16x32_bf16 v[110:113], v[198:201], v[154:157], v[110:113]
	v_mfma_f32_16x16x32_bf16 v[102:105], v[186:189], v[162:165], v[102:105]
	v_mfma_f32_16x16x32_bf16 v[94:97], v[198:201], v[162:165], v[94:97]
	v_mfma_f32_16x16x32_bf16 v[86:89], v[186:189], v[170:173], v[86:89]
	v_mfma_f32_16x16x32_bf16 v[78:81], v[198:201], v[170:173], v[78:81]
	v_mfma_f32_16x16x32_bf16 v[70:73], v[186:189], v[178:181], v[70:73]
	v_mfma_f32_16x16x32_bf16 v[66:69], v[198:201], v[178:181], v[66:69]
	v_mfma_f32_16x16x32_bf16 v[118:121], v[190:193], v[158:161], v[118:121]
	v_mfma_f32_16x16x32_bf16 v[110:113], v[202:205], v[158:161], v[110:113]
	v_mfma_f32_16x16x32_bf16 v[102:105], v[190:193], v[166:169], v[102:105]
	v_mfma_f32_16x16x32_bf16 v[94:97], v[202:205], v[166:169], v[94:97]
	v_mfma_f32_16x16x32_bf16 v[86:89], v[190:193], v[174:177], v[86:89]
	v_mfma_f32_16x16x32_bf16 v[78:81], v[202:205], v[174:177], v[78:81]
	v_mfma_f32_16x16x32_bf16 v[70:73], v[190:193], v[182:185], v[70:73]
	v_mfma_f32_16x16x32_bf16 v[66:69], v[202:205], v[182:185], v[66:69]
	s_setprio 0
	s_mov_b32 m0, s39
	v_lshl_add_u64 v[206:207], v[210:211], 0, s[66:67]
	s_barrier
	ds_read_b128 v[154:157], v244 offset:49152
	ds_read_b128 v[158:161], v244 offset:50176
	ds_read_b128 v[162:165], v244 offset:51200
	ds_read_b128 v[166:169], v244 offset:52224
	ds_read_b128 v[170:173], v244 offset:53248
	ds_read_b128 v[174:177], v244 offset:54272
	ds_read_b128 v[178:181], v244 offset:55296
	ds_read_b128 v[182:185], v244 offset:56320
	global_load_lds_dwordx4 v[206:207], off
	v_lshl_add_u64 v[206:207], v[212:213], 0, s[66:67]
	s_mov_b32 m0, s40
	s_nop 0
	global_load_lds_dwordx4 v[206:207], off
	s_barrier
	s_waitcnt lgkmcnt(0)
	s_setprio 1
	s_waitcnt lgkmcnt(0)
	v_mfma_f32_16x16x32_bf16 v[62:65], v[130:133], v[154:157], v[62:65]
	v_mfma_f32_16x16x32_bf16 v[58:61], v[138:141], v[154:157], v[58:61]
	v_mfma_f32_16x16x32_bf16 v[50:53], v[130:133], v[162:165], v[50:53]
	v_mfma_f32_16x16x32_bf16 v[40:43], v[138:141], v[162:165], v[40:43]
	v_mfma_f32_16x16x32_bf16 v[32:35], v[130:133], v[170:173], v[32:35]
	v_mfma_f32_16x16x32_bf16 v[24:27], v[138:141], v[170:173], v[24:27]
	v_mfma_f32_16x16x32_bf16 v[16:19], v[130:133], v[178:181], v[16:19]
	v_mfma_f32_16x16x32_bf16 v[8:11], v[138:141], v[178:181], v[8:11]
	v_mfma_f32_16x16x32_bf16 v[62:65], v[134:137], v[158:161], v[62:65]
	v_mfma_f32_16x16x32_bf16 v[58:61], v[142:145], v[158:161], v[58:61]
	v_mfma_f32_16x16x32_bf16 v[50:53], v[134:137], v[166:169], v[50:53]
	v_mfma_f32_16x16x32_bf16 v[40:43], v[142:145], v[166:169], v[40:43]
	v_mfma_f32_16x16x32_bf16 v[32:35], v[134:137], v[174:177], v[32:35]
	v_mfma_f32_16x16x32_bf16 v[24:27], v[142:145], v[174:177], v[24:27]
	v_mfma_f32_16x16x32_bf16 v[16:19], v[134:137], v[182:185], v[16:19]
	v_mfma_f32_16x16x32_bf16 v[8:11], v[142:145], v[182:185], v[8:11]
	s_setprio 0
	s_barrier
	s_add_u32 s18, s22, 0xb0080
	s_addc_u32 s19, s23, 0
	s_add_i32 s22, s24, s30
	v_lshl_add_u64 v[130:131], s[18:19], 0, v[48:49]
	s_mov_b32 m0, s22
	s_nop 0
	global_load_lds_dwordx4 v[130:131], off
	v_lshl_add_u64 v[130:131], s[18:19], 0, v[146:147]
	s_add_i32 m0, s22, 0x2000
	s_nop 0
	global_load_lds_dwordx4 v[130:131], off
	s_waitcnt vmcnt(6)
	s_barrier
	s_setprio 1
	v_mfma_f32_16x16x32_bf16 v[54:57], v[186:189], v[154:157], v[54:57]
	v_mfma_f32_16x16x32_bf16 v[44:47], v[198:201], v[154:157], v[44:47]
	v_mfma_f32_16x16x32_bf16 v[36:39], v[186:189], v[162:165], v[36:39]
	v_mfma_f32_16x16x32_bf16 v[28:31], v[198:201], v[162:165], v[28:31]
	v_mfma_f32_16x16x32_bf16 v[20:23], v[186:189], v[170:173], v[20:23]
	v_mfma_f32_16x16x32_bf16 v[12:15], v[198:201], v[170:173], v[12:15]
	v_mfma_f32_16x16x32_bf16 v[4:7], v[186:189], v[178:181], v[4:7]
	v_mfma_f32_16x16x32_bf16 v[0:3], v[198:201], v[178:181], v[0:3]
	v_mfma_f32_16x16x32_bf16 v[54:57], v[190:193], v[158:161], v[54:57]
	v_mfma_f32_16x16x32_bf16 v[44:47], v[202:205], v[158:161], v[44:47]
	v_mfma_f32_16x16x32_bf16 v[36:39], v[190:193], v[166:169], v[36:39]
	v_mfma_f32_16x16x32_bf16 v[28:31], v[202:205], v[166:169], v[28:31]
	v_mfma_f32_16x16x32_bf16 v[20:23], v[190:193], v[174:177], v[20:23]
	v_mfma_f32_16x16x32_bf16 v[12:15], v[202:205], v[174:177], v[12:15]
	v_mfma_f32_16x16x32_bf16 v[4:7], v[190:193], v[182:185], v[4:7]
	v_mfma_f32_16x16x32_bf16 v[0:3], v[202:205], v[182:185], v[0:3]
	s_setprio 0
	s_add_i32 s46, s46, 2
	s_add_u32 s44, s44, 0x100
	s_addc_u32 s45, s45, 0
	s_cmp_gt_u32 s46, 41
	s_mov_b64 s[18:19], s[20:21]
	s_barrier
	s_cbranch_scc0 .LBB0_1435
	s_mul_hi_i32 s18, s16, 0x38e38e39
	s_lshr_b32 s19, s18, 31
	s_ashr_i32 s18, s18, 1
	s_add_i32 s18, s18, s19
	s_mul_i32 s19, s18, -9
	v_lshl_or_b32 v154, s17, 8, v243
	s_sub_i32 s17, 0, s16
	s_cmp_lg_u32 s19, s17
	s_cselect_b32 s17, s18, 32
	s_mul_hi_i32 s19, s17, 0x6000
	s_mulk_i32 s17, 0x6000
	s_add_u32 s18, s37, s17
	s_addc_u32 s19, s38, s19
	s_ashr_i32 s17, s16, 31
	s_lshl_b64 s[16:17], s[16:17], 18
	v_ashrrev_i32_e32 v155, 31, v154
	v_lshl_add_u64 v[156:157], s[16:17], 0, v[148:149]
	v_lshl_add_u64 v[130:131], v[154:155], 2, s[18:19]
	v_lshl_add_u64 v[154:155], v[156:157], 0, v[154:155]
	v_lshlrev_b64 v[184:185], 1, v[154:155]
	v_lshl_add_u64 v[154:155], s[10:11], 0, v[184:185]
	global_load_dwordx4 v[142:145], v[130:131], off
	global_load_dwordx4 v[138:141], v[130:131], off offset:64
	global_load_dwordx4 v[134:137], v[130:131], off offset:512
	s_nop 0
	global_load_dwordx4 v[130:133], v[130:131], off offset:576
	s_nop 0
	global_load_dwordx2 v[222:223], v[154:155], off
	global_load_dwordx2 v[220:221], v[154:155], off offset:32
	global_load_dwordx2 v[218:219], v[154:155], off offset:256
	global_load_dwordx2 v[216:217], v[154:155], off offset:288
	v_add_co_u32_e32 v156, vcc, s91, v154
	s_mov_b32 s16, 0x40000
	s_nop 0
	v_addc_co_u32_e32 v157, vcc, 0, v155, vcc
	global_load_dwordx2 v[214:215], v[156:157], off
	global_load_dwordx2 v[212:213], v[156:157], off offset:32
	global_load_dwordx2 v[210:211], v[156:157], off offset:256
	global_load_dwordx2 v[208:209], v[156:157], off offset:288
	v_add_co_u32_e32 v156, vcc, s89, v154
	s_mov_b32 s17, 0x48000
	s_nop 0
	v_addc_co_u32_e32 v157, vcc, 0, v155, vcc
	global_load_dwordx2 v[206:207], v[156:157], off
	global_load_dwordx2 v[204:205], v[156:157], off offset:32
	global_load_dwordx2 v[202:203], v[156:157], off offset:256
	global_load_dwordx2 v[200:201], v[156:157], off offset:288
	v_add_co_u32_e32 v156, vcc, s83, v154
	s_mov_b32 s18, 0x50000
	s_nop 0
	v_addc_co_u32_e32 v157, vcc, 0, v155, vcc
	global_load_dwordx2 v[198:199], v[156:157], off
	global_load_dwordx2 v[192:193], v[156:157], off offset:32
	global_load_dwordx2 v[190:191], v[156:157], off offset:256
	global_load_dwordx2 v[188:189], v[156:157], off offset:288
	v_add_co_u32_e32 v156, vcc, s16, v154
	s_mov_b32 s19, 0x58000
	s_nop 0
	v_addc_co_u32_e32 v157, vcc, 0, v155, vcc
	global_load_dwordx2 v[186:187], v[156:157], off
	global_load_dwordx2 v[182:183], v[156:157], off offset:32
	global_load_dwordx2 v[180:181], v[156:157], off offset:256
	global_load_dwordx2 v[178:179], v[156:157], off offset:288
	v_add_co_u32_e32 v156, vcc, s17, v154
	v_lshl_add_u64 v[184:185], s[6:7], 0, v[184:185]
	s_nop 0
	v_addc_co_u32_e32 v157, vcc, 0, v155, vcc
	global_load_dwordx2 v[176:177], v[156:157], off
	global_load_dwordx2 v[174:175], v[156:157], off offset:32
	global_load_dwordx2 v[172:173], v[156:157], off offset:256
	global_load_dwordx2 v[170:171], v[156:157], off offset:288
	v_add_co_u32_e32 v156, vcc, s18, v154
	s_mov_b64 s[20:21], s[14:15]
	s_nop 0
	v_addc_co_u32_e32 v157, vcc, 0, v155, vcc
	global_load_dwordx2 v[168:169], v[156:157], off
	global_load_dwordx2 v[166:167], v[156:157], off offset:32
	global_load_dwordx2 v[164:165], v[156:157], off offset:256
	global_load_dwordx2 v[162:163], v[156:157], off offset:288
	v_add_co_u32_e32 v154, vcc, s19, v154
	s_waitcnt vmcnt(0)
	v_lshlrev_b32_e32 v234, 16, v222
	v_and_b32_e32 v235, 0xffff0000, v222
	v_lshlrev_b32_e32 v222, 16, v223
	v_and_b32_e32 v223, 0xffff0000, v223
	v_pk_fma_f32 v[128:129], v[128:129], v[144:145], v[222:223]
	v_pk_fma_f32 v[126:127], v[126:127], v[142:143], v[234:235]
	v_addc_co_u32_e32 v155, vcc, 0, v155, vcc
	v_cvt_pk_bf16_f32 v126, v126, v127
	v_cvt_pk_bf16_f32 v127, v128, v129
	global_load_dwordx2 v[160:161], v[154:155], off
	global_load_dwordx2 v[158:159], v[154:155], off offset:32
	global_load_dwordx2 v[156:157], v[154:155], off offset:256
	s_nop 0
	global_load_dwordx2 v[154:155], v[154:155], off offset:288
	v_lshlrev_b32_e32 v128, 16, v221
	global_store_dwordx2 v[184:185], v[126:127], off
	v_lshlrev_b32_e32 v126, 16, v220
	v_and_b32_e32 v127, 0xffff0000, v220
	v_and_b32_e32 v129, 0xffff0000, v221
	v_pk_fma_f32 v[124:125], v[124:125], v[140:141], v[128:129]
	v_pk_fma_f32 v[122:123], v[122:123], v[138:139], v[126:127]
	s_nop 0
	v_cvt_pk_bf16_f32 v122, v122, v123
	v_cvt_pk_bf16_f32 v123, v124, v125
	global_store_dwordx2 v[184:185], v[122:123], off offset:32
	v_lshlrev_b32_e32 v122, 16, v218
	v_and_b32_e32 v123, 0xffff0000, v218
	v_lshlrev_b32_e32 v124, 16, v219
	v_and_b32_e32 v125, 0xffff0000, v219
	v_pk_fma_f32 v[120:121], v[120:121], v[136:137], v[124:125]
	v_pk_fma_f32 v[118:119], v[118:119], v[134:135], v[122:123]
	s_nop 0
	v_cvt_pk_bf16_f32 v118, v118, v119
	v_cvt_pk_bf16_f32 v119, v120, v121
	global_store_dwordx2 v[184:185], v[118:119], off offset:256
	v_lshlrev_b32_e32 v118, 16, v216
	v_and_b32_e32 v119, 0xffff0000, v216
	v_lshlrev_b32_e32 v120, 16, v217
	v_and_b32_e32 v121, 0xffff0000, v217
	v_pk_fma_f32 v[112:113], v[112:113], v[132:133], v[120:121]
	v_pk_fma_f32 v[110:111], v[110:111], v[130:131], v[118:119]
	s_nop 0
	v_cvt_pk_bf16_f32 v110, v110, v111
	v_cvt_pk_bf16_f32 v111, v112, v113
	global_store_dwordx2 v[184:185], v[110:111], off offset:288
	v_lshlrev_b32_e32 v110, 16, v214
	v_and_b32_e32 v111, 0xffff0000, v214
	v_lshlrev_b32_e32 v112, 16, v215
	v_and_b32_e32 v113, 0xffff0000, v215
	v_pk_fma_f32 v[112:113], v[116:117], v[144:145], v[112:113]
	v_pk_fma_f32 v[110:111], v[114:115], v[142:143], v[110:111]
	v_lshlrev_b32_e32 v114, 16, v213
	v_cvt_pk_bf16_f32 v110, v110, v111
	v_cvt_pk_bf16_f32 v111, v112, v113
	v_add_co_u32_e32 v112, vcc, s91, v184
	v_and_b32_e32 v115, 0xffff0000, v213
	s_nop 0
	v_addc_co_u32_e32 v113, vcc, 0, v185, vcc
	global_store_dwordx2 v[112:113], v[110:111], off
	v_lshlrev_b32_e32 v110, 16, v212
	v_and_b32_e32 v111, 0xffff0000, v212
	v_pk_fma_f32 v[108:109], v[108:109], v[140:141], v[114:115]
	v_pk_fma_f32 v[106:107], v[106:107], v[138:139], v[110:111]
	s_nop 0
	v_cvt_pk_bf16_f32 v106, v106, v107
	v_cvt_pk_bf16_f32 v107, v108, v109
	global_store_dwordx2 v[112:113], v[106:107], off offset:32
	v_lshlrev_b32_e32 v106, 16, v210
	v_and_b32_e32 v107, 0xffff0000, v210
	v_lshlrev_b32_e32 v108, 16, v211
	v_and_b32_e32 v109, 0xffff0000, v211
	v_pk_fma_f32 v[104:105], v[104:105], v[136:137], v[108:109]
	v_pk_fma_f32 v[102:103], v[102:103], v[134:135], v[106:107]
	s_nop 0
	v_cvt_pk_bf16_f32 v102, v102, v103
	v_cvt_pk_bf16_f32 v103, v104, v105
	global_store_dwordx2 v[112:113], v[102:103], off offset:256
	v_lshlrev_b32_e32 v102, 16, v208
	v_and_b32_e32 v103, 0xffff0000, v208
	v_lshlrev_b32_e32 v104, 16, v209
	v_and_b32_e32 v105, 0xffff0000, v209
	v_pk_fma_f32 v[96:97], v[96:97], v[132:133], v[104:105]
	v_pk_fma_f32 v[94:95], v[94:95], v[130:131], v[102:103]
	s_nop 0
	v_cvt_pk_bf16_f32 v94, v94, v95
	v_cvt_pk_bf16_f32 v95, v96, v97
	global_store_dwordx2 v[112:113], v[94:95], off offset:288
	v_lshlrev_b32_e32 v94, 16, v206
	v_and_b32_e32 v95, 0xffff0000, v206
	v_lshlrev_b32_e32 v96, 16, v207
	v_and_b32_e32 v97, 0xffff0000, v207
	v_pk_fma_f32 v[96:97], v[100:101], v[144:145], v[96:97]
	v_pk_fma_f32 v[94:95], v[98:99], v[142:143], v[94:95]
	v_lshlrev_b32_e32 v98, 16, v205
	v_cvt_pk_bf16_f32 v94, v94, v95
	v_cvt_pk_bf16_f32 v95, v96, v97
	v_add_co_u32_e32 v96, vcc, s89, v184
	v_and_b32_e32 v99, 0xffff0000, v205
	s_nop 0
	v_addc_co_u32_e32 v97, vcc, 0, v185, vcc
	global_store_dwordx2 v[96:97], v[94:95], off
	v_lshlrev_b32_e32 v94, 16, v204
	v_and_b32_e32 v95, 0xffff0000, v204
	v_pk_fma_f32 v[92:93], v[92:93], v[140:141], v[98:99]
	v_pk_fma_f32 v[90:91], v[90:91], v[138:139], v[94:95]
	s_nop 0
	v_cvt_pk_bf16_f32 v90, v90, v91
	v_cvt_pk_bf16_f32 v91, v92, v93
	global_store_dwordx2 v[96:97], v[90:91], off offset:32
	v_lshlrev_b32_e32 v90, 16, v202
	v_and_b32_e32 v91, 0xffff0000, v202
	v_lshlrev_b32_e32 v92, 16, v203
	v_and_b32_e32 v93, 0xffff0000, v203
	v_pk_fma_f32 v[88:89], v[88:89], v[136:137], v[92:93]
	v_pk_fma_f32 v[86:87], v[86:87], v[134:135], v[90:91]
	s_nop 0
	v_cvt_pk_bf16_f32 v86, v86, v87
	v_cvt_pk_bf16_f32 v87, v88, v89
	global_store_dwordx2 v[96:97], v[86:87], off offset:256
	v_lshlrev_b32_e32 v86, 16, v200
	v_and_b32_e32 v87, 0xffff0000, v200
	v_lshlrev_b32_e32 v88, 16, v201
	v_and_b32_e32 v89, 0xffff0000, v201
	v_pk_fma_f32 v[80:81], v[80:81], v[132:133], v[88:89]
	v_pk_fma_f32 v[78:79], v[78:79], v[130:131], v[86:87]
	s_nop 0
	v_cvt_pk_bf16_f32 v78, v78, v79
	v_cvt_pk_bf16_f32 v79, v80, v81
	global_store_dwordx2 v[96:97], v[78:79], off offset:288
	v_lshlrev_b32_e32 v78, 16, v198
	v_and_b32_e32 v79, 0xffff0000, v198
	v_lshlrev_b32_e32 v80, 16, v199
	v_and_b32_e32 v81, 0xffff0000, v199
	v_pk_fma_f32 v[80:81], v[84:85], v[144:145], v[80:81]
	v_pk_fma_f32 v[78:79], v[82:83], v[142:143], v[78:79]
	v_lshlrev_b32_e32 v82, 16, v193
	v_cvt_pk_bf16_f32 v78, v78, v79
	v_cvt_pk_bf16_f32 v79, v80, v81
	v_add_co_u32_e32 v80, vcc, s83, v184
	v_and_b32_e32 v83, 0xffff0000, v193
	s_nop 0
	v_addc_co_u32_e32 v81, vcc, 0, v185, vcc
	global_store_dwordx2 v[80:81], v[78:79], off
	v_lshlrev_b32_e32 v78, 16, v192
	v_and_b32_e32 v79, 0xffff0000, v192
	v_pk_fma_f32 v[76:77], v[76:77], v[140:141], v[82:83]
	v_pk_fma_f32 v[74:75], v[74:75], v[138:139], v[78:79]
	s_nop 0
	v_cvt_pk_bf16_f32 v74, v74, v75
	v_cvt_pk_bf16_f32 v75, v76, v77
	global_store_dwordx2 v[80:81], v[74:75], off offset:32
	v_lshlrev_b32_e32 v74, 16, v190
	v_and_b32_e32 v75, 0xffff0000, v190
	v_lshlrev_b32_e32 v76, 16, v191
	v_and_b32_e32 v77, 0xffff0000, v191
	v_pk_fma_f32 v[72:73], v[72:73], v[136:137], v[76:77]
	v_pk_fma_f32 v[70:71], v[70:71], v[134:135], v[74:75]
	s_nop 0
	v_cvt_pk_bf16_f32 v70, v70, v71
	v_cvt_pk_bf16_f32 v71, v72, v73
	global_store_dwordx2 v[80:81], v[70:71], off offset:256
	v_lshlrev_b32_e32 v70, 16, v188
	v_and_b32_e32 v71, 0xffff0000, v188
	v_lshlrev_b32_e32 v72, 16, v189
	v_and_b32_e32 v73, 0xffff0000, v189
	v_pk_fma_f32 v[68:69], v[68:69], v[132:133], v[72:73]
	v_pk_fma_f32 v[66:67], v[66:67], v[130:131], v[70:71]
	s_nop 0
	v_cvt_pk_bf16_f32 v66, v66, v67
	v_cvt_pk_bf16_f32 v67, v68, v69
	global_store_dwordx2 v[80:81], v[66:67], off offset:288
	v_lshlrev_b32_e32 v66, 16, v186
	v_and_b32_e32 v67, 0xffff0000, v186
	v_lshlrev_b32_e32 v68, 16, v187
	v_and_b32_e32 v69, 0xffff0000, v187
	v_pk_fma_f32 v[64:65], v[64:65], v[144:145], v[68:69]
	v_pk_fma_f32 v[62:63], v[62:63], v[142:143], v[66:67]
	v_lshlrev_b32_e32 v66, 16, v183
	v_cvt_pk_bf16_f32 v62, v62, v63
	v_cvt_pk_bf16_f32 v63, v64, v65
	v_add_co_u32_e32 v64, vcc, s16, v184
	v_and_b32_e32 v67, 0xffff0000, v183
	s_nop 0
	v_addc_co_u32_e32 v65, vcc, 0, v185, vcc
	global_store_dwordx2 v[64:65], v[62:63], off
	v_lshlrev_b32_e32 v62, 16, v182
	v_and_b32_e32 v63, 0xffff0000, v182
	v_pk_fma_f32 v[60:61], v[60:61], v[140:141], v[66:67]
	v_pk_fma_f32 v[58:59], v[58:59], v[138:139], v[62:63]
	s_mov_b32 s16, s43
	v_cvt_pk_bf16_f32 v58, v58, v59
	v_cvt_pk_bf16_f32 v59, v60, v61
	global_store_dwordx2 v[64:65], v[58:59], off offset:32
	v_lshlrev_b32_e32 v58, 16, v180
	v_and_b32_e32 v59, 0xffff0000, v180
	v_lshlrev_b32_e32 v60, 16, v181
	v_and_b32_e32 v61, 0xffff0000, v181
	v_pk_fma_f32 v[56:57], v[56:57], v[136:137], v[60:61]
	v_pk_fma_f32 v[54:55], v[54:55], v[134:135], v[58:59]
	s_nop 0
	v_cvt_pk_bf16_f32 v54, v54, v55
	v_cvt_pk_bf16_f32 v55, v56, v57
	global_store_dwordx2 v[64:65], v[54:55], off offset:256
	v_lshlrev_b32_e32 v54, 16, v178
	v_and_b32_e32 v55, 0xffff0000, v178
	v_lshlrev_b32_e32 v56, 16, v179
	v_and_b32_e32 v57, 0xffff0000, v179
	v_pk_fma_f32 v[46:47], v[46:47], v[132:133], v[56:57]
	v_pk_fma_f32 v[44:45], v[44:45], v[130:131], v[54:55]
	s_nop 0
	v_cvt_pk_bf16_f32 v44, v44, v45
	v_cvt_pk_bf16_f32 v45, v46, v47
	global_store_dwordx2 v[64:65], v[44:45], off offset:288
	v_lshlrev_b32_e32 v44, 16, v176
	v_and_b32_e32 v45, 0xffff0000, v176
	v_lshlrev_b32_e32 v46, 16, v177
	v_and_b32_e32 v47, 0xffff0000, v177
	v_pk_fma_f32 v[46:47], v[52:53], v[144:145], v[46:47]
	v_pk_fma_f32 v[44:45], v[50:51], v[142:143], v[44:45]
	v_lshlrev_b32_e32 v50, 16, v175
	v_cvt_pk_bf16_f32 v44, v44, v45
	v_cvt_pk_bf16_f32 v45, v46, v47
	v_add_co_u32_e32 v46, vcc, s17, v184
	v_and_b32_e32 v51, 0xffff0000, v175
	s_nop 0
	v_addc_co_u32_e32 v47, vcc, 0, v185, vcc
	global_store_dwordx2 v[46:47], v[44:45], off
	v_lshlrev_b32_e32 v44, 16, v174
	v_and_b32_e32 v45, 0xffff0000, v174
	v_pk_fma_f32 v[42:43], v[42:43], v[140:141], v[50:51]
	v_pk_fma_f32 v[40:41], v[40:41], v[138:139], v[44:45]
	s_mov_b32 s17, s42
	v_cvt_pk_bf16_f32 v40, v40, v41
	v_cvt_pk_bf16_f32 v41, v42, v43
	global_store_dwordx2 v[46:47], v[40:41], off offset:32
	v_lshlrev_b32_e32 v40, 16, v172
	v_and_b32_e32 v41, 0xffff0000, v172
	v_lshlrev_b32_e32 v42, 16, v173
	v_and_b32_e32 v43, 0xffff0000, v173
	v_pk_fma_f32 v[38:39], v[38:39], v[136:137], v[42:43]
	v_pk_fma_f32 v[36:37], v[36:37], v[134:135], v[40:41]
	s_nop 0
	v_cvt_pk_bf16_f32 v36, v36, v37
	v_cvt_pk_bf16_f32 v37, v38, v39
	global_store_dwordx2 v[46:47], v[36:37], off offset:256
	v_lshlrev_b32_e32 v36, 16, v170
	v_and_b32_e32 v37, 0xffff0000, v170
	v_lshlrev_b32_e32 v38, 16, v171
	v_and_b32_e32 v39, 0xffff0000, v171
	v_pk_fma_f32 v[30:31], v[30:31], v[132:133], v[38:39]
	v_pk_fma_f32 v[28:29], v[28:29], v[130:131], v[36:37]
	s_nop 0
	v_cvt_pk_bf16_f32 v28, v28, v29
	v_cvt_pk_bf16_f32 v29, v30, v31
	global_store_dwordx2 v[46:47], v[28:29], off offset:288
	v_lshlrev_b32_e32 v28, 16, v168
	v_and_b32_e32 v29, 0xffff0000, v168
	v_lshlrev_b32_e32 v30, 16, v169
	v_and_b32_e32 v31, 0xffff0000, v169
	v_pk_fma_f32 v[30:31], v[34:35], v[144:145], v[30:31]
	v_pk_fma_f32 v[28:29], v[32:33], v[142:143], v[28:29]
	v_lshlrev_b32_e32 v32, 16, v167
	v_cvt_pk_bf16_f32 v28, v28, v29
	v_cvt_pk_bf16_f32 v29, v30, v31
	v_add_co_u32_e32 v30, vcc, s18, v184
	v_and_b32_e32 v33, 0xffff0000, v167
	s_nop 0
	v_addc_co_u32_e32 v31, vcc, 0, v185, vcc
	global_store_dwordx2 v[30:31], v[28:29], off
	v_lshlrev_b32_e32 v28, 16, v166
	v_and_b32_e32 v29, 0xffff0000, v166
	v_pk_fma_f32 v[26:27], v[26:27], v[140:141], v[32:33]
	v_pk_fma_f32 v[24:25], v[24:25], v[138:139], v[28:29]
	s_nop 0
	v_cvt_pk_bf16_f32 v24, v24, v25
	v_cvt_pk_bf16_f32 v25, v26, v27
	global_store_dwordx2 v[30:31], v[24:25], off offset:32
	v_lshlrev_b32_e32 v24, 16, v164
	v_and_b32_e32 v25, 0xffff0000, v164
	v_lshlrev_b32_e32 v26, 16, v165
	v_and_b32_e32 v27, 0xffff0000, v165
	v_pk_fma_f32 v[22:23], v[22:23], v[136:137], v[26:27]
	v_pk_fma_f32 v[20:21], v[20:21], v[134:135], v[24:25]
	s_nop 0
	v_cvt_pk_bf16_f32 v20, v20, v21
	v_cvt_pk_bf16_f32 v21, v22, v23
	global_store_dwordx2 v[30:31], v[20:21], off offset:256
	v_lshlrev_b32_e32 v20, 16, v162
	v_and_b32_e32 v21, 0xffff0000, v162
	v_lshlrev_b32_e32 v22, 16, v163
	v_and_b32_e32 v23, 0xffff0000, v163
	v_pk_fma_f32 v[14:15], v[14:15], v[132:133], v[22:23]
	v_pk_fma_f32 v[12:13], v[12:13], v[130:131], v[20:21]
	s_nop 0
	v_cvt_pk_bf16_f32 v12, v12, v13
	v_cvt_pk_bf16_f32 v13, v14, v15
	global_store_dwordx2 v[30:31], v[12:13], off offset:288
	s_waitcnt vmcnt(28)
	v_lshlrev_b32_e32 v12, 16, v160
	v_and_b32_e32 v13, 0xffff0000, v160
	v_lshlrev_b32_e32 v14, 16, v161
	v_and_b32_e32 v15, 0xffff0000, v161
	v_pk_fma_f32 v[14:15], v[18:19], v[144:145], v[14:15]
	v_pk_fma_f32 v[12:13], v[16:17], v[142:143], v[12:13]
	v_lshlrev_b32_e32 v16, 16, v159
	v_cvt_pk_bf16_f32 v12, v12, v13
	v_cvt_pk_bf16_f32 v13, v14, v15
	v_add_co_u32_e32 v14, vcc, s19, v184
	v_and_b32_e32 v17, 0xffff0000, v159
	s_nop 0
	v_addc_co_u32_e32 v15, vcc, 0, v185, vcc
	global_store_dwordx2 v[14:15], v[12:13], off
	v_lshlrev_b32_e32 v12, 16, v158
	v_and_b32_e32 v13, 0xffff0000, v158
	v_pk_fma_f32 v[10:11], v[10:11], v[140:141], v[16:17]
	v_pk_fma_f32 v[8:9], v[8:9], v[138:139], v[12:13]
	s_and_b64 vcc, exec, s[0:1]
	v_cvt_pk_bf16_f32 v8, v8, v9
	v_cvt_pk_bf16_f32 v9, v10, v11
	global_store_dwordx2 v[14:15], v[8:9], off offset:32
	v_lshlrev_b32_e32 v8, 16, v156
	v_and_b32_e32 v9, 0xffff0000, v156
	v_lshlrev_b32_e32 v10, 16, v157
	v_and_b32_e32 v11, 0xffff0000, v157
	v_pk_fma_f32 v[6:7], v[6:7], v[136:137], v[10:11]
	v_pk_fma_f32 v[4:5], v[4:5], v[134:135], v[8:9]
	s_mov_b64 s[18:19], s[12:13]
	v_cvt_pk_bf16_f32 v4, v4, v5
	v_cvt_pk_bf16_f32 v5, v6, v7
	global_store_dwordx2 v[14:15], v[4:5], off offset:256
	v_lshlrev_b32_e32 v4, 16, v154
	v_and_b32_e32 v5, 0xffff0000, v154
	v_lshlrev_b32_e32 v6, 16, v155
	v_and_b32_e32 v7, 0xffff0000, v155
	v_pk_fma_f32 v[2:3], v[2:3], v[132:133], v[6:7]
	v_pk_fma_f32 v[0:1], v[0:1], v[130:131], v[4:5]
	s_nop 0
	v_cvt_pk_bf16_f32 v0, v0, v1
	v_cvt_pk_bf16_f32 v1, v2, v3
	global_store_dwordx2 v[14:15], v[0:1], off offset:288
	s_cbranch_vccz .LBB0_1432
	s_waitcnt vmcnt(0)
	s_cmpk_gt_u32 s29, 0xff
	s_cbranch_scc1 .LBB0_1439
	s_barrier
